# combo17: combo11 with the GEMM K-loops' per-segment s_setprio toggling replaced by one static s_setprio 1 for waves 4-7 per GEMM phase
# baseline (speedup 1.0000x reference)
; #define LAS __attribute__((address_space(3)))
; #define K_TID ((wave_s << 6) | lane_fresh())
; __device__ __forceinline__ void scan_unit(const float* logf, float* F2, int bh, LAS double* sd, int tid) {
;     const int b = bh / 6, h = bh % 6;
;     const float* src = logf + (size_t)b * SEQ * 6 + h;
;     double loc[8]; double run = 0.0;
; #pragma unroll
;     for (int i = 0; i < 8; ++i) { run += (double)src[(size_t)(8 * tid + i) * 6]; loc[i] = run; }
;     sd[tid] = run;
;     __syncthreads();
;     if (tid < 64) {
;         double v[8], tot = 0.0;
; #pragma unroll
;         for (int k = 0; k < 8; ++k) { v[k] = tot; tot += sd[8 * tid + k]; }
;         double inc = tot;
; #pragma unroll
;         for (int o = 1; o < 64; o <<= 1) {
;             const int src = (tid >= o) ? tid - o : tid;
;             const unsigned long long u_ = __builtin_bit_cast(unsigned long long, inc);
;             const unsigned lo_ = (unsigned)__builtin_amdgcn_ds_bpermute(src << 2, (int)(unsigned)u_), hi_ = (unsigned)__builtin_amdgcn_ds_bpermute(src << 2, (int)(unsigned)(u_ >> 32));
;             const double up = __builtin_bit_cast(double, ((unsigned long long)hi_ << 32) | lo_);
;             if (tid >= o) inc += up;
;         }
;         const double base = inc - tot;
; #pragma unroll
;         for (int k = 0; k < 8; ++k) sd[8 * tid + k] = base + v[k];
; __global__ void __launch_bounds__(512, 2) fwd_megakernel(Args a) {
;     ...
;             if (bx < 48) { int tid_l = K_TID, bh_l = bx; asm volatile("" : "+v"(tid_l), "+s"(bh_l)); scan_unit(P_LOGF, P_F2, bh_l, (LAS double*)lds, tid_l); }
.LBB0_238:
	s_or_b64 exec, exec, s[4:5]
	s_cmp_lt_i32 s74, 48
	s_cselect_b64 s[0:1], -1, 0
	v_writelane_b32 v251, s0, 3
	s_cmp_gt_i32 s74, 47
	s_waitcnt lgkmcnt(0)
	s_barrier
	s_cselect_b32 s98, 1, 0
	s_cmp_ge_u32 s82, 0x100
	s_cbranch_scc0 .Lprio_skip_11
	s_setprio 1
.Lprio_skip_11:
	s_cmp_lg_u32 s98, 0
	v_writelane_b32 v251, s1, 4
	s_cbranch_scc1 .LBB0_242
	s_mov_b32 s0, -1
	s_mov_b32 s6, s74
	v_mbcnt_lo_u32_b32 v0, s0, 0
	v_mbcnt_hi_u32_b32 v0, s0, v0
	s_mov_b64 s[0:1], s[46:47]
	v_or_b32_e32 v18, s82, v0
	s_load_dwordx2 s[0:1], s[0:1], 0x98
	s_mul_hi_i32 s4, s6, 0x2aaaaaab
	s_lshr_b32 s5, s4, 31
	s_add_i32 s5, s4, s5
	s_mul_i32 s4, s5, 6
	s_sub_i32 s4, s6, s4
	v_mov_b32_e32 v2, 0x18000
	s_waitcnt lgkmcnt(0)
	v_mov_b64_e32 v[0:1], s[0:1]
	v_mad_i64_i32 v[0:1], s[0:1], s5, v2, v[0:1]
	s_ashr_i32 s5, s4, 31
	s_lshl_b64 s[0:1], s[4:5], 2
	v_lshl_add_u64 v[0:1], v[0:1], 0, s[0:1]
	s_mov_b64 s[0:1], 0x17804000
	v_lshl_add_u64 v[2:3], v[0:1], 0, s[0:1]
	v_lshlrev_b32_e32 v0, 3, v18
	v_or_b32_e32 v1, 1, v0
	v_mad_i64_i32 v[6:7], s[0:1], v1, 24, v[2:3]
	v_or_b32_e32 v1, 2, v0
	v_mad_i64_i32 v[8:9], s[0:1], v1, 24, v[2:3]
	v_or_b32_e32 v1, 3, v0
	v_mad_i64_i32 v[10:11], s[0:1], v1, 24, v[2:3]
	v_or_b32_e32 v1, 4, v0
	v_mad_i64_i32 v[12:13], s[0:1], v1, 24, v[2:3]
	v_or_b32_e32 v1, 5, v0
	v_mad_i64_i32 v[14:15], s[0:1], v1, 24, v[2:3]
	v_or_b32_e32 v1, 6, v0
	s_mov_b64 s[2:3], s[46:47]
	v_mad_i64_i32 v[4:5], s[0:1], v0, 24, v[2:3]
	v_mad_i64_i32 v[16:17], s[0:1], v1, 24, v[2:3]
	v_or_b32_e32 v1, 7, v0
	v_mad_i64_i32 v[2:3], s[0:1], v1, 24, v[2:3]
	global_load_dword v19, v[4:5], off
	global_load_dword v20, v[6:7], off
	global_load_dword v21, v[8:9], off
	global_load_dword v22, v[10:11], off
	global_load_dword v23, v[12:13], off
	global_load_dword v24, v[14:15], off
	global_load_dword v25, v[16:17], off
	global_load_dword v26, v[2:3], off
	s_load_dwordx2 s[0:1], s[2:3], 0x98
	v_ashrrev_i32_e32 v1, 31, v0
	v_cmp_gt_i32_e32 vcc, 64, v18
	s_waitcnt vmcnt(7)
	v_cvt_f64_f32_e32 v[2:3], v19
	s_waitcnt vmcnt(6)
	v_cvt_f64_f32_e32 v[4:5], v20
	v_add_f64 v[14:15], v[2:3], 0
	s_waitcnt vmcnt(5)
	v_cvt_f64_f32_e32 v[6:7], v21
	v_add_f64 v[16:17], v[14:15], v[4:5]
	s_waitcnt vmcnt(4)
	v_cvt_f64_f32_e32 v[8:9], v22
	v_add_f64 v[10:11], v[16:17], v[6:7]
	s_waitcnt vmcnt(3)
	v_cvt_f64_f32_e32 v[20:21], v23
	v_add_f64 v[12:13], v[10:11], v[8:9]
	s_waitcnt vmcnt(2)
	v_cvt_f64_f32_e32 v[22:23], v24
	v_add_f64 v[6:7], v[12:13], v[20:21]
	s_waitcnt vmcnt(1)
	v_cvt_f64_f32_e32 v[24:25], v25
	v_add_f64 v[8:9], v[6:7], v[22:23]
	s_waitcnt vmcnt(0)
	v_cvt_f64_f32_e32 v[26:27], v26
	v_add_f64 v[2:3], v[8:9], v[24:25]
	v_add_f64 v[4:5], v[2:3], v[26:27]
	ds_write_b64 v0, v[4:5]
	s_waitcnt lgkmcnt(0)
	s_barrier
	s_and_saveexec_b64 s[8:9], vcc
	s_cbranch_execz .LBB0_241
	v_lshlrev_b32_e32 v40, 6, v18
	ds_read_b128 v[20:23], v40
	ds_read_b128 v[24:27], v40 offset:16
	ds_read_b128 v[28:31], v40 offset:32
	ds_read_b128 v[32:35], v40 offset:48
	v_cmp_lt_i32_e32 vcc, 0, v18
	s_waitcnt lgkmcnt(3)
	v_add_f64 v[20:21], v[20:21], 0
	v_add_f64 v[22:23], v[20:21], v[22:23]
	s_waitcnt lgkmcnt(2)
	v_add_f64 v[24:25], v[22:23], v[24:25]
	v_add_f64 v[26:27], v[24:25], v[26:27]
	s_waitcnt lgkmcnt(1)
	v_add_f64 v[28:29], v[26:27], v[28:29]
	v_add_f64 v[30:31], v[28:29], v[30:31]
	s_waitcnt lgkmcnt(0)
	v_add_f64 v[32:33], v[30:31], v[32:33]
	v_subbrev_co_u32_e64 v19, s[4:5], 0, v18, vcc
	v_add_f64 v[34:35], v[32:33], v[34:35]
	v_lshlrev_b32_e32 v19, 2, v19
	ds_bpermute_b32 v36, v19, v34
	ds_bpermute_b32 v37, v19, v35
	v_mov_b32_e32 v19, 0x3ffffffe
	s_waitcnt lgkmcnt(0)
	v_add_f64 v[36:37], v[34:35], v[36:37]
	v_cndmask_b32_e32 v37, v35, v37, vcc
	v_cndmask_b32_e32 v36, v34, v36, vcc
	v_cmp_gt_i32_e32 vcc, 2, v18
	s_nop 1
	v_cndmask_b32_e64 v19, v19, 0, vcc
	v_add_lshl_u32 v19, v19, v18, 2
	ds_bpermute_b32 v38, v19, v36
	ds_bpermute_b32 v39, v19, v37
	v_mov_b32_e32 v19, 0x3ffffffc
	s_waitcnt lgkmcnt(0)
	v_add_f64 v[38:39], v[36:37], v[38:39]
	v_cndmask_b32_e32 v37, v39, v37, vcc
	v_cndmask_b32_e32 v36, v38, v36, vcc
	v_cmp_gt_i32_e32 vcc, 4, v18
	s_nop 1
	v_cndmask_b32_e64 v19, v19, 0, vcc
	v_add_lshl_u32 v19, v19, v18, 2
	ds_bpermute_b32 v38, v19, v36
	ds_bpermute_b32 v39, v19, v37
	v_mov_b32_e32 v19, 0x3ffffff8
	s_waitcnt lgkmcnt(0)
	v_add_f64 v[38:39], v[36:37], v[38:39]
	v_cndmask_b32_e32 v37, v39, v37, vcc
	v_cndmask_b32_e32 v36, v38, v36, vcc
	v_cmp_gt_i32_e32 vcc, 8, v18
	s_nop 1
	v_cndmask_b32_e64 v19, v19, 0, vcc
	v_add_lshl_u32 v19, v19, v18, 2
	ds_bpermute_b32 v38, v19, v36
	ds_bpermute_b32 v39, v19, v37
	v_mov_b32_e32 v19, 0x3ffffff0
	s_waitcnt lgkmcnt(0)
	v_add_f64 v[38:39], v[36:37], v[38:39]
	v_cndmask_b32_e32 v37, v39, v37, vcc
	v_cndmask_b32_e32 v36, v38, v36, vcc
	v_cmp_gt_i32_e32 vcc, 16, v18
	s_nop 1
	v_cndmask_b32_e64 v19, v19, 0, vcc
	v_add_lshl_u32 v19, v19, v18, 2
	ds_bpermute_b32 v38, v19, v36
	ds_bpermute_b32 v39, v19, v37
	v_mov_b32_e32 v19, 0x3fffffe0
	s_waitcnt lgkmcnt(0)
	v_add_f64 v[38:39], v[36:37], v[38:39]
	v_cndmask_b32_e32 v37, v39, v37, vcc
	v_cndmask_b32_e32 v36, v38, v36, vcc
	v_cmp_gt_i32_e32 vcc, 32, v18
	s_nop 1
	v_cndmask_b32_e64 v19, v19, 0, vcc
	v_add_lshl_u32 v19, v19, v18, 2
	ds_bpermute_b32 v18, v19, v36
	ds_bpermute_b32 v19, v19, v37
	s_waitcnt lgkmcnt(0)
	v_add_f64 v[18:19], v[36:37], v[18:19]
	v_cndmask_b32_e32 v19, v19, v37, vcc
	v_cndmask_b32_e32 v18, v18, v36, vcc
	v_add_f64 v[34:35], v[18:19], -v[34:35]
	v_add_f64 v[18:19], v[34:35], 0
	v_add_f64 v[20:21], v[20:21], v[34:35]
	ds_write_b128 v40, v[18:21]
	v_add_f64 v[18:19], v[22:23], v[34:35]
	v_add_f64 v[20:21], v[24:25], v[34:35]
	ds_write_b128 v40, v[18:21] offset:16
	v_add_f64 v[18:19], v[26:27], v[34:35]
	v_add_f64 v[20:21], v[28:29], v[34:35]
	ds_write_b128 v40, v[18:21] offset:32
	v_add_f64 v[18:19], v[30:31], v[34:35]
	v_add_f64 v[20:21], v[32:33], v[34:35]
	ds_write_b128 v40, v[18:21] offset:48

; #define PG8_STAGE(bufoff, gbase, voff) do { _Pragma("unroll") for (int _i = 0; _i < 2; ++_i) \
;         __builtin_amdgcn_global_load_lds((const unsigned*)((const char*)(gbase) + (voff)[_i]), (PG8_LAS unsigned*)(lds + (bufoff) + ldsw + _i * 8192), 16, 0, 0); } while (0)
; #define PG8_LDA(dst, b, h) do { _Pragma("unroll") for (int m = 0; m < 4; ++m) _Pragma("unroll") for (int k = 0; k < 2; ++k) dst[m][k] = *(const PG8_LAS bf16x8*)(lds + PG8_SA(b, h) + aoff + m * 2048 + k * 1024); } while (0)
; #define PG8_LDB(dst, b, h) do { _Pragma("unroll") for (int n = 0; n < 2; ++n) _Pragma("unroll") for (int k = 0; k < 2; ++k) dst[n][k] = *(const PG8_LAS bf16x8*)(lds + PG8_SB(b, h) + boff + n * 2048 + k * 1024); } while (0)
; #define PG8_MMA(ai, bj, At, Bt) do { __builtin_amdgcn_s_setprio(1); _Pragma("unroll") for (int m = 0; m < 4; ++m) _Pragma("unroll") for (int n = 0; n < 2; ++n) _Pragma("unroll") for (int k = 0; k < 2; ++k) \
;         acc[ai][bj][m][n] = __builtin_amdgcn_mfma_f32_16x16x32_bf16(Bt[n][k], At[m][k], acc[ai][bj][m][n], 0, 0, 0); __builtin_amdgcn_s_setprio(0); } while (0)
; #define PG8_WAIT_V(n) asm volatile("s_waitcnt vmcnt(" #n ")" ::: "memory")
; #define PG8_WAIT_L(n) asm volatile("s_waitcnt lgkmcnt(" #n ")" ::: "memory")
; #define PG8_BAR __builtin_amdgcn_s_barrier()
; #define PG8_SCHED __builtin_amdgcn_sched_barrier(0)
; template <class Epi, class Sched, bool ALIGN_EPI = false, bool SP2 = false>
; __device__ __forceinline__ void gemm_phase(PG8_LAS unsigned char* lds, const Gemm g, const Sched& S, const Epi& E, const int tid_arg) {
;     ...
;             PG8_LDB(B0, 0, 0); PG8_LDB(B1, 0, 1); PG8_SCHED; PG8_LDA(At, 0, 0); PG8_STAGE(PG8_SA(1, 1), a1 + hstep, voffA);
;             PG8_WAIT_V(8); PG8_WAIT_L(0); PG8_BAR; PG8_MMA(0, 0, At, B0); PG8_MMA(0, 1, At, B1); PG8_BAR; PG8_SCHED;
;             PG8_LDA(At, 0, 1); PG8_STAGE(PG8_SB(0, 0), b2, voffB); PG8_STAGE(PG8_SB(0, 1), b2 + hstep, voffB); PG8_STAGE(PG8_SA(0, 0), a2, voffA);
;             PG8_WAIT_V(8); PG8_WAIT_L(0); PG8_BAR; PG8_MMA(1, 0, At, B0); PG8_MMA(1, 1, At, B1); PG8_BAR; PG8_SCHED;
.LBB0_253:
	ds_read_b128 v[144:147], v166
	ds_read_b128 v[148:151], v167
	ds_read_b128 v[152:155], v168
	ds_read_b128 v[156:159], v169
	ds_read_b128 v[184:187], v170
	ds_read_b128 v[188:191], v171
	ds_read_b128 v[192:195], v172
	ds_read_b128 v[196:199], v173
	s_add_u32 s0, s8, 0xfffc0080
	s_addc_u32 s1, s9, -1
	s_cmp_eq_u32 s70, 12
	s_cselect_b32 s35, s23, s1
	s_cselect_b32 s34, s36, s0
	s_cselect_b32 s1, s21, s69
	s_cselect_b32 s0, s37, s68
	s_mov_b32 m0, s57
	v_lshl_add_u64 v[160:161], s[8:9], 0, v[138:139]
	ds_read_b128 v[200:203], v165
	ds_read_b128 v[204:207], v165 offset:1024
	ds_read_b128 v[208:211], v165 offset:2048
	ds_read_b128 v[212:215], v165 offset:3072
	ds_read_b128 v[216:219], v165 offset:4096
	ds_read_b128 v[220:223], v165 offset:5120
	ds_read_b128 v[224:227], v165 offset:6144
	ds_read_b128 v[228:231], v165 offset:7168
	global_load_lds_dwordx4 v[160:161], off
	v_lshl_add_u64 v[160:161], s[8:9], 0, v[136:137]
	s_mov_b32 m0, s58
	s_nop 0
	global_load_lds_dwordx4 v[160:161], off
	s_waitcnt vmcnt(8)
	s_waitcnt lgkmcnt(0)
	s_barrier
	v_mfma_f32_16x16x32_bf16 v[124:127], v[144:147], v[200:203], v[124:127]
	v_mfma_f32_16x16x32_bf16 v[120:123], v[152:155], v[200:203], v[120:123]
	v_mfma_f32_16x16x32_bf16 v[108:111], v[144:147], v[208:211], v[108:111]
	v_mfma_f32_16x16x32_bf16 v[104:107], v[152:155], v[208:211], v[104:107]
	v_mfma_f32_16x16x32_bf16 v[92:95], v[144:147], v[216:219], v[92:95]
	v_mfma_f32_16x16x32_bf16 v[88:91], v[152:155], v[216:219], v[88:91]
	v_mfma_f32_16x16x32_bf16 v[76:79], v[144:147], v[224:227], v[76:79]
	v_mfma_f32_16x16x32_bf16 v[72:75], v[152:155], v[224:227], v[72:75]
	v_mfma_f32_16x16x32_bf16 v[124:127], v[148:151], v[204:207], v[124:127]
	v_mfma_f32_16x16x32_bf16 v[120:123], v[156:159], v[204:207], v[120:123]
	v_mfma_f32_16x16x32_bf16 v[108:111], v[148:151], v[212:215], v[108:111]
	v_mfma_f32_16x16x32_bf16 v[104:107], v[156:159], v[212:215], v[104:107]
	v_mfma_f32_16x16x32_bf16 v[92:95], v[148:151], v[220:223], v[92:95]
	v_mfma_f32_16x16x32_bf16 v[88:91], v[156:159], v[220:223], v[88:91]
	v_mfma_f32_16x16x32_bf16 v[76:79], v[148:151], v[228:231], v[76:79]
	v_mfma_f32_16x16x32_bf16 v[72:75], v[156:159], v[228:231], v[72:75]
	v_mfma_f32_16x16x32_bf16 v[116:119], v[184:187], v[200:203], v[116:119]
	v_mfma_f32_16x16x32_bf16 v[112:115], v[192:195], v[200:203], v[112:115]
	v_mfma_f32_16x16x32_bf16 v[100:103], v[184:187], v[208:211], v[100:103]
	v_mfma_f32_16x16x32_bf16 v[96:99], v[192:195], v[208:211], v[96:99]
	v_mfma_f32_16x16x32_bf16 v[84:87], v[184:187], v[216:219], v[84:87]
	v_mfma_f32_16x16x32_bf16 v[80:83], v[192:195], v[216:219], v[80:83]
	v_mfma_f32_16x16x32_bf16 v[68:71], v[184:187], v[224:227], v[68:71]
	v_mfma_f32_16x16x32_bf16 v[64:67], v[192:195], v[224:227], v[64:67]
	v_mfma_f32_16x16x32_bf16 v[116:119], v[188:191], v[204:207], v[116:119]
	v_mfma_f32_16x16x32_bf16 v[112:115], v[196:199], v[204:207], v[112:115]
	v_mfma_f32_16x16x32_bf16 v[100:103], v[188:191], v[212:215], v[100:103]
	v_mfma_f32_16x16x32_bf16 v[96:99], v[196:199], v[212:215], v[96:99]
	v_mfma_f32_16x16x32_bf16 v[84:87], v[188:191], v[220:223], v[84:87]
	v_mfma_f32_16x16x32_bf16 v[80:83], v[196:199], v[220:223], v[80:83]
	v_mfma_f32_16x16x32_bf16 v[68:71], v[188:191], v[228:231], v[68:71]
	v_mfma_f32_16x16x32_bf16 v[64:67], v[196:199], v[228:231], v[64:67]
	s_barrier
	s_mov_b32 m0, s29
	v_lshl_add_u64 v[160:161], s[0:1], 0, v[130:131]
	s_add_u32 s72, s0, 0x40000
	ds_read_b128 v[200:203], v165 offset:16384
	ds_read_b128 v[204:207], v165 offset:17408
	ds_read_b128 v[208:211], v165 offset:18432
	ds_read_b128 v[212:215], v165 offset:19456
	ds_read_b128 v[216:219], v165 offset:20480
	ds_read_b128 v[220:223], v165 offset:21504
	ds_read_b128 v[224:227], v165 offset:22528
	ds_read_b128 v[228:231], v165 offset:23552
	global_load_lds_dwordx4 v[160:161], off
	v_lshl_add_u64 v[232:233], s[0:1], 0, v[134:135]
	s_mov_b32 m0, s31
	s_addc_u32 s73, s1, 0
	global_load_lds_dwordx4 v[232:233], off
	v_lshl_add_u64 v[234:235], s[72:73], 0, v[130:131]
	s_mov_b32 m0, s40
	v_lshl_add_u64 v[236:237], s[34:35], 0, v[132:133]
	global_load_lds_dwordx4 v[234:235], off
	v_lshl_add_u64 v[234:235], s[72:73], 0, v[134:135]
	s_mov_b32 m0, s41
	s_nop 0
	global_load_lds_dwordx4 v[234:235], off
	v_lshl_add_u64 v[234:235], s[34:35], 0, v[128:129]
	s_mov_b32 m0, s39
	s_nop 0
	global_load_lds_dwordx4 v[234:235], off
	s_mov_b32 m0, s42
	s_nop 0
	global_load_lds_dwordx4 v[236:237], off
	s_waitcnt vmcnt(8)
	s_waitcnt lgkmcnt(0)
	s_barrier
	v_mfma_f32_16x16x32_bf16 v[60:63], v[144:147], v[200:203], v[60:63]
	v_mfma_f32_16x16x32_bf16 v[56:59], v[152:155], v[200:203], v[56:59]
	v_mfma_f32_16x16x32_bf16 v[44:47], v[144:147], v[208:211], v[44:47]
	v_mfma_f32_16x16x32_bf16 v[40:43], v[152:155], v[208:211], v[40:43]
	v_mfma_f32_16x16x32_bf16 v[28:31], v[144:147], v[216:219], v[28:31]
	v_mfma_f32_16x16x32_bf16 v[24:27], v[152:155], v[216:219], v[24:27]
	v_mfma_f32_16x16x32_bf16 v[12:15], v[144:147], v[224:227], v[12:15]
	v_mfma_f32_16x16x32_bf16 v[8:11], v[152:155], v[224:227], v[8:11]
	v_mfma_f32_16x16x32_bf16 v[60:63], v[148:151], v[204:207], v[60:63]
	v_mfma_f32_16x16x32_bf16 v[56:59], v[156:159], v[204:207], v[56:59]
	v_mfma_f32_16x16x32_bf16 v[44:47], v[148:151], v[212:215], v[44:47]
	v_mfma_f32_16x16x32_bf16 v[40:43], v[156:159], v[212:215], v[40:43]
	v_mfma_f32_16x16x32_bf16 v[28:31], v[148:151], v[220:223], v[28:31]
	v_mfma_f32_16x16x32_bf16 v[24:27], v[156:159], v[220:223], v[24:27]
	v_mfma_f32_16x16x32_bf16 v[12:15], v[148:151], v[228:231], v[12:15]
	v_mfma_f32_16x16x32_bf16 v[8:11], v[156:159], v[228:231], v[8:11]
	v_mfma_f32_16x16x32_bf16 v[52:55], v[184:187], v[200:203], v[52:55]
	v_mfma_f32_16x16x32_bf16 v[48:51], v[192:195], v[200:203], v[48:51]
	v_mfma_f32_16x16x32_bf16 v[36:39], v[184:187], v[208:211], v[36:39]
	v_mfma_f32_16x16x32_bf16 v[32:35], v[192:195], v[208:211], v[32:35]
	v_mfma_f32_16x16x32_bf16 v[20:23], v[184:187], v[216:219], v[20:23]
	v_mfma_f32_16x16x32_bf16 v[16:19], v[192:195], v[216:219], v[16:19]
	v_mfma_f32_16x16x32_bf16 v[4:7], v[184:187], v[224:227], v[4:7]
	v_mfma_f32_16x16x32_bf16 v[0:3], v[192:195], v[224:227], v[0:3]
	v_mfma_f32_16x16x32_bf16 v[52:55], v[188:191], v[204:207], v[52:55]
	v_mfma_f32_16x16x32_bf16 v[48:51], v[196:199], v[204:207], v[48:51]
	v_mfma_f32_16x16x32_bf16 v[36:39], v[188:191], v[212:215], v[36:39]
	v_mfma_f32_16x16x32_bf16 v[32:35], v[196:199], v[212:215], v[32:35]
	v_mfma_f32_16x16x32_bf16 v[20:23], v[188:191], v[220:223], v[20:23]
	v_mfma_f32_16x16x32_bf16 v[16:19], v[196:199], v[220:223], v[16:19]
	v_mfma_f32_16x16x32_bf16 v[4:7], v[188:191], v[228:231], v[4:7]
	v_mfma_f32_16x16x32_bf16 v[0:3], v[196:199], v[228:231], v[0:3]
	s_barrier
; #define PG8_STAGE(bufoff, gbase, voff) do { _Pragma("unroll") for (int _i = 0; _i < 2; ++_i) \
;         __builtin_amdgcn_global_load_lds((const unsigned*)((const char*)(gbase) + (voff)[_i]), (PG8_LAS unsigned*)(lds + (bufoff) + ldsw + _i * 8192), 16, 0, 0); } while (0)
; #define PG8_LDA(dst, b, h) do { _Pragma("unroll") for (int m = 0; m < 4; ++m) _Pragma("unroll") for (int k = 0; k < 2; ++k) dst[m][k] = *(const PG8_LAS bf16x8*)(lds + PG8_SA(b, h) + aoff + m * 2048 + k * 1024); } while (0)
; #define PG8_LDB(dst, b, h) do { _Pragma("unroll") for (int n = 0; n < 2; ++n) _Pragma("unroll") for (int k = 0; k < 2; ++k) dst[n][k] = *(const PG8_LAS bf16x8*)(lds + PG8_SB(b, h) + boff + n * 2048 + k * 1024); } while (0)
; #define PG8_MMA(ai, bj, At, Bt) do { __builtin_amdgcn_s_setprio(1); _Pragma("unroll") for (int m = 0; m < 4; ++m) _Pragma("unroll") for (int n = 0; n < 2; ++n) _Pragma("unroll") for (int k = 0; k < 2; ++k) \
;         acc[ai][bj][m][n] = __builtin_amdgcn_mfma_f32_16x16x32_bf16(Bt[n][k], At[m][k], acc[ai][bj][m][n], 0, 0, 0); __builtin_amdgcn_s_setprio(0); } while (0)
; #define PG8_WAIT_V(n) asm volatile("s_waitcnt vmcnt(" #n ")" ::: "memory")
; #define PG8_WAIT_L(n) asm volatile("s_waitcnt lgkmcnt(" #n ")" ::: "memory")
; #define PG8_BAR __builtin_amdgcn_s_barrier()
; #define PG8_SCHED __builtin_amdgcn_sched_barrier(0)
; template <class Epi, class Sched, bool ALIGN_EPI = false, bool SP2 = false>
; __device__ __forceinline__ void gemm_phase(PG8_LAS unsigned char* lds, const Gemm g, const Sched& S, const Epi& E, const int tid_arg) {
;     ...
;         for (int t = 0; t < nt; t += 2) {
;     ...
;             PG8_LDB(B0, 1, 0); PG8_LDB(B1, 1, 1); PG8_SCHED; PG8_LDA(At, 1, 0); PG8_STAGE(PG8_SA(0, 1), a2 + hstep, voffA);
;             PG8_WAIT_V(8); PG8_WAIT_L(0); PG8_BAR; PG8_MMA(0, 0, At, B0); PG8_MMA(0, 1, At, B1); PG8_BAR; PG8_SCHED;
;             PG8_LDA(At, 1, 1); PG8_STAGE(PG8_SB(1, 0), b3, voffB); PG8_STAGE(PG8_SB(1, 1), b3 + hstep, voffB); PG8_STAGE(PG8_SA(1, 0), a3, voffA);
;             PG8_WAIT_V(8); PG8_WAIT_L(0); PG8_BAR; PG8_MMA(1, 0, At, B0); PG8_MMA(1, 1, At, B1); PG8_BAR; PG8_SCHED;
	ds_read_b128 v[144:147], v174
	ds_read_b128 v[148:151], v175
	ds_read_b128 v[152:155], v176
	ds_read_b128 v[156:159], v177
	ds_read_b128 v[184:187], v178
	ds_read_b128 v[188:191], v179
	ds_read_b128 v[192:195], v180
	ds_read_b128 v[196:199], v181
	s_add_u32 s34, s34, 0x40000
	s_addc_u32 s35, s35, 0
	s_mov_b32 m0, s43
	v_lshl_add_u64 v[238:239], s[34:35], 0, v[128:129]
	ds_read_b128 v[200:203], v165 offset:32768
	ds_read_b128 v[204:207], v165 offset:33792
	ds_read_b128 v[208:211], v165 offset:34816
	ds_read_b128 v[212:215], v165 offset:35840
	ds_read_b128 v[216:219], v165 offset:36864
	ds_read_b128 v[220:223], v165 offset:37888
	ds_read_b128 v[224:227], v165 offset:38912
	ds_read_b128 v[228:231], v165 offset:39936
	global_load_lds_dwordx4 v[238:239], off
	v_lshl_add_u64 v[238:239], s[34:35], 0, v[132:133]
	s_mov_b32 m0, s44
	s_nop 0
	global_load_lds_dwordx4 v[238:239], off
	s_waitcnt vmcnt(8)
	s_waitcnt lgkmcnt(0)
	s_barrier
	v_mfma_f32_16x16x32_bf16 v[124:127], v[144:147], v[200:203], v[124:127]
	v_mfma_f32_16x16x32_bf16 v[120:123], v[152:155], v[200:203], v[120:123]
	v_mfma_f32_16x16x32_bf16 v[108:111], v[144:147], v[208:211], v[108:111]
	v_mfma_f32_16x16x32_bf16 v[104:107], v[152:155], v[208:211], v[104:107]
	v_mfma_f32_16x16x32_bf16 v[92:95], v[144:147], v[216:219], v[92:95]
	v_mfma_f32_16x16x32_bf16 v[88:91], v[152:155], v[216:219], v[88:91]
	v_mfma_f32_16x16x32_bf16 v[76:79], v[144:147], v[224:227], v[76:79]
	v_mfma_f32_16x16x32_bf16 v[72:75], v[152:155], v[224:227], v[72:75]
	v_mfma_f32_16x16x32_bf16 v[124:127], v[148:151], v[204:207], v[124:127]
	v_mfma_f32_16x16x32_bf16 v[120:123], v[156:159], v[204:207], v[120:123]
	v_mfma_f32_16x16x32_bf16 v[108:111], v[148:151], v[212:215], v[108:111]
	v_mfma_f32_16x16x32_bf16 v[104:107], v[156:159], v[212:215], v[104:107]
	v_mfma_f32_16x16x32_bf16 v[92:95], v[148:151], v[220:223], v[92:95]
	v_mfma_f32_16x16x32_bf16 v[88:91], v[156:159], v[220:223], v[88:91]
	v_mfma_f32_16x16x32_bf16 v[76:79], v[148:151], v[228:231], v[76:79]
	v_mfma_f32_16x16x32_bf16 v[72:75], v[156:159], v[228:231], v[72:75]
	v_mfma_f32_16x16x32_bf16 v[116:119], v[184:187], v[200:203], v[116:119]
	v_mfma_f32_16x16x32_bf16 v[112:115], v[192:195], v[200:203], v[112:115]
	v_mfma_f32_16x16x32_bf16 v[100:103], v[184:187], v[208:211], v[100:103]
	v_mfma_f32_16x16x32_bf16 v[96:99], v[192:195], v[208:211], v[96:99]
	v_mfma_f32_16x16x32_bf16 v[84:87], v[184:187], v[216:219], v[84:87]
	v_mfma_f32_16x16x32_bf16 v[80:83], v[192:195], v[216:219], v[80:83]
	v_mfma_f32_16x16x32_bf16 v[68:71], v[184:187], v[224:227], v[68:71]
	v_mfma_f32_16x16x32_bf16 v[64:67], v[192:195], v[224:227], v[64:67]
	v_mfma_f32_16x16x32_bf16 v[116:119], v[188:191], v[204:207], v[116:119]
	v_mfma_f32_16x16x32_bf16 v[112:115], v[196:199], v[204:207], v[112:115]
	v_mfma_f32_16x16x32_bf16 v[100:103], v[188:191], v[212:215], v[100:103]
	v_mfma_f32_16x16x32_bf16 v[96:99], v[196:199], v[212:215], v[96:99]
	v_mfma_f32_16x16x32_bf16 v[84:87], v[188:191], v[220:223], v[84:87]
	v_mfma_f32_16x16x32_bf16 v[80:83], v[196:199], v[220:223], v[80:83]
	v_mfma_f32_16x16x32_bf16 v[68:71], v[188:191], v[228:231], v[68:71]
	v_mfma_f32_16x16x32_bf16 v[64:67], v[196:199], v[228:231], v[64:67]
	s_barrier
	s_mov_b32 m0, s47
	v_lshl_add_u64 v[160:161], v[160:161], 0, s[14:15]
	s_add_u32 s0, s0, 0x40080
	ds_read_b128 v[200:203], v165 offset:49152
	ds_read_b128 v[204:207], v165 offset:50176
	ds_read_b128 v[208:211], v165 offset:51200
	ds_read_b128 v[212:215], v165 offset:52224
	ds_read_b128 v[216:219], v165 offset:53248
	ds_read_b128 v[220:223], v165 offset:54272
	ds_read_b128 v[224:227], v165 offset:55296
	ds_read_b128 v[228:231], v165 offset:56320
	global_load_lds_dwordx4 v[160:161], off
	v_lshl_add_u64 v[160:161], v[232:233], 0, s[14:15]
	s_mov_b32 m0, s48
	s_addc_u32 s1, s1, 0
	global_load_lds_dwordx4 v[160:161], off
	v_lshl_add_u64 v[160:161], s[0:1], 0, v[130:131]
	s_mov_b32 m0, s51
	s_nop 0
	global_load_lds_dwordx4 v[160:161], off
	v_lshl_add_u64 v[160:161], s[0:1], 0, v[134:135]
	s_mov_b32 m0, s52
	s_nop 0
	global_load_lds_dwordx4 v[160:161], off
	v_lshl_add_u64 v[160:161], v[234:235], 0, s[14:15]
	s_mov_b32 m0, s49
	s_nop 0
	global_load_lds_dwordx4 v[160:161], off
	v_lshl_add_u64 v[160:161], v[236:237], 0, s[14:15]
	s_mov_b32 m0, s50
	s_nop 0
	global_load_lds_dwordx4 v[160:161], off
	s_waitcnt vmcnt(8)
	s_waitcnt lgkmcnt(0)
	s_barrier
	v_mfma_f32_16x16x32_bf16 v[60:63], v[144:147], v[200:203], v[60:63]
	v_mfma_f32_16x16x32_bf16 v[56:59], v[152:155], v[200:203], v[56:59]
	v_mfma_f32_16x16x32_bf16 v[44:47], v[144:147], v[208:211], v[44:47]
	v_mfma_f32_16x16x32_bf16 v[40:43], v[152:155], v[208:211], v[40:43]
	v_mfma_f32_16x16x32_bf16 v[28:31], v[144:147], v[216:219], v[28:31]
	v_mfma_f32_16x16x32_bf16 v[24:27], v[152:155], v[216:219], v[24:27]
	v_mfma_f32_16x16x32_bf16 v[12:15], v[144:147], v[224:227], v[12:15]
	v_mfma_f32_16x16x32_bf16 v[8:11], v[152:155], v[224:227], v[8:11]
	v_mfma_f32_16x16x32_bf16 v[60:63], v[148:151], v[204:207], v[60:63]
	v_mfma_f32_16x16x32_bf16 v[56:59], v[156:159], v[204:207], v[56:59]
	v_mfma_f32_16x16x32_bf16 v[44:47], v[148:151], v[212:215], v[44:47]
	v_mfma_f32_16x16x32_bf16 v[40:43], v[156:159], v[212:215], v[40:43]
	v_mfma_f32_16x16x32_bf16 v[28:31], v[148:151], v[220:223], v[28:31]
	v_mfma_f32_16x16x32_bf16 v[24:27], v[156:159], v[220:223], v[24:27]
	v_mfma_f32_16x16x32_bf16 v[12:15], v[148:151], v[228:231], v[12:15]
	v_mfma_f32_16x16x32_bf16 v[8:11], v[156:159], v[228:231], v[8:11]
	v_mfma_f32_16x16x32_bf16 v[52:55], v[184:187], v[200:203], v[52:55]
	v_mfma_f32_16x16x32_bf16 v[48:51], v[192:195], v[200:203], v[48:51]
	v_mfma_f32_16x16x32_bf16 v[36:39], v[184:187], v[208:211], v[36:39]
	v_mfma_f32_16x16x32_bf16 v[32:35], v[192:195], v[208:211], v[32:35]
	v_mfma_f32_16x16x32_bf16 v[20:23], v[184:187], v[216:219], v[20:23]
	v_mfma_f32_16x16x32_bf16 v[16:19], v[192:195], v[216:219], v[16:19]
	v_mfma_f32_16x16x32_bf16 v[4:7], v[184:187], v[224:227], v[4:7]
	v_mfma_f32_16x16x32_bf16 v[0:3], v[192:195], v[224:227], v[0:3]
	v_mfma_f32_16x16x32_bf16 v[52:55], v[188:191], v[204:207], v[52:55]
	v_mfma_f32_16x16x32_bf16 v[48:51], v[196:199], v[204:207], v[48:51]
	v_mfma_f32_16x16x32_bf16 v[36:39], v[188:191], v[212:215], v[36:39]
	v_mfma_f32_16x16x32_bf16 v[32:35], v[196:199], v[212:215], v[32:35]
	v_mfma_f32_16x16x32_bf16 v[20:23], v[188:191], v[220:223], v[20:23]
	v_mfma_f32_16x16x32_bf16 v[16:19], v[196:199], v[220:223], v[16:19]
	v_mfma_f32_16x16x32_bf16 v[4:7], v[188:191], v[228:231], v[4:7]
	v_mfma_f32_16x16x32_bf16 v[0:3], v[196:199], v[228:231], v[0:3]
	s_barrier
	s_add_i32 s70, s70, 2
	s_add_u32 s68, s68, 0x100
	s_addc_u32 s69, s69, 0
	s_add_u32 s8, s8, 0x100
	s_addc_u32 s9, s9, 0
	s_cmp_gt_u32 s70, 13
	s_cbranch_scc0 .LBB0_253
	s_and_b64 vcc, exec, s[16:17]
	s_cbranch_vccz .LBB0_256
	s_barrier

; #define PG8_WAIT_V(n) asm volatile("s_waitcnt vmcnt(" #n ")" ::: "memory")
; #define PG8_BAR __builtin_amdgcn_s_barrier()
; __device__ __forceinline__ void xcd_barrier(const XcdBarrier& b, const bool xb_is_leader) {
;     asm volatile("s_waitcnt vmcnt(0)" ::: "memory");
;     __syncthreads();
;     if (xb_is_leader) {
;         unsigned* bar = b.bar;
;         __builtin_amdgcn_s_waitcnt(0);
;         unsigned nloc = b.st[0], nx = b.st[1];
;         if (nloc == 0u) { xcd_barrier_complete(bar, b.x, nloc, nx); b.st[0] = nloc; b.st[1] = nx; }
; template <class Epi, class Sched, bool ALIGN_EPI = false, bool SP2 = false>
; __device__ __forceinline__ void gemm_phase(PG8_LAS unsigned char* lds, const Gemm g, const Sched& S, const Epi& E, const int tid_arg) {
;     ...
;     PG8_WAIT_V(0);
;     if constexpr (!ALIGN_EPI) { if (wr == 0) PG8_BAR; }
;     PG8_BAR;
.LBB0_293:
	s_mov_b32 s0, -1
	s_nop 0
	v_mbcnt_lo_u32_b32 v0, s0, 0
	v_mbcnt_hi_u32_b32 v0, s0, v0
	s_setprio 0
	s_waitcnt vmcnt(0)
	s_waitcnt vmcnt(0)
	v_or_b32_e32 v0, s82, v0
	v_cmp_eq_u32_e32 vcc, 0, v0
	s_barrier
	s_and_saveexec_b64 s[4:5], vcc
	s_cbranch_execz .LBB0_345
	v_mov_b32_e32 v0, 0x22000
	s_waitcnt vmcnt(0) expcnt(0) lgkmcnt(0)
	ds_read_b32 v2, v0
	v_mov_b32_e32 v0, 0x22004
	ds_read_b32 v0, v0
	s_waitcnt lgkmcnt(1)
	v_cmp_ne_u32_e32 vcc, 0, v2
	s_cbranch_vccnz .LBB0_309
	v_readlane_b32 s0, v251, 0
	v_readlane_b32 s1, v251, 1
	v_readlane_b32 s2, v251, 2
	s_mul_i32 s2, s1, s2
	s_mul_i32 s2, s2, s0
	s_add_u32 s0, s76, 0x1000
	s_addc_u32 s1, s77, 0
	s_add_u32 s6, s76, 0x1100
	s_addc_u32 s7, s77, 0
	s_add_u32 s8, s76, 0x1200
	s_addc_u32 s9, s77, 0
	s_add_u32 s10, s76, 0x1300
	s_addc_u32 s11, s77, 0
	s_mov_b32 s3, 1
	v_mov_b32_e32 v16, 0
	s_branch .LBB0_297

; #define LAS __attribute__((address_space(3)))
; #define AIN(i) (kargs()->in[i])
; #define AWS (kargs()->ws)
; #define K_TID ((wave_s << 6) | lane_fresh())
; template <class Epi, class Sched, bool ALIGN_EPI = false, bool SP2 = false>
; __device__ __forceinline__ void gemm_phase(PG8_LAS unsigned char* lds, const Gemm g, const Sched& S, const Epi& E, const int tid_arg) {
;     ...
;     Unit cur, nxt; int ui = 0;
;     if (!S.next(0, cur)) return;
; __global__ void __launch_bounds__(512, 2) fwd_megakernel(Args a) {
;     ...
;             pg8::Gemm g{P_HN, (const bf16_t*)(AWS + WS_WOUT + l * SZ_WOUT), T, DM, DM}; pg8::StaticOrder S; S.init(T, DM, G, bx);
;             pg8::EpiResid E{(l == 0) ? AIN(0) : (const float*)nullptr, P_HB, P_RSQ + (size_t)(2 * l) * T, (LAS float*)(lds + LDS_XCH)};
;             pg8::gemm_phase<pg8::EpiResid, pg8::StaticOrder, true, true>(lds, g, S, E, K_TID);
.LBB0_514:
	s_or_b64 exec, exec, s[4:5]
	s_mov_b64 s[0:1], s[46:47]
	s_waitcnt lgkmcnt(0)
	s_barrier
	s_cselect_b32 s98, 1, 0
	s_cmp_ge_u32 s82, 0x100
	s_cbranch_scc0 .Lprio_skip_12
	s_setprio 1
.Lprio_skip_12:
	s_cmp_lg_u32 s98, 0
	s_mov_b64 s[2:3], s[46:47]
	s_load_dwordx2 s[0:1], s[0:1], 0x98
	s_load_dwordx2 s[12:13], s[2:3], 0x98
	s_mov_b64 s[2:3], s[46:47]
	s_load_dwordx2 s[6:7], s[2:3], 0x0
	s_mov_b64 s[2:3], s[46:47]
	s_load_dwordx2 s[8:9], s[2:3], 0x98
	s_mov_b64 s[2:3], s[46:47]
	s_load_dwordx2 s[18:19], s[2:3], 0x98
	s_mov_b32 s2, -1
	s_cmpk_lt_i32 s86, 0x200
	v_mbcnt_lo_u32_b32 v0, s2, 0
	v_mbcnt_hi_u32_b32 v0, s2, v0
	s_cselect_b64 s[84:85], -1, 0
	v_or_b32_e32 v8, s82, v0
	s_cmpk_gt_i32 s86, 0x1ff
	v_readfirstlane_b32 s22, v8
	s_cbranch_scc1 .LBB0_520
	s_lshr_b32 s2, s87, 29
	s_add_i32 s2, s86, s2
	s_and_b32 s3, s2, -8
	s_sub_i32 s3, s86, s3
	s_cmp_gt_i32 s3, -1
	s_cbranch_scc0 .LBB0_517
	s_lshl_b32 s10, s3, 6
	s_cbranch_execz .LBB0_518
	s_branch .LBB0_519

; #define PG8_STAGE(bufoff, gbase, voff) do { _Pragma("unroll") for (int _i = 0; _i < 2; ++_i) \
;         __builtin_amdgcn_global_load_lds((const unsigned*)((const char*)(gbase) + (voff)[_i]), (PG8_LAS unsigned*)(lds + (bufoff) + ldsw + _i * 8192), 16, 0, 0); } while (0)
; #define PG8_LDA(dst, b, h) do { _Pragma("unroll") for (int m = 0; m < 4; ++m) _Pragma("unroll") for (int k = 0; k < 2; ++k) dst[m][k] = *(const PG8_LAS bf16x8*)(lds + PG8_SA(b, h) + aoff + m * 2048 + k * 1024); } while (0)
; #define PG8_LDB(dst, b, h) do { _Pragma("unroll") for (int n = 0; n < 2; ++n) _Pragma("unroll") for (int k = 0; k < 2; ++k) dst[n][k] = *(const PG8_LAS bf16x8*)(lds + PG8_SB(b, h) + boff + n * 2048 + k * 1024); } while (0)
; #define PG8_MMA(ai, bj, At, Bt) do { __builtin_amdgcn_s_setprio(1); _Pragma("unroll") for (int m = 0; m < 4; ++m) _Pragma("unroll") for (int n = 0; n < 2; ++n) _Pragma("unroll") for (int k = 0; k < 2; ++k) \
;         acc[ai][bj][m][n] = __builtin_amdgcn_mfma_f32_16x16x32_bf16(Bt[n][k], At[m][k], acc[ai][bj][m][n], 0, 0, 0); __builtin_amdgcn_s_setprio(0); } while (0)
; #define PG8_WAIT_V(n) asm volatile("s_waitcnt vmcnt(" #n ")" ::: "memory")
; #define PG8_WAIT_L(n) asm volatile("s_waitcnt lgkmcnt(" #n ")" ::: "memory")
; #define PG8_BAR __builtin_amdgcn_s_barrier()
; #define PG8_SCHED __builtin_amdgcn_sched_barrier(0)
; template <class Epi, class Sched, bool ALIGN_EPI = false, bool SP2 = false>
; __device__ __forceinline__ void gemm_phase(PG8_LAS unsigned char* lds, const Gemm g, const Sched& S, const Epi& E, const int tid_arg) {
;     ...
;             PG8_LDB(B0, 0, 0); PG8_LDB(B1, 0, 1); PG8_SCHED; PG8_LDA(At, 0, 0); PG8_STAGE(PG8_SA(1, 1), a1 + hstep, voffA);
;             PG8_WAIT_V(8); PG8_WAIT_L(0); PG8_BAR; PG8_MMA(0, 0, At, B0); PG8_MMA(0, 1, At, B1); PG8_BAR; PG8_SCHED;
;             PG8_LDA(At, 0, 1); PG8_STAGE(PG8_SB(0, 0), b2, voffB); PG8_STAGE(PG8_SB(0, 1), b2 + hstep, voffB); PG8_STAGE(PG8_SA(0, 0), a2, voffA);
;             PG8_WAIT_V(8); PG8_WAIT_L(0); PG8_BAR; PG8_MMA(1, 0, At, B0); PG8_MMA(1, 1, At, B1); PG8_BAR; PG8_SCHED;
.LBB0_533:
	ds_read_b128 v[128:131], v165
	ds_read_b128 v[132:135], v166
	ds_read_b128 v[152:155], v167
	ds_read_b128 v[156:159], v168
	ds_read_b128 v[182:185], v169
	ds_read_b128 v[186:189], v170
	ds_read_b128 v[190:193], v171
	ds_read_b128 v[194:197], v172
	s_add_u32 s0, s12, 0xfffc0080
	s_addc_u32 s1, s13, -1
	s_cmp_eq_u32 s65, 12
	s_cselect_b32 s37, s11, s1
	s_cselect_b32 s36, s29, s0
	s_cselect_b32 s1, s27, s64
	s_cselect_b32 s0, s62, s63
	s_mov_b32 m0, s59
	v_lshl_add_u64 v[160:161], s[12:13], 0, v[146:147]
	ds_read_b128 v[198:201], v164
	ds_read_b128 v[202:205], v164 offset:1024
	ds_read_b128 v[206:209], v164 offset:2048
	ds_read_b128 v[210:213], v164 offset:3072
	ds_read_b128 v[214:217], v164 offset:4096
	ds_read_b128 v[218:221], v164 offset:5120
	ds_read_b128 v[222:225], v164 offset:6144
	ds_read_b128 v[226:229], v164 offset:7168
	global_load_lds_dwordx4 v[160:161], off
	v_lshl_add_u64 v[160:161], s[12:13], 0, v[144:145]
	s_mov_b32 m0, s60
	s_nop 0
	global_load_lds_dwordx4 v[160:161], off
	s_waitcnt vmcnt(8)
	s_waitcnt lgkmcnt(0)
	s_barrier
	v_mfma_f32_16x16x32_bf16 v[124:127], v[128:131], v[198:201], v[124:127]
	v_mfma_f32_16x16x32_bf16 v[120:123], v[152:155], v[198:201], v[120:123]
	v_mfma_f32_16x16x32_bf16 v[108:111], v[128:131], v[206:209], v[108:111]
	v_mfma_f32_16x16x32_bf16 v[104:107], v[152:155], v[206:209], v[104:107]
	v_mfma_f32_16x16x32_bf16 v[92:95], v[128:131], v[214:217], v[92:95]
	v_mfma_f32_16x16x32_bf16 v[88:91], v[152:155], v[214:217], v[88:91]
	v_mfma_f32_16x16x32_bf16 v[76:79], v[128:131], v[222:225], v[76:79]
	v_mfma_f32_16x16x32_bf16 v[72:75], v[152:155], v[222:225], v[72:75]
	v_mfma_f32_16x16x32_bf16 v[124:127], v[132:135], v[202:205], v[124:127]
	v_mfma_f32_16x16x32_bf16 v[120:123], v[156:159], v[202:205], v[120:123]
	v_mfma_f32_16x16x32_bf16 v[108:111], v[132:135], v[210:213], v[108:111]
	v_mfma_f32_16x16x32_bf16 v[104:107], v[156:159], v[210:213], v[104:107]
	v_mfma_f32_16x16x32_bf16 v[92:95], v[132:135], v[218:221], v[92:95]
	v_mfma_f32_16x16x32_bf16 v[88:91], v[156:159], v[218:221], v[88:91]
	v_mfma_f32_16x16x32_bf16 v[76:79], v[132:135], v[226:229], v[76:79]
	v_mfma_f32_16x16x32_bf16 v[72:75], v[156:159], v[226:229], v[72:75]
	v_mfma_f32_16x16x32_bf16 v[116:119], v[182:185], v[198:201], v[116:119]
	v_mfma_f32_16x16x32_bf16 v[112:115], v[190:193], v[198:201], v[112:115]
	v_mfma_f32_16x16x32_bf16 v[100:103], v[182:185], v[206:209], v[100:103]
	v_mfma_f32_16x16x32_bf16 v[96:99], v[190:193], v[206:209], v[96:99]
	v_mfma_f32_16x16x32_bf16 v[84:87], v[182:185], v[214:217], v[84:87]
	v_mfma_f32_16x16x32_bf16 v[80:83], v[190:193], v[214:217], v[80:83]
	v_mfma_f32_16x16x32_bf16 v[68:71], v[182:185], v[222:225], v[68:71]
	v_mfma_f32_16x16x32_bf16 v[64:67], v[190:193], v[222:225], v[64:67]
	v_mfma_f32_16x16x32_bf16 v[116:119], v[186:189], v[202:205], v[116:119]
	v_mfma_f32_16x16x32_bf16 v[112:115], v[194:197], v[202:205], v[112:115]
	v_mfma_f32_16x16x32_bf16 v[100:103], v[186:189], v[210:213], v[100:103]
	v_mfma_f32_16x16x32_bf16 v[96:99], v[194:197], v[210:213], v[96:99]
	v_mfma_f32_16x16x32_bf16 v[84:87], v[186:189], v[218:221], v[84:87]
	v_mfma_f32_16x16x32_bf16 v[80:83], v[194:197], v[218:221], v[80:83]
	v_mfma_f32_16x16x32_bf16 v[68:71], v[186:189], v[226:229], v[68:71]
	v_mfma_f32_16x16x32_bf16 v[64:67], v[194:197], v[226:229], v[64:67]
	s_barrier
	s_mov_b32 m0, s5
	v_lshl_add_u64 v[160:161], s[0:1], 0, v[138:139]
	s_add_u32 s66, s0, 0x40000
	ds_read_b128 v[198:201], v164 offset:16384
	ds_read_b128 v[202:205], v164 offset:17408
	ds_read_b128 v[206:209], v164 offset:18432
	ds_read_b128 v[210:213], v164 offset:19456
	ds_read_b128 v[214:217], v164 offset:20480
	ds_read_b128 v[218:221], v164 offset:21504
	ds_read_b128 v[222:225], v164 offset:22528
	ds_read_b128 v[226:229], v164 offset:23552
	global_load_lds_dwordx4 v[160:161], off
	v_lshl_add_u64 v[230:231], s[0:1], 0, v[142:143]
	s_mov_b32 m0, s40
	s_addc_u32 s67, s1, 0
	global_load_lds_dwordx4 v[230:231], off
	v_lshl_add_u64 v[232:233], s[66:67], 0, v[138:139]
	s_mov_b32 m0, s41
	v_lshl_add_u64 v[234:235], s[36:37], 0, v[140:141]
	global_load_lds_dwordx4 v[232:233], off
	v_lshl_add_u64 v[232:233], s[66:67], 0, v[142:143]
	s_mov_b32 m0, s42
	s_nop 0
	global_load_lds_dwordx4 v[232:233], off
	v_lshl_add_u64 v[232:233], s[36:37], 0, v[136:137]
	s_mov_b32 m0, s39
	s_nop 0
	global_load_lds_dwordx4 v[232:233], off
	s_mov_b32 m0, s43
	s_nop 0
	global_load_lds_dwordx4 v[234:235], off
	s_waitcnt vmcnt(8)
	s_waitcnt lgkmcnt(0)
	s_barrier
	v_mfma_f32_16x16x32_bf16 v[60:63], v[128:131], v[198:201], v[60:63]
	v_mfma_f32_16x16x32_bf16 v[56:59], v[152:155], v[198:201], v[56:59]
	v_mfma_f32_16x16x32_bf16 v[44:47], v[128:131], v[206:209], v[44:47]
	v_mfma_f32_16x16x32_bf16 v[40:43], v[152:155], v[206:209], v[40:43]
	v_mfma_f32_16x16x32_bf16 v[28:31], v[128:131], v[214:217], v[28:31]
	v_mfma_f32_16x16x32_bf16 v[24:27], v[152:155], v[214:217], v[24:27]
	v_mfma_f32_16x16x32_bf16 v[12:15], v[128:131], v[222:225], v[12:15]
	v_mfma_f32_16x16x32_bf16 v[8:11], v[152:155], v[222:225], v[8:11]
	v_mfma_f32_16x16x32_bf16 v[60:63], v[132:135], v[202:205], v[60:63]
	v_mfma_f32_16x16x32_bf16 v[56:59], v[156:159], v[202:205], v[56:59]
	v_mfma_f32_16x16x32_bf16 v[44:47], v[132:135], v[210:213], v[44:47]
	v_mfma_f32_16x16x32_bf16 v[40:43], v[156:159], v[210:213], v[40:43]
	v_mfma_f32_16x16x32_bf16 v[28:31], v[132:135], v[218:221], v[28:31]
	v_mfma_f32_16x16x32_bf16 v[24:27], v[156:159], v[218:221], v[24:27]
	v_mfma_f32_16x16x32_bf16 v[12:15], v[132:135], v[226:229], v[12:15]
	v_mfma_f32_16x16x32_bf16 v[8:11], v[156:159], v[226:229], v[8:11]
	v_mfma_f32_16x16x32_bf16 v[52:55], v[182:185], v[198:201], v[52:55]
	v_mfma_f32_16x16x32_bf16 v[48:51], v[190:193], v[198:201], v[48:51]
	v_mfma_f32_16x16x32_bf16 v[36:39], v[182:185], v[206:209], v[36:39]
	v_mfma_f32_16x16x32_bf16 v[32:35], v[190:193], v[206:209], v[32:35]
	v_mfma_f32_16x16x32_bf16 v[20:23], v[182:185], v[214:217], v[20:23]
	v_mfma_f32_16x16x32_bf16 v[16:19], v[190:193], v[214:217], v[16:19]
	v_mfma_f32_16x16x32_bf16 v[4:7], v[182:185], v[222:225], v[4:7]
	v_mfma_f32_16x16x32_bf16 v[0:3], v[190:193], v[222:225], v[0:3]
	v_mfma_f32_16x16x32_bf16 v[52:55], v[186:189], v[202:205], v[52:55]
	v_mfma_f32_16x16x32_bf16 v[48:51], v[194:197], v[202:205], v[48:51]
	v_mfma_f32_16x16x32_bf16 v[36:39], v[186:189], v[210:213], v[36:39]
	v_mfma_f32_16x16x32_bf16 v[32:35], v[194:197], v[210:213], v[32:35]
	v_mfma_f32_16x16x32_bf16 v[20:23], v[186:189], v[218:221], v[20:23]
	v_mfma_f32_16x16x32_bf16 v[16:19], v[194:197], v[218:221], v[16:19]
	v_mfma_f32_16x16x32_bf16 v[4:7], v[186:189], v[226:229], v[4:7]
	v_mfma_f32_16x16x32_bf16 v[0:3], v[194:197], v[226:229], v[0:3]
	s_barrier
; #define PG8_STAGE(bufoff, gbase, voff) do { _Pragma("unroll") for (int _i = 0; _i < 2; ++_i) \
;         __builtin_amdgcn_global_load_lds((const unsigned*)((const char*)(gbase) + (voff)[_i]), (PG8_LAS unsigned*)(lds + (bufoff) + ldsw + _i * 8192), 16, 0, 0); } while (0)
; #define PG8_LDA(dst, b, h) do { _Pragma("unroll") for (int m = 0; m < 4; ++m) _Pragma("unroll") for (int k = 0; k < 2; ++k) dst[m][k] = *(const PG8_LAS bf16x8*)(lds + PG8_SA(b, h) + aoff + m * 2048 + k * 1024); } while (0)
; #define PG8_LDB(dst, b, h) do { _Pragma("unroll") for (int n = 0; n < 2; ++n) _Pragma("unroll") for (int k = 0; k < 2; ++k) dst[n][k] = *(const PG8_LAS bf16x8*)(lds + PG8_SB(b, h) + boff + n * 2048 + k * 1024); } while (0)
; #define PG8_MMA(ai, bj, At, Bt) do { __builtin_amdgcn_s_setprio(1); _Pragma("unroll") for (int m = 0; m < 4; ++m) _Pragma("unroll") for (int n = 0; n < 2; ++n) _Pragma("unroll") for (int k = 0; k < 2; ++k) \
;         acc[ai][bj][m][n] = __builtin_amdgcn_mfma_f32_16x16x32_bf16(Bt[n][k], At[m][k], acc[ai][bj][m][n], 0, 0, 0); __builtin_amdgcn_s_setprio(0); } while (0)
; #define PG8_WAIT_V(n) asm volatile("s_waitcnt vmcnt(" #n ")" ::: "memory")
; #define PG8_WAIT_L(n) asm volatile("s_waitcnt lgkmcnt(" #n ")" ::: "memory")
; #define PG8_BAR __builtin_amdgcn_s_barrier()
; #define PG8_SCHED __builtin_amdgcn_sched_barrier(0)
; template <class Epi, class Sched, bool ALIGN_EPI = false, bool SP2 = false>
; __device__ __forceinline__ void gemm_phase(PG8_LAS unsigned char* lds, const Gemm g, const Sched& S, const Epi& E, const int tid_arg) {
;     ...
;         for (int t = 0; t < nt; t += 2) {
;     ...
;             PG8_LDB(B0, 1, 0); PG8_LDB(B1, 1, 1); PG8_SCHED; PG8_LDA(At, 1, 0); PG8_STAGE(PG8_SA(0, 1), a2 + hstep, voffA);
;             PG8_WAIT_V(8); PG8_WAIT_L(0); PG8_BAR; PG8_MMA(0, 0, At, B0); PG8_MMA(0, 1, At, B1); PG8_BAR; PG8_SCHED;
;             PG8_LDA(At, 1, 1); PG8_STAGE(PG8_SB(1, 0), b3, voffB); PG8_STAGE(PG8_SB(1, 1), b3 + hstep, voffB); PG8_STAGE(PG8_SA(1, 0), a3, voffA);
;             PG8_WAIT_V(8); PG8_WAIT_L(0); PG8_BAR; PG8_MMA(1, 0, At, B0); PG8_MMA(1, 1, At, B1); PG8_BAR; PG8_SCHED;
	ds_read_b128 v[128:131], v173
	ds_read_b128 v[132:135], v174
	ds_read_b128 v[152:155], v175
	ds_read_b128 v[156:159], v176
	ds_read_b128 v[182:185], v177
	ds_read_b128 v[186:189], v178
	ds_read_b128 v[190:193], v179
	ds_read_b128 v[194:197], v180
	s_add_u32 s36, s36, 0x40000
	s_addc_u32 s37, s37, 0
	s_mov_b32 m0, s44
	v_lshl_add_u64 v[236:237], s[36:37], 0, v[136:137]
	ds_read_b128 v[198:201], v164 offset:32768
	ds_read_b128 v[202:205], v164 offset:33792
	ds_read_b128 v[206:209], v164 offset:34816
	ds_read_b128 v[210:213], v164 offset:35840
	ds_read_b128 v[214:217], v164 offset:36864
	ds_read_b128 v[218:221], v164 offset:37888
	ds_read_b128 v[222:225], v164 offset:38912
	ds_read_b128 v[226:229], v164 offset:39936
	global_load_lds_dwordx4 v[236:237], off
	v_lshl_add_u64 v[236:237], s[36:37], 0, v[140:141]
	s_mov_b32 m0, s45
	s_nop 0
	global_load_lds_dwordx4 v[236:237], off
	s_waitcnt vmcnt(8)
	s_waitcnt lgkmcnt(0)
	s_barrier
	v_mfma_f32_16x16x32_bf16 v[124:127], v[128:131], v[198:201], v[124:127]
	v_mfma_f32_16x16x32_bf16 v[120:123], v[152:155], v[198:201], v[120:123]
	v_mfma_f32_16x16x32_bf16 v[108:111], v[128:131], v[206:209], v[108:111]
	v_mfma_f32_16x16x32_bf16 v[104:107], v[152:155], v[206:209], v[104:107]
	v_mfma_f32_16x16x32_bf16 v[92:95], v[128:131], v[214:217], v[92:95]
	v_mfma_f32_16x16x32_bf16 v[88:91], v[152:155], v[214:217], v[88:91]
	v_mfma_f32_16x16x32_bf16 v[76:79], v[128:131], v[222:225], v[76:79]
	v_mfma_f32_16x16x32_bf16 v[72:75], v[152:155], v[222:225], v[72:75]
	v_mfma_f32_16x16x32_bf16 v[124:127], v[132:135], v[202:205], v[124:127]
	v_mfma_f32_16x16x32_bf16 v[120:123], v[156:159], v[202:205], v[120:123]
	v_mfma_f32_16x16x32_bf16 v[108:111], v[132:135], v[210:213], v[108:111]
	v_mfma_f32_16x16x32_bf16 v[104:107], v[156:159], v[210:213], v[104:107]
	v_mfma_f32_16x16x32_bf16 v[92:95], v[132:135], v[218:221], v[92:95]
	v_mfma_f32_16x16x32_bf16 v[88:91], v[156:159], v[218:221], v[88:91]
	v_mfma_f32_16x16x32_bf16 v[76:79], v[132:135], v[226:229], v[76:79]
	v_mfma_f32_16x16x32_bf16 v[72:75], v[156:159], v[226:229], v[72:75]
	v_mfma_f32_16x16x32_bf16 v[116:119], v[182:185], v[198:201], v[116:119]
	v_mfma_f32_16x16x32_bf16 v[112:115], v[190:193], v[198:201], v[112:115]
	v_mfma_f32_16x16x32_bf16 v[100:103], v[182:185], v[206:209], v[100:103]
	v_mfma_f32_16x16x32_bf16 v[96:99], v[190:193], v[206:209], v[96:99]
	v_mfma_f32_16x16x32_bf16 v[84:87], v[182:185], v[214:217], v[84:87]
	v_mfma_f32_16x16x32_bf16 v[80:83], v[190:193], v[214:217], v[80:83]
	v_mfma_f32_16x16x32_bf16 v[68:71], v[182:185], v[222:225], v[68:71]
	v_mfma_f32_16x16x32_bf16 v[64:67], v[190:193], v[222:225], v[64:67]
	v_mfma_f32_16x16x32_bf16 v[116:119], v[186:189], v[202:205], v[116:119]
	v_mfma_f32_16x16x32_bf16 v[112:115], v[194:197], v[202:205], v[112:115]
	v_mfma_f32_16x16x32_bf16 v[100:103], v[186:189], v[210:213], v[100:103]
	v_mfma_f32_16x16x32_bf16 v[96:99], v[194:197], v[210:213], v[96:99]
	v_mfma_f32_16x16x32_bf16 v[84:87], v[186:189], v[218:221], v[84:87]
	v_mfma_f32_16x16x32_bf16 v[80:83], v[194:197], v[218:221], v[80:83]
	v_mfma_f32_16x16x32_bf16 v[68:71], v[186:189], v[226:229], v[68:71]
	v_mfma_f32_16x16x32_bf16 v[64:67], v[194:197], v[226:229], v[64:67]
	s_barrier
	s_mov_b32 m0, s49
	v_lshl_add_u64 v[160:161], v[160:161], 0, s[20:21]
	s_add_u32 s0, s0, 0x40080
	ds_read_b128 v[198:201], v164 offset:49152
	ds_read_b128 v[202:205], v164 offset:50176
	ds_read_b128 v[206:209], v164 offset:51200
	ds_read_b128 v[210:213], v164 offset:52224
	ds_read_b128 v[214:217], v164 offset:53248
	ds_read_b128 v[218:221], v164 offset:54272
	ds_read_b128 v[222:225], v164 offset:55296
	ds_read_b128 v[226:229], v164 offset:56320
	global_load_lds_dwordx4 v[160:161], off
	v_lshl_add_u64 v[160:161], v[230:231], 0, s[20:21]
	s_mov_b32 m0, s50
	s_addc_u32 s1, s1, 0
	global_load_lds_dwordx4 v[160:161], off
	v_lshl_add_u64 v[160:161], s[0:1], 0, v[138:139]
	s_mov_b32 m0, s53
	s_nop 0
	global_load_lds_dwordx4 v[160:161], off
	v_lshl_add_u64 v[160:161], s[0:1], 0, v[142:143]
	s_mov_b32 m0, s54
	s_nop 0
	global_load_lds_dwordx4 v[160:161], off
	v_lshl_add_u64 v[160:161], v[232:233], 0, s[20:21]
	s_mov_b32 m0, s51
	s_nop 0
	global_load_lds_dwordx4 v[160:161], off
	v_lshl_add_u64 v[160:161], v[234:235], 0, s[20:21]
	s_mov_b32 m0, s52
	s_nop 0
	global_load_lds_dwordx4 v[160:161], off
	s_waitcnt vmcnt(8)
	s_waitcnt lgkmcnt(0)
	s_barrier
	v_mfma_f32_16x16x32_bf16 v[60:63], v[128:131], v[198:201], v[60:63]
	v_mfma_f32_16x16x32_bf16 v[56:59], v[152:155], v[198:201], v[56:59]
	v_mfma_f32_16x16x32_bf16 v[44:47], v[128:131], v[206:209], v[44:47]
	v_mfma_f32_16x16x32_bf16 v[40:43], v[152:155], v[206:209], v[40:43]
	v_mfma_f32_16x16x32_bf16 v[28:31], v[128:131], v[214:217], v[28:31]
	v_mfma_f32_16x16x32_bf16 v[24:27], v[152:155], v[214:217], v[24:27]
	v_mfma_f32_16x16x32_bf16 v[12:15], v[128:131], v[222:225], v[12:15]
	v_mfma_f32_16x16x32_bf16 v[8:11], v[152:155], v[222:225], v[8:11]
	v_mfma_f32_16x16x32_bf16 v[60:63], v[132:135], v[202:205], v[60:63]
	v_mfma_f32_16x16x32_bf16 v[56:59], v[156:159], v[202:205], v[56:59]
	v_mfma_f32_16x16x32_bf16 v[44:47], v[132:135], v[210:213], v[44:47]
	v_mfma_f32_16x16x32_bf16 v[40:43], v[156:159], v[210:213], v[40:43]
	v_mfma_f32_16x16x32_bf16 v[28:31], v[132:135], v[218:221], v[28:31]
	v_mfma_f32_16x16x32_bf16 v[24:27], v[156:159], v[218:221], v[24:27]
	v_mfma_f32_16x16x32_bf16 v[12:15], v[132:135], v[226:229], v[12:15]
	v_mfma_f32_16x16x32_bf16 v[8:11], v[156:159], v[226:229], v[8:11]
	v_mfma_f32_16x16x32_bf16 v[52:55], v[182:185], v[198:201], v[52:55]
	v_mfma_f32_16x16x32_bf16 v[48:51], v[190:193], v[198:201], v[48:51]
	v_mfma_f32_16x16x32_bf16 v[36:39], v[182:185], v[206:209], v[36:39]
	v_mfma_f32_16x16x32_bf16 v[32:35], v[190:193], v[206:209], v[32:35]
	v_mfma_f32_16x16x32_bf16 v[20:23], v[182:185], v[214:217], v[20:23]
	v_mfma_f32_16x16x32_bf16 v[16:19], v[190:193], v[214:217], v[16:19]
	v_mfma_f32_16x16x32_bf16 v[4:7], v[182:185], v[222:225], v[4:7]
	v_mfma_f32_16x16x32_bf16 v[0:3], v[190:193], v[222:225], v[0:3]
	v_mfma_f32_16x16x32_bf16 v[52:55], v[186:189], v[202:205], v[52:55]
	v_mfma_f32_16x16x32_bf16 v[48:51], v[194:197], v[202:205], v[48:51]
	v_mfma_f32_16x16x32_bf16 v[36:39], v[186:189], v[210:213], v[36:39]
	v_mfma_f32_16x16x32_bf16 v[32:35], v[194:197], v[210:213], v[32:35]
	v_mfma_f32_16x16x32_bf16 v[20:23], v[186:189], v[218:221], v[20:23]
	v_mfma_f32_16x16x32_bf16 v[16:19], v[194:197], v[218:221], v[16:19]
	v_mfma_f32_16x16x32_bf16 v[4:7], v[186:189], v[226:229], v[4:7]
	v_mfma_f32_16x16x32_bf16 v[0:3], v[194:197], v[226:229], v[0:3]
	s_barrier
	s_add_i32 s65, s65, 2
	s_add_u32 s63, s63, 0x100
	s_addc_u32 s64, s64, 0
	s_add_u32 s12, s12, 0x100
	s_addc_u32 s13, s13, 0
	s_cmp_gt_u32 s65, 13
	s_cbranch_scc0 .LBB0_533
	s_and_b64 vcc, exec, s[22:23]
	s_cbranch_vccz .LBB0_536
	s_barrier

; #define PG8_WAIT_V(n) asm volatile("s_waitcnt vmcnt(" #n ")" ::: "memory")
; #define PG8_BAR __builtin_amdgcn_s_barrier()
; __device__ __forceinline__ void xcd_barrier(const XcdBarrier& b, const bool xb_is_leader) {
;     asm volatile("s_waitcnt vmcnt(0)" ::: "memory");
;     __syncthreads();
;     if (xb_is_leader) {
;         unsigned* bar = b.bar;
;         __builtin_amdgcn_s_waitcnt(0);
;         unsigned nloc = b.st[0], nx = b.st[1];
;         if (nloc == 0u) { xcd_barrier_complete(bar, b.x, nloc, nx); b.st[0] = nloc; b.st[1] = nx; }
; template <class Epi, class Sched, bool ALIGN_EPI = false, bool SP2 = false>
; __device__ __forceinline__ void gemm_phase(PG8_LAS unsigned char* lds, const Gemm g, const Sched& S, const Epi& E, const int tid_arg) {
;     ...
;     PG8_WAIT_V(0);
;     if constexpr (!ALIGN_EPI) { if (wr == 0) PG8_BAR; }
;     PG8_BAR;
.LBB0_622:
	s_waitcnt lgkmcnt(0)
	s_mov_b32 s0, -1
	s_nop 0
	v_mbcnt_lo_u32_b32 v0, s0, 0
	v_mbcnt_hi_u32_b32 v0, s0, v0
	s_setprio 0
	s_waitcnt vmcnt(0)
	s_nop 0
	v_or_b32_e32 v0, s82, v0
	v_cmp_eq_u32_e32 vcc, 0, v0
	s_barrier
	s_and_saveexec_b64 s[4:5], vcc
	s_cbranch_execz .LBB0_674
	v_mov_b32_e32 v0, 0x22000
	s_waitcnt vmcnt(0) expcnt(0) lgkmcnt(0)
	ds_read_b32 v2, v0
	v_mov_b32_e32 v0, 0x22004
	ds_read_b32 v0, v0
	s_waitcnt lgkmcnt(1)
	v_cmp_ne_u32_e32 vcc, 0, v2
	s_cbranch_vccnz .LBB0_638
	v_readlane_b32 s0, v251, 0
	v_readlane_b32 s1, v251, 1
	v_readlane_b32 s2, v251, 2
	s_mul_i32 s2, s1, s2
	s_mul_i32 s2, s2, s0
	s_add_u32 s0, s76, 0x1000
	s_addc_u32 s1, s77, 0
	s_add_u32 s6, s76, 0x1100
	s_addc_u32 s7, s77, 0
	s_add_u32 s8, s76, 0x1200
	s_addc_u32 s9, s77, 0
	s_add_u32 s10, s76, 0x1300
	s_addc_u32 s11, s77, 0
	s_mov_b32 s3, 1
	v_mov_b32_e32 v16, 0
	s_branch .LBB0_626

; #define LAS __attribute__((address_space(3)))
; #define AIN(i) (kargs()->in[i])
; #define AWS (kargs()->ws)
; #define K_TID ((wave_s << 6) | lane_fresh())
;     __host__ __device__ bool next(int i, Unit& u) const {
;         const long L = (long)i * G + c; if (L >= nwg) return false;
;         int wgid = (int)L; { const int q = nwg / NXCD, r = nwg % NXCD, xcd = wgid % NXCD, off = wgid / NXCD; wgid = (xcd < r ? xcd * (q + 1) : r * (q + 1) + (xcd - r) * q) + off; }
;         const int nig = WGM * nN, gid = wgid / nig, fm = gid * WGM, gsz = (nM - fm) < WGM ? (nM - fm) : WGM;
;         u.pm = fm + ((wgid % nig) % gsz); u.pn = (wgid % nig) / gsz; return true;
; __global__ void __launch_bounds__(512, 2) fwd_megakernel(Args a) {
;     ...
;             pg8::Gemm g{P_HB, (const bf16_t*)(AWS + WS_WUP + l * SZ_WUP), T, UPN, DM}; pg8::StaticOrder S; S.init(T, UPN, G, bx);
;             pg8::EpiUp E{P_Zb, AIN(12) + (size_t)l * 3 * UPN, AIN(13) + l * UPN, P_EDGE, (LAS float*)(lds + LDS_XCH), P_RSQ + (size_t)(2 * l) * T, (LAS float*)(lds + LDS_PRM), (LAS float*)(lds + LDS_RSD)};
;     ...
;             pg8::gemm_phase<pg8::EpiUp, pg8::StaticOrder, true, true>(lds, g, S, E, K_TID);
.LBB0_674:
	s_or_b64 exec, exec, s[4:5]
	s_mov_b64 s[4:5], s[46:47]
	s_mov_b64 s[10:11], s[46:47]
	s_mov_b64 s[0:1], s[46:47]
	s_mov_b64 s[6:7], s[46:47]
	s_mov_b64 s[8:9], s[46:47]
	s_mov_b64 s[12:13], s[46:47]
	s_mov_b64 s[14:15], s[46:47]
	s_mov_b32 s2, -1
	s_waitcnt lgkmcnt(0)
	s_barrier
	s_cselect_b32 s98, 1, 0
	s_cmp_ge_u32 s82, 0x100
	s_cbranch_scc0 .Lprio_skip_13
	s_setprio 1
.Lprio_skip_13:
	s_cmp_lg_u32 s98, 0
	s_cmpk_lt_i32 s86, 0xb00
	v_mbcnt_lo_u32_b32 v0, s2, 0
	v_mbcnt_hi_u32_b32 v0, s2, v0
	s_cselect_b64 s[16:17], -1, 0
	v_or_b32_e32 v8, s82, v0
	s_cmpk_gt_i32 s86, 0xaff
	v_readfirstlane_b32 s28, v8
	s_cbranch_scc1 .LBB0_676
	s_lshr_b32 s2, s87, 29
	s_add_i32 s2, s86, s2
	s_ashr_i32 s3, s2, 3
	s_and_b32 s2, s2, -8
	s_sub_i32 s2, s86, s2
	s_cmp_lt_i32 s2, 0
	s_movk_i32 s18, 0x161
	s_cselect_b32 s18, s18, 0x160
	s_mul_i32 s2, s18, s2
	s_add_i32 s2, s2, s3
	s_mul_hi_i32 s3, s2, 0x2e8ba2e9
	s_lshr_b32 s18, s3, 31
	s_ashr_i32 s3, s3, 5
	s_add_i32 s3, s3, s18
	s_lshl_b32 s18, s3, 3
	s_mulk_i32 s3, 0xb0
	s_sub_i32 s2, s2, s3
	s_sext_i32_i16 s3, s2
	s_bfe_u32 s3, s3, 0x3001c
	s_add_i32 s3, s2, s3
	s_sext_i32_i16 s19, s3
	s_and_b32 s3, s3, 0xfff8
	s_sub_i32 s2, s2, s3
	s_sext_i32_i16 s2, s2
	s_add_i32 s42, s18, s2
	s_ashr_i32 s44, s19, 3

; #define PG8_STAGE(bufoff, gbase, voff) do { _Pragma("unroll") for (int _i = 0; _i < 2; ++_i) \
;         __builtin_amdgcn_global_load_lds((const unsigned*)((const char*)(gbase) + (voff)[_i]), (PG8_LAS unsigned*)(lds + (bufoff) + ldsw + _i * 8192), 16, 0, 0); } while (0)
; #define PG8_LDA(dst, b, h) do { _Pragma("unroll") for (int m = 0; m < 4; ++m) _Pragma("unroll") for (int k = 0; k < 2; ++k) dst[m][k] = *(const PG8_LAS bf16x8*)(lds + PG8_SA(b, h) + aoff + m * 2048 + k * 1024); } while (0)
; #define PG8_LDB(dst, b, h) do { _Pragma("unroll") for (int n = 0; n < 2; ++n) _Pragma("unroll") for (int k = 0; k < 2; ++k) dst[n][k] = *(const PG8_LAS bf16x8*)(lds + PG8_SB(b, h) + boff + n * 2048 + k * 1024); } while (0)
; #define PG8_MMA(ai, bj, At, Bt) do { __builtin_amdgcn_s_setprio(1); _Pragma("unroll") for (int m = 0; m < 4; ++m) _Pragma("unroll") for (int n = 0; n < 2; ++n) _Pragma("unroll") for (int k = 0; k < 2; ++k) \
;         acc[ai][bj][m][n] = __builtin_amdgcn_mfma_f32_16x16x32_bf16(Bt[n][k], At[m][k], acc[ai][bj][m][n], 0, 0, 0); __builtin_amdgcn_s_setprio(0); } while (0)
; #define PG8_WAIT_V(n) asm volatile("s_waitcnt vmcnt(" #n ")" ::: "memory")
; #define PG8_WAIT_L(n) asm volatile("s_waitcnt lgkmcnt(" #n ")" ::: "memory")
; #define PG8_BAR __builtin_amdgcn_s_barrier()
; #define PG8_SCHED __builtin_amdgcn_sched_barrier(0)
; template <class Epi, class Sched, bool ALIGN_EPI = false, bool SP2 = false>
; __device__ __forceinline__ void gemm_phase(PG8_LAS unsigned char* lds, const Gemm g, const Sched& S, const Epi& E, const int tid_arg) {
;     ...
;             PG8_LDB(B0, 0, 0); PG8_LDB(B1, 0, 1); PG8_SCHED; PG8_LDA(At, 0, 0); PG8_STAGE(PG8_SA(1, 1), a1 + hstep, voffA);
;             PG8_WAIT_V(8); PG8_WAIT_L(0); PG8_BAR; PG8_MMA(0, 0, At, B0); PG8_MMA(0, 1, At, B1); PG8_BAR; PG8_SCHED;
;             PG8_LDA(At, 0, 1); PG8_STAGE(PG8_SB(0, 0), b2, voffB); PG8_STAGE(PG8_SB(0, 1), b2 + hstep, voffB); PG8_STAGE(PG8_SA(0, 0), a2, voffA);
;             PG8_WAIT_V(8); PG8_WAIT_L(0); PG8_BAR; PG8_MMA(1, 0, At, B0); PG8_MMA(1, 1, At, B1); PG8_BAR; PG8_SCHED;
.LBB0_685:
	ds_read_b128 v[72:75], v207
	ds_read_b128 v[100:103], v208
	ds_read_b128 v[136:139], v209
	ds_read_b128 v[140:143], v210
	ds_read_b128 v[144:147], v211
	ds_read_b128 v[148:151], v212
	ds_read_b128 v[152:155], v213
	ds_read_b128 v[156:159], v214
	s_add_u32 s10, s4, 0x100
	s_addc_u32 s11, s5, 0
	s_cmp_eq_u32 s79, 12
	s_cselect_b32 s15, s17, s11
	s_cselect_b32 s14, s37, s10
	s_cselect_b32 s1, s35, s78
	s_cselect_b32 s0, s46, s47
	s_mov_b32 m0, s72
	v_lshl_add_u64 v[184:185], s[4:5], 0, v[196:197]
	ds_read_b128 v[160:163], v206
	ds_read_b128 v[164:167], v206 offset:1024
	ds_read_b128 v[168:171], v206 offset:2048
	ds_read_b128 v[172:175], v206 offset:3072
	ds_read_b128 v[176:179], v206 offset:4096
	ds_read_b128 v[180:183], v206 offset:5120
	ds_read_b128 v[226:229], v206 offset:6144
	ds_read_b128 v[230:233], v206 offset:7168
	global_load_lds_dwordx4 v[184:185], off
	v_lshl_add_u64 v[184:185], s[4:5], 0, v[194:195]
	s_mov_b32 m0, s73
	s_nop 0
	global_load_lds_dwordx4 v[184:185], off
	s_waitcnt vmcnt(8)
	s_waitcnt lgkmcnt(0)
	s_barrier
	v_mfma_f32_16x16x32_bf16 v[132:135], v[72:75], v[160:163], v[132:135]
	v_mfma_f32_16x16x32_bf16 v[60:63], v[136:139], v[160:163], v[60:63]
	v_mfma_f32_16x16x32_bf16 v[124:127], v[72:75], v[168:171], v[124:127]
	v_mfma_f32_16x16x32_bf16 v[52:55], v[136:139], v[168:171], v[52:55]
	v_mfma_f32_16x16x32_bf16 v[116:119], v[72:75], v[176:179], v[116:119]
	v_mfma_f32_16x16x32_bf16 v[44:47], v[136:139], v[176:179], v[44:47]
	v_mfma_f32_16x16x32_bf16 v[108:111], v[72:75], v[226:229], v[108:111]
	v_mfma_f32_16x16x32_bf16 v[36:39], v[136:139], v[226:229], v[36:39]
	v_mfma_f32_16x16x32_bf16 v[132:135], v[100:103], v[164:167], v[132:135]
	v_mfma_f32_16x16x32_bf16 v[60:63], v[140:143], v[164:167], v[60:63]
	v_mfma_f32_16x16x32_bf16 v[124:127], v[100:103], v[172:175], v[124:127]
	v_mfma_f32_16x16x32_bf16 v[52:55], v[140:143], v[172:175], v[52:55]
	v_mfma_f32_16x16x32_bf16 v[116:119], v[100:103], v[180:183], v[116:119]
	v_mfma_f32_16x16x32_bf16 v[44:47], v[140:143], v[180:183], v[44:47]
	v_mfma_f32_16x16x32_bf16 v[108:111], v[100:103], v[230:233], v[108:111]
	v_mfma_f32_16x16x32_bf16 v[36:39], v[140:143], v[230:233], v[36:39]
	v_mfma_f32_16x16x32_bf16 v[128:131], v[144:147], v[160:163], v[128:131]
	v_mfma_f32_16x16x32_bf16 v[56:59], v[152:155], v[160:163], v[56:59]
	v_mfma_f32_16x16x32_bf16 v[120:123], v[144:147], v[168:171], v[120:123]
	v_mfma_f32_16x16x32_bf16 v[48:51], v[152:155], v[168:171], v[48:51]
	v_mfma_f32_16x16x32_bf16 v[112:115], v[144:147], v[176:179], v[112:115]
	v_mfma_f32_16x16x32_bf16 v[40:43], v[152:155], v[176:179], v[40:43]
	v_mfma_f32_16x16x32_bf16 v[104:107], v[144:147], v[226:229], v[104:107]
	v_mfma_f32_16x16x32_bf16 v[32:35], v[152:155], v[226:229], v[32:35]
	v_mfma_f32_16x16x32_bf16 v[128:131], v[148:151], v[164:167], v[128:131]
	v_mfma_f32_16x16x32_bf16 v[56:59], v[156:159], v[164:167], v[56:59]
	v_mfma_f32_16x16x32_bf16 v[120:123], v[148:151], v[172:175], v[120:123]
	v_mfma_f32_16x16x32_bf16 v[48:51], v[156:159], v[172:175], v[48:51]
	v_mfma_f32_16x16x32_bf16 v[112:115], v[148:151], v[180:183], v[112:115]
	v_mfma_f32_16x16x32_bf16 v[40:43], v[156:159], v[180:183], v[40:43]
	v_mfma_f32_16x16x32_bf16 v[104:107], v[148:151], v[230:233], v[104:107]
	v_mfma_f32_16x16x32_bf16 v[32:35], v[156:159], v[230:233], v[32:35]
	s_barrier
	s_mov_b32 m0, s43
	v_lshl_add_u64 v[184:185], s[0:1], 0, v[188:189]
	s_add_u32 s4, s0, 0x40000
	ds_read_b128 v[160:163], v206 offset:16384
	ds_read_b128 v[164:167], v206 offset:17408
	ds_read_b128 v[168:171], v206 offset:18432
	ds_read_b128 v[172:175], v206 offset:19456
	ds_read_b128 v[176:179], v206 offset:20480
	ds_read_b128 v[180:183], v206 offset:21504
	ds_read_b128 v[226:229], v206 offset:22528
	ds_read_b128 v[230:233], v206 offset:23552
	global_load_lds_dwordx4 v[184:185], off
	v_lshl_add_u64 v[202:203], s[0:1], 0, v[192:193]
	s_mov_b32 m0, s45
	s_addc_u32 s5, s1, 0
	global_load_lds_dwordx4 v[202:203], off
	v_lshl_add_u64 v[234:235], s[4:5], 0, v[188:189]
	s_mov_b32 m0, s50
	v_lshl_add_u64 v[236:237], s[14:15], 0, v[190:191]
	global_load_lds_dwordx4 v[234:235], off
	v_lshl_add_u64 v[234:235], s[4:5], 0, v[192:193]
	s_mov_b32 m0, s51
	s_nop 0
	global_load_lds_dwordx4 v[234:235], off
	v_lshl_add_u64 v[234:235], s[14:15], 0, v[186:187]
	s_mov_b32 m0, s49
	s_nop 0
	global_load_lds_dwordx4 v[234:235], off
	s_mov_b32 m0, s52
	s_nop 0
	global_load_lds_dwordx4 v[236:237], off
	s_waitcnt vmcnt(8)
	s_waitcnt lgkmcnt(0)
	s_barrier
	v_mfma_f32_16x16x32_bf16 v[96:99], v[72:75], v[160:163], v[96:99]
	v_mfma_f32_16x16x32_bf16 v[28:31], v[136:139], v[160:163], v[28:31]
	v_mfma_f32_16x16x32_bf16 v[88:91], v[72:75], v[168:171], v[88:91]
	v_mfma_f32_16x16x32_bf16 v[20:23], v[136:139], v[168:171], v[20:23]
	v_mfma_f32_16x16x32_bf16 v[80:83], v[72:75], v[176:179], v[80:83]
	v_mfma_f32_16x16x32_bf16 v[12:15], v[136:139], v[176:179], v[12:15]
	v_mfma_f32_16x16x32_bf16 v[68:71], v[72:75], v[226:229], v[68:71]
	v_mfma_f32_16x16x32_bf16 v[4:7], v[136:139], v[226:229], v[4:7]
	v_mfma_f32_16x16x32_bf16 v[96:99], v[100:103], v[164:167], v[96:99]
	v_mfma_f32_16x16x32_bf16 v[28:31], v[140:143], v[164:167], v[28:31]
	v_mfma_f32_16x16x32_bf16 v[88:91], v[100:103], v[172:175], v[88:91]
	v_mfma_f32_16x16x32_bf16 v[20:23], v[140:143], v[172:175], v[20:23]
	v_mfma_f32_16x16x32_bf16 v[80:83], v[100:103], v[180:183], v[80:83]
	v_mfma_f32_16x16x32_bf16 v[12:15], v[140:143], v[180:183], v[12:15]
	v_mfma_f32_16x16x32_bf16 v[68:71], v[100:103], v[230:233], v[68:71]
	v_mfma_f32_16x16x32_bf16 v[4:7], v[140:143], v[230:233], v[4:7]
	v_mfma_f32_16x16x32_bf16 v[24:27], v[152:155], v[160:163], v[24:27]
	v_mfma_f32_16x16x32_bf16 v[84:87], v[144:147], v[168:171], v[84:87]
	v_mfma_f32_16x16x32_bf16 v[16:19], v[152:155], v[168:171], v[16:19]
	v_mfma_f32_16x16x32_bf16 v[76:79], v[144:147], v[176:179], v[76:79]
	v_mfma_f32_16x16x32_bf16 v[8:11], v[152:155], v[176:179], v[8:11]
	v_mfma_f32_16x16x32_bf16 v[64:67], v[144:147], v[226:229], v[64:67]
	v_mfma_f32_16x16x32_bf16 v[0:3], v[152:155], v[226:229], v[0:3]
	v_mfma_f32_16x16x32_bf16 v[72:75], v[144:147], v[160:163], v[92:95]
	v_mfma_f32_16x16x32_bf16 v[24:27], v[156:159], v[164:167], v[24:27]
	v_mfma_f32_16x16x32_bf16 v[84:87], v[148:151], v[172:175], v[84:87]
	v_mfma_f32_16x16x32_bf16 v[16:19], v[156:159], v[172:175], v[16:19]
	v_mfma_f32_16x16x32_bf16 v[76:79], v[148:151], v[180:183], v[76:79]
	v_mfma_f32_16x16x32_bf16 v[8:11], v[156:159], v[180:183], v[8:11]
	v_mfma_f32_16x16x32_bf16 v[64:67], v[148:151], v[230:233], v[64:67]
	v_mfma_f32_16x16x32_bf16 v[0:3], v[156:159], v[230:233], v[0:3]
	v_mfma_f32_16x16x32_bf16 v[72:75], v[148:151], v[164:167], v[72:75]
	s_barrier
; #define PG8_STAGE(bufoff, gbase, voff) do { _Pragma("unroll") for (int _i = 0; _i < 2; ++_i) \
;         __builtin_amdgcn_global_load_lds((const unsigned*)((const char*)(gbase) + (voff)[_i]), (PG8_LAS unsigned*)(lds + (bufoff) + ldsw + _i * 8192), 16, 0, 0); } while (0)
; #define PG8_LDA(dst, b, h) do { _Pragma("unroll") for (int m = 0; m < 4; ++m) _Pragma("unroll") for (int k = 0; k < 2; ++k) dst[m][k] = *(const PG8_LAS bf16x8*)(lds + PG8_SA(b, h) + aoff + m * 2048 + k * 1024); } while (0)
; #define PG8_LDB(dst, b, h) do { _Pragma("unroll") for (int n = 0; n < 2; ++n) _Pragma("unroll") for (int k = 0; k < 2; ++k) dst[n][k] = *(const PG8_LAS bf16x8*)(lds + PG8_SB(b, h) + boff + n * 2048 + k * 1024); } while (0)
; #define PG8_MMA(ai, bj, At, Bt) do { __builtin_amdgcn_s_setprio(1); _Pragma("unroll") for (int m = 0; m < 4; ++m) _Pragma("unroll") for (int n = 0; n < 2; ++n) _Pragma("unroll") for (int k = 0; k < 2; ++k) \
;         acc[ai][bj][m][n] = __builtin_amdgcn_mfma_f32_16x16x32_bf16(Bt[n][k], At[m][k], acc[ai][bj][m][n], 0, 0, 0); __builtin_amdgcn_s_setprio(0); } while (0)
; #define PG8_WAIT_V(n) asm volatile("s_waitcnt vmcnt(" #n ")" ::: "memory")
; #define PG8_WAIT_L(n) asm volatile("s_waitcnt lgkmcnt(" #n ")" ::: "memory")
; #define PG8_BAR __builtin_amdgcn_s_barrier()
; #define PG8_SCHED __builtin_amdgcn_sched_barrier(0)
; template <class Epi, class Sched, bool ALIGN_EPI = false, bool SP2 = false>
; __device__ __forceinline__ void gemm_phase(PG8_LAS unsigned char* lds, const Gemm g, const Sched& S, const Epi& E, const int tid_arg) {
;     ...
;         for (int t = 0; t < nt; t += 2) {
;     ...
;             PG8_LDB(B0, 1, 0); PG8_LDB(B1, 1, 1); PG8_SCHED; PG8_LDA(At, 1, 0); PG8_STAGE(PG8_SA(0, 1), a2 + hstep, voffA);
;             PG8_WAIT_V(8); PG8_WAIT_L(0); PG8_BAR; PG8_MMA(0, 0, At, B0); PG8_MMA(0, 1, At, B1); PG8_BAR; PG8_SCHED;
;             PG8_LDA(At, 1, 1); PG8_STAGE(PG8_SB(1, 0), b3, voffB); PG8_STAGE(PG8_SB(1, 1), b3 + hstep, voffB); PG8_STAGE(PG8_SA(1, 0), a3, voffA);
;             PG8_WAIT_V(8); PG8_WAIT_L(0); PG8_BAR; PG8_MMA(1, 0, At, B0); PG8_MMA(1, 1, At, B1); PG8_BAR; PG8_SCHED;
	ds_read_b128 v[92:95], v215
	ds_read_b128 v[100:103], v216
	ds_read_b128 v[136:139], v217
	ds_read_b128 v[140:143], v218
	ds_read_b128 v[144:147], v219
	ds_read_b128 v[148:151], v220
	ds_read_b128 v[152:155], v221
	ds_read_b128 v[156:159], v222
	s_add_u32 s4, s14, 0x40000
	s_addc_u32 s5, s15, 0
	s_mov_b32 m0, s53
	v_lshl_add_u64 v[238:239], s[4:5], 0, v[186:187]
	ds_read_b128 v[160:163], v206 offset:32768
	ds_read_b128 v[164:167], v206 offset:33792
	ds_read_b128 v[168:171], v206 offset:34816
	ds_read_b128 v[172:175], v206 offset:35840
	ds_read_b128 v[176:179], v206 offset:36864
	ds_read_b128 v[180:183], v206 offset:37888
	ds_read_b128 v[226:229], v206 offset:38912
	ds_read_b128 v[230:233], v206 offset:39936
	global_load_lds_dwordx4 v[238:239], off
	v_lshl_add_u64 v[238:239], s[4:5], 0, v[190:191]
	s_mov_b32 m0, s54
	s_nop 0
	global_load_lds_dwordx4 v[238:239], off
	s_waitcnt vmcnt(8)
	s_waitcnt lgkmcnt(0)
	s_barrier
	v_mfma_f32_16x16x32_bf16 v[132:135], v[92:95], v[160:163], v[132:135]
	v_mfma_f32_16x16x32_bf16 v[60:63], v[136:139], v[160:163], v[60:63]
	v_mfma_f32_16x16x32_bf16 v[124:127], v[92:95], v[168:171], v[124:127]
	v_mfma_f32_16x16x32_bf16 v[52:55], v[136:139], v[168:171], v[52:55]
	v_mfma_f32_16x16x32_bf16 v[116:119], v[92:95], v[176:179], v[116:119]
	v_mfma_f32_16x16x32_bf16 v[44:47], v[136:139], v[176:179], v[44:47]
	v_mfma_f32_16x16x32_bf16 v[108:111], v[92:95], v[226:229], v[108:111]
	v_mfma_f32_16x16x32_bf16 v[36:39], v[136:139], v[226:229], v[36:39]
	v_mfma_f32_16x16x32_bf16 v[132:135], v[100:103], v[164:167], v[132:135]
	v_mfma_f32_16x16x32_bf16 v[60:63], v[140:143], v[164:167], v[60:63]
	v_mfma_f32_16x16x32_bf16 v[124:127], v[100:103], v[172:175], v[124:127]
	v_mfma_f32_16x16x32_bf16 v[52:55], v[140:143], v[172:175], v[52:55]
	v_mfma_f32_16x16x32_bf16 v[116:119], v[100:103], v[180:183], v[116:119]
	v_mfma_f32_16x16x32_bf16 v[44:47], v[140:143], v[180:183], v[44:47]
	v_mfma_f32_16x16x32_bf16 v[108:111], v[100:103], v[230:233], v[108:111]
	v_mfma_f32_16x16x32_bf16 v[36:39], v[140:143], v[230:233], v[36:39]
	v_mfma_f32_16x16x32_bf16 v[128:131], v[144:147], v[160:163], v[128:131]
	v_mfma_f32_16x16x32_bf16 v[56:59], v[152:155], v[160:163], v[56:59]
	v_mfma_f32_16x16x32_bf16 v[120:123], v[144:147], v[168:171], v[120:123]
	v_mfma_f32_16x16x32_bf16 v[48:51], v[152:155], v[168:171], v[48:51]
	v_mfma_f32_16x16x32_bf16 v[112:115], v[144:147], v[176:179], v[112:115]
	v_mfma_f32_16x16x32_bf16 v[40:43], v[152:155], v[176:179], v[40:43]
	v_mfma_f32_16x16x32_bf16 v[104:107], v[144:147], v[226:229], v[104:107]
	v_mfma_f32_16x16x32_bf16 v[32:35], v[152:155], v[226:229], v[32:35]
	v_mfma_f32_16x16x32_bf16 v[128:131], v[148:151], v[164:167], v[128:131]
	v_mfma_f32_16x16x32_bf16 v[56:59], v[156:159], v[164:167], v[56:59]
	v_mfma_f32_16x16x32_bf16 v[120:123], v[148:151], v[172:175], v[120:123]
	v_mfma_f32_16x16x32_bf16 v[48:51], v[156:159], v[172:175], v[48:51]
	v_mfma_f32_16x16x32_bf16 v[112:115], v[148:151], v[180:183], v[112:115]
	v_mfma_f32_16x16x32_bf16 v[40:43], v[156:159], v[180:183], v[40:43]
	v_mfma_f32_16x16x32_bf16 v[104:107], v[148:151], v[230:233], v[104:107]
	v_mfma_f32_16x16x32_bf16 v[32:35], v[156:159], v[230:233], v[32:35]
	s_barrier
	s_mov_b32 m0, s59
	v_lshl_add_u64 v[184:185], v[184:185], 0, s[24:25]
	s_add_u32 s0, s0, 0x40080
	ds_read_b128 v[160:163], v206 offset:49152
	ds_read_b128 v[164:167], v206 offset:50176
	ds_read_b128 v[168:171], v206 offset:51200
	ds_read_b128 v[172:175], v206 offset:52224
	ds_read_b128 v[176:179], v206 offset:53248
	ds_read_b128 v[180:183], v206 offset:54272
	ds_read_b128 v[226:229], v206 offset:55296
	ds_read_b128 v[230:233], v206 offset:56320
	global_load_lds_dwordx4 v[184:185], off
	v_lshl_add_u64 v[184:185], v[202:203], 0, s[24:25]
	s_mov_b32 m0, s60
	s_addc_u32 s1, s1, 0
	global_load_lds_dwordx4 v[184:185], off
	v_lshl_add_u64 v[184:185], s[0:1], 0, v[188:189]
	s_mov_b32 m0, s63
	s_nop 0
	global_load_lds_dwordx4 v[184:185], off
	v_lshl_add_u64 v[184:185], s[0:1], 0, v[192:193]
	s_mov_b32 m0, s64
	s_nop 0
	global_load_lds_dwordx4 v[184:185], off
	v_lshl_add_u64 v[184:185], v[234:235], 0, s[24:25]
	s_mov_b32 m0, s61
	s_nop 0
	global_load_lds_dwordx4 v[184:185], off
	v_lshl_add_u64 v[184:185], v[236:237], 0, s[24:25]
	s_mov_b32 m0, s62
	s_nop 0
	global_load_lds_dwordx4 v[184:185], off
	s_waitcnt vmcnt(8)
	s_waitcnt lgkmcnt(0)
	s_barrier
	v_mfma_f32_16x16x32_bf16 v[96:99], v[92:95], v[160:163], v[96:99]
	v_mfma_f32_16x16x32_bf16 v[28:31], v[136:139], v[160:163], v[28:31]
	v_mfma_f32_16x16x32_bf16 v[88:91], v[92:95], v[168:171], v[88:91]
	v_mfma_f32_16x16x32_bf16 v[20:23], v[136:139], v[168:171], v[20:23]
	v_mfma_f32_16x16x32_bf16 v[80:83], v[92:95], v[176:179], v[80:83]
	v_mfma_f32_16x16x32_bf16 v[12:15], v[136:139], v[176:179], v[12:15]
	v_mfma_f32_16x16x32_bf16 v[68:71], v[92:95], v[226:229], v[68:71]
	v_mfma_f32_16x16x32_bf16 v[4:7], v[136:139], v[226:229], v[4:7]
	v_mfma_f32_16x16x32_bf16 v[96:99], v[100:103], v[164:167], v[96:99]
	v_mfma_f32_16x16x32_bf16 v[28:31], v[140:143], v[164:167], v[28:31]
	v_mfma_f32_16x16x32_bf16 v[88:91], v[100:103], v[172:175], v[88:91]
	v_mfma_f32_16x16x32_bf16 v[20:23], v[140:143], v[172:175], v[20:23]
	v_mfma_f32_16x16x32_bf16 v[80:83], v[100:103], v[180:183], v[80:83]
	v_mfma_f32_16x16x32_bf16 v[12:15], v[140:143], v[180:183], v[12:15]
	v_mfma_f32_16x16x32_bf16 v[68:71], v[100:103], v[230:233], v[68:71]
	v_mfma_f32_16x16x32_bf16 v[4:7], v[140:143], v[230:233], v[4:7]
	v_mfma_f32_16x16x32_bf16 v[72:75], v[144:147], v[160:163], v[72:75]
	v_mfma_f32_16x16x32_bf16 v[92:95], v[148:151], v[164:167], v[72:75]
	v_mfma_f32_16x16x32_bf16 v[72:75], v[144:147], v[168:171], v[84:87]
	v_mfma_f32_16x16x32_bf16 v[24:27], v[152:155], v[160:163], v[24:27]
	v_mfma_f32_16x16x32_bf16 v[84:87], v[148:151], v[172:175], v[72:75]
	v_mfma_f32_16x16x32_bf16 v[16:19], v[152:155], v[168:171], v[16:19]
	v_mfma_f32_16x16x32_bf16 v[72:75], v[144:147], v[176:179], v[76:79]
	v_mfma_f32_16x16x32_bf16 v[8:11], v[152:155], v[176:179], v[8:11]
	v_mfma_f32_16x16x32_bf16 v[64:67], v[144:147], v[226:229], v[64:67]
	v_mfma_f32_16x16x32_bf16 v[0:3], v[152:155], v[226:229], v[0:3]
	v_mfma_f32_16x16x32_bf16 v[24:27], v[156:159], v[164:167], v[24:27]
	v_mfma_f32_16x16x32_bf16 v[16:19], v[156:159], v[172:175], v[16:19]
	v_mfma_f32_16x16x32_bf16 v[76:79], v[148:151], v[180:183], v[72:75]
	v_mfma_f32_16x16x32_bf16 v[8:11], v[156:159], v[180:183], v[8:11]
	v_mfma_f32_16x16x32_bf16 v[64:67], v[148:151], v[230:233], v[64:67]
	v_mfma_f32_16x16x32_bf16 v[0:3], v[156:159], v[230:233], v[0:3]
	s_barrier
	s_add_i32 s79, s79, 2
	s_add_u32 s47, s47, 0x100
	s_addc_u32 s78, s78, 0
	s_cmp_gt_u32 s79, 13
	s_mov_b64 s[4:5], s[10:11]
	s_cbranch_scc0 .LBB0_685
	s_and_b64 vcc, exec, s[26:27]
	s_cbranch_vccz .LBB0_688
	s_barrier

; #define PG8_WAIT_V(n) asm volatile("s_waitcnt vmcnt(" #n ")" ::: "memory")
; #define PG8_BAR __builtin_amdgcn_s_barrier()
; __device__ __forceinline__ void xcd_barrier(const XcdBarrier& b, const bool xb_is_leader) {
;     asm volatile("s_waitcnt vmcnt(0)" ::: "memory");
;     __syncthreads();
;     if (xb_is_leader) {
;         unsigned* bar = b.bar;
;         __builtin_amdgcn_s_waitcnt(0);
;         unsigned nloc = b.st[0], nx = b.st[1];
;         if (nloc == 0u) { xcd_barrier_complete(bar, b.x, nloc, nx); b.st[0] = nloc; b.st[1] = nx; }
; template <class Epi, class Sched, bool ALIGN_EPI = false, bool SP2 = false>
; __device__ __forceinline__ void gemm_phase(PG8_LAS unsigned char* lds, const Gemm g, const Sched& S, const Epi& E, const int tid_arg) {
;     ...
;     PG8_WAIT_V(0);
;     if constexpr (!ALIGN_EPI) { if (wr == 0) PG8_BAR; }
;     PG8_BAR;
.LBB0_731:
	s_mov_b32 s0, -1
	s_nop 0
	v_mbcnt_lo_u32_b32 v0, s0, 0
	v_mbcnt_hi_u32_b32 v0, s0, v0
	s_setprio 0
	s_waitcnt vmcnt(0)
	s_waitcnt vmcnt(0) lgkmcnt(0)
	v_or_b32_e32 v0, s82, v0
	v_cmp_eq_u32_e32 vcc, 0, v0
	s_barrier
	s_and_saveexec_b64 s[4:5], vcc
	s_cbranch_execz .LBB0_783
	v_mov_b32_e32 v0, 0x22000
	s_waitcnt vmcnt(0) expcnt(0) lgkmcnt(0)
	ds_read_b32 v2, v0
	v_mov_b32_e32 v0, 0x22004
	ds_read_b32 v0, v0
	s_waitcnt lgkmcnt(1)
	v_cmp_ne_u32_e32 vcc, 0, v2
	s_cbranch_vccnz .LBB0_747
	v_readlane_b32 s0, v251, 0
	v_readlane_b32 s1, v251, 1
	v_readlane_b32 s2, v251, 2
	s_mul_i32 s2, s1, s2
	s_mul_i32 s2, s2, s0
	s_add_u32 s0, s76, 0x1000
	s_addc_u32 s1, s77, 0
	s_add_u32 s6, s76, 0x1100
	s_addc_u32 s7, s77, 0
	s_add_u32 s8, s76, 0x1200
	s_addc_u32 s9, s77, 0
	s_add_u32 s10, s76, 0x1300
	s_addc_u32 s11, s77, 0
	s_mov_b32 s3, 1
	v_mov_b32_e32 v16, 0
	s_branch .LBB0_735

; #define AIN(i) (kargs()->in[i])
; #define AWS (kargs()->ws)
; #define K_TID ((wave_s << 6) | lane_fresh())
; __device__ __forceinline__ void fix_rows(bf16_t* A, const float* edge, const float* cw, const float* cb, int pm, int tid) {
;     const bool hasprev = (pm & 15) != 0;
; #pragma unroll
;     for (int it_ = 0; it_ < 6; ++it_) {
;         const int ch = tid + 512 * it_; if (ch >= DFF) break;
;         const int pn = ch >> 7, ci = ch & 127;
; __global__ void __launch_bounds__(512, 2) fwd_megakernel(Args a) {
;     ...
;             pg8::Gemm g{P_Zb, (const bf16_t*)(AWS + WS_WDN + l * SZ_WDN), T, DM, DFF}; pg8::StaticOrder S; S.init(T, DM, G, bx);
;             pg8::Unit u;
;             int tid_l = K_TID; asm volatile("" : "+v"(tid_l));
;             for (int i = 0; S.next(i, u); ++i) fix_rows(P_Zb, P_EDGE, AIN(12) + (size_t)l * 3 * UPN, AIN(13) + l * UPN, u.pm, tid_l);
.Lprio_skip_14:
	s_cmp_lg_u32 s98, 0
	s_load_dwordx2 s[4:5], s[0:1], 0x98
	s_mov_b64 s[0:1], s[46:47]
	s_load_dwordx2 s[6:7], s[0:1], 0x98
	s_mov_b32 s0, -1
	v_mov_b32_e32 v1, 0
	v_mbcnt_lo_u32_b32 v0, s0, 0
	v_mbcnt_hi_u32_b32 v0, s0, v0
	v_readlane_b32 s0, v251, 0
	s_ashr_i32 s73, s0, 31
	v_or_b32_e32 v8, s82, v0
	s_mov_b32 s78, s0
	s_movk_i32 s0, 0xb00
	v_mov_b64_e32 v[4:5], 0x1ff
	v_cmp_gt_i32_e64 s[10:11], s0, v8
	v_add_u32_e32 v2, 0x200, v8
	s_movk_i32 s0, 0x900
	v_cmp_gt_i32_e64 s[12:13], s0, v8
	v_ashrrev_i32_e32 v23, 7, v2
	v_add_u32_e32 v2, 0x400, v8
	s_movk_i32 s0, 0x700
	v_cmp_gt_i32_e64 s[14:15], s0, v8
	v_ashrrev_i32_e32 v24, 7, v2
	v_add_u32_e32 v2, 0x600, v8
	s_movk_i32 s0, 0x500
	v_cmp_gt_i32_e64 s[16:17], s0, v8
	v_ashrrev_i32_e32 v25, 7, v2
	v_add_u32_e32 v2, 0x800, v8
	s_movk_i32 s0, 0x300
	v_and_b32_e32 v0, 0x7f, v8
	v_ashrrev_i32_e32 v9, 31, v8
	v_cmp_gt_i32_e64 s[18:19], s0, v8
	v_ashrrev_i32_e32 v26, 7, v2
	v_add_u32_e32 v2, 0xa00, v8
	s_movk_i32 s0, 0x100
	v_ashrrev_i32_e32 v22, 7, v8
	v_cmp_gt_i32_e64 s[20:21], s0, v8
	v_ashrrev_i32_e32 v27, 7, v2
	v_mov_b64_e32 v[2:3], 0x200
	v_lshlrev_b64 v[6:7], 2, v[8:9]
	s_movk_i32 s2, 0x2000
	s_mov_b32 s3, 0x8000
	s_mov_b32 s33, 0xd000
	v_lshlrev_b64 v[8:9], 1, v[8:9]
	v_lshlrev_b32_e32 v0, 2, v0
	s_mov_b64 s[8:9], s[86:87]
	v_readlane_b32 s1, v251, 1
	s_branch .LBB0_787

; #define PG8_STAGE(bufoff, gbase, voff) do { _Pragma("unroll") for (int _i = 0; _i < 2; ++_i) \
;         __builtin_amdgcn_global_load_lds((const unsigned*)((const char*)(gbase) + (voff)[_i]), (PG8_LAS unsigned*)(lds + (bufoff) + ldsw + _i * 8192), 16, 0, 0); } while (0)
; #define PG8_LDA(dst, b, h) do { _Pragma("unroll") for (int m = 0; m < 4; ++m) _Pragma("unroll") for (int k = 0; k < 2; ++k) dst[m][k] = *(const PG8_LAS bf16x8*)(lds + PG8_SA(b, h) + aoff + m * 2048 + k * 1024); } while (0)
; #define PG8_LDB(dst, b, h) do { _Pragma("unroll") for (int n = 0; n < 2; ++n) _Pragma("unroll") for (int k = 0; k < 2; ++k) dst[n][k] = *(const PG8_LAS bf16x8*)(lds + PG8_SB(b, h) + boff + n * 2048 + k * 1024); } while (0)
; #define PG8_MMA(ai, bj, At, Bt) do { __builtin_amdgcn_s_setprio(1); _Pragma("unroll") for (int m = 0; m < 4; ++m) _Pragma("unroll") for (int n = 0; n < 2; ++n) _Pragma("unroll") for (int k = 0; k < 2; ++k) \
;         acc[ai][bj][m][n] = __builtin_amdgcn_mfma_f32_16x16x32_bf16(Bt[n][k], At[m][k], acc[ai][bj][m][n], 0, 0, 0); __builtin_amdgcn_s_setprio(0); } while (0)
; #define PG8_WAIT_V(n) asm volatile("s_waitcnt vmcnt(" #n ")" ::: "memory")
; #define PG8_WAIT_L(n) asm volatile("s_waitcnt lgkmcnt(" #n ")" ::: "memory")
; #define PG8_BAR __builtin_amdgcn_s_barrier()
; #define PG8_SCHED __builtin_amdgcn_sched_barrier(0)
; template <class Epi, class Sched, bool ALIGN_EPI = false, bool SP2 = false>
; __device__ __forceinline__ void gemm_phase(PG8_LAS unsigned char* lds, const Gemm g, const Sched& S, const Epi& E, const int tid_arg) {
;     ...
;             PG8_LDB(B0, 0, 0); PG8_LDB(B1, 0, 1); PG8_SCHED; PG8_LDA(At, 0, 0); PG8_STAGE(PG8_SA(1, 1), a1 + hstep, voffA);
;             PG8_WAIT_V(8); PG8_WAIT_L(0); PG8_BAR; PG8_MMA(0, 0, At, B0); PG8_MMA(0, 1, At, B1); PG8_BAR; PG8_SCHED;
;             PG8_LDA(At, 0, 1); PG8_STAGE(PG8_SB(0, 0), b2, voffB); PG8_STAGE(PG8_SB(0, 1), b2 + hstep, voffB); PG8_STAGE(PG8_SA(0, 0), a2, voffA);
;             PG8_WAIT_V(8); PG8_WAIT_L(0); PG8_BAR; PG8_MMA(1, 0, At, B0); PG8_MMA(1, 1, At, B1); PG8_BAR; PG8_SCHED;
.LBB0_871:
	ds_read_b128 v[144:147], v151
	ds_read_b128 v[168:171], v152
	ds_read_b128 v[172:175], v153
	ds_read_b128 v[176:179], v154
	ds_read_b128 v[180:183], v155
	ds_read_b128 v[184:187], v156
	ds_read_b128 v[188:191], v157
	ds_read_b128 v[192:195], v158
	s_add_u32 s22, s4, 0x100
	s_addc_u32 s23, s5, 0
	s_cmp_eq_u32 s57, 40
	s_cselect_b32 s25, s13, s23
	s_cselect_b32 s24, s12, s22
	s_cselect_b32 s1, s21, s56
	s_cselect_b32 s0, s20, s55
	s_mov_b32 m0, s48
	v_lshl_add_u64 v[228:229], s[4:5], 0, v[138:139]
	ds_read_b128 v[196:199], v150
	ds_read_b128 v[200:203], v150 offset:1024
	ds_read_b128 v[204:207], v150 offset:2048
	ds_read_b128 v[208:211], v150 offset:3072
	ds_read_b128 v[212:215], v150 offset:4096
	ds_read_b128 v[216:219], v150 offset:5120
	ds_read_b128 v[220:223], v150 offset:6144
	ds_read_b128 v[224:227], v150 offset:7168
	global_load_lds_dwordx4 v[228:229], off
	v_lshl_add_u64 v[228:229], s[4:5], 0, v[136:137]
	s_mov_b32 m0, s49
	s_nop 0
	global_load_lds_dwordx4 v[228:229], off
	s_waitcnt vmcnt(8)
	s_waitcnt lgkmcnt(0)
	s_barrier
	v_mfma_f32_16x16x32_bf16 v[124:127], v[144:147], v[196:199], v[124:127]
	v_mfma_f32_16x16x32_bf16 v[120:123], v[172:175], v[196:199], v[120:123]
	v_mfma_f32_16x16x32_bf16 v[108:111], v[144:147], v[204:207], v[108:111]
	v_mfma_f32_16x16x32_bf16 v[104:107], v[172:175], v[204:207], v[104:107]
	v_mfma_f32_16x16x32_bf16 v[92:95], v[144:147], v[212:215], v[92:95]
	v_mfma_f32_16x16x32_bf16 v[88:91], v[172:175], v[212:215], v[88:91]
	v_mfma_f32_16x16x32_bf16 v[76:79], v[144:147], v[220:223], v[76:79]
	v_mfma_f32_16x16x32_bf16 v[72:75], v[172:175], v[220:223], v[72:75]
	v_mfma_f32_16x16x32_bf16 v[124:127], v[168:171], v[200:203], v[124:127]
	v_mfma_f32_16x16x32_bf16 v[120:123], v[176:179], v[200:203], v[120:123]
	v_mfma_f32_16x16x32_bf16 v[108:111], v[168:171], v[208:211], v[108:111]
	v_mfma_f32_16x16x32_bf16 v[104:107], v[176:179], v[208:211], v[104:107]
	v_mfma_f32_16x16x32_bf16 v[92:95], v[168:171], v[216:219], v[92:95]
	v_mfma_f32_16x16x32_bf16 v[88:91], v[176:179], v[216:219], v[88:91]
	v_mfma_f32_16x16x32_bf16 v[76:79], v[168:171], v[224:227], v[76:79]
	v_mfma_f32_16x16x32_bf16 v[72:75], v[176:179], v[224:227], v[72:75]
	v_mfma_f32_16x16x32_bf16 v[116:119], v[180:183], v[196:199], v[116:119]
	v_mfma_f32_16x16x32_bf16 v[112:115], v[188:191], v[196:199], v[112:115]
	v_mfma_f32_16x16x32_bf16 v[100:103], v[180:183], v[204:207], v[100:103]
	v_mfma_f32_16x16x32_bf16 v[96:99], v[188:191], v[204:207], v[96:99]
	v_mfma_f32_16x16x32_bf16 v[84:87], v[180:183], v[212:215], v[84:87]
	v_mfma_f32_16x16x32_bf16 v[80:83], v[188:191], v[212:215], v[80:83]
	v_mfma_f32_16x16x32_bf16 v[68:71], v[180:183], v[220:223], v[68:71]
	v_mfma_f32_16x16x32_bf16 v[64:67], v[188:191], v[220:223], v[64:67]
	v_mfma_f32_16x16x32_bf16 v[116:119], v[184:187], v[200:203], v[116:119]
	v_mfma_f32_16x16x32_bf16 v[112:115], v[192:195], v[200:203], v[112:115]
	v_mfma_f32_16x16x32_bf16 v[100:103], v[184:187], v[208:211], v[100:103]
	v_mfma_f32_16x16x32_bf16 v[96:99], v[192:195], v[208:211], v[96:99]
	v_mfma_f32_16x16x32_bf16 v[84:87], v[184:187], v[216:219], v[84:87]
	v_mfma_f32_16x16x32_bf16 v[80:83], v[192:195], v[216:219], v[80:83]
	v_mfma_f32_16x16x32_bf16 v[68:71], v[184:187], v[224:227], v[68:71]
	v_mfma_f32_16x16x32_bf16 v[64:67], v[192:195], v[224:227], v[64:67]
	s_barrier
	s_mov_b32 m0, s29
	v_lshl_add_u64 v[228:229], s[0:1], 0, v[130:131]
	s_add_u32 s4, s0, 0xb0000
	ds_read_b128 v[196:199], v150 offset:16384
	ds_read_b128 v[200:203], v150 offset:17408
	ds_read_b128 v[204:207], v150 offset:18432
	ds_read_b128 v[208:211], v150 offset:19456
	ds_read_b128 v[212:215], v150 offset:20480
	ds_read_b128 v[216:219], v150 offset:21504
	ds_read_b128 v[220:223], v150 offset:22528
	ds_read_b128 v[224:227], v150 offset:23552
	global_load_lds_dwordx4 v[228:229], off
	v_lshl_add_u64 v[230:231], s[0:1], 0, v[134:135]
	s_mov_b32 m0, s30
	s_addc_u32 s5, s1, 0
	global_load_lds_dwordx4 v[230:231], off
	v_lshl_add_u64 v[232:233], s[4:5], 0, v[130:131]
	s_mov_b32 m0, s31
	v_lshl_add_u64 v[234:235], s[24:25], 0, v[132:133]
	global_load_lds_dwordx4 v[232:233], off
	v_lshl_add_u64 v[232:233], s[4:5], 0, v[134:135]
	s_mov_b32 m0, s33
	s_nop 0
	global_load_lds_dwordx4 v[232:233], off
	v_lshl_add_u64 v[232:233], s[24:25], 0, v[128:129]
	s_mov_b32 m0, s28
	s_nop 0
	global_load_lds_dwordx4 v[232:233], off
	s_mov_b32 m0, s34
	s_nop 0
	global_load_lds_dwordx4 v[234:235], off
	s_waitcnt vmcnt(8)
	s_waitcnt lgkmcnt(0)
	s_barrier
	v_mfma_f32_16x16x32_bf16 v[60:63], v[144:147], v[196:199], v[60:63]
	v_mfma_f32_16x16x32_bf16 v[56:59], v[172:175], v[196:199], v[56:59]
	v_mfma_f32_16x16x32_bf16 v[44:47], v[144:147], v[204:207], v[44:47]
	v_mfma_f32_16x16x32_bf16 v[40:43], v[172:175], v[204:207], v[40:43]
	v_mfma_f32_16x16x32_bf16 v[28:31], v[144:147], v[212:215], v[28:31]
	v_mfma_f32_16x16x32_bf16 v[24:27], v[172:175], v[212:215], v[24:27]
	v_mfma_f32_16x16x32_bf16 v[12:15], v[144:147], v[220:223], v[12:15]
	v_mfma_f32_16x16x32_bf16 v[8:11], v[172:175], v[220:223], v[8:11]
	v_mfma_f32_16x16x32_bf16 v[60:63], v[168:171], v[200:203], v[60:63]
	v_mfma_f32_16x16x32_bf16 v[56:59], v[176:179], v[200:203], v[56:59]
	v_mfma_f32_16x16x32_bf16 v[44:47], v[168:171], v[208:211], v[44:47]
	v_mfma_f32_16x16x32_bf16 v[40:43], v[176:179], v[208:211], v[40:43]
	v_mfma_f32_16x16x32_bf16 v[28:31], v[168:171], v[216:219], v[28:31]
	v_mfma_f32_16x16x32_bf16 v[24:27], v[176:179], v[216:219], v[24:27]
	v_mfma_f32_16x16x32_bf16 v[12:15], v[168:171], v[224:227], v[12:15]
	v_mfma_f32_16x16x32_bf16 v[8:11], v[176:179], v[224:227], v[8:11]
	v_mfma_f32_16x16x32_bf16 v[52:55], v[180:183], v[196:199], v[52:55]
	v_mfma_f32_16x16x32_bf16 v[48:51], v[188:191], v[196:199], v[48:51]
	v_mfma_f32_16x16x32_bf16 v[36:39], v[180:183], v[204:207], v[36:39]
	v_mfma_f32_16x16x32_bf16 v[32:35], v[188:191], v[204:207], v[32:35]
	v_mfma_f32_16x16x32_bf16 v[20:23], v[180:183], v[212:215], v[20:23]
	v_mfma_f32_16x16x32_bf16 v[16:19], v[188:191], v[212:215], v[16:19]
	v_mfma_f32_16x16x32_bf16 v[4:7], v[180:183], v[220:223], v[4:7]
	v_mfma_f32_16x16x32_bf16 v[0:3], v[188:191], v[220:223], v[0:3]
	v_mfma_f32_16x16x32_bf16 v[52:55], v[184:187], v[200:203], v[52:55]
	v_mfma_f32_16x16x32_bf16 v[48:51], v[192:195], v[200:203], v[48:51]
	v_mfma_f32_16x16x32_bf16 v[36:39], v[184:187], v[208:211], v[36:39]
	v_mfma_f32_16x16x32_bf16 v[32:35], v[192:195], v[208:211], v[32:35]
	v_mfma_f32_16x16x32_bf16 v[20:23], v[184:187], v[216:219], v[20:23]
	v_mfma_f32_16x16x32_bf16 v[16:19], v[192:195], v[216:219], v[16:19]
	v_mfma_f32_16x16x32_bf16 v[4:7], v[184:187], v[224:227], v[4:7]
	v_mfma_f32_16x16x32_bf16 v[0:3], v[192:195], v[224:227], v[0:3]
	s_barrier
; #define PG8_STAGE(bufoff, gbase, voff) do { _Pragma("unroll") for (int _i = 0; _i < 2; ++_i) \
;         __builtin_amdgcn_global_load_lds((const unsigned*)((const char*)(gbase) + (voff)[_i]), (PG8_LAS unsigned*)(lds + (bufoff) + ldsw + _i * 8192), 16, 0, 0); } while (0)
; #define PG8_LDA(dst, b, h) do { _Pragma("unroll") for (int m = 0; m < 4; ++m) _Pragma("unroll") for (int k = 0; k < 2; ++k) dst[m][k] = *(const PG8_LAS bf16x8*)(lds + PG8_SA(b, h) + aoff + m * 2048 + k * 1024); } while (0)
; #define PG8_LDB(dst, b, h) do { _Pragma("unroll") for (int n = 0; n < 2; ++n) _Pragma("unroll") for (int k = 0; k < 2; ++k) dst[n][k] = *(const PG8_LAS bf16x8*)(lds + PG8_SB(b, h) + boff + n * 2048 + k * 1024); } while (0)
; #define PG8_MMA(ai, bj, At, Bt) do { __builtin_amdgcn_s_setprio(1); _Pragma("unroll") for (int m = 0; m < 4; ++m) _Pragma("unroll") for (int n = 0; n < 2; ++n) _Pragma("unroll") for (int k = 0; k < 2; ++k) \
;         acc[ai][bj][m][n] = __builtin_amdgcn_mfma_f32_16x16x32_bf16(Bt[n][k], At[m][k], acc[ai][bj][m][n], 0, 0, 0); __builtin_amdgcn_s_setprio(0); } while (0)
; #define PG8_WAIT_V(n) asm volatile("s_waitcnt vmcnt(" #n ")" ::: "memory")
; #define PG8_WAIT_L(n) asm volatile("s_waitcnt lgkmcnt(" #n ")" ::: "memory")
; #define PG8_BAR __builtin_amdgcn_s_barrier()
; #define PG8_SCHED __builtin_amdgcn_sched_barrier(0)
; template <class Epi, class Sched, bool ALIGN_EPI = false, bool SP2 = false>
; __device__ __forceinline__ void gemm_phase(PG8_LAS unsigned char* lds, const Gemm g, const Sched& S, const Epi& E, const int tid_arg) {
;     ...
;         for (int t = 0; t < nt; t += 2) {
;     ...
;             PG8_LDB(B0, 1, 0); PG8_LDB(B1, 1, 1); PG8_SCHED; PG8_LDA(At, 1, 0); PG8_STAGE(PG8_SA(0, 1), a2 + hstep, voffA);
;             PG8_WAIT_V(8); PG8_WAIT_L(0); PG8_BAR; PG8_MMA(0, 0, At, B0); PG8_MMA(0, 1, At, B1); PG8_BAR; PG8_SCHED;
;             PG8_LDA(At, 1, 1); PG8_STAGE(PG8_SB(1, 0), b3, voffB); PG8_STAGE(PG8_SB(1, 1), b3 + hstep, voffB); PG8_STAGE(PG8_SA(1, 0), a3, voffA);
;             PG8_WAIT_V(8); PG8_WAIT_L(0); PG8_BAR; PG8_MMA(1, 0, At, B0); PG8_MMA(1, 1, At, B1); PG8_BAR; PG8_SCHED;
	ds_read_b128 v[144:147], v159
	ds_read_b128 v[168:171], v160
	ds_read_b128 v[172:175], v161
	ds_read_b128 v[176:179], v162
	ds_read_b128 v[180:183], v163
	ds_read_b128 v[184:187], v164
	ds_read_b128 v[188:191], v165
	ds_read_b128 v[192:195], v166
	s_add_u32 s4, s24, 0xb0000
	s_addc_u32 s5, s25, 0
	s_mov_b32 m0, s35
	v_lshl_add_u64 v[236:237], s[4:5], 0, v[128:129]
	ds_read_b128 v[196:199], v150 offset:32768
	ds_read_b128 v[200:203], v150 offset:33792
	ds_read_b128 v[204:207], v150 offset:34816
	ds_read_b128 v[208:211], v150 offset:35840
	ds_read_b128 v[212:215], v150 offset:36864
	ds_read_b128 v[216:219], v150 offset:37888
	ds_read_b128 v[220:223], v150 offset:38912
	ds_read_b128 v[224:227], v150 offset:39936
	global_load_lds_dwordx4 v[236:237], off
	v_lshl_add_u64 v[236:237], s[4:5], 0, v[132:133]
	s_mov_b32 m0, s36
	s_nop 0
	global_load_lds_dwordx4 v[236:237], off
	s_waitcnt vmcnt(8)
	s_waitcnt lgkmcnt(0)
	s_barrier
	v_mfma_f32_16x16x32_bf16 v[124:127], v[144:147], v[196:199], v[124:127]
	v_mfma_f32_16x16x32_bf16 v[120:123], v[172:175], v[196:199], v[120:123]
	v_mfma_f32_16x16x32_bf16 v[108:111], v[144:147], v[204:207], v[108:111]
	v_mfma_f32_16x16x32_bf16 v[104:107], v[172:175], v[204:207], v[104:107]
	v_mfma_f32_16x16x32_bf16 v[92:95], v[144:147], v[212:215], v[92:95]
	v_mfma_f32_16x16x32_bf16 v[88:91], v[172:175], v[212:215], v[88:91]
	v_mfma_f32_16x16x32_bf16 v[76:79], v[144:147], v[220:223], v[76:79]
	v_mfma_f32_16x16x32_bf16 v[72:75], v[172:175], v[220:223], v[72:75]
	v_mfma_f32_16x16x32_bf16 v[124:127], v[168:171], v[200:203], v[124:127]
	v_mfma_f32_16x16x32_bf16 v[120:123], v[176:179], v[200:203], v[120:123]
	v_mfma_f32_16x16x32_bf16 v[108:111], v[168:171], v[208:211], v[108:111]
	v_mfma_f32_16x16x32_bf16 v[104:107], v[176:179], v[208:211], v[104:107]
	v_mfma_f32_16x16x32_bf16 v[92:95], v[168:171], v[216:219], v[92:95]
	v_mfma_f32_16x16x32_bf16 v[88:91], v[176:179], v[216:219], v[88:91]
	v_mfma_f32_16x16x32_bf16 v[76:79], v[168:171], v[224:227], v[76:79]
	v_mfma_f32_16x16x32_bf16 v[72:75], v[176:179], v[224:227], v[72:75]
	v_mfma_f32_16x16x32_bf16 v[116:119], v[180:183], v[196:199], v[116:119]
	v_mfma_f32_16x16x32_bf16 v[112:115], v[188:191], v[196:199], v[112:115]
	v_mfma_f32_16x16x32_bf16 v[100:103], v[180:183], v[204:207], v[100:103]
	v_mfma_f32_16x16x32_bf16 v[96:99], v[188:191], v[204:207], v[96:99]
	v_mfma_f32_16x16x32_bf16 v[84:87], v[180:183], v[212:215], v[84:87]
	v_mfma_f32_16x16x32_bf16 v[80:83], v[188:191], v[212:215], v[80:83]
	v_mfma_f32_16x16x32_bf16 v[68:71], v[180:183], v[220:223], v[68:71]
	v_mfma_f32_16x16x32_bf16 v[64:67], v[188:191], v[220:223], v[64:67]
	v_mfma_f32_16x16x32_bf16 v[116:119], v[184:187], v[200:203], v[116:119]
	v_mfma_f32_16x16x32_bf16 v[112:115], v[192:195], v[200:203], v[112:115]
	v_mfma_f32_16x16x32_bf16 v[100:103], v[184:187], v[208:211], v[100:103]
	v_mfma_f32_16x16x32_bf16 v[96:99], v[192:195], v[208:211], v[96:99]
	v_mfma_f32_16x16x32_bf16 v[84:87], v[184:187], v[216:219], v[84:87]
	v_mfma_f32_16x16x32_bf16 v[80:83], v[192:195], v[216:219], v[80:83]
	v_mfma_f32_16x16x32_bf16 v[68:71], v[184:187], v[224:227], v[68:71]
	v_mfma_f32_16x16x32_bf16 v[64:67], v[192:195], v[224:227], v[64:67]
	s_barrier
	s_mov_b32 m0, s40
	v_lshl_add_u64 v[228:229], v[228:229], 0, s[16:17]
	s_add_u32 s0, s0, 0xb0080
	ds_read_b128 v[196:199], v150 offset:49152
	ds_read_b128 v[200:203], v150 offset:50176
	ds_read_b128 v[204:207], v150 offset:51200
	ds_read_b128 v[208:211], v150 offset:52224
	ds_read_b128 v[212:215], v150 offset:53248
	ds_read_b128 v[216:219], v150 offset:54272
	ds_read_b128 v[220:223], v150 offset:55296
	ds_read_b128 v[224:227], v150 offset:56320
	global_load_lds_dwordx4 v[228:229], off
	v_lshl_add_u64 v[228:229], v[230:231], 0, s[16:17]
	s_mov_b32 m0, s41
	s_addc_u32 s1, s1, 0
	global_load_lds_dwordx4 v[228:229], off
	v_lshl_add_u64 v[228:229], s[0:1], 0, v[130:131]
	s_mov_b32 m0, s44
	s_nop 0
	global_load_lds_dwordx4 v[228:229], off
	v_lshl_add_u64 v[228:229], s[0:1], 0, v[134:135]
	s_mov_b32 m0, s45
	s_nop 0
	global_load_lds_dwordx4 v[228:229], off
	v_lshl_add_u64 v[228:229], v[232:233], 0, s[16:17]
	s_mov_b32 m0, s42
	s_nop 0
	global_load_lds_dwordx4 v[228:229], off
	v_lshl_add_u64 v[228:229], v[234:235], 0, s[16:17]
	s_mov_b32 m0, s43
	s_nop 0
	global_load_lds_dwordx4 v[228:229], off
	s_waitcnt vmcnt(8)
	s_waitcnt lgkmcnt(0)
	s_barrier
	v_mfma_f32_16x16x32_bf16 v[60:63], v[144:147], v[196:199], v[60:63]
	v_mfma_f32_16x16x32_bf16 v[56:59], v[172:175], v[196:199], v[56:59]
	v_mfma_f32_16x16x32_bf16 v[44:47], v[144:147], v[204:207], v[44:47]
	v_mfma_f32_16x16x32_bf16 v[40:43], v[172:175], v[204:207], v[40:43]
	v_mfma_f32_16x16x32_bf16 v[28:31], v[144:147], v[212:215], v[28:31]
	v_mfma_f32_16x16x32_bf16 v[24:27], v[172:175], v[212:215], v[24:27]
	v_mfma_f32_16x16x32_bf16 v[12:15], v[144:147], v[220:223], v[12:15]
	v_mfma_f32_16x16x32_bf16 v[8:11], v[172:175], v[220:223], v[8:11]
	v_mfma_f32_16x16x32_bf16 v[60:63], v[168:171], v[200:203], v[60:63]
	v_mfma_f32_16x16x32_bf16 v[56:59], v[176:179], v[200:203], v[56:59]
	v_mfma_f32_16x16x32_bf16 v[44:47], v[168:171], v[208:211], v[44:47]
	v_mfma_f32_16x16x32_bf16 v[40:43], v[176:179], v[208:211], v[40:43]
	v_mfma_f32_16x16x32_bf16 v[28:31], v[168:171], v[216:219], v[28:31]
	v_mfma_f32_16x16x32_bf16 v[24:27], v[176:179], v[216:219], v[24:27]
	v_mfma_f32_16x16x32_bf16 v[12:15], v[168:171], v[224:227], v[12:15]
	v_mfma_f32_16x16x32_bf16 v[8:11], v[176:179], v[224:227], v[8:11]
	v_mfma_f32_16x16x32_bf16 v[52:55], v[180:183], v[196:199], v[52:55]
	v_mfma_f32_16x16x32_bf16 v[48:51], v[188:191], v[196:199], v[48:51]
	v_mfma_f32_16x16x32_bf16 v[36:39], v[180:183], v[204:207], v[36:39]
	v_mfma_f32_16x16x32_bf16 v[32:35], v[188:191], v[204:207], v[32:35]
	v_mfma_f32_16x16x32_bf16 v[20:23], v[180:183], v[212:215], v[20:23]
	v_mfma_f32_16x16x32_bf16 v[16:19], v[188:191], v[212:215], v[16:19]
	v_mfma_f32_16x16x32_bf16 v[4:7], v[180:183], v[220:223], v[4:7]
	v_mfma_f32_16x16x32_bf16 v[0:3], v[188:191], v[220:223], v[0:3]
	v_mfma_f32_16x16x32_bf16 v[52:55], v[184:187], v[200:203], v[52:55]
	v_mfma_f32_16x16x32_bf16 v[48:51], v[192:195], v[200:203], v[48:51]
	v_mfma_f32_16x16x32_bf16 v[36:39], v[184:187], v[208:211], v[36:39]
	v_mfma_f32_16x16x32_bf16 v[32:35], v[192:195], v[208:211], v[32:35]
	v_mfma_f32_16x16x32_bf16 v[20:23], v[184:187], v[216:219], v[20:23]
	v_mfma_f32_16x16x32_bf16 v[16:19], v[192:195], v[216:219], v[16:19]
	v_mfma_f32_16x16x32_bf16 v[4:7], v[184:187], v[224:227], v[4:7]
	v_mfma_f32_16x16x32_bf16 v[0:3], v[192:195], v[224:227], v[0:3]
	s_barrier
	s_add_i32 s57, s57, 2
	s_add_u32 s55, s55, 0x100
	s_addc_u32 s56, s56, 0
	s_cmp_gt_u32 s57, 41
	s_mov_b64 s[4:5], s[22:23]
	s_cbranch_scc0 .LBB0_871
	s_and_b64 vcc, exec, s[18:19]
	s_cbranch_vccz .LBB0_874
	s_barrier

; #define PG8_WAIT_V(n) asm volatile("s_waitcnt vmcnt(" #n ")" ::: "memory")
; #define PG8_BAR __builtin_amdgcn_s_barrier()
; __device__ __forceinline__ void xcd_barrier(const XcdBarrier& b, const bool xb_is_leader) {
;     asm volatile("s_waitcnt vmcnt(0)" ::: "memory");
;     __syncthreads();
;     if (xb_is_leader) {
;         unsigned* bar = b.bar;
;         __builtin_amdgcn_s_waitcnt(0);
;         unsigned nloc = b.st[0], nx = b.st[1];
;         if (nloc == 0u) { xcd_barrier_complete(bar, b.x, nloc, nx); b.st[0] = nloc; b.st[1] = nx; }
; template <class Epi, class Sched, bool ALIGN_EPI = false, bool SP2 = false>
; __device__ __forceinline__ void gemm_phase(PG8_LAS unsigned char* lds, const Gemm g, const Sched& S, const Epi& E, const int tid_arg) {
;     ...
;     PG8_WAIT_V(0);
;     if constexpr (!ALIGN_EPI) { if (wr == 0) PG8_BAR; }
;     PG8_BAR;
.LBB0_896:
	s_mov_b32 s0, -1
	s_nop 0
	v_mbcnt_lo_u32_b32 v0, s0, 0
	v_mbcnt_hi_u32_b32 v0, s0, v0
	s_setprio 0
	s_waitcnt vmcnt(0)
	s_waitcnt lgkmcnt(0)
	v_or_b32_e32 v0, s82, v0
	v_cmp_eq_u32_e32 vcc, 0, v0
	s_barrier
	s_and_saveexec_b64 s[4:5], vcc
	s_cbranch_execz .LBB0_948
	v_mov_b32_e32 v0, 0x22000
	s_waitcnt vmcnt(0) expcnt(0) lgkmcnt(0)
	ds_read_b32 v2, v0
	v_mov_b32_e32 v0, 0x22004
	ds_read_b32 v0, v0
	s_waitcnt lgkmcnt(1)
	v_cmp_ne_u32_e32 vcc, 0, v2
	s_cbranch_vccnz .LBB0_912
	v_readlane_b32 s0, v251, 0
	v_readlane_b32 s1, v251, 1
	v_readlane_b32 s2, v251, 2
	s_mul_i32 s2, s1, s2
	s_mul_i32 s2, s2, s0
	s_add_u32 s0, s76, 0x1000
	s_addc_u32 s1, s77, 0
	s_add_u32 s6, s76, 0x1100
	s_addc_u32 s7, s77, 0
	s_add_u32 s8, s76, 0x1200
	s_addc_u32 s9, s77, 0
	s_add_u32 s10, s76, 0x1300
	s_addc_u32 s11, s77, 0
	s_mov_b32 s3, 1
	v_mov_b32_e32 v16, 0
	s_branch .LBB0_900

; #define AWS (kargs()->ws)
; #define K_TID ((wave_s << 6) | lane_fresh())
; template <class Epi, class Sched, bool ALIGN_EPI = false, bool SP2 = false>
; __device__ __forceinline__ void gemm_phase(PG8_LAS unsigned char* lds, const Gemm g, const Sched& S, const Epi& E, const int tid_arg) {
;     ...
;     Unit cur, nxt; int ui = 0;
;     if (!S.next(0, cur)) return;
; __global__ void __launch_bounds__(512, 2) fwd_megakernel(Args a) {
;     ...
;             bf16_t* SG = P_Zb;
;             pg8::StaticOrder S; S.init(T, DM, G, bx);
;             { pg8::Gemm g{P_HB, (const bf16_t*)(AWS + WS_WGT + l * SZ_WGT), T, DM, DM}; pg8::EpiSig E{SG, P_RSQ + (size_t)(2 * l + 1) * T};
;               pg8::gemm_phase<pg8::EpiSig, pg8::StaticOrder, true, true>(lds, g, S, E, K_TID);
.Lprio_skip_15:
	s_cmp_lg_u32 s98, 0
	s_load_dwordx2 s[0:1], s[0:1], 0x98
	s_mov_b64 s[8:9], s[46:47]
	s_mov_b64 s[10:11], s[46:47]
	s_mov_b32 s3, -1
	s_waitcnt lgkmcnt(0)
	s_add_u32 s16, s0, 0x9804000
	s_addc_u32 s17, s1, 0
	s_mov_b64 s[0:1], s[46:47]
	s_mov_b32 s2, -1
	v_mbcnt_lo_u32_b32 v0, s3, 0
	v_mbcnt_hi_u32_b32 v0, s3, v0
	s_and_b64 vcc, exec, s[80:81]
	v_or_b32_e32 v8, s82, v0
	s_nop 0
	v_readfirstlane_b32 s14, v8
	s_cbranch_vccnz .LBB0_972
	s_load_dwordx2 s[6:7], s[8:9], 0x98
	s_load_dwordx2 s[4:5], s[10:11], 0x98
	s_lshr_b32 s3, s87, 29
	s_add_i32 s3, s86, s3
	s_and_b32 s8, s3, -8
	s_sub_i32 s11, s86, s8
	s_cmp_gt_i32 s11, -1
	s_cbranch_scc0 .LBB0_951
	s_lshl_b32 s10, s11, 6
	s_load_dwordx2 s[0:1], s[0:1], 0x98
	s_cbranch_execz .LBB0_952
	s_branch .LBB0_953

; #define PG8_STAGE(bufoff, gbase, voff) do { _Pragma("unroll") for (int _i = 0; _i < 2; ++_i) \
;         __builtin_amdgcn_global_load_lds((const unsigned*)((const char*)(gbase) + (voff)[_i]), (PG8_LAS unsigned*)(lds + (bufoff) + ldsw + _i * 8192), 16, 0, 0); } while (0)
; #define PG8_LDA(dst, b, h) do { _Pragma("unroll") for (int m = 0; m < 4; ++m) _Pragma("unroll") for (int k = 0; k < 2; ++k) dst[m][k] = *(const PG8_LAS bf16x8*)(lds + PG8_SA(b, h) + aoff + m * 2048 + k * 1024); } while (0)
; #define PG8_LDB(dst, b, h) do { _Pragma("unroll") for (int n = 0; n < 2; ++n) _Pragma("unroll") for (int k = 0; k < 2; ++k) dst[n][k] = *(const PG8_LAS bf16x8*)(lds + PG8_SB(b, h) + boff + n * 2048 + k * 1024); } while (0)
; #define PG8_MMA(ai, bj, At, Bt) do { __builtin_amdgcn_s_setprio(1); _Pragma("unroll") for (int m = 0; m < 4; ++m) _Pragma("unroll") for (int n = 0; n < 2; ++n) _Pragma("unroll") for (int k = 0; k < 2; ++k) \
;         acc[ai][bj][m][n] = __builtin_amdgcn_mfma_f32_16x16x32_bf16(Bt[n][k], At[m][k], acc[ai][bj][m][n], 0, 0, 0); __builtin_amdgcn_s_setprio(0); } while (0)
; #define PG8_WAIT_V(n) asm volatile("s_waitcnt vmcnt(" #n ")" ::: "memory")
; #define PG8_WAIT_L(n) asm volatile("s_waitcnt lgkmcnt(" #n ")" ::: "memory")
; #define PG8_BAR __builtin_amdgcn_s_barrier()
; #define PG8_SCHED __builtin_amdgcn_sched_barrier(0)
; template <class Epi, class Sched, bool ALIGN_EPI = false, bool SP2 = false>
; __device__ __forceinline__ void gemm_phase(PG8_LAS unsigned char* lds, const Gemm g, const Sched& S, const Epi& E, const int tid_arg) {
;     ...
;             PG8_LDB(B0, 0, 0); PG8_LDB(B1, 0, 1); PG8_SCHED; PG8_LDA(At, 0, 0); PG8_STAGE(PG8_SA(1, 1), a1 + hstep, voffA);
;             PG8_WAIT_V(8); PG8_WAIT_L(0); PG8_BAR; PG8_MMA(0, 0, At, B0); PG8_MMA(0, 1, At, B1); PG8_BAR; PG8_SCHED;
;             PG8_LDA(At, 0, 1); PG8_STAGE(PG8_SB(0, 0), b2, voffB); PG8_STAGE(PG8_SB(0, 1), b2 + hstep, voffB); PG8_STAGE(PG8_SA(0, 0), a2, voffA);
;             PG8_WAIT_V(8); PG8_WAIT_L(0); PG8_BAR; PG8_MMA(1, 0, At, B0); PG8_MMA(1, 1, At, B1); PG8_BAR; PG8_SCHED;
.LBB0_965:
	ds_read_b128 v[170:173], v151
	ds_read_b128 v[174:177], v153
	ds_read_b128 v[178:181], v155
	ds_read_b128 v[182:185], v156
	ds_read_b128 v[186:189], v157
	ds_read_b128 v[190:193], v158
	ds_read_b128 v[194:197], v159
	ds_read_b128 v[198:201], v160
	s_add_u32 s0, s40, 0xfffc0080
	s_addc_u32 s1, s41, -1
	s_cmp_eq_u32 s72, 12
	s_cselect_b32 s43, s35, s1
	s_cselect_b32 s42, s68, s0
	s_cselect_b32 s1, s31, s71
	s_cselect_b32 s0, s69, s70
	s_mov_b32 m0, s60
	v_lshl_add_u64 v[234:235], s[40:41], 0, v[138:139]
	ds_read_b128 v[202:205], v149
	ds_read_b128 v[206:209], v149 offset:1024
	ds_read_b128 v[210:213], v149 offset:2048
	ds_read_b128 v[214:217], v149 offset:3072
	ds_read_b128 v[218:221], v149 offset:4096
	ds_read_b128 v[222:225], v149 offset:5120
	ds_read_b128 v[226:229], v149 offset:6144
	ds_read_b128 v[230:233], v149 offset:7168
	global_load_lds_dwordx4 v[234:235], off
	v_lshl_add_u64 v[234:235], s[40:41], 0, v[136:137]
	s_mov_b32 m0, s61
	s_nop 0
	global_load_lds_dwordx4 v[234:235], off
	s_waitcnt vmcnt(8)
	s_waitcnt lgkmcnt(0)
	s_barrier
	v_mfma_f32_16x16x32_bf16 v[124:127], v[170:173], v[202:205], v[124:127]
	v_mfma_f32_16x16x32_bf16 v[120:123], v[178:181], v[202:205], v[120:123]
	v_mfma_f32_16x16x32_bf16 v[108:111], v[170:173], v[210:213], v[108:111]
	v_mfma_f32_16x16x32_bf16 v[104:107], v[178:181], v[210:213], v[104:107]
	v_mfma_f32_16x16x32_bf16 v[92:95], v[170:173], v[218:221], v[92:95]
	v_mfma_f32_16x16x32_bf16 v[88:91], v[178:181], v[218:221], v[88:91]
	v_mfma_f32_16x16x32_bf16 v[76:79], v[170:173], v[226:229], v[76:79]
	v_mfma_f32_16x16x32_bf16 v[72:75], v[178:181], v[226:229], v[72:75]
	v_mfma_f32_16x16x32_bf16 v[124:127], v[174:177], v[206:209], v[124:127]
	v_mfma_f32_16x16x32_bf16 v[120:123], v[182:185], v[206:209], v[120:123]
	v_mfma_f32_16x16x32_bf16 v[108:111], v[174:177], v[214:217], v[108:111]
	v_mfma_f32_16x16x32_bf16 v[104:107], v[182:185], v[214:217], v[104:107]
	v_mfma_f32_16x16x32_bf16 v[92:95], v[174:177], v[222:225], v[92:95]
	v_mfma_f32_16x16x32_bf16 v[88:91], v[182:185], v[222:225], v[88:91]
	v_mfma_f32_16x16x32_bf16 v[76:79], v[174:177], v[230:233], v[76:79]
	v_mfma_f32_16x16x32_bf16 v[72:75], v[182:185], v[230:233], v[72:75]
	v_mfma_f32_16x16x32_bf16 v[116:119], v[186:189], v[202:205], v[116:119]
	v_mfma_f32_16x16x32_bf16 v[112:115], v[194:197], v[202:205], v[112:115]
	v_mfma_f32_16x16x32_bf16 v[100:103], v[186:189], v[210:213], v[100:103]
	v_mfma_f32_16x16x32_bf16 v[96:99], v[194:197], v[210:213], v[96:99]
	v_mfma_f32_16x16x32_bf16 v[84:87], v[186:189], v[218:221], v[84:87]
	v_mfma_f32_16x16x32_bf16 v[80:83], v[194:197], v[218:221], v[80:83]
	v_mfma_f32_16x16x32_bf16 v[68:71], v[186:189], v[226:229], v[68:71]
	v_mfma_f32_16x16x32_bf16 v[64:67], v[194:197], v[226:229], v[64:67]
	v_mfma_f32_16x16x32_bf16 v[116:119], v[190:193], v[206:209], v[116:119]
	v_mfma_f32_16x16x32_bf16 v[112:115], v[198:201], v[206:209], v[112:115]
	v_mfma_f32_16x16x32_bf16 v[100:103], v[190:193], v[214:217], v[100:103]
	v_mfma_f32_16x16x32_bf16 v[96:99], v[198:201], v[214:217], v[96:99]
	v_mfma_f32_16x16x32_bf16 v[84:87], v[190:193], v[222:225], v[84:87]
	v_mfma_f32_16x16x32_bf16 v[80:83], v[198:201], v[222:225], v[80:83]
	v_mfma_f32_16x16x32_bf16 v[68:71], v[190:193], v[230:233], v[68:71]
	v_mfma_f32_16x16x32_bf16 v[64:67], v[198:201], v[230:233], v[64:67]
	s_barrier
	s_mov_b32 m0, s5
	v_lshl_add_u64 v[234:235], s[0:1], 0, v[130:131]
	s_add_u32 s74, s0, 0x40000
	ds_read_b128 v[202:205], v149 offset:16384
	ds_read_b128 v[206:209], v149 offset:17408
	ds_read_b128 v[210:213], v149 offset:18432
	ds_read_b128 v[214:217], v149 offset:19456
	ds_read_b128 v[218:221], v149 offset:20480
	ds_read_b128 v[222:225], v149 offset:21504
	ds_read_b128 v[226:229], v149 offset:22528
	ds_read_b128 v[230:233], v149 offset:23552
	global_load_lds_dwordx4 v[234:235], off
	v_lshl_add_u64 v[236:237], s[0:1], 0, v[134:135]
	s_mov_b32 m0, s47
	s_addc_u32 s75, s1, 0
	global_load_lds_dwordx4 v[236:237], off
	v_lshl_add_u64 v[238:239], s[74:75], 0, v[130:131]
	s_mov_b32 m0, s48
	v_lshl_add_u64 v[240:241], s[42:43], 0, v[132:133]
	global_load_lds_dwordx4 v[238:239], off
	v_lshl_add_u64 v[238:239], s[74:75], 0, v[134:135]
	s_mov_b32 m0, s49
	s_nop 0
	global_load_lds_dwordx4 v[238:239], off
	v_lshl_add_u64 v[238:239], s[42:43], 0, v[128:129]
	s_mov_b32 m0, s46
	s_nop 0
	global_load_lds_dwordx4 v[238:239], off
	s_mov_b32 m0, s50
	s_nop 0
	global_load_lds_dwordx4 v[240:241], off
	s_waitcnt vmcnt(8)
	s_waitcnt lgkmcnt(0)
	s_barrier
	v_mfma_f32_16x16x32_bf16 v[60:63], v[170:173], v[202:205], v[60:63]
	v_mfma_f32_16x16x32_bf16 v[56:59], v[178:181], v[202:205], v[56:59]
	v_mfma_f32_16x16x32_bf16 v[44:47], v[170:173], v[210:213], v[44:47]
	v_mfma_f32_16x16x32_bf16 v[40:43], v[178:181], v[210:213], v[40:43]
	v_mfma_f32_16x16x32_bf16 v[28:31], v[170:173], v[218:221], v[28:31]
	v_mfma_f32_16x16x32_bf16 v[24:27], v[178:181], v[218:221], v[24:27]
	v_mfma_f32_16x16x32_bf16 v[12:15], v[170:173], v[226:229], v[12:15]
	v_mfma_f32_16x16x32_bf16 v[8:11], v[178:181], v[226:229], v[8:11]
	v_mfma_f32_16x16x32_bf16 v[60:63], v[174:177], v[206:209], v[60:63]
	v_mfma_f32_16x16x32_bf16 v[56:59], v[182:185], v[206:209], v[56:59]
	v_mfma_f32_16x16x32_bf16 v[44:47], v[174:177], v[214:217], v[44:47]
	v_mfma_f32_16x16x32_bf16 v[40:43], v[182:185], v[214:217], v[40:43]
	v_mfma_f32_16x16x32_bf16 v[28:31], v[174:177], v[222:225], v[28:31]
	v_mfma_f32_16x16x32_bf16 v[24:27], v[182:185], v[222:225], v[24:27]
	v_mfma_f32_16x16x32_bf16 v[12:15], v[174:177], v[230:233], v[12:15]
	v_mfma_f32_16x16x32_bf16 v[8:11], v[182:185], v[230:233], v[8:11]
	v_mfma_f32_16x16x32_bf16 v[52:55], v[186:189], v[202:205], v[52:55]
	v_mfma_f32_16x16x32_bf16 v[48:51], v[194:197], v[202:205], v[48:51]
	v_mfma_f32_16x16x32_bf16 v[36:39], v[186:189], v[210:213], v[36:39]
	v_mfma_f32_16x16x32_bf16 v[32:35], v[194:197], v[210:213], v[32:35]
	v_mfma_f32_16x16x32_bf16 v[20:23], v[186:189], v[218:221], v[20:23]
	v_mfma_f32_16x16x32_bf16 v[16:19], v[194:197], v[218:221], v[16:19]
	v_mfma_f32_16x16x32_bf16 v[4:7], v[186:189], v[226:229], v[4:7]
	v_mfma_f32_16x16x32_bf16 v[0:3], v[194:197], v[226:229], v[0:3]
	v_mfma_f32_16x16x32_bf16 v[52:55], v[190:193], v[206:209], v[52:55]
	v_mfma_f32_16x16x32_bf16 v[48:51], v[198:201], v[206:209], v[48:51]
	v_mfma_f32_16x16x32_bf16 v[36:39], v[190:193], v[214:217], v[36:39]
	v_mfma_f32_16x16x32_bf16 v[32:35], v[198:201], v[214:217], v[32:35]
	v_mfma_f32_16x16x32_bf16 v[20:23], v[190:193], v[222:225], v[20:23]
	v_mfma_f32_16x16x32_bf16 v[16:19], v[198:201], v[222:225], v[16:19]
	v_mfma_f32_16x16x32_bf16 v[4:7], v[190:193], v[230:233], v[4:7]
	v_mfma_f32_16x16x32_bf16 v[0:3], v[198:201], v[230:233], v[0:3]
	s_barrier
; #define PG8_STAGE(bufoff, gbase, voff) do { _Pragma("unroll") for (int _i = 0; _i < 2; ++_i) \
;         __builtin_amdgcn_global_load_lds((const unsigned*)((const char*)(gbase) + (voff)[_i]), (PG8_LAS unsigned*)(lds + (bufoff) + ldsw + _i * 8192), 16, 0, 0); } while (0)
; #define PG8_LDA(dst, b, h) do { _Pragma("unroll") for (int m = 0; m < 4; ++m) _Pragma("unroll") for (int k = 0; k < 2; ++k) dst[m][k] = *(const PG8_LAS bf16x8*)(lds + PG8_SA(b, h) + aoff + m * 2048 + k * 1024); } while (0)
; #define PG8_LDB(dst, b, h) do { _Pragma("unroll") for (int n = 0; n < 2; ++n) _Pragma("unroll") for (int k = 0; k < 2; ++k) dst[n][k] = *(const PG8_LAS bf16x8*)(lds + PG8_SB(b, h) + boff + n * 2048 + k * 1024); } while (0)
; #define PG8_MMA(ai, bj, At, Bt) do { __builtin_amdgcn_s_setprio(1); _Pragma("unroll") for (int m = 0; m < 4; ++m) _Pragma("unroll") for (int n = 0; n < 2; ++n) _Pragma("unroll") for (int k = 0; k < 2; ++k) \
;         acc[ai][bj][m][n] = __builtin_amdgcn_mfma_f32_16x16x32_bf16(Bt[n][k], At[m][k], acc[ai][bj][m][n], 0, 0, 0); __builtin_amdgcn_s_setprio(0); } while (0)
; #define PG8_WAIT_V(n) asm volatile("s_waitcnt vmcnt(" #n ")" ::: "memory")
; #define PG8_WAIT_L(n) asm volatile("s_waitcnt lgkmcnt(" #n ")" ::: "memory")
; #define PG8_BAR __builtin_amdgcn_s_barrier()
; #define PG8_SCHED __builtin_amdgcn_sched_barrier(0)
; template <class Epi, class Sched, bool ALIGN_EPI = false, bool SP2 = false>
; __device__ __forceinline__ void gemm_phase(PG8_LAS unsigned char* lds, const Gemm g, const Sched& S, const Epi& E, const int tid_arg) {
;     ...
;         for (int t = 0; t < nt; t += 2) {
;     ...
;             PG8_LDB(B0, 1, 0); PG8_LDB(B1, 1, 1); PG8_SCHED; PG8_LDA(At, 1, 0); PG8_STAGE(PG8_SA(0, 1), a2 + hstep, voffA);
;             PG8_WAIT_V(8); PG8_WAIT_L(0); PG8_BAR; PG8_MMA(0, 0, At, B0); PG8_MMA(0, 1, At, B1); PG8_BAR; PG8_SCHED;
;             PG8_LDA(At, 1, 1); PG8_STAGE(PG8_SB(1, 0), b3, voffB); PG8_STAGE(PG8_SB(1, 1), b3 + hstep, voffB); PG8_STAGE(PG8_SA(1, 0), a3, voffA);
;             PG8_WAIT_V(8); PG8_WAIT_L(0); PG8_BAR; PG8_MMA(1, 0, At, B0); PG8_MMA(1, 1, At, B1); PG8_BAR; PG8_SCHED;
	ds_read_b128 v[170:173], v161
	ds_read_b128 v[174:177], v162
	ds_read_b128 v[178:181], v163
	ds_read_b128 v[182:185], v164
	ds_read_b128 v[186:189], v165
	ds_read_b128 v[190:193], v166
	ds_read_b128 v[194:197], v167
	ds_read_b128 v[198:201], v168
	s_add_u32 s42, s42, 0x40000
	s_addc_u32 s43, s43, 0
	s_mov_b32 m0, s51
	v_lshl_add_u64 v[242:243], s[42:43], 0, v[128:129]
	ds_read_b128 v[202:205], v149 offset:32768
	ds_read_b128 v[206:209], v149 offset:33792
	ds_read_b128 v[210:213], v149 offset:34816
	ds_read_b128 v[214:217], v149 offset:35840
	ds_read_b128 v[218:221], v149 offset:36864
	ds_read_b128 v[222:225], v149 offset:37888
	ds_read_b128 v[226:229], v149 offset:38912
	ds_read_b128 v[230:233], v149 offset:39936
	global_load_lds_dwordx4 v[242:243], off
	v_lshl_add_u64 v[242:243], s[42:43], 0, v[132:133]
	s_mov_b32 m0, s52
	s_nop 0
	global_load_lds_dwordx4 v[242:243], off
	s_waitcnt vmcnt(8)
	s_waitcnt lgkmcnt(0)
	s_barrier
	v_mfma_f32_16x16x32_bf16 v[124:127], v[170:173], v[202:205], v[124:127]
	v_mfma_f32_16x16x32_bf16 v[120:123], v[178:181], v[202:205], v[120:123]
	v_mfma_f32_16x16x32_bf16 v[108:111], v[170:173], v[210:213], v[108:111]
	v_mfma_f32_16x16x32_bf16 v[104:107], v[178:181], v[210:213], v[104:107]
	v_mfma_f32_16x16x32_bf16 v[92:95], v[170:173], v[218:221], v[92:95]
	v_mfma_f32_16x16x32_bf16 v[88:91], v[178:181], v[218:221], v[88:91]
	v_mfma_f32_16x16x32_bf16 v[76:79], v[170:173], v[226:229], v[76:79]
	v_mfma_f32_16x16x32_bf16 v[72:75], v[178:181], v[226:229], v[72:75]
	v_mfma_f32_16x16x32_bf16 v[124:127], v[174:177], v[206:209], v[124:127]
	v_mfma_f32_16x16x32_bf16 v[120:123], v[182:185], v[206:209], v[120:123]
	v_mfma_f32_16x16x32_bf16 v[108:111], v[174:177], v[214:217], v[108:111]
	v_mfma_f32_16x16x32_bf16 v[104:107], v[182:185], v[214:217], v[104:107]
	v_mfma_f32_16x16x32_bf16 v[92:95], v[174:177], v[222:225], v[92:95]
	v_mfma_f32_16x16x32_bf16 v[88:91], v[182:185], v[222:225], v[88:91]
	v_mfma_f32_16x16x32_bf16 v[76:79], v[174:177], v[230:233], v[76:79]
	v_mfma_f32_16x16x32_bf16 v[72:75], v[182:185], v[230:233], v[72:75]
	v_mfma_f32_16x16x32_bf16 v[116:119], v[186:189], v[202:205], v[116:119]
	v_mfma_f32_16x16x32_bf16 v[112:115], v[194:197], v[202:205], v[112:115]
	v_mfma_f32_16x16x32_bf16 v[100:103], v[186:189], v[210:213], v[100:103]
	v_mfma_f32_16x16x32_bf16 v[96:99], v[194:197], v[210:213], v[96:99]
	v_mfma_f32_16x16x32_bf16 v[84:87], v[186:189], v[218:221], v[84:87]
	v_mfma_f32_16x16x32_bf16 v[80:83], v[194:197], v[218:221], v[80:83]
	v_mfma_f32_16x16x32_bf16 v[68:71], v[186:189], v[226:229], v[68:71]
	v_mfma_f32_16x16x32_bf16 v[64:67], v[194:197], v[226:229], v[64:67]
	v_mfma_f32_16x16x32_bf16 v[116:119], v[190:193], v[206:209], v[116:119]
	v_mfma_f32_16x16x32_bf16 v[112:115], v[198:201], v[206:209], v[112:115]
	v_mfma_f32_16x16x32_bf16 v[100:103], v[190:193], v[214:217], v[100:103]
	v_mfma_f32_16x16x32_bf16 v[96:99], v[198:201], v[214:217], v[96:99]
	v_mfma_f32_16x16x32_bf16 v[84:87], v[190:193], v[222:225], v[84:87]
	v_mfma_f32_16x16x32_bf16 v[80:83], v[198:201], v[222:225], v[80:83]
	v_mfma_f32_16x16x32_bf16 v[68:71], v[190:193], v[230:233], v[68:71]
	v_mfma_f32_16x16x32_bf16 v[64:67], v[198:201], v[230:233], v[64:67]
	s_barrier
	s_mov_b32 m0, s54
	v_lshl_add_u64 v[234:235], v[234:235], 0, s[12:13]
	s_add_u32 s0, s0, 0x40080
	ds_read_b128 v[202:205], v149 offset:49152
	ds_read_b128 v[206:209], v149 offset:50176
	ds_read_b128 v[210:213], v149 offset:51200
	ds_read_b128 v[214:217], v149 offset:52224
	ds_read_b128 v[218:221], v149 offset:53248
	ds_read_b128 v[222:225], v149 offset:54272
	ds_read_b128 v[226:229], v149 offset:55296
	ds_read_b128 v[230:233], v149 offset:56320
	global_load_lds_dwordx4 v[234:235], off
	v_lshl_add_u64 v[234:235], v[236:237], 0, s[12:13]
	s_mov_b32 m0, s55
	s_addc_u32 s1, s1, 0
	global_load_lds_dwordx4 v[234:235], off
	v_lshl_add_u64 v[234:235], s[0:1], 0, v[130:131]
	s_mov_b32 m0, s58
	s_nop 0
	global_load_lds_dwordx4 v[234:235], off
	v_lshl_add_u64 v[234:235], s[0:1], 0, v[134:135]
	s_mov_b32 m0, s59
	s_nop 0
	global_load_lds_dwordx4 v[234:235], off
	v_lshl_add_u64 v[234:235], v[238:239], 0, s[12:13]
	s_mov_b32 m0, s56
	s_nop 0
	global_load_lds_dwordx4 v[234:235], off
	v_lshl_add_u64 v[234:235], v[240:241], 0, s[12:13]
	s_mov_b32 m0, s57
	s_nop 0
	global_load_lds_dwordx4 v[234:235], off
	s_waitcnt vmcnt(8)
	s_waitcnt lgkmcnt(0)
	s_barrier
	v_mfma_f32_16x16x32_bf16 v[60:63], v[170:173], v[202:205], v[60:63]
	v_mfma_f32_16x16x32_bf16 v[56:59], v[178:181], v[202:205], v[56:59]
	v_mfma_f32_16x16x32_bf16 v[44:47], v[170:173], v[210:213], v[44:47]
	v_mfma_f32_16x16x32_bf16 v[40:43], v[178:181], v[210:213], v[40:43]
	v_mfma_f32_16x16x32_bf16 v[28:31], v[170:173], v[218:221], v[28:31]
	v_mfma_f32_16x16x32_bf16 v[24:27], v[178:181], v[218:221], v[24:27]
	v_mfma_f32_16x16x32_bf16 v[12:15], v[170:173], v[226:229], v[12:15]
	v_mfma_f32_16x16x32_bf16 v[8:11], v[178:181], v[226:229], v[8:11]
	v_mfma_f32_16x16x32_bf16 v[60:63], v[174:177], v[206:209], v[60:63]
	v_mfma_f32_16x16x32_bf16 v[56:59], v[182:185], v[206:209], v[56:59]
	v_mfma_f32_16x16x32_bf16 v[44:47], v[174:177], v[214:217], v[44:47]
	v_mfma_f32_16x16x32_bf16 v[40:43], v[182:185], v[214:217], v[40:43]
	v_mfma_f32_16x16x32_bf16 v[28:31], v[174:177], v[222:225], v[28:31]
	v_mfma_f32_16x16x32_bf16 v[24:27], v[182:185], v[222:225], v[24:27]
	v_mfma_f32_16x16x32_bf16 v[12:15], v[174:177], v[230:233], v[12:15]
	v_mfma_f32_16x16x32_bf16 v[8:11], v[182:185], v[230:233], v[8:11]
	v_mfma_f32_16x16x32_bf16 v[52:55], v[186:189], v[202:205], v[52:55]
	v_mfma_f32_16x16x32_bf16 v[48:51], v[194:197], v[202:205], v[48:51]
	v_mfma_f32_16x16x32_bf16 v[36:39], v[186:189], v[210:213], v[36:39]
	v_mfma_f32_16x16x32_bf16 v[32:35], v[194:197], v[210:213], v[32:35]
	v_mfma_f32_16x16x32_bf16 v[20:23], v[186:189], v[218:221], v[20:23]
	v_mfma_f32_16x16x32_bf16 v[16:19], v[194:197], v[218:221], v[16:19]
	v_mfma_f32_16x16x32_bf16 v[4:7], v[186:189], v[226:229], v[4:7]
	v_mfma_f32_16x16x32_bf16 v[0:3], v[194:197], v[226:229], v[0:3]
	v_mfma_f32_16x16x32_bf16 v[52:55], v[190:193], v[206:209], v[52:55]
	v_mfma_f32_16x16x32_bf16 v[48:51], v[198:201], v[206:209], v[48:51]
	v_mfma_f32_16x16x32_bf16 v[36:39], v[190:193], v[214:217], v[36:39]
	v_mfma_f32_16x16x32_bf16 v[32:35], v[198:201], v[214:217], v[32:35]
	v_mfma_f32_16x16x32_bf16 v[20:23], v[190:193], v[222:225], v[20:23]
	v_mfma_f32_16x16x32_bf16 v[16:19], v[198:201], v[222:225], v[16:19]
	v_mfma_f32_16x16x32_bf16 v[4:7], v[190:193], v[230:233], v[4:7]
	v_mfma_f32_16x16x32_bf16 v[0:3], v[198:201], v[230:233], v[0:3]
	s_barrier
	s_add_i32 s72, s72, 2
	s_add_u32 s70, s70, 0x100
	s_addc_u32 s71, s71, 0
	s_add_u32 s40, s40, 0x100
	s_addc_u32 s41, s41, 0
	s_cmp_gt_u32 s72, 13
	s_cbranch_scc0 .LBB0_965
	s_and_b64 vcc, exec, s[14:15]
	s_cbranch_vccz .LBB0_968
	s_barrier

; #define PG8_WAIT_V(n) asm volatile("s_waitcnt vmcnt(" #n ")" ::: "memory")
; #define PG8_BAR __builtin_amdgcn_s_barrier()
; __device__ __forceinline__ void xcd_barrier(const XcdBarrier& b, const bool xb_is_leader) {
;     asm volatile("s_waitcnt vmcnt(0)" ::: "memory");
;     __syncthreads();
;     if (xb_is_leader) {
;         unsigned* bar = b.bar;
;         __builtin_amdgcn_s_waitcnt(0);
;         unsigned nloc = b.st[0], nx = b.st[1];
;         if (nloc == 0u) { xcd_barrier_complete(bar, b.x, nloc, nx); b.st[0] = nloc; b.st[1] = nx; }
; template <class Epi, class Sched, bool ALIGN_EPI = false, bool SP2 = false>
; __device__ __forceinline__ void gemm_phase(PG8_LAS unsigned char* lds, const Gemm g, const Sched& S, const Epi& E, const int tid_arg) {
;     ...
;     PG8_WAIT_V(0);
;     if constexpr (!ALIGN_EPI) { if (wr == 0) PG8_BAR; }
;     PG8_BAR;
.LBB0_972:
	s_nop 0
	v_mbcnt_lo_u32_b32 v0, s2, 0
	v_mbcnt_hi_u32_b32 v0, s2, v0
	s_setprio 0
	s_waitcnt vmcnt(0)
	s_nop 0
	v_or_b32_e32 v0, s82, v0
	v_cmp_eq_u32_e32 vcc, 0, v0
	s_barrier
	s_and_saveexec_b64 s[4:5], vcc
	s_cbranch_execz .LBB0_1024
	v_mov_b32_e32 v0, 0x22000
	s_waitcnt vmcnt(0) expcnt(0) lgkmcnt(0)
	ds_read_b32 v2, v0
	v_mov_b32_e32 v0, 0x22004
	ds_read_b32 v0, v0
	s_waitcnt lgkmcnt(1)
	v_cmp_ne_u32_e32 vcc, 0, v2
	s_cbranch_vccnz .LBB0_988
	v_readlane_b32 s0, v251, 0
	v_readlane_b32 s1, v251, 1
	v_readlane_b32 s2, v251, 2
	s_mul_i32 s2, s1, s2
	s_mul_i32 s2, s2, s0
	s_add_u32 s0, s76, 0x1000
	s_addc_u32 s1, s77, 0
	s_add_u32 s6, s76, 0x1100
	s_addc_u32 s7, s77, 0
	s_add_u32 s8, s76, 0x1200
	s_addc_u32 s9, s77, 0
	s_add_u32 s10, s76, 0x1300
	s_addc_u32 s11, s77, 0
	s_mov_b32 s3, 1
	v_mov_b32_e32 v16, 0
	s_branch .LBB0_976

; #define AOUT (kargs()->out)
; #define AWS (kargs()->ws)
; #define K_TID ((wave_s << 6) | lane_fresh())
; template <class Epi, class Sched, bool ALIGN_EPI = false, bool SP2 = false>
; __device__ __forceinline__ void gemm_phase(PG8_LAS unsigned char* lds, const Gemm g, const Sched& S, const Epi& E, const int tid_arg) {
;     ...
;     Unit cur, nxt; int ui = 0;
;     if (!S.next(0, cur)) return;
; __global__ void __launch_bounds__(512, 2) fwd_megakernel(Args a) {
;     ...
;             { int kple = PLED; asm volatile("" : "+s"(kple));
;               pg8::Gemm g{P_PB + (size_t)l * T * PLED, (const bf16_t*)(AWS + WS_WPJ + l * SZ_WPJ), T, DM, kple}; pg8::EpiMulAdd E{SG, P_HB, (l == 1) ? AOUT : (float*)nullptr};
;               pg8::gemm_phase<pg8::EpiMulAdd, pg8::StaticOrder, true, true>(lds, g, S, E, K_TID); }
.LBB0_1024:
	s_or_b64 exec, exec, s[4:5]
	s_movk_i32 s10, 0x100
	s_mov_b64 s[8:9], s[46:47]
	s_mov_b64 s[12:13], s[46:47]
	s_mov_b64 s[0:1], s[46:47]
	s_mov_b32 s3, -1
	s_waitcnt lgkmcnt(0)
	s_barrier
	s_cselect_b32 s98, 1, 0
	s_cmp_ge_u32 s82, 0x100
	s_cbranch_scc0 .Lprio_skip_16
	s_setprio 1
.Lprio_skip_16:
	s_cmp_lg_u32 s98, 0
	s_mov_b32 s2, -1
	v_mbcnt_lo_u32_b32 v0, s3, 0
	v_mbcnt_hi_u32_b32 v0, s3, v0
	s_and_b64 vcc, exec, s[84:85]
	v_or_b32_e32 v12, s82, v0
	s_nop 0
	v_readfirstlane_b32 s14, v12
	s_cbranch_vccz .LBB0_1053
	s_load_dwordx2 s[6:7], s[8:9], 0x98
	s_load_dwordx2 s[4:5], s[12:13], 0x98
	s_lshr_b32 s3, s87, 29
	s_add_i32 s3, s86, s3
	s_and_b32 s8, s3, -8
	s_sub_i32 s11, s86, s8
	s_cmp_gt_i32 s11, -1
	s_cbranch_scc0 .LBB0_1027
	s_lshl_b32 s12, s11, 6
	s_load_dwordx2 s[0:1], s[0:1], 0x98
	s_cbranch_execz .LBB0_1028
	s_branch .LBB0_1029

; #define PG8_STAGE(bufoff, gbase, voff) do { _Pragma("unroll") for (int _i = 0; _i < 2; ++_i) \
;         __builtin_amdgcn_global_load_lds((const unsigned*)((const char*)(gbase) + (voff)[_i]), (PG8_LAS unsigned*)(lds + (bufoff) + ldsw + _i * 8192), 16, 0, 0); } while (0)
; #define PG8_LDA(dst, b, h) do { _Pragma("unroll") for (int m = 0; m < 4; ++m) _Pragma("unroll") for (int k = 0; k < 2; ++k) dst[m][k] = *(const PG8_LAS bf16x8*)(lds + PG8_SA(b, h) + aoff + m * 2048 + k * 1024); } while (0)
; #define PG8_LDB(dst, b, h) do { _Pragma("unroll") for (int n = 0; n < 2; ++n) _Pragma("unroll") for (int k = 0; k < 2; ++k) dst[n][k] = *(const PG8_LAS bf16x8*)(lds + PG8_SB(b, h) + boff + n * 2048 + k * 1024); } while (0)
; #define PG8_MMA(ai, bj, At, Bt) do { __builtin_amdgcn_s_setprio(1); _Pragma("unroll") for (int m = 0; m < 4; ++m) _Pragma("unroll") for (int n = 0; n < 2; ++n) _Pragma("unroll") for (int k = 0; k < 2; ++k) \
;         acc[ai][bj][m][n] = __builtin_amdgcn_mfma_f32_16x16x32_bf16(Bt[n][k], At[m][k], acc[ai][bj][m][n], 0, 0, 0); __builtin_amdgcn_s_setprio(0); } while (0)
; #define PG8_WAIT_V(n) asm volatile("s_waitcnt vmcnt(" #n ")" ::: "memory")
; #define PG8_WAIT_L(n) asm volatile("s_waitcnt lgkmcnt(" #n ")" ::: "memory")
; #define PG8_BAR __builtin_amdgcn_s_barrier()
; #define PG8_SCHED __builtin_amdgcn_sched_barrier(0)
; template <class Epi, class Sched, bool ALIGN_EPI = false, bool SP2 = false>
; __device__ __forceinline__ void gemm_phase(PG8_LAS unsigned char* lds, const Gemm g, const Sched& S, const Epi& E, const int tid_arg) {
;     ...
;             PG8_LDB(B0, 0, 0); PG8_LDB(B1, 0, 1); PG8_SCHED; PG8_LDA(At, 0, 0); PG8_STAGE(PG8_SA(1, 1), a1 + hstep, voffA);
;             PG8_WAIT_V(8); PG8_WAIT_L(0); PG8_BAR; PG8_MMA(0, 0, At, B0); PG8_MMA(0, 1, At, B1); PG8_BAR; PG8_SCHED;
;             PG8_LDA(At, 0, 1); PG8_STAGE(PG8_SB(0, 0), b2, voffB); PG8_STAGE(PG8_SB(0, 1), b2 + hstep, voffB); PG8_STAGE(PG8_SA(0, 0), a2, voffA);
;             PG8_WAIT_V(8); PG8_WAIT_L(0); PG8_BAR; PG8_MMA(1, 0, At, B0); PG8_MMA(1, 1, At, B1); PG8_BAR; PG8_SCHED;
.LBB0_1046:
	ds_read_b128 v[144:147], v151
	ds_read_b128 v[168:171], v152
	ds_read_b128 v[172:175], v153
	ds_read_b128 v[176:179], v154
	ds_read_b128 v[180:183], v155
	ds_read_b128 v[184:187], v156
	ds_read_b128 v[188:191], v157
	ds_read_b128 v[192:195], v158
	s_add_i32 s30, s0, 2
	s_add_u32 s31, s4, 0x80
	s_addc_u32 s1, s5, 0
	s_cmp_eq_u32 s52, s0
	s_cselect_b32 s0, s14, s31
	s_cselect_b32 s1, s15, s1
	s_cselect_b32 s63, s29, s61
	s_cselect_b32 s62, s28, s60
	s_mov_b32 m0, s53
	v_lshl_add_u64 v[228:229], s[4:5], 0, v[138:139]
	ds_read_b128 v[196:199], v150
	ds_read_b128 v[200:203], v150 offset:1024
	ds_read_b128 v[204:207], v150 offset:2048
	ds_read_b128 v[208:211], v150 offset:3072
	ds_read_b128 v[212:215], v150 offset:4096
	ds_read_b128 v[216:219], v150 offset:5120
	ds_read_b128 v[220:223], v150 offset:6144
	ds_read_b128 v[224:227], v150 offset:7168
	global_load_lds_dwordx4 v[228:229], off
	v_lshl_add_u64 v[228:229], s[4:5], 0, v[136:137]
	s_mov_b32 m0, s54
	s_nop 0
	global_load_lds_dwordx4 v[228:229], off
	s_waitcnt vmcnt(8)
	s_waitcnt lgkmcnt(0)
	s_barrier
	v_mfma_f32_16x16x32_bf16 v[124:127], v[144:147], v[196:199], v[124:127]
	v_mfma_f32_16x16x32_bf16 v[120:123], v[172:175], v[196:199], v[120:123]
	v_mfma_f32_16x16x32_bf16 v[108:111], v[144:147], v[204:207], v[108:111]
	v_mfma_f32_16x16x32_bf16 v[104:107], v[172:175], v[204:207], v[104:107]
	v_mfma_f32_16x16x32_bf16 v[92:95], v[144:147], v[212:215], v[92:95]
	v_mfma_f32_16x16x32_bf16 v[88:91], v[172:175], v[212:215], v[88:91]
	v_mfma_f32_16x16x32_bf16 v[76:79], v[144:147], v[220:223], v[76:79]
	v_mfma_f32_16x16x32_bf16 v[72:75], v[172:175], v[220:223], v[72:75]
	v_mfma_f32_16x16x32_bf16 v[124:127], v[168:171], v[200:203], v[124:127]
	v_mfma_f32_16x16x32_bf16 v[120:123], v[176:179], v[200:203], v[120:123]
	v_mfma_f32_16x16x32_bf16 v[108:111], v[168:171], v[208:211], v[108:111]
	v_mfma_f32_16x16x32_bf16 v[104:107], v[176:179], v[208:211], v[104:107]
	v_mfma_f32_16x16x32_bf16 v[92:95], v[168:171], v[216:219], v[92:95]
	v_mfma_f32_16x16x32_bf16 v[88:91], v[176:179], v[216:219], v[88:91]
	v_mfma_f32_16x16x32_bf16 v[76:79], v[168:171], v[224:227], v[76:79]
	v_mfma_f32_16x16x32_bf16 v[72:75], v[176:179], v[224:227], v[72:75]
	v_mfma_f32_16x16x32_bf16 v[116:119], v[180:183], v[196:199], v[116:119]
	v_mfma_f32_16x16x32_bf16 v[112:115], v[188:191], v[196:199], v[112:115]
	v_mfma_f32_16x16x32_bf16 v[100:103], v[180:183], v[204:207], v[100:103]
	v_mfma_f32_16x16x32_bf16 v[96:99], v[188:191], v[204:207], v[96:99]
	v_mfma_f32_16x16x32_bf16 v[84:87], v[180:183], v[212:215], v[84:87]
	v_mfma_f32_16x16x32_bf16 v[80:83], v[188:191], v[212:215], v[80:83]
	v_mfma_f32_16x16x32_bf16 v[68:71], v[180:183], v[220:223], v[68:71]
	v_mfma_f32_16x16x32_bf16 v[64:67], v[188:191], v[220:223], v[64:67]
	v_mfma_f32_16x16x32_bf16 v[116:119], v[184:187], v[200:203], v[116:119]
	v_mfma_f32_16x16x32_bf16 v[112:115], v[192:195], v[200:203], v[112:115]
	v_mfma_f32_16x16x32_bf16 v[100:103], v[184:187], v[208:211], v[100:103]
	v_mfma_f32_16x16x32_bf16 v[96:99], v[192:195], v[208:211], v[96:99]
	v_mfma_f32_16x16x32_bf16 v[84:87], v[184:187], v[216:219], v[84:87]
	v_mfma_f32_16x16x32_bf16 v[80:83], v[192:195], v[216:219], v[80:83]
	v_mfma_f32_16x16x32_bf16 v[68:71], v[184:187], v[224:227], v[68:71]
	v_mfma_f32_16x16x32_bf16 v[64:67], v[192:195], v[224:227], v[64:67]
	s_barrier
	s_mov_b32 m0, s37
	v_lshl_add_u64 v[228:229], s[62:63], 0, v[130:131]
	v_lshl_add_u64 v[230:231], s[62:63], 0, v[134:135]
	s_add_u32 s62, s62, s6
	ds_read_b128 v[196:199], v150 offset:16384
	ds_read_b128 v[200:203], v150 offset:17408
	ds_read_b128 v[204:207], v150 offset:18432
	ds_read_b128 v[208:211], v150 offset:19456
	ds_read_b128 v[212:215], v150 offset:20480
	ds_read_b128 v[216:219], v150 offset:21504
	ds_read_b128 v[220:223], v150 offset:22528
	ds_read_b128 v[224:227], v150 offset:23552
	global_load_lds_dwordx4 v[228:229], off
	s_mov_b32 m0, s38
	s_addc_u32 s63, s63, s7
	global_load_lds_dwordx4 v[230:231], off
	v_lshl_add_u64 v[232:233], s[62:63], 0, v[130:131]
	s_mov_b32 m0, s39
	v_lshl_add_u64 v[234:235], s[62:63], 0, v[134:135]
	global_load_lds_dwordx4 v[232:233], off
	s_mov_b32 m0, s40
	v_lshl_add_u64 v[236:237], s[0:1], 0, v[128:129]
	global_load_lds_dwordx4 v[234:235], off
	s_mov_b32 m0, s36
	v_lshl_add_u64 v[238:239], s[0:1], 0, v[132:133]
	global_load_lds_dwordx4 v[236:237], off
	s_mov_b32 m0, s41
	s_nop 0
	global_load_lds_dwordx4 v[238:239], off
	s_waitcnt vmcnt(8)
	s_waitcnt lgkmcnt(0)
	s_barrier
	v_mfma_f32_16x16x32_bf16 v[60:63], v[144:147], v[196:199], v[60:63]
	v_mfma_f32_16x16x32_bf16 v[56:59], v[172:175], v[196:199], v[56:59]
	v_mfma_f32_16x16x32_bf16 v[44:47], v[144:147], v[204:207], v[44:47]
	v_mfma_f32_16x16x32_bf16 v[40:43], v[172:175], v[204:207], v[40:43]
	v_mfma_f32_16x16x32_bf16 v[28:31], v[144:147], v[212:215], v[28:31]
	v_mfma_f32_16x16x32_bf16 v[24:27], v[172:175], v[212:215], v[24:27]
	v_mfma_f32_16x16x32_bf16 v[12:15], v[144:147], v[220:223], v[12:15]
	v_mfma_f32_16x16x32_bf16 v[8:11], v[172:175], v[220:223], v[8:11]
	v_mfma_f32_16x16x32_bf16 v[60:63], v[168:171], v[200:203], v[60:63]
	v_mfma_f32_16x16x32_bf16 v[56:59], v[176:179], v[200:203], v[56:59]
	v_mfma_f32_16x16x32_bf16 v[44:47], v[168:171], v[208:211], v[44:47]
	v_mfma_f32_16x16x32_bf16 v[40:43], v[176:179], v[208:211], v[40:43]
	v_mfma_f32_16x16x32_bf16 v[28:31], v[168:171], v[216:219], v[28:31]
	v_mfma_f32_16x16x32_bf16 v[24:27], v[176:179], v[216:219], v[24:27]
	v_mfma_f32_16x16x32_bf16 v[12:15], v[168:171], v[224:227], v[12:15]
	v_mfma_f32_16x16x32_bf16 v[8:11], v[176:179], v[224:227], v[8:11]
	v_mfma_f32_16x16x32_bf16 v[52:55], v[180:183], v[196:199], v[52:55]
	v_mfma_f32_16x16x32_bf16 v[48:51], v[188:191], v[196:199], v[48:51]
	v_mfma_f32_16x16x32_bf16 v[36:39], v[180:183], v[204:207], v[36:39]
	v_mfma_f32_16x16x32_bf16 v[32:35], v[188:191], v[204:207], v[32:35]
	v_mfma_f32_16x16x32_bf16 v[20:23], v[180:183], v[212:215], v[20:23]
	v_mfma_f32_16x16x32_bf16 v[16:19], v[188:191], v[212:215], v[16:19]
	v_mfma_f32_16x16x32_bf16 v[4:7], v[180:183], v[220:223], v[4:7]
	v_mfma_f32_16x16x32_bf16 v[0:3], v[188:191], v[220:223], v[0:3]
	v_mfma_f32_16x16x32_bf16 v[52:55], v[184:187], v[200:203], v[52:55]
	v_mfma_f32_16x16x32_bf16 v[48:51], v[192:195], v[200:203], v[48:51]
	v_mfma_f32_16x16x32_bf16 v[36:39], v[184:187], v[208:211], v[36:39]
	v_mfma_f32_16x16x32_bf16 v[32:35], v[192:195], v[208:211], v[32:35]
	v_mfma_f32_16x16x32_bf16 v[20:23], v[184:187], v[216:219], v[20:23]
	v_mfma_f32_16x16x32_bf16 v[16:19], v[192:195], v[216:219], v[16:19]
	v_mfma_f32_16x16x32_bf16 v[4:7], v[184:187], v[224:227], v[4:7]
	v_mfma_f32_16x16x32_bf16 v[0:3], v[192:195], v[224:227], v[0:3]
	s_barrier
; #define PG8_STAGE(bufoff, gbase, voff) do { _Pragma("unroll") for (int _i = 0; _i < 2; ++_i) \
;         __builtin_amdgcn_global_load_lds((const unsigned*)((const char*)(gbase) + (voff)[_i]), (PG8_LAS unsigned*)(lds + (bufoff) + ldsw + _i * 8192), 16, 0, 0); } while (0)
; #define PG8_LDA(dst, b, h) do { _Pragma("unroll") for (int m = 0; m < 4; ++m) _Pragma("unroll") for (int k = 0; k < 2; ++k) dst[m][k] = *(const PG8_LAS bf16x8*)(lds + PG8_SA(b, h) + aoff + m * 2048 + k * 1024); } while (0)
; #define PG8_LDB(dst, b, h) do { _Pragma("unroll") for (int n = 0; n < 2; ++n) _Pragma("unroll") for (int k = 0; k < 2; ++k) dst[n][k] = *(const PG8_LAS bf16x8*)(lds + PG8_SB(b, h) + boff + n * 2048 + k * 1024); } while (0)
; #define PG8_MMA(ai, bj, At, Bt) do { __builtin_amdgcn_s_setprio(1); _Pragma("unroll") for (int m = 0; m < 4; ++m) _Pragma("unroll") for (int n = 0; n < 2; ++n) _Pragma("unroll") for (int k = 0; k < 2; ++k) \
;         acc[ai][bj][m][n] = __builtin_amdgcn_mfma_f32_16x16x32_bf16(Bt[n][k], At[m][k], acc[ai][bj][m][n], 0, 0, 0); __builtin_amdgcn_s_setprio(0); } while (0)
; #define PG8_WAIT_V(n) asm volatile("s_waitcnt vmcnt(" #n ")" ::: "memory")
; #define PG8_WAIT_L(n) asm volatile("s_waitcnt lgkmcnt(" #n ")" ::: "memory")
; #define PG8_BAR __builtin_amdgcn_s_barrier()
; #define PG8_SCHED __builtin_amdgcn_sched_barrier(0)
; template <class Epi, class Sched, bool ALIGN_EPI = false, bool SP2 = false>
; __device__ __forceinline__ void gemm_phase(PG8_LAS unsigned char* lds, const Gemm g, const Sched& S, const Epi& E, const int tid_arg) {
;     ...
;         for (int t = 0; t < nt; t += 2) {
;     ...
;             PG8_LDB(B0, 1, 0); PG8_LDB(B1, 1, 1); PG8_SCHED; PG8_LDA(At, 1, 0); PG8_STAGE(PG8_SA(0, 1), a2 + hstep, voffA);
;             PG8_WAIT_V(8); PG8_WAIT_L(0); PG8_BAR; PG8_MMA(0, 0, At, B0); PG8_MMA(0, 1, At, B1); PG8_BAR; PG8_SCHED;
;             PG8_LDA(At, 1, 1); PG8_STAGE(PG8_SB(1, 0), b3, voffB); PG8_STAGE(PG8_SB(1, 1), b3 + hstep, voffB); PG8_STAGE(PG8_SA(1, 0), a3, voffA);
;             PG8_WAIT_V(8); PG8_WAIT_L(0); PG8_BAR; PG8_MMA(1, 0, At, B0); PG8_MMA(1, 1, At, B1); PG8_BAR; PG8_SCHED;
	ds_read_b128 v[144:147], v159
	ds_read_b128 v[168:171], v160
	ds_read_b128 v[172:175], v161
	ds_read_b128 v[176:179], v162
	ds_read_b128 v[180:183], v163
	ds_read_b128 v[184:187], v164
	ds_read_b128 v[188:191], v165
	ds_read_b128 v[192:195], v166
	s_add_u32 s0, s0, s6
	s_addc_u32 s1, s1, s7
	s_mov_b32 m0, s42
	v_lshl_add_u64 v[240:241], s[0:1], 0, v[128:129]
	ds_read_b128 v[196:199], v150 offset:32768
	ds_read_b128 v[200:203], v150 offset:33792
	ds_read_b128 v[204:207], v150 offset:34816
	ds_read_b128 v[208:211], v150 offset:35840
	ds_read_b128 v[212:215], v150 offset:36864
	ds_read_b128 v[216:219], v150 offset:37888
	ds_read_b128 v[220:223], v150 offset:38912
	ds_read_b128 v[224:227], v150 offset:39936
	global_load_lds_dwordx4 v[240:241], off
	v_lshl_add_u64 v[240:241], s[0:1], 0, v[132:133]
	s_mov_b32 m0, s43
	s_nop 0
	global_load_lds_dwordx4 v[240:241], off
	s_waitcnt vmcnt(8)
	s_waitcnt lgkmcnt(0)
	s_barrier
	v_mfma_f32_16x16x32_bf16 v[124:127], v[144:147], v[196:199], v[124:127]
	v_mfma_f32_16x16x32_bf16 v[120:123], v[172:175], v[196:199], v[120:123]
	v_mfma_f32_16x16x32_bf16 v[108:111], v[144:147], v[204:207], v[108:111]
	v_mfma_f32_16x16x32_bf16 v[104:107], v[172:175], v[204:207], v[104:107]
	v_mfma_f32_16x16x32_bf16 v[92:95], v[144:147], v[212:215], v[92:95]
	v_mfma_f32_16x16x32_bf16 v[88:91], v[172:175], v[212:215], v[88:91]
	v_mfma_f32_16x16x32_bf16 v[76:79], v[144:147], v[220:223], v[76:79]
	v_mfma_f32_16x16x32_bf16 v[72:75], v[172:175], v[220:223], v[72:75]
	v_mfma_f32_16x16x32_bf16 v[124:127], v[168:171], v[200:203], v[124:127]
	v_mfma_f32_16x16x32_bf16 v[120:123], v[176:179], v[200:203], v[120:123]
	v_mfma_f32_16x16x32_bf16 v[108:111], v[168:171], v[208:211], v[108:111]
	v_mfma_f32_16x16x32_bf16 v[104:107], v[176:179], v[208:211], v[104:107]
	v_mfma_f32_16x16x32_bf16 v[92:95], v[168:171], v[216:219], v[92:95]
	v_mfma_f32_16x16x32_bf16 v[88:91], v[176:179], v[216:219], v[88:91]
	v_mfma_f32_16x16x32_bf16 v[76:79], v[168:171], v[224:227], v[76:79]
	v_mfma_f32_16x16x32_bf16 v[72:75], v[176:179], v[224:227], v[72:75]
	v_mfma_f32_16x16x32_bf16 v[116:119], v[180:183], v[196:199], v[116:119]
	v_mfma_f32_16x16x32_bf16 v[112:115], v[188:191], v[196:199], v[112:115]
	v_mfma_f32_16x16x32_bf16 v[100:103], v[180:183], v[204:207], v[100:103]
	v_mfma_f32_16x16x32_bf16 v[96:99], v[188:191], v[204:207], v[96:99]
	v_mfma_f32_16x16x32_bf16 v[84:87], v[180:183], v[212:215], v[84:87]
	v_mfma_f32_16x16x32_bf16 v[80:83], v[188:191], v[212:215], v[80:83]
	v_mfma_f32_16x16x32_bf16 v[68:71], v[180:183], v[220:223], v[68:71]
	v_mfma_f32_16x16x32_bf16 v[64:67], v[188:191], v[220:223], v[64:67]
	v_mfma_f32_16x16x32_bf16 v[116:119], v[184:187], v[200:203], v[116:119]
	v_mfma_f32_16x16x32_bf16 v[112:115], v[192:195], v[200:203], v[112:115]
	v_mfma_f32_16x16x32_bf16 v[100:103], v[184:187], v[208:211], v[100:103]
	v_mfma_f32_16x16x32_bf16 v[96:99], v[192:195], v[208:211], v[96:99]
	v_mfma_f32_16x16x32_bf16 v[84:87], v[184:187], v[216:219], v[84:87]
	v_mfma_f32_16x16x32_bf16 v[80:83], v[192:195], v[216:219], v[80:83]
	v_mfma_f32_16x16x32_bf16 v[68:71], v[184:187], v[224:227], v[68:71]
	v_mfma_f32_16x16x32_bf16 v[64:67], v[192:195], v[224:227], v[64:67]
	s_barrier
	s_mov_b32 m0, s44
	v_lshl_add_u64 v[228:229], v[228:229], 0, s[22:23]
	ds_read_b128 v[196:199], v150 offset:49152
	ds_read_b128 v[200:203], v150 offset:50176
	ds_read_b128 v[204:207], v150 offset:51200
	ds_read_b128 v[208:211], v150 offset:52224
	ds_read_b128 v[212:215], v150 offset:53248
	ds_read_b128 v[216:219], v150 offset:54272
	ds_read_b128 v[220:223], v150 offset:55296
	ds_read_b128 v[224:227], v150 offset:56320
	global_load_lds_dwordx4 v[228:229], off
	v_lshl_add_u64 v[228:229], v[230:231], 0, s[22:23]
	s_mov_b32 m0, s45
	s_nop 0
	global_load_lds_dwordx4 v[228:229], off
	v_lshl_add_u64 v[228:229], v[232:233], 0, s[22:23]
	s_mov_b32 m0, s48
	s_nop 0
	global_load_lds_dwordx4 v[228:229], off
	v_lshl_add_u64 v[228:229], v[234:235], 0, s[22:23]
	s_mov_b32 m0, s49
	s_nop 0
	global_load_lds_dwordx4 v[228:229], off
	v_lshl_add_u64 v[228:229], v[236:237], 0, s[22:23]
	s_mov_b32 m0, s46
	s_nop 0
	global_load_lds_dwordx4 v[228:229], off
	v_lshl_add_u64 v[228:229], v[238:239], 0, s[22:23]
	s_mov_b32 m0, s47
	s_nop 0
	global_load_lds_dwordx4 v[228:229], off
	s_waitcnt vmcnt(8)
	s_waitcnt lgkmcnt(0)
	s_barrier
	v_mfma_f32_16x16x32_bf16 v[60:63], v[144:147], v[196:199], v[60:63]
	v_mfma_f32_16x16x32_bf16 v[56:59], v[172:175], v[196:199], v[56:59]
	v_mfma_f32_16x16x32_bf16 v[44:47], v[144:147], v[204:207], v[44:47]
	v_mfma_f32_16x16x32_bf16 v[40:43], v[172:175], v[204:207], v[40:43]
	v_mfma_f32_16x16x32_bf16 v[28:31], v[144:147], v[212:215], v[28:31]
	v_mfma_f32_16x16x32_bf16 v[24:27], v[172:175], v[212:215], v[24:27]
	v_mfma_f32_16x16x32_bf16 v[12:15], v[144:147], v[220:223], v[12:15]
	v_mfma_f32_16x16x32_bf16 v[8:11], v[172:175], v[220:223], v[8:11]
	v_mfma_f32_16x16x32_bf16 v[60:63], v[168:171], v[200:203], v[60:63]
	v_mfma_f32_16x16x32_bf16 v[56:59], v[176:179], v[200:203], v[56:59]
	v_mfma_f32_16x16x32_bf16 v[44:47], v[168:171], v[208:211], v[44:47]
	v_mfma_f32_16x16x32_bf16 v[40:43], v[176:179], v[208:211], v[40:43]
	v_mfma_f32_16x16x32_bf16 v[28:31], v[168:171], v[216:219], v[28:31]
	v_mfma_f32_16x16x32_bf16 v[24:27], v[176:179], v[216:219], v[24:27]
	v_mfma_f32_16x16x32_bf16 v[12:15], v[168:171], v[224:227], v[12:15]
	v_mfma_f32_16x16x32_bf16 v[8:11], v[176:179], v[224:227], v[8:11]
	v_mfma_f32_16x16x32_bf16 v[52:55], v[180:183], v[196:199], v[52:55]
	v_mfma_f32_16x16x32_bf16 v[48:51], v[188:191], v[196:199], v[48:51]
	v_mfma_f32_16x16x32_bf16 v[36:39], v[180:183], v[204:207], v[36:39]
	v_mfma_f32_16x16x32_bf16 v[32:35], v[188:191], v[204:207], v[32:35]
	v_mfma_f32_16x16x32_bf16 v[20:23], v[180:183], v[212:215], v[20:23]
	v_mfma_f32_16x16x32_bf16 v[16:19], v[188:191], v[212:215], v[16:19]
	v_mfma_f32_16x16x32_bf16 v[4:7], v[180:183], v[220:223], v[4:7]
	v_mfma_f32_16x16x32_bf16 v[0:3], v[188:191], v[220:223], v[0:3]
	v_mfma_f32_16x16x32_bf16 v[52:55], v[184:187], v[200:203], v[52:55]
	v_mfma_f32_16x16x32_bf16 v[48:51], v[192:195], v[200:203], v[48:51]
	v_mfma_f32_16x16x32_bf16 v[36:39], v[184:187], v[208:211], v[36:39]
	v_mfma_f32_16x16x32_bf16 v[32:35], v[192:195], v[208:211], v[32:35]
	v_mfma_f32_16x16x32_bf16 v[20:23], v[184:187], v[216:219], v[20:23]
	v_mfma_f32_16x16x32_bf16 v[16:19], v[192:195], v[216:219], v[16:19]
	v_mfma_f32_16x16x32_bf16 v[4:7], v[184:187], v[224:227], v[4:7]
	v_mfma_f32_16x16x32_bf16 v[0:3], v[192:195], v[224:227], v[0:3]
	s_barrier
	s_add_u32 s60, s60, 0x100
	s_addc_u32 s61, s61, 0
	s_add_u32 s4, s4, 0x100
	s_addc_u32 s5, s5, 0
	s_cmp_ge_i32 s30, s50
	s_mov_b32 s0, s30
	s_cbranch_scc0 .LBB0_1046

; #define PG8_WAIT_V(n) asm volatile("s_waitcnt vmcnt(" #n ")" ::: "memory")
; #define PG8_BAR __builtin_amdgcn_s_barrier()
; __device__ __forceinline__ void xcd_barrier(const XcdBarrier& b, const bool xb_is_leader) {
;     asm volatile("s_waitcnt vmcnt(0)" ::: "memory");
;     __syncthreads();
;     if (xb_is_leader) {
;         unsigned* bar = b.bar;
;         __builtin_amdgcn_s_waitcnt(0);
;         unsigned nloc = b.st[0], nx = b.st[1];
;         if (nloc == 0u) { xcd_barrier_complete(bar, b.x, nloc, nx); b.st[0] = nloc; b.st[1] = nx; }
; template <class Epi, class Sched, bool ALIGN_EPI = false, bool SP2 = false>
; __device__ __forceinline__ void gemm_phase(PG8_LAS unsigned char* lds, const Gemm g, const Sched& S, const Epi& E, const int tid_arg) {
;     ...
;     PG8_WAIT_V(0);
;     if constexpr (!ALIGN_EPI) { if (wr == 0) PG8_BAR; }
;     PG8_BAR;
.LBB0_1053:
	s_nop 0
	v_mbcnt_lo_u32_b32 v0, s2, 0
	v_mbcnt_hi_u32_b32 v0, s2, v0
	s_setprio 0
	s_waitcnt vmcnt(0)
	s_waitcnt lgkmcnt(0)
	v_or_b32_e32 v0, s82, v0
	v_cmp_eq_u32_e32 vcc, 0, v0
	s_barrier
	s_and_saveexec_b64 s[4:5], vcc
	s_cbranch_execz .LBB0_1105
	v_mov_b32_e32 v0, 0x22000
	s_waitcnt vmcnt(0) expcnt(0) lgkmcnt(0)
	ds_read_b32 v2, v0
	v_mov_b32_e32 v0, 0x22004
	ds_read_b32 v0, v0
	s_waitcnt lgkmcnt(1)
	v_cmp_ne_u32_e32 vcc, 0, v2
	s_cbranch_vccnz .LBB0_1069
	v_readlane_b32 s0, v251, 0
	v_readlane_b32 s1, v251, 1
	v_readlane_b32 s2, v251, 2
	s_mul_i32 s2, s1, s2
	s_mul_i32 s2, s2, s0
	s_add_u32 s0, s76, 0x1000
	s_addc_u32 s1, s77, 0
	s_add_u32 s6, s76, 0x1100
	s_addc_u32 s7, s77, 0
	s_add_u32 s8, s76, 0x1200
	s_addc_u32 s9, s77, 0
	s_add_u32 s10, s76, 0x1300
	s_addc_u32 s11, s77, 0
	s_mov_b32 s3, 1
	v_mov_b32_e32 v16, 0
	s_branch .LBB0_1057

; #define LAS __attribute__((address_space(3)))
; #define K_TID ((wave_s << 6) | lane_fresh())
; __device__ __forceinline__ void scan_unit(const float* logf, float* F2, int bh, LAS double* sd, int tid) {
;     const int b = bh / 6, h = bh % 6;
;     const float* src = logf + (size_t)b * SEQ * 6 + h;
;     double loc[8]; double run = 0.0;
; #pragma unroll
;     for (int i = 0; i < 8; ++i) { run += (double)src[(size_t)(8 * tid + i) * 6]; loc[i] = run; }
;     sd[tid] = run;
;     __syncthreads();
;     if (tid < 64) {
;         double v[8], tot = 0.0;
; #pragma unroll
;         for (int k = 0; k < 8; ++k) { v[k] = tot; tot += sd[8 * tid + k]; }
;         double inc = tot;
; #pragma unroll
;         for (int o = 1; o < 64; o <<= 1) {
;             const int src = (tid >= o) ? tid - o : tid;
;             const unsigned long long u_ = __builtin_bit_cast(unsigned long long, inc);
;             const unsigned lo_ = (unsigned)__builtin_amdgcn_ds_bpermute(src << 2, (int)(unsigned)u_), hi_ = (unsigned)__builtin_amdgcn_ds_bpermute(src << 2, (int)(unsigned)(u_ >> 32));
;             const double up = __builtin_bit_cast(double, ((unsigned long long)hi_ << 32) | lo_);
;             if (tid >= o) inc += up;
;         }
;         const double base = inc - tot;
; #pragma unroll
;         for (int k = 0; k < 8; ++k) sd[8 * tid + k] = base + v[k];
; __global__ void __launch_bounds__(512, 2) fwd_megakernel(Args a) {
;     ...
;             if (bx < 48) { int tid_l = K_TID, bh_l = bx; asm volatile("" : "+v"(tid_l), "+s"(bh_l)); scan_unit(P_LOGF, P_F2, bh_l, (LAS double*)lds, tid_l); }
.LBB0_1164:
	s_or_b64 exec, exec, s[4:5]
	v_readlane_b32 s0, v251, 3
	v_readlane_b32 s1, v251, 4
	s_andn2_b64 vcc, exec, s[0:1]
	s_waitcnt lgkmcnt(0)
	s_barrier
	s_cselect_b32 s98, 1, 0
	s_cmp_ge_u32 s82, 0x100
	s_cbranch_scc0 .Lprio_skip_17
	s_setprio 1
.Lprio_skip_17:
	s_cmp_lg_u32 s98, 0
	s_cbranch_vccnz .LBB0_1168
	s_mov_b32 s0, -1
	s_mov_b32 s4, s86
	v_mbcnt_lo_u32_b32 v0, s0, 0
	v_mbcnt_hi_u32_b32 v0, s0, v0
	s_mov_b64 s[0:1], s[46:47]
	s_waitcnt vmcnt(3)
	v_or_b32_e32 v18, s82, v0
	s_load_dwordx2 s[0:1], s[0:1], 0x98
	s_mul_hi_i32 s5, s4, 0x2aaaaaab
	s_lshr_b32 s6, s5, 31
	s_add_i32 s5, s5, s6
	s_mul_i32 s6, s5, 6
	s_sub_i32 s6, s4, s6
	v_mov_b32_e32 v2, 0x18000
	s_waitcnt lgkmcnt(0)
	v_mov_b64_e32 v[0:1], s[0:1]
	v_mad_i64_i32 v[0:1], s[0:1], s5, v2, v[0:1]
	s_ashr_i32 s7, s6, 31
	s_lshl_b64 s[0:1], s[6:7], 2
	v_lshl_add_u64 v[0:1], v[0:1], 0, s[0:1]
	s_mov_b64 s[0:1], 0x17804000
	v_lshl_add_u64 v[2:3], v[0:1], 0, s[0:1]
	v_lshlrev_b32_e32 v0, 3, v18
	v_or_b32_e32 v1, 1, v0
	v_mad_i64_i32 v[6:7], s[0:1], v1, 24, v[2:3]
	v_or_b32_e32 v1, 2, v0
	v_mad_i64_i32 v[8:9], s[0:1], v1, 24, v[2:3]
	v_or_b32_e32 v1, 3, v0
	v_mad_i64_i32 v[10:11], s[0:1], v1, 24, v[2:3]
	v_or_b32_e32 v1, 4, v0
	v_mad_i64_i32 v[12:13], s[0:1], v1, 24, v[2:3]
	v_or_b32_e32 v1, 5, v0
	v_mad_i64_i32 v[14:15], s[0:1], v1, 24, v[2:3]
	v_or_b32_e32 v1, 6, v0
	s_mov_b64 s[2:3], s[46:47]
	v_mad_i64_i32 v[4:5], s[0:1], v0, 24, v[2:3]
	v_mad_i64_i32 v[16:17], s[0:1], v1, 24, v[2:3]
	v_or_b32_e32 v1, 7, v0
	v_mad_i64_i32 v[2:3], s[0:1], v1, 24, v[2:3]
	global_load_dword v19, v[4:5], off
	global_load_dword v20, v[6:7], off
	global_load_dword v21, v[8:9], off
	global_load_dword v22, v[10:11], off
	global_load_dword v23, v[12:13], off
	global_load_dword v24, v[14:15], off
	global_load_dword v25, v[16:17], off
	global_load_dword v26, v[2:3], off
	s_load_dwordx2 s[0:1], s[2:3], 0x98
	v_ashrrev_i32_e32 v1, 31, v0
	v_cmp_gt_i32_e32 vcc, 64, v18
	s_waitcnt vmcnt(7)
	v_cvt_f64_f32_e32 v[2:3], v19
	s_waitcnt vmcnt(6)
	v_cvt_f64_f32_e32 v[4:5], v20
	v_add_f64 v[14:15], v[2:3], 0
	s_waitcnt vmcnt(5)
	v_cvt_f64_f32_e32 v[6:7], v21
	v_add_f64 v[16:17], v[14:15], v[4:5]
	s_waitcnt vmcnt(4)
	v_cvt_f64_f32_e32 v[8:9], v22
	v_add_f64 v[10:11], v[16:17], v[6:7]
	s_waitcnt vmcnt(3)
	v_cvt_f64_f32_e32 v[20:21], v23
	v_add_f64 v[12:13], v[10:11], v[8:9]
	s_waitcnt vmcnt(2)
	v_cvt_f64_f32_e32 v[22:23], v24
	v_add_f64 v[6:7], v[12:13], v[20:21]
	s_waitcnt vmcnt(1)
	v_cvt_f64_f32_e32 v[24:25], v25
	v_add_f64 v[8:9], v[6:7], v[22:23]
	s_waitcnt vmcnt(0)
	v_cvt_f64_f32_e32 v[26:27], v26
	v_add_f64 v[2:3], v[8:9], v[24:25]
	v_add_f64 v[4:5], v[2:3], v[26:27]
	ds_write_b64 v0, v[4:5]
	s_waitcnt lgkmcnt(0)
	s_barrier
	s_and_saveexec_b64 s[6:7], vcc
	s_cbranch_execz .LBB0_1167
	v_lshlrev_b32_e32 v40, 6, v18
	ds_read_b128 v[20:23], v40
	ds_read_b128 v[24:27], v40 offset:16
	ds_read_b128 v[28:31], v40 offset:32
	ds_read_b128 v[32:35], v40 offset:48
	v_cmp_lt_i32_e32 vcc, 0, v18
	s_waitcnt lgkmcnt(3)
	v_add_f64 v[20:21], v[20:21], 0
	v_add_f64 v[22:23], v[20:21], v[22:23]
	s_waitcnt lgkmcnt(2)
	v_add_f64 v[24:25], v[22:23], v[24:25]
	v_add_f64 v[26:27], v[24:25], v[26:27]
	s_waitcnt lgkmcnt(1)
	v_add_f64 v[28:29], v[26:27], v[28:29]
	v_add_f64 v[30:31], v[28:29], v[30:31]
	s_waitcnt lgkmcnt(0)
	v_add_f64 v[32:33], v[30:31], v[32:33]
	v_subbrev_co_u32_e64 v19, s[10:11], 0, v18, vcc
	v_add_f64 v[34:35], v[32:33], v[34:35]
	v_lshlrev_b32_e32 v19, 2, v19
	ds_bpermute_b32 v36, v19, v34
	ds_bpermute_b32 v37, v19, v35
	v_mov_b32_e32 v19, 0x3ffffffe
	s_waitcnt lgkmcnt(0)
	v_add_f64 v[36:37], v[34:35], v[36:37]
	v_cndmask_b32_e32 v37, v35, v37, vcc
	v_cndmask_b32_e32 v36, v34, v36, vcc
	v_cmp_gt_i32_e32 vcc, 2, v18
	s_nop 1
	v_cndmask_b32_e64 v19, v19, 0, vcc
	v_add_lshl_u32 v19, v19, v18, 2
	ds_bpermute_b32 v38, v19, v36
	ds_bpermute_b32 v39, v19, v37
	v_mov_b32_e32 v19, 0x3ffffffc
	s_waitcnt lgkmcnt(0)
	v_add_f64 v[38:39], v[36:37], v[38:39]
	v_cndmask_b32_e32 v37, v39, v37, vcc
	v_cndmask_b32_e32 v36, v38, v36, vcc
	v_cmp_gt_i32_e32 vcc, 4, v18
	s_nop 1
	v_cndmask_b32_e64 v19, v19, 0, vcc
	v_add_lshl_u32 v19, v19, v18, 2
	ds_bpermute_b32 v38, v19, v36
	ds_bpermute_b32 v39, v19, v37
	v_mov_b32_e32 v19, 0x3ffffff8
	s_waitcnt lgkmcnt(0)
	v_add_f64 v[38:39], v[36:37], v[38:39]
	v_cndmask_b32_e32 v37, v39, v37, vcc
	v_cndmask_b32_e32 v36, v38, v36, vcc
	v_cmp_gt_i32_e32 vcc, 8, v18
	s_nop 1
	v_cndmask_b32_e64 v19, v19, 0, vcc
	v_add_lshl_u32 v19, v19, v18, 2
	ds_bpermute_b32 v38, v19, v36
	ds_bpermute_b32 v39, v19, v37
	v_mov_b32_e32 v19, 0x3ffffff0
	s_waitcnt lgkmcnt(0)
	v_add_f64 v[38:39], v[36:37], v[38:39]
	v_cndmask_b32_e32 v37, v39, v37, vcc
	v_cndmask_b32_e32 v36, v38, v36, vcc
	v_cmp_gt_i32_e32 vcc, 16, v18
	s_nop 1
	v_cndmask_b32_e64 v19, v19, 0, vcc
	v_add_lshl_u32 v19, v19, v18, 2
	ds_bpermute_b32 v38, v19, v36
	ds_bpermute_b32 v39, v19, v37
	v_mov_b32_e32 v19, 0x3fffffe0
	s_waitcnt lgkmcnt(0)
	v_add_f64 v[38:39], v[36:37], v[38:39]
	v_cndmask_b32_e32 v37, v39, v37, vcc
	v_cndmask_b32_e32 v36, v38, v36, vcc
	v_cmp_gt_i32_e32 vcc, 32, v18
	s_nop 1
	v_cndmask_b32_e64 v19, v19, 0, vcc
	v_add_lshl_u32 v19, v19, v18, 2
	ds_bpermute_b32 v18, v19, v36
	ds_bpermute_b32 v19, v19, v37
	s_waitcnt lgkmcnt(0)
	v_add_f64 v[18:19], v[36:37], v[18:19]
	v_cndmask_b32_e32 v19, v19, v37, vcc
	v_cndmask_b32_e32 v18, v18, v36, vcc
	v_add_f64 v[34:35], v[18:19], -v[34:35]
	v_add_f64 v[18:19], v[34:35], 0
	v_add_f64 v[20:21], v[20:21], v[34:35]
	ds_write_b128 v40, v[18:21]
	v_add_f64 v[18:19], v[22:23], v[34:35]
	v_add_f64 v[20:21], v[24:25], v[34:35]
	ds_write_b128 v40, v[18:21] offset:16
	v_add_f64 v[18:19], v[26:27], v[34:35]
	v_add_f64 v[20:21], v[28:29], v[34:35]
	ds_write_b128 v40, v[18:21] offset:32
	v_add_f64 v[18:19], v[30:31], v[34:35]
	v_add_f64 v[20:21], v[32:33], v[34:35]
	ds_write_b128 v40, v[18:21] offset:48

; #define PG8_STAGE(bufoff, gbase, voff) do { _Pragma("unroll") for (int _i = 0; _i < 2; ++_i) \
;         __builtin_amdgcn_global_load_lds((const unsigned*)((const char*)(gbase) + (voff)[_i]), (PG8_LAS unsigned*)(lds + (bufoff) + ldsw + _i * 8192), 16, 0, 0); } while (0)
; #define PG8_LDA(dst, b, h) do { _Pragma("unroll") for (int m = 0; m < 4; ++m) _Pragma("unroll") for (int k = 0; k < 2; ++k) dst[m][k] = *(const PG8_LAS bf16x8*)(lds + PG8_SA(b, h) + aoff + m * 2048 + k * 1024); } while (0)
; #define PG8_LDB(dst, b, h) do { _Pragma("unroll") for (int n = 0; n < 2; ++n) _Pragma("unroll") for (int k = 0; k < 2; ++k) dst[n][k] = *(const PG8_LAS bf16x8*)(lds + PG8_SB(b, h) + boff + n * 2048 + k * 1024); } while (0)
; #define PG8_MMA(ai, bj, At, Bt) do { __builtin_amdgcn_s_setprio(1); _Pragma("unroll") for (int m = 0; m < 4; ++m) _Pragma("unroll") for (int n = 0; n < 2; ++n) _Pragma("unroll") for (int k = 0; k < 2; ++k) \
;         acc[ai][bj][m][n] = __builtin_amdgcn_mfma_f32_16x16x32_bf16(Bt[n][k], At[m][k], acc[ai][bj][m][n], 0, 0, 0); __builtin_amdgcn_s_setprio(0); } while (0)
; #define PG8_WAIT_V(n) asm volatile("s_waitcnt vmcnt(" #n ")" ::: "memory")
; #define PG8_WAIT_L(n) asm volatile("s_waitcnt lgkmcnt(" #n ")" ::: "memory")
; #define PG8_BAR __builtin_amdgcn_s_barrier()
; #define PG8_SCHED __builtin_amdgcn_sched_barrier(0)
; template <class Epi, class Sched, bool ALIGN_EPI = false, bool SP2 = false>
; __device__ __forceinline__ void gemm_phase(PG8_LAS unsigned char* lds, const Gemm g, const Sched& S, const Epi& E, const int tid_arg) {
;     ...
;             PG8_LDB(B0, 0, 0); PG8_LDB(B1, 0, 1); PG8_SCHED; PG8_LDA(At, 0, 0); PG8_STAGE(PG8_SA(1, 1), a1 + hstep, voffA);
;             PG8_WAIT_V(8); PG8_WAIT_L(0); PG8_BAR; PG8_MMA(0, 0, At, B0); PG8_MMA(0, 1, At, B1); PG8_BAR; PG8_SCHED;
;             PG8_LDA(At, 0, 1); PG8_STAGE(PG8_SB(0, 0), b2, voffB); PG8_STAGE(PG8_SB(0, 1), b2 + hstep, voffB); PG8_STAGE(PG8_SA(0, 0), a2, voffA);
;             PG8_WAIT_V(8); PG8_WAIT_L(0); PG8_BAR; PG8_MMA(1, 0, At, B0); PG8_MMA(1, 1, At, B1); PG8_BAR; PG8_SCHED;
.LBB0_1179:
	ds_read_b128 v[144:147], v166
	ds_read_b128 v[148:151], v167
	ds_read_b128 v[152:155], v168
	ds_read_b128 v[156:159], v169
	ds_read_b128 v[184:187], v170
	ds_read_b128 v[188:191], v171
	ds_read_b128 v[192:195], v172
	ds_read_b128 v[196:199], v173
	s_add_u32 s0, s4, 0xfffc0080
	s_addc_u32 s1, s5, -1
	s_cmp_eq_u32 s68, 12
	s_cselect_b32 s11, s25, s1
	s_cselect_b32 s10, s36, s0
	s_cselect_b32 s1, s23, s67
	s_cselect_b32 s0, s37, s66
	s_mov_b32 m0, s55
	v_lshl_add_u64 v[160:161], s[4:5], 0, v[138:139]
	ds_read_b128 v[200:203], v165
	ds_read_b128 v[204:207], v165 offset:1024
	ds_read_b128 v[208:211], v165 offset:2048
	ds_read_b128 v[212:215], v165 offset:3072
	ds_read_b128 v[216:219], v165 offset:4096
	ds_read_b128 v[220:223], v165 offset:5120
	ds_read_b128 v[224:227], v165 offset:6144
	ds_read_b128 v[228:231], v165 offset:7168
	global_load_lds_dwordx4 v[160:161], off
	v_lshl_add_u64 v[160:161], s[4:5], 0, v[136:137]
	s_mov_b32 m0, s56
	s_nop 0
	global_load_lds_dwordx4 v[160:161], off
	s_waitcnt vmcnt(8)
	s_waitcnt lgkmcnt(0)
	s_barrier
	v_mfma_f32_16x16x32_bf16 v[124:127], v[144:147], v[200:203], v[124:127]
	v_mfma_f32_16x16x32_bf16 v[120:123], v[152:155], v[200:203], v[120:123]
	v_mfma_f32_16x16x32_bf16 v[108:111], v[144:147], v[208:211], v[108:111]
	v_mfma_f32_16x16x32_bf16 v[104:107], v[152:155], v[208:211], v[104:107]
	v_mfma_f32_16x16x32_bf16 v[92:95], v[144:147], v[216:219], v[92:95]
	v_mfma_f32_16x16x32_bf16 v[88:91], v[152:155], v[216:219], v[88:91]
	v_mfma_f32_16x16x32_bf16 v[76:79], v[144:147], v[224:227], v[76:79]
	v_mfma_f32_16x16x32_bf16 v[72:75], v[152:155], v[224:227], v[72:75]
	v_mfma_f32_16x16x32_bf16 v[124:127], v[148:151], v[204:207], v[124:127]
	v_mfma_f32_16x16x32_bf16 v[120:123], v[156:159], v[204:207], v[120:123]
	v_mfma_f32_16x16x32_bf16 v[108:111], v[148:151], v[212:215], v[108:111]
	v_mfma_f32_16x16x32_bf16 v[104:107], v[156:159], v[212:215], v[104:107]
	v_mfma_f32_16x16x32_bf16 v[92:95], v[148:151], v[220:223], v[92:95]
	v_mfma_f32_16x16x32_bf16 v[88:91], v[156:159], v[220:223], v[88:91]
	v_mfma_f32_16x16x32_bf16 v[76:79], v[148:151], v[228:231], v[76:79]
	v_mfma_f32_16x16x32_bf16 v[72:75], v[156:159], v[228:231], v[72:75]
	v_mfma_f32_16x16x32_bf16 v[116:119], v[184:187], v[200:203], v[116:119]
	v_mfma_f32_16x16x32_bf16 v[112:115], v[192:195], v[200:203], v[112:115]
	v_mfma_f32_16x16x32_bf16 v[100:103], v[184:187], v[208:211], v[100:103]
	v_mfma_f32_16x16x32_bf16 v[96:99], v[192:195], v[208:211], v[96:99]
	v_mfma_f32_16x16x32_bf16 v[84:87], v[184:187], v[216:219], v[84:87]
	v_mfma_f32_16x16x32_bf16 v[80:83], v[192:195], v[216:219], v[80:83]
	v_mfma_f32_16x16x32_bf16 v[68:71], v[184:187], v[224:227], v[68:71]
	v_mfma_f32_16x16x32_bf16 v[64:67], v[192:195], v[224:227], v[64:67]
	v_mfma_f32_16x16x32_bf16 v[116:119], v[188:191], v[204:207], v[116:119]
	v_mfma_f32_16x16x32_bf16 v[112:115], v[196:199], v[204:207], v[112:115]
	v_mfma_f32_16x16x32_bf16 v[100:103], v[188:191], v[212:215], v[100:103]
	v_mfma_f32_16x16x32_bf16 v[96:99], v[196:199], v[212:215], v[96:99]
	v_mfma_f32_16x16x32_bf16 v[84:87], v[188:191], v[220:223], v[84:87]
	v_mfma_f32_16x16x32_bf16 v[80:83], v[196:199], v[220:223], v[80:83]
	v_mfma_f32_16x16x32_bf16 v[68:71], v[188:191], v[228:231], v[68:71]
	v_mfma_f32_16x16x32_bf16 v[64:67], v[196:199], v[228:231], v[64:67]
	s_barrier
	s_mov_b32 m0, s31
	v_lshl_add_u64 v[160:161], s[0:1], 0, v[130:131]
	s_add_u32 s70, s0, 0x40000
	ds_read_b128 v[200:203], v165 offset:16384
	ds_read_b128 v[204:207], v165 offset:17408
	ds_read_b128 v[208:211], v165 offset:18432
	ds_read_b128 v[212:215], v165 offset:19456
	ds_read_b128 v[216:219], v165 offset:20480
	ds_read_b128 v[220:223], v165 offset:21504
	ds_read_b128 v[224:227], v165 offset:22528
	ds_read_b128 v[228:231], v165 offset:23552
	global_load_lds_dwordx4 v[160:161], off
	v_lshl_add_u64 v[232:233], s[0:1], 0, v[134:135]
	s_mov_b32 m0, s35
	s_addc_u32 s71, s1, 0
	global_load_lds_dwordx4 v[232:233], off
	v_lshl_add_u64 v[234:235], s[70:71], 0, v[130:131]
	s_mov_b32 m0, s40
	v_lshl_add_u64 v[236:237], s[10:11], 0, v[132:133]
	global_load_lds_dwordx4 v[234:235], off
	v_lshl_add_u64 v[234:235], s[70:71], 0, v[134:135]
	s_mov_b32 m0, s41
	s_nop 0
	global_load_lds_dwordx4 v[234:235], off
	v_lshl_add_u64 v[234:235], s[10:11], 0, v[128:129]
	s_mov_b32 m0, s39
	s_nop 0
	global_load_lds_dwordx4 v[234:235], off
	s_mov_b32 m0, s42
	s_nop 0
	global_load_lds_dwordx4 v[236:237], off
	s_waitcnt vmcnt(8)
	s_waitcnt lgkmcnt(0)
	s_barrier
	v_mfma_f32_16x16x32_bf16 v[60:63], v[144:147], v[200:203], v[60:63]
	v_mfma_f32_16x16x32_bf16 v[56:59], v[152:155], v[200:203], v[56:59]
	v_mfma_f32_16x16x32_bf16 v[44:47], v[144:147], v[208:211], v[44:47]
	v_mfma_f32_16x16x32_bf16 v[40:43], v[152:155], v[208:211], v[40:43]
	v_mfma_f32_16x16x32_bf16 v[28:31], v[144:147], v[216:219], v[28:31]
	v_mfma_f32_16x16x32_bf16 v[24:27], v[152:155], v[216:219], v[24:27]
	v_mfma_f32_16x16x32_bf16 v[12:15], v[144:147], v[224:227], v[12:15]
	v_mfma_f32_16x16x32_bf16 v[8:11], v[152:155], v[224:227], v[8:11]
	v_mfma_f32_16x16x32_bf16 v[60:63], v[148:151], v[204:207], v[60:63]
	v_mfma_f32_16x16x32_bf16 v[56:59], v[156:159], v[204:207], v[56:59]
	v_mfma_f32_16x16x32_bf16 v[44:47], v[148:151], v[212:215], v[44:47]
	v_mfma_f32_16x16x32_bf16 v[40:43], v[156:159], v[212:215], v[40:43]
	v_mfma_f32_16x16x32_bf16 v[28:31], v[148:151], v[220:223], v[28:31]
	v_mfma_f32_16x16x32_bf16 v[24:27], v[156:159], v[220:223], v[24:27]
	v_mfma_f32_16x16x32_bf16 v[12:15], v[148:151], v[228:231], v[12:15]
	v_mfma_f32_16x16x32_bf16 v[8:11], v[156:159], v[228:231], v[8:11]
	v_mfma_f32_16x16x32_bf16 v[52:55], v[184:187], v[200:203], v[52:55]
	v_mfma_f32_16x16x32_bf16 v[48:51], v[192:195], v[200:203], v[48:51]
	v_mfma_f32_16x16x32_bf16 v[36:39], v[184:187], v[208:211], v[36:39]
	v_mfma_f32_16x16x32_bf16 v[32:35], v[192:195], v[208:211], v[32:35]
	v_mfma_f32_16x16x32_bf16 v[20:23], v[184:187], v[216:219], v[20:23]
	v_mfma_f32_16x16x32_bf16 v[16:19], v[192:195], v[216:219], v[16:19]
	v_mfma_f32_16x16x32_bf16 v[4:7], v[184:187], v[224:227], v[4:7]
	v_mfma_f32_16x16x32_bf16 v[0:3], v[192:195], v[224:227], v[0:3]
	v_mfma_f32_16x16x32_bf16 v[52:55], v[188:191], v[204:207], v[52:55]
	v_mfma_f32_16x16x32_bf16 v[48:51], v[196:199], v[204:207], v[48:51]
	v_mfma_f32_16x16x32_bf16 v[36:39], v[188:191], v[212:215], v[36:39]
	v_mfma_f32_16x16x32_bf16 v[32:35], v[196:199], v[212:215], v[32:35]
	v_mfma_f32_16x16x32_bf16 v[20:23], v[188:191], v[220:223], v[20:23]
	v_mfma_f32_16x16x32_bf16 v[16:19], v[196:199], v[220:223], v[16:19]
	v_mfma_f32_16x16x32_bf16 v[4:7], v[188:191], v[228:231], v[4:7]
	v_mfma_f32_16x16x32_bf16 v[0:3], v[196:199], v[228:231], v[0:3]
	s_barrier
; #define PG8_STAGE(bufoff, gbase, voff) do { _Pragma("unroll") for (int _i = 0; _i < 2; ++_i) \
;         __builtin_amdgcn_global_load_lds((const unsigned*)((const char*)(gbase) + (voff)[_i]), (PG8_LAS unsigned*)(lds + (bufoff) + ldsw + _i * 8192), 16, 0, 0); } while (0)
; #define PG8_LDA(dst, b, h) do { _Pragma("unroll") for (int m = 0; m < 4; ++m) _Pragma("unroll") for (int k = 0; k < 2; ++k) dst[m][k] = *(const PG8_LAS bf16x8*)(lds + PG8_SA(b, h) + aoff + m * 2048 + k * 1024); } while (0)
; #define PG8_LDB(dst, b, h) do { _Pragma("unroll") for (int n = 0; n < 2; ++n) _Pragma("unroll") for (int k = 0; k < 2; ++k) dst[n][k] = *(const PG8_LAS bf16x8*)(lds + PG8_SB(b, h) + boff + n * 2048 + k * 1024); } while (0)
; #define PG8_MMA(ai, bj, At, Bt) do { __builtin_amdgcn_s_setprio(1); _Pragma("unroll") for (int m = 0; m < 4; ++m) _Pragma("unroll") for (int n = 0; n < 2; ++n) _Pragma("unroll") for (int k = 0; k < 2; ++k) \
;         acc[ai][bj][m][n] = __builtin_amdgcn_mfma_f32_16x16x32_bf16(Bt[n][k], At[m][k], acc[ai][bj][m][n], 0, 0, 0); __builtin_amdgcn_s_setprio(0); } while (0)
; #define PG8_WAIT_V(n) asm volatile("s_waitcnt vmcnt(" #n ")" ::: "memory")
; #define PG8_WAIT_L(n) asm volatile("s_waitcnt lgkmcnt(" #n ")" ::: "memory")
; #define PG8_BAR __builtin_amdgcn_s_barrier()
; #define PG8_SCHED __builtin_amdgcn_sched_barrier(0)
; template <class Epi, class Sched, bool ALIGN_EPI = false, bool SP2 = false>
; __device__ __forceinline__ void gemm_phase(PG8_LAS unsigned char* lds, const Gemm g, const Sched& S, const Epi& E, const int tid_arg) {
;     ...
;         for (int t = 0; t < nt; t += 2) {
;     ...
;             PG8_LDB(B0, 1, 0); PG8_LDB(B1, 1, 1); PG8_SCHED; PG8_LDA(At, 1, 0); PG8_STAGE(PG8_SA(0, 1), a2 + hstep, voffA);
;             PG8_WAIT_V(8); PG8_WAIT_L(0); PG8_BAR; PG8_MMA(0, 0, At, B0); PG8_MMA(0, 1, At, B1); PG8_BAR; PG8_SCHED;
;             PG8_LDA(At, 1, 1); PG8_STAGE(PG8_SB(1, 0), b3, voffB); PG8_STAGE(PG8_SB(1, 1), b3 + hstep, voffB); PG8_STAGE(PG8_SA(1, 0), a3, voffA);
;             PG8_WAIT_V(8); PG8_WAIT_L(0); PG8_BAR; PG8_MMA(1, 0, At, B0); PG8_MMA(1, 1, At, B1); PG8_BAR; PG8_SCHED;
	ds_read_b128 v[144:147], v174
	ds_read_b128 v[148:151], v175
	ds_read_b128 v[152:155], v176
	ds_read_b128 v[156:159], v177
	ds_read_b128 v[184:187], v178
	ds_read_b128 v[188:191], v179
	ds_read_b128 v[192:195], v180
	ds_read_b128 v[196:199], v181
	s_add_u32 s10, s10, 0x40000
	s_addc_u32 s11, s11, 0
	s_mov_b32 m0, s43
	v_lshl_add_u64 v[238:239], s[10:11], 0, v[128:129]
	ds_read_b128 v[200:203], v165 offset:32768
	ds_read_b128 v[204:207], v165 offset:33792
	ds_read_b128 v[208:211], v165 offset:34816
	ds_read_b128 v[212:215], v165 offset:35840
	ds_read_b128 v[216:219], v165 offset:36864
	ds_read_b128 v[220:223], v165 offset:37888
	ds_read_b128 v[224:227], v165 offset:38912
	ds_read_b128 v[228:231], v165 offset:39936
	global_load_lds_dwordx4 v[238:239], off
	v_lshl_add_u64 v[238:239], s[10:11], 0, v[132:133]
	s_mov_b32 m0, s44
	s_nop 0
	global_load_lds_dwordx4 v[238:239], off
	s_waitcnt vmcnt(8)
	s_waitcnt lgkmcnt(0)
	s_barrier
	v_mfma_f32_16x16x32_bf16 v[124:127], v[144:147], v[200:203], v[124:127]
	v_mfma_f32_16x16x32_bf16 v[120:123], v[152:155], v[200:203], v[120:123]
	v_mfma_f32_16x16x32_bf16 v[108:111], v[144:147], v[208:211], v[108:111]
	v_mfma_f32_16x16x32_bf16 v[104:107], v[152:155], v[208:211], v[104:107]
	v_mfma_f32_16x16x32_bf16 v[92:95], v[144:147], v[216:219], v[92:95]
	v_mfma_f32_16x16x32_bf16 v[88:91], v[152:155], v[216:219], v[88:91]
	v_mfma_f32_16x16x32_bf16 v[76:79], v[144:147], v[224:227], v[76:79]
	v_mfma_f32_16x16x32_bf16 v[72:75], v[152:155], v[224:227], v[72:75]
	v_mfma_f32_16x16x32_bf16 v[124:127], v[148:151], v[204:207], v[124:127]
	v_mfma_f32_16x16x32_bf16 v[120:123], v[156:159], v[204:207], v[120:123]
	v_mfma_f32_16x16x32_bf16 v[108:111], v[148:151], v[212:215], v[108:111]
	v_mfma_f32_16x16x32_bf16 v[104:107], v[156:159], v[212:215], v[104:107]
	v_mfma_f32_16x16x32_bf16 v[92:95], v[148:151], v[220:223], v[92:95]
	v_mfma_f32_16x16x32_bf16 v[88:91], v[156:159], v[220:223], v[88:91]
	v_mfma_f32_16x16x32_bf16 v[76:79], v[148:151], v[228:231], v[76:79]
	v_mfma_f32_16x16x32_bf16 v[72:75], v[156:159], v[228:231], v[72:75]
	v_mfma_f32_16x16x32_bf16 v[116:119], v[184:187], v[200:203], v[116:119]
	v_mfma_f32_16x16x32_bf16 v[112:115], v[192:195], v[200:203], v[112:115]
	v_mfma_f32_16x16x32_bf16 v[100:103], v[184:187], v[208:211], v[100:103]
	v_mfma_f32_16x16x32_bf16 v[96:99], v[192:195], v[208:211], v[96:99]
	v_mfma_f32_16x16x32_bf16 v[84:87], v[184:187], v[216:219], v[84:87]
	v_mfma_f32_16x16x32_bf16 v[80:83], v[192:195], v[216:219], v[80:83]
	v_mfma_f32_16x16x32_bf16 v[68:71], v[184:187], v[224:227], v[68:71]
	v_mfma_f32_16x16x32_bf16 v[64:67], v[192:195], v[224:227], v[64:67]
	v_mfma_f32_16x16x32_bf16 v[116:119], v[188:191], v[204:207], v[116:119]
	v_mfma_f32_16x16x32_bf16 v[112:115], v[196:199], v[204:207], v[112:115]
	v_mfma_f32_16x16x32_bf16 v[100:103], v[188:191], v[212:215], v[100:103]
	v_mfma_f32_16x16x32_bf16 v[96:99], v[196:199], v[212:215], v[96:99]
	v_mfma_f32_16x16x32_bf16 v[84:87], v[188:191], v[220:223], v[84:87]
	v_mfma_f32_16x16x32_bf16 v[80:83], v[196:199], v[220:223], v[80:83]
	v_mfma_f32_16x16x32_bf16 v[68:71], v[188:191], v[228:231], v[68:71]
	v_mfma_f32_16x16x32_bf16 v[64:67], v[196:199], v[228:231], v[64:67]
	s_barrier
	s_mov_b32 m0, s47
	v_lshl_add_u64 v[160:161], v[160:161], 0, s[16:17]
	s_add_u32 s0, s0, 0x40080
	ds_read_b128 v[200:203], v165 offset:49152
	ds_read_b128 v[204:207], v165 offset:50176
	ds_read_b128 v[208:211], v165 offset:51200
	ds_read_b128 v[212:215], v165 offset:52224
	ds_read_b128 v[216:219], v165 offset:53248
	ds_read_b128 v[220:223], v165 offset:54272
	ds_read_b128 v[224:227], v165 offset:55296
	ds_read_b128 v[228:231], v165 offset:56320
	global_load_lds_dwordx4 v[160:161], off
	v_lshl_add_u64 v[160:161], v[232:233], 0, s[16:17]
	s_mov_b32 m0, s48
	s_addc_u32 s1, s1, 0
	global_load_lds_dwordx4 v[160:161], off
	v_lshl_add_u64 v[160:161], s[0:1], 0, v[130:131]
	s_mov_b32 m0, s51
	s_nop 0
	global_load_lds_dwordx4 v[160:161], off
	v_lshl_add_u64 v[160:161], s[0:1], 0, v[134:135]
	s_mov_b32 m0, s52
	s_nop 0
	global_load_lds_dwordx4 v[160:161], off
	v_lshl_add_u64 v[160:161], v[234:235], 0, s[16:17]
	s_mov_b32 m0, s49
	s_nop 0
	global_load_lds_dwordx4 v[160:161], off
	v_lshl_add_u64 v[160:161], v[236:237], 0, s[16:17]
	s_mov_b32 m0, s50
	s_nop 0
	global_load_lds_dwordx4 v[160:161], off
	s_waitcnt vmcnt(8)
	s_waitcnt lgkmcnt(0)
	s_barrier
	v_mfma_f32_16x16x32_bf16 v[60:63], v[144:147], v[200:203], v[60:63]
	v_mfma_f32_16x16x32_bf16 v[56:59], v[152:155], v[200:203], v[56:59]
	v_mfma_f32_16x16x32_bf16 v[44:47], v[144:147], v[208:211], v[44:47]
	v_mfma_f32_16x16x32_bf16 v[40:43], v[152:155], v[208:211], v[40:43]
	v_mfma_f32_16x16x32_bf16 v[28:31], v[144:147], v[216:219], v[28:31]
	v_mfma_f32_16x16x32_bf16 v[24:27], v[152:155], v[216:219], v[24:27]
	v_mfma_f32_16x16x32_bf16 v[12:15], v[144:147], v[224:227], v[12:15]
	v_mfma_f32_16x16x32_bf16 v[8:11], v[152:155], v[224:227], v[8:11]
	v_mfma_f32_16x16x32_bf16 v[60:63], v[148:151], v[204:207], v[60:63]
	v_mfma_f32_16x16x32_bf16 v[56:59], v[156:159], v[204:207], v[56:59]
	v_mfma_f32_16x16x32_bf16 v[44:47], v[148:151], v[212:215], v[44:47]
	v_mfma_f32_16x16x32_bf16 v[40:43], v[156:159], v[212:215], v[40:43]
	v_mfma_f32_16x16x32_bf16 v[28:31], v[148:151], v[220:223], v[28:31]
	v_mfma_f32_16x16x32_bf16 v[24:27], v[156:159], v[220:223], v[24:27]
	v_mfma_f32_16x16x32_bf16 v[12:15], v[148:151], v[228:231], v[12:15]
	v_mfma_f32_16x16x32_bf16 v[8:11], v[156:159], v[228:231], v[8:11]
	v_mfma_f32_16x16x32_bf16 v[52:55], v[184:187], v[200:203], v[52:55]
	v_mfma_f32_16x16x32_bf16 v[48:51], v[192:195], v[200:203], v[48:51]
	v_mfma_f32_16x16x32_bf16 v[36:39], v[184:187], v[208:211], v[36:39]
	v_mfma_f32_16x16x32_bf16 v[32:35], v[192:195], v[208:211], v[32:35]
	v_mfma_f32_16x16x32_bf16 v[20:23], v[184:187], v[216:219], v[20:23]
	v_mfma_f32_16x16x32_bf16 v[16:19], v[192:195], v[216:219], v[16:19]
	v_mfma_f32_16x16x32_bf16 v[4:7], v[184:187], v[224:227], v[4:7]
	v_mfma_f32_16x16x32_bf16 v[0:3], v[192:195], v[224:227], v[0:3]
	v_mfma_f32_16x16x32_bf16 v[52:55], v[188:191], v[204:207], v[52:55]
	v_mfma_f32_16x16x32_bf16 v[48:51], v[196:199], v[204:207], v[48:51]
	v_mfma_f32_16x16x32_bf16 v[36:39], v[188:191], v[212:215], v[36:39]
	v_mfma_f32_16x16x32_bf16 v[32:35], v[196:199], v[212:215], v[32:35]
	v_mfma_f32_16x16x32_bf16 v[20:23], v[188:191], v[220:223], v[20:23]
	v_mfma_f32_16x16x32_bf16 v[16:19], v[196:199], v[220:223], v[16:19]
	v_mfma_f32_16x16x32_bf16 v[4:7], v[188:191], v[228:231], v[4:7]
	v_mfma_f32_16x16x32_bf16 v[0:3], v[196:199], v[228:231], v[0:3]
	s_barrier
	s_add_i32 s68, s68, 2
	s_add_u32 s66, s66, 0x100
	s_addc_u32 s67, s67, 0
	s_add_u32 s4, s4, 0x100
	s_addc_u32 s5, s5, 0
	s_cmp_gt_u32 s68, 13
	s_cbranch_scc0 .LBB0_1179
	s_and_b64 vcc, exec, s[18:19]
	s_cbranch_vccz .LBB0_1182
	s_barrier

; #define LAS __attribute__((address_space(3)))
; #define AIN(i) (kargs()->in[i])
; #define AWS (kargs()->ws)
; #define K_TID ((wave_s << 6) | lane_fresh())
; template <class Epi, class Sched, bool ALIGN_EPI = false, bool SP2 = false>
; __device__ __forceinline__ void gemm_phase(PG8_LAS unsigned char* lds, const Gemm g, const Sched& S, const Epi& E, const int tid_arg) {
;     ...
;     Unit cur, nxt; int ui = 0;
;     if (!S.next(0, cur)) return;
; __global__ void __launch_bounds__(512, 2) fwd_megakernel(Args a) {
;     ...
;             pg8::Gemm g{P_HN, (const bf16_t*)(AWS + WS_WOUT + l * SZ_WOUT), T, DM, DM}; pg8::StaticOrder S; S.init(T, DM, G, bx);
;             pg8::EpiResid E{(l == 0) ? AIN(0) : (const float*)nullptr, P_HB, P_RSQ + (size_t)(2 * l) * T, (LAS float*)(lds + LDS_XCH)};
;             pg8::gemm_phase<pg8::EpiResid, pg8::StaticOrder, true, true>(lds, g, S, E, K_TID);
.Lprio_skip_18:
	s_cmp_lg_u32 s98, 0
	s_mov_b64 s[2:3], s[46:47]
	s_load_dwordx2 s[0:1], s[0:1], 0x98
	s_load_dwordx2 s[8:9], s[2:3], 0x98
	s_mov_b64 s[2:3], s[46:47]
	s_load_dwordx2 s[6:7], s[2:3], 0x98
	s_mov_b64 s[2:3], s[46:47]
	s_load_dwordx2 s[12:13], s[2:3], 0x98
	s_mov_b32 s2, -1
	s_and_b64 vcc, exec, s[88:89]
	v_mbcnt_lo_u32_b32 v0, s2, 0
	v_mbcnt_hi_u32_b32 v0, s2, v0
	s_nop 0
	v_or_b32_e32 v8, s84, v0
	s_nop 0
	v_readfirstlane_b32 s16, v8
	s_cbranch_vccnz .LBB0_1446
	s_lshr_b32 s2, s87, 29
	s_add_i32 s2, s86, s2
	s_and_b32 s3, s2, -8
	s_sub_i32 s3, s86, s3
	s_cmp_gt_i32 s3, -1
	s_cbranch_scc0 .LBB0_1443
	s_lshl_b32 s10, s3, 6
	s_cbranch_execz .LBB0_1444
	s_branch .LBB0_1445

; #define PG8_STAGE(bufoff, gbase, voff) do { _Pragma("unroll") for (int _i = 0; _i < 2; ++_i) \
;         __builtin_amdgcn_global_load_lds((const unsigned*)((const char*)(gbase) + (voff)[_i]), (PG8_LAS unsigned*)(lds + (bufoff) + ldsw + _i * 8192), 16, 0, 0); } while (0)
; #define PG8_LDA(dst, b, h) do { _Pragma("unroll") for (int m = 0; m < 4; ++m) _Pragma("unroll") for (int k = 0; k < 2; ++k) dst[m][k] = *(const PG8_LAS bf16x8*)(lds + PG8_SA(b, h) + aoff + m * 2048 + k * 1024); } while (0)
; #define PG8_WAIT_V(n) asm volatile("s_waitcnt vmcnt(" #n ")" ::: "memory")
; #define PG8_WAIT_L(n) asm volatile("s_waitcnt lgkmcnt(" #n ")" ::: "memory")
; #define PG8_BAR __builtin_amdgcn_s_barrier()
; template <class Epi, class Sched, bool ALIGN_EPI = false, bool SP2 = false>
; __device__ __forceinline__ void gemm_phase(PG8_LAS unsigned char* lds, const Gemm g, const Sched& S, const Epi& E, const int tid_arg) {
;     ...
;         for (int t = 0; t < nt; t += 2) {
;             const bool last = (t == nt - 2);
;             const char* a1 = cA + (size_t)(t + 1) * kstep;
;             const char* a2 = last ? nA : cA + (size_t)(t + 2) * kstep; const char* b2 = last ? nB : cB + (size_t)(t + 2) * kstep;
;             const char* a3 = a2 + kstep; const char* b3 = b2 + kstep;
;             if (last && has_next) S.a_ready(nxt);
;             if constexpr (SP2) {
;             PG8_LDB(B0, 0, 0); PG8_LDB(B1, 0, 1); PG8_SCHED; PG8_LDA(At, 0, 0); PG8_STAGE(PG8_SA(1, 1), a1 + hstep, voffA);
;             PG8_WAIT_V(8); PG8_WAIT_L(0); PG8_BAR; PG8_MMA(0, 0, At, B0); PG8_MMA(0, 1, At, B1); PG8_BAR; PG8_SCHED;
;             PG8_LDA(At, 0, 1); PG8_STAGE(PG8_SB(0, 0), b2, voffB); PG8_STAGE(PG8_SB(0, 1), b2 + hstep, voffB); PG8_STAGE(PG8_SA(0, 0), a2, voffA);
;             PG8_WAIT_V(8); PG8_WAIT_L(0); PG8_BAR; PG8_MMA(1, 0, At, B0); PG8_MMA(1, 1, At, B1); PG8_BAR; PG8_SCHED;
;             PG8_LDB(B0, 1, 0); PG8_LDB(B1, 1, 1); PG8_SCHED; PG8_LDA(At, 1, 0); PG8_STAGE(PG8_SA(0, 1), a2 + hstep, voffA);
;             PG8_WAIT_V(8); PG8_WAIT_L(0); PG8_BAR; PG8_MMA(0, 0, At, B0); PG8_MMA(0, 1, At, B1); PG8_BAR; PG8_SCHED;
;             PG8_LDA(At, 1, 1); PG8_STAGE(PG8_SB(1, 0), b3, voffB); PG8_STAGE(PG8_SB(1, 1), b3 + hstep, voffB); PG8_STAGE(PG8_SA(1, 0), a3, voffA);
;             PG8_WAIT_V(8); PG8_WAIT_L(0); PG8_BAR; PG8_MMA(1, 0, At, B0); PG8_MMA(1, 1, At, B1); PG8_BAR; PG8_SCHED;
.LBB0_1459:
	ds_read_b128 v[144:147], v151
	ds_read_b128 v[168:171], v152
	ds_read_b128 v[172:175], v153
	ds_read_b128 v[176:179], v154
	ds_read_b128 v[180:183], v155
	ds_read_b128 v[184:187], v156
	ds_read_b128 v[188:191], v157
	ds_read_b128 v[192:195], v158
	s_add_u32 s0, s28, 0xfffc0080
	s_addc_u32 s1, s29, -1
	s_cmp_eq_u32 s59, 12
	s_cselect_b32 s31, s21, s1
	s_cselect_b32 s30, s27, s0
	s_cselect_b32 s1, s19, s58
	s_cselect_b32 s0, s56, s57
	s_mov_b32 m0, s53
	v_lshl_add_u64 v[228:229], s[28:29], 0, v[138:139]
	ds_read_b128 v[196:199], v150
	ds_read_b128 v[200:203], v150 offset:1024
	ds_read_b128 v[204:207], v150 offset:2048
	ds_read_b128 v[208:211], v150 offset:3072
	ds_read_b128 v[212:215], v150 offset:4096
	ds_read_b128 v[216:219], v150 offset:5120
	ds_read_b128 v[220:223], v150 offset:6144
	ds_read_b128 v[224:227], v150 offset:7168
	global_load_lds_dwordx4 v[228:229], off
	v_lshl_add_u64 v[228:229], s[28:29], 0, v[136:137]
	s_mov_b32 m0, s54
	s_nop 0
	global_load_lds_dwordx4 v[228:229], off
	s_waitcnt vmcnt(8)
	s_waitcnt lgkmcnt(0)
	s_barrier
	v_mfma_f32_16x16x32_bf16 v[124:127], v[144:147], v[196:199], v[124:127]
	v_mfma_f32_16x16x32_bf16 v[120:123], v[172:175], v[196:199], v[120:123]
	v_mfma_f32_16x16x32_bf16 v[108:111], v[144:147], v[204:207], v[108:111]
	v_mfma_f32_16x16x32_bf16 v[104:107], v[172:175], v[204:207], v[104:107]
	v_mfma_f32_16x16x32_bf16 v[92:95], v[144:147], v[212:215], v[92:95]
	v_mfma_f32_16x16x32_bf16 v[88:91], v[172:175], v[212:215], v[88:91]
	v_mfma_f32_16x16x32_bf16 v[76:79], v[144:147], v[220:223], v[76:79]
	v_mfma_f32_16x16x32_bf16 v[72:75], v[172:175], v[220:223], v[72:75]
	v_mfma_f32_16x16x32_bf16 v[124:127], v[168:171], v[200:203], v[124:127]
	v_mfma_f32_16x16x32_bf16 v[120:123], v[176:179], v[200:203], v[120:123]
	v_mfma_f32_16x16x32_bf16 v[108:111], v[168:171], v[208:211], v[108:111]
	v_mfma_f32_16x16x32_bf16 v[104:107], v[176:179], v[208:211], v[104:107]
	v_mfma_f32_16x16x32_bf16 v[92:95], v[168:171], v[216:219], v[92:95]
	v_mfma_f32_16x16x32_bf16 v[88:91], v[176:179], v[216:219], v[88:91]
	v_mfma_f32_16x16x32_bf16 v[76:79], v[168:171], v[224:227], v[76:79]
	v_mfma_f32_16x16x32_bf16 v[72:75], v[176:179], v[224:227], v[72:75]
	v_mfma_f32_16x16x32_bf16 v[116:119], v[180:183], v[196:199], v[116:119]
	v_mfma_f32_16x16x32_bf16 v[112:115], v[188:191], v[196:199], v[112:115]
	v_mfma_f32_16x16x32_bf16 v[100:103], v[180:183], v[204:207], v[100:103]
	v_mfma_f32_16x16x32_bf16 v[96:99], v[188:191], v[204:207], v[96:99]
	v_mfma_f32_16x16x32_bf16 v[84:87], v[180:183], v[212:215], v[84:87]
	v_mfma_f32_16x16x32_bf16 v[80:83], v[188:191], v[212:215], v[80:83]
	v_mfma_f32_16x16x32_bf16 v[68:71], v[180:183], v[220:223], v[68:71]
	v_mfma_f32_16x16x32_bf16 v[64:67], v[188:191], v[220:223], v[64:67]
	v_mfma_f32_16x16x32_bf16 v[116:119], v[184:187], v[200:203], v[116:119]
	v_mfma_f32_16x16x32_bf16 v[112:115], v[192:195], v[200:203], v[112:115]
	v_mfma_f32_16x16x32_bf16 v[100:103], v[184:187], v[208:211], v[100:103]
	v_mfma_f32_16x16x32_bf16 v[96:99], v[192:195], v[208:211], v[96:99]
	v_mfma_f32_16x16x32_bf16 v[84:87], v[184:187], v[216:219], v[84:87]
	v_mfma_f32_16x16x32_bf16 v[80:83], v[192:195], v[216:219], v[80:83]
	v_mfma_f32_16x16x32_bf16 v[68:71], v[184:187], v[224:227], v[68:71]
	v_mfma_f32_16x16x32_bf16 v[64:67], v[192:195], v[224:227], v[64:67]
	s_barrier
	s_mov_b32 m0, s5
	v_lshl_add_u64 v[228:229], s[0:1], 0, v[130:131]
	s_add_u32 s60, s0, 0x40000
	ds_read_b128 v[196:199], v150 offset:16384
	ds_read_b128 v[200:203], v150 offset:17408
	ds_read_b128 v[204:207], v150 offset:18432
	ds_read_b128 v[208:211], v150 offset:19456
	ds_read_b128 v[212:215], v150 offset:20480
	ds_read_b128 v[216:219], v150 offset:21504
	ds_read_b128 v[220:223], v150 offset:22528
	ds_read_b128 v[224:227], v150 offset:23552
	global_load_lds_dwordx4 v[228:229], off
	v_lshl_add_u64 v[230:231], s[0:1], 0, v[134:135]
	s_mov_b32 m0, s36
	s_addc_u32 s61, s1, 0
	global_load_lds_dwordx4 v[230:231], off
	v_lshl_add_u64 v[232:233], s[60:61], 0, v[130:131]
	s_mov_b32 m0, s37
	v_lshl_add_u64 v[234:235], s[30:31], 0, v[132:133]
	global_load_lds_dwordx4 v[232:233], off
	v_lshl_add_u64 v[232:233], s[60:61], 0, v[134:135]
	s_mov_b32 m0, s38
	s_nop 0
	global_load_lds_dwordx4 v[232:233], off
	v_lshl_add_u64 v[232:233], s[30:31], 0, v[128:129]
	s_mov_b32 m0, s35
	s_nop 0
	global_load_lds_dwordx4 v[232:233], off
	s_mov_b32 m0, s39
	s_nop 0
	global_load_lds_dwordx4 v[234:235], off
	s_waitcnt vmcnt(8)
	s_waitcnt lgkmcnt(0)
	s_barrier
	v_mfma_f32_16x16x32_bf16 v[60:63], v[144:147], v[196:199], v[60:63]
	v_mfma_f32_16x16x32_bf16 v[56:59], v[172:175], v[196:199], v[56:59]
	v_mfma_f32_16x16x32_bf16 v[44:47], v[144:147], v[204:207], v[44:47]
	v_mfma_f32_16x16x32_bf16 v[40:43], v[172:175], v[204:207], v[40:43]
	v_mfma_f32_16x16x32_bf16 v[28:31], v[144:147], v[212:215], v[28:31]
	v_mfma_f32_16x16x32_bf16 v[24:27], v[172:175], v[212:215], v[24:27]
	v_mfma_f32_16x16x32_bf16 v[12:15], v[144:147], v[220:223], v[12:15]
	v_mfma_f32_16x16x32_bf16 v[8:11], v[172:175], v[220:223], v[8:11]
	v_mfma_f32_16x16x32_bf16 v[60:63], v[168:171], v[200:203], v[60:63]
	v_mfma_f32_16x16x32_bf16 v[56:59], v[176:179], v[200:203], v[56:59]
	v_mfma_f32_16x16x32_bf16 v[44:47], v[168:171], v[208:211], v[44:47]
	v_mfma_f32_16x16x32_bf16 v[40:43], v[176:179], v[208:211], v[40:43]
	v_mfma_f32_16x16x32_bf16 v[28:31], v[168:171], v[216:219], v[28:31]
	v_mfma_f32_16x16x32_bf16 v[24:27], v[176:179], v[216:219], v[24:27]
	v_mfma_f32_16x16x32_bf16 v[12:15], v[168:171], v[224:227], v[12:15]
	v_mfma_f32_16x16x32_bf16 v[8:11], v[176:179], v[224:227], v[8:11]
	v_mfma_f32_16x16x32_bf16 v[52:55], v[180:183], v[196:199], v[52:55]
	v_mfma_f32_16x16x32_bf16 v[48:51], v[188:191], v[196:199], v[48:51]
	v_mfma_f32_16x16x32_bf16 v[36:39], v[180:183], v[204:207], v[36:39]
	v_mfma_f32_16x16x32_bf16 v[32:35], v[188:191], v[204:207], v[32:35]
	v_mfma_f32_16x16x32_bf16 v[20:23], v[180:183], v[212:215], v[20:23]
	v_mfma_f32_16x16x32_bf16 v[16:19], v[188:191], v[212:215], v[16:19]
	v_mfma_f32_16x16x32_bf16 v[4:7], v[180:183], v[220:223], v[4:7]
	v_mfma_f32_16x16x32_bf16 v[0:3], v[188:191], v[220:223], v[0:3]
	v_mfma_f32_16x16x32_bf16 v[52:55], v[184:187], v[200:203], v[52:55]
	v_mfma_f32_16x16x32_bf16 v[48:51], v[192:195], v[200:203], v[48:51]
	v_mfma_f32_16x16x32_bf16 v[36:39], v[184:187], v[208:211], v[36:39]
	v_mfma_f32_16x16x32_bf16 v[32:35], v[192:195], v[208:211], v[32:35]
	v_mfma_f32_16x16x32_bf16 v[20:23], v[184:187], v[216:219], v[20:23]
	v_mfma_f32_16x16x32_bf16 v[16:19], v[192:195], v[216:219], v[16:19]
	v_mfma_f32_16x16x32_bf16 v[4:7], v[184:187], v[224:227], v[4:7]
	v_mfma_f32_16x16x32_bf16 v[0:3], v[192:195], v[224:227], v[0:3]
	s_barrier
; #define PG8_STAGE(bufoff, gbase, voff) do { _Pragma("unroll") for (int _i = 0; _i < 2; ++_i) \
;         __builtin_amdgcn_global_load_lds((const unsigned*)((const char*)(gbase) + (voff)[_i]), (PG8_LAS unsigned*)(lds + (bufoff) + ldsw + _i * 8192), 16, 0, 0); } while (0)
; #define PG8_LDA(dst, b, h) do { _Pragma("unroll") for (int m = 0; m < 4; ++m) _Pragma("unroll") for (int k = 0; k < 2; ++k) dst[m][k] = *(const PG8_LAS bf16x8*)(lds + PG8_SA(b, h) + aoff + m * 2048 + k * 1024); } while (0)
; #define PG8_WAIT_V(n) asm volatile("s_waitcnt vmcnt(" #n ")" ::: "memory")
; #define PG8_WAIT_L(n) asm volatile("s_waitcnt lgkmcnt(" #n ")" ::: "memory")
; #define PG8_BAR __builtin_amdgcn_s_barrier()
; template <class Epi, class Sched, bool ALIGN_EPI = false, bool SP2 = false>
; __device__ __forceinline__ void gemm_phase(PG8_LAS unsigned char* lds, const Gemm g, const Sched& S, const Epi& E, const int tid_arg) {
;     ...
;         for (int t = 0; t < nt; t += 2) {
;             const bool last = (t == nt - 2);
;             const char* a1 = cA + (size_t)(t + 1) * kstep;
;             const char* a2 = last ? nA : cA + (size_t)(t + 2) * kstep; const char* b2 = last ? nB : cB + (size_t)(t + 2) * kstep;
;             const char* a3 = a2 + kstep; const char* b3 = b2 + kstep;
;             if (last && has_next) S.a_ready(nxt);
;             if constexpr (SP2) {
;             PG8_LDB(B0, 0, 0); PG8_LDB(B1, 0, 1); PG8_SCHED; PG8_LDA(At, 0, 0); PG8_STAGE(PG8_SA(1, 1), a1 + hstep, voffA);
;             PG8_WAIT_V(8); PG8_WAIT_L(0); PG8_BAR; PG8_MMA(0, 0, At, B0); PG8_MMA(0, 1, At, B1); PG8_BAR; PG8_SCHED;
;             PG8_LDA(At, 0, 1); PG8_STAGE(PG8_SB(0, 0), b2, voffB); PG8_STAGE(PG8_SB(0, 1), b2 + hstep, voffB); PG8_STAGE(PG8_SA(0, 0), a2, voffA);
;             PG8_WAIT_V(8); PG8_WAIT_L(0); PG8_BAR; PG8_MMA(1, 0, At, B0); PG8_MMA(1, 1, At, B1); PG8_BAR; PG8_SCHED;
;             PG8_LDB(B0, 1, 0); PG8_LDB(B1, 1, 1); PG8_SCHED; PG8_LDA(At, 1, 0); PG8_STAGE(PG8_SA(0, 1), a2 + hstep, voffA);
;             PG8_WAIT_V(8); PG8_WAIT_L(0); PG8_BAR; PG8_MMA(0, 0, At, B0); PG8_MMA(0, 1, At, B1); PG8_BAR; PG8_SCHED;
;             PG8_LDA(At, 1, 1); PG8_STAGE(PG8_SB(1, 0), b3, voffB); PG8_STAGE(PG8_SB(1, 1), b3 + hstep, voffB); PG8_STAGE(PG8_SA(1, 0), a3, voffA);
;             PG8_WAIT_V(8); PG8_WAIT_L(0); PG8_BAR; PG8_MMA(1, 0, At, B0); PG8_MMA(1, 1, At, B1); PG8_BAR; PG8_SCHED;
	ds_read_b128 v[144:147], v159
	ds_read_b128 v[168:171], v160
	ds_read_b128 v[172:175], v161
	ds_read_b128 v[176:179], v162
	ds_read_b128 v[180:183], v163
	ds_read_b128 v[184:187], v164
	ds_read_b128 v[188:191], v165
	ds_read_b128 v[192:195], v166
	s_add_u32 s30, s30, 0x40000
	s_addc_u32 s31, s31, 0
	s_mov_b32 m0, s40
	v_lshl_add_u64 v[236:237], s[30:31], 0, v[128:129]
	ds_read_b128 v[196:199], v150 offset:32768
	ds_read_b128 v[200:203], v150 offset:33792
	ds_read_b128 v[204:207], v150 offset:34816
	ds_read_b128 v[208:211], v150 offset:35840
	ds_read_b128 v[212:215], v150 offset:36864
	ds_read_b128 v[216:219], v150 offset:37888
	ds_read_b128 v[220:223], v150 offset:38912
	ds_read_b128 v[224:227], v150 offset:39936
	global_load_lds_dwordx4 v[236:237], off
	v_lshl_add_u64 v[236:237], s[30:31], 0, v[132:133]
	s_mov_b32 m0, s41
	s_nop 0
	global_load_lds_dwordx4 v[236:237], off
	s_waitcnt vmcnt(8)
	s_waitcnt lgkmcnt(0)
	s_barrier
	v_mfma_f32_16x16x32_bf16 v[124:127], v[144:147], v[196:199], v[124:127]
	v_mfma_f32_16x16x32_bf16 v[120:123], v[172:175], v[196:199], v[120:123]
	v_mfma_f32_16x16x32_bf16 v[108:111], v[144:147], v[204:207], v[108:111]
	v_mfma_f32_16x16x32_bf16 v[104:107], v[172:175], v[204:207], v[104:107]
	v_mfma_f32_16x16x32_bf16 v[92:95], v[144:147], v[212:215], v[92:95]
	v_mfma_f32_16x16x32_bf16 v[88:91], v[172:175], v[212:215], v[88:91]
	v_mfma_f32_16x16x32_bf16 v[76:79], v[144:147], v[220:223], v[76:79]
	v_mfma_f32_16x16x32_bf16 v[72:75], v[172:175], v[220:223], v[72:75]
	v_mfma_f32_16x16x32_bf16 v[124:127], v[168:171], v[200:203], v[124:127]
	v_mfma_f32_16x16x32_bf16 v[120:123], v[176:179], v[200:203], v[120:123]
	v_mfma_f32_16x16x32_bf16 v[108:111], v[168:171], v[208:211], v[108:111]
	v_mfma_f32_16x16x32_bf16 v[104:107], v[176:179], v[208:211], v[104:107]
	v_mfma_f32_16x16x32_bf16 v[92:95], v[168:171], v[216:219], v[92:95]
	v_mfma_f32_16x16x32_bf16 v[88:91], v[176:179], v[216:219], v[88:91]
	v_mfma_f32_16x16x32_bf16 v[76:79], v[168:171], v[224:227], v[76:79]
	v_mfma_f32_16x16x32_bf16 v[72:75], v[176:179], v[224:227], v[72:75]
	v_mfma_f32_16x16x32_bf16 v[116:119], v[180:183], v[196:199], v[116:119]
	v_mfma_f32_16x16x32_bf16 v[112:115], v[188:191], v[196:199], v[112:115]
	v_mfma_f32_16x16x32_bf16 v[100:103], v[180:183], v[204:207], v[100:103]
	v_mfma_f32_16x16x32_bf16 v[96:99], v[188:191], v[204:207], v[96:99]
	v_mfma_f32_16x16x32_bf16 v[84:87], v[180:183], v[212:215], v[84:87]
	v_mfma_f32_16x16x32_bf16 v[80:83], v[188:191], v[212:215], v[80:83]
	v_mfma_f32_16x16x32_bf16 v[68:71], v[180:183], v[220:223], v[68:71]
	v_mfma_f32_16x16x32_bf16 v[64:67], v[188:191], v[220:223], v[64:67]
	v_mfma_f32_16x16x32_bf16 v[116:119], v[184:187], v[200:203], v[116:119]
	v_mfma_f32_16x16x32_bf16 v[112:115], v[192:195], v[200:203], v[112:115]
	v_mfma_f32_16x16x32_bf16 v[100:103], v[184:187], v[208:211], v[100:103]
	v_mfma_f32_16x16x32_bf16 v[96:99], v[192:195], v[208:211], v[96:99]
	v_mfma_f32_16x16x32_bf16 v[84:87], v[184:187], v[216:219], v[84:87]
	v_mfma_f32_16x16x32_bf16 v[80:83], v[192:195], v[216:219], v[80:83]
	v_mfma_f32_16x16x32_bf16 v[68:71], v[184:187], v[224:227], v[68:71]
	v_mfma_f32_16x16x32_bf16 v[64:67], v[192:195], v[224:227], v[64:67]
	s_barrier
	s_mov_b32 m0, s45
	v_lshl_add_u64 v[228:229], v[228:229], 0, s[14:15]
	s_add_u32 s0, s0, 0x40080
	ds_read_b128 v[196:199], v150 offset:49152
	ds_read_b128 v[200:203], v150 offset:50176
	ds_read_b128 v[204:207], v150 offset:51200
	ds_read_b128 v[208:211], v150 offset:52224
	ds_read_b128 v[212:215], v150 offset:53248
	ds_read_b128 v[216:219], v150 offset:54272
	ds_read_b128 v[220:223], v150 offset:55296
	ds_read_b128 v[224:227], v150 offset:56320
	global_load_lds_dwordx4 v[228:229], off
	v_lshl_add_u64 v[228:229], v[230:231], 0, s[14:15]
	s_mov_b32 m0, s46
	s_addc_u32 s1, s1, 0
	global_load_lds_dwordx4 v[228:229], off
	v_lshl_add_u64 v[228:229], s[0:1], 0, v[130:131]
	s_mov_b32 m0, s49
	s_nop 0
	global_load_lds_dwordx4 v[228:229], off
	v_lshl_add_u64 v[228:229], s[0:1], 0, v[134:135]
	s_mov_b32 m0, s50
	s_nop 0
	global_load_lds_dwordx4 v[228:229], off
	v_lshl_add_u64 v[228:229], v[232:233], 0, s[14:15]
	s_mov_b32 m0, s47
	s_nop 0
	global_load_lds_dwordx4 v[228:229], off
	v_lshl_add_u64 v[228:229], v[234:235], 0, s[14:15]
	s_mov_b32 m0, s48
	s_nop 0
	global_load_lds_dwordx4 v[228:229], off
	s_waitcnt vmcnt(8)
	s_waitcnt lgkmcnt(0)
	s_barrier
	v_mfma_f32_16x16x32_bf16 v[60:63], v[144:147], v[196:199], v[60:63]
	v_mfma_f32_16x16x32_bf16 v[56:59], v[172:175], v[196:199], v[56:59]
	v_mfma_f32_16x16x32_bf16 v[44:47], v[144:147], v[204:207], v[44:47]
	v_mfma_f32_16x16x32_bf16 v[40:43], v[172:175], v[204:207], v[40:43]
	v_mfma_f32_16x16x32_bf16 v[28:31], v[144:147], v[212:215], v[28:31]
	v_mfma_f32_16x16x32_bf16 v[24:27], v[172:175], v[212:215], v[24:27]
	v_mfma_f32_16x16x32_bf16 v[12:15], v[144:147], v[220:223], v[12:15]
	v_mfma_f32_16x16x32_bf16 v[8:11], v[172:175], v[220:223], v[8:11]
	v_mfma_f32_16x16x32_bf16 v[60:63], v[168:171], v[200:203], v[60:63]
	v_mfma_f32_16x16x32_bf16 v[56:59], v[176:179], v[200:203], v[56:59]
	v_mfma_f32_16x16x32_bf16 v[44:47], v[168:171], v[208:211], v[44:47]
	v_mfma_f32_16x16x32_bf16 v[40:43], v[176:179], v[208:211], v[40:43]
	v_mfma_f32_16x16x32_bf16 v[28:31], v[168:171], v[216:219], v[28:31]
	v_mfma_f32_16x16x32_bf16 v[24:27], v[176:179], v[216:219], v[24:27]
	v_mfma_f32_16x16x32_bf16 v[12:15], v[168:171], v[224:227], v[12:15]
	v_mfma_f32_16x16x32_bf16 v[8:11], v[176:179], v[224:227], v[8:11]
	v_mfma_f32_16x16x32_bf16 v[52:55], v[180:183], v[196:199], v[52:55]
	v_mfma_f32_16x16x32_bf16 v[48:51], v[188:191], v[196:199], v[48:51]
	v_mfma_f32_16x16x32_bf16 v[36:39], v[180:183], v[204:207], v[36:39]
	v_mfma_f32_16x16x32_bf16 v[32:35], v[188:191], v[204:207], v[32:35]
	v_mfma_f32_16x16x32_bf16 v[20:23], v[180:183], v[212:215], v[20:23]
	v_mfma_f32_16x16x32_bf16 v[16:19], v[188:191], v[212:215], v[16:19]
	v_mfma_f32_16x16x32_bf16 v[4:7], v[180:183], v[220:223], v[4:7]
	v_mfma_f32_16x16x32_bf16 v[0:3], v[188:191], v[220:223], v[0:3]
	v_mfma_f32_16x16x32_bf16 v[52:55], v[184:187], v[200:203], v[52:55]
	v_mfma_f32_16x16x32_bf16 v[48:51], v[192:195], v[200:203], v[48:51]
	v_mfma_f32_16x16x32_bf16 v[36:39], v[184:187], v[208:211], v[36:39]
	v_mfma_f32_16x16x32_bf16 v[32:35], v[192:195], v[208:211], v[32:35]
	v_mfma_f32_16x16x32_bf16 v[20:23], v[184:187], v[216:219], v[20:23]
	v_mfma_f32_16x16x32_bf16 v[16:19], v[192:195], v[216:219], v[16:19]
	v_mfma_f32_16x16x32_bf16 v[4:7], v[184:187], v[224:227], v[4:7]
	v_mfma_f32_16x16x32_bf16 v[0:3], v[192:195], v[224:227], v[0:3]
	s_barrier
	s_add_i32 s59, s59, 2
	s_add_u32 s57, s57, 0x100
	s_addc_u32 s58, s58, 0
	s_add_u32 s28, s28, 0x100
	s_addc_u32 s29, s29, 0
	s_cmp_gt_u32 s59, 13
	s_cbranch_scc0 .LBB0_1459
	s_and_b64 vcc, exec, s[16:17]
	s_cbranch_vccz .LBB0_1462
	s_barrier

; #define PG8_WAIT_V(n) asm volatile("s_waitcnt vmcnt(" #n ")" ::: "memory")
; #define PG8_BAR __builtin_amdgcn_s_barrier()
; __device__ __forceinline__ void xcd_barrier(const XcdBarrier& b, const bool xb_is_leader) {
;     asm volatile("s_waitcnt vmcnt(0)" ::: "memory");
;     __syncthreads();
;     if (xb_is_leader) {
;         unsigned* bar = b.bar;
;         __builtin_amdgcn_s_waitcnt(0);
;         unsigned nloc = b.st[0], nx = b.st[1];
;         if (nloc == 0u) { xcd_barrier_complete(bar, b.x, nloc, nx); b.st[0] = nloc; b.st[1] = nx; }
; template <class Epi, class Sched, bool ALIGN_EPI = false, bool SP2 = false>
; __device__ __forceinline__ void gemm_phase(PG8_LAS unsigned char* lds, const Gemm g, const Sched& S, const Epi& E, const int tid_arg) {
;     ...
;     PG8_WAIT_V(0);
;     if constexpr (!ALIGN_EPI) { if (wr == 0) PG8_BAR; }
;     PG8_BAR;
.LBB0_1484:
	s_waitcnt lgkmcnt(0)
	s_mov_b32 s0, -1
	s_nop 0
	v_mbcnt_lo_u32_b32 v0, s0, 0
	v_mbcnt_hi_u32_b32 v0, s0, v0
	s_setprio 0
	s_waitcnt vmcnt(0)
	s_nop 0
	v_or_b32_e32 v0, s84, v0
	v_cmp_eq_u32_e32 vcc, 0, v0
	s_barrier
	s_and_saveexec_b64 s[4:5], vcc
	s_cbranch_execz .LBB0_1536
	v_mov_b32_e32 v0, 0x22000
	s_waitcnt vmcnt(0) expcnt(0) lgkmcnt(0)
	ds_read_b32 v2, v0
	v_mov_b32_e32 v0, 0x22004
	ds_read_b32 v0, v0
	s_waitcnt lgkmcnt(1)
	v_cmp_ne_u32_e32 vcc, 0, v2
	s_cbranch_vccnz .LBB0_1500
	v_readlane_b32 s0, v251, 0
	v_readlane_b32 s1, v251, 1
	v_readlane_b32 s2, v251, 2
	s_mul_i32 s2, s1, s2
	s_mul_i32 s2, s2, s0
	s_add_u32 s0, s76, 0x1000
	s_addc_u32 s1, s77, 0
	s_add_u32 s6, s76, 0x1100
	s_addc_u32 s7, s77, 0
	s_add_u32 s8, s76, 0x1200
	s_addc_u32 s9, s77, 0
	s_add_u32 s10, s76, 0x1300
	s_addc_u32 s11, s77, 0
	s_mov_b32 s3, 1
	v_mov_b32_e32 v16, 0
	s_branch .LBB0_1488

; __device__ __forceinline__ void xcd_barrier(const XcdBarrier& b, const bool xb_is_leader) {
;     ...
;     }
;     __syncthreads();
; }
;     __host__ __device__ bool next(int i, Unit& u) const {
;         const long L = (long)i * G + c; if (L >= nwg) return false;
;         int wgid = (int)L; { const int q = nwg / NXCD, r = nwg % NXCD, xcd = wgid % NXCD, off = wgid / NXCD; wgid = (xcd < r ? xcd * (q + 1) : r * (q + 1) + (xcd - r) * q) + off; }
;         const int nig = WGM * nN, gid = wgid / nig, fm = gid * WGM, gsz = (nM - fm) < WGM ? (nM - fm) : WGM;
;         u.pm = fm + ((wgid % nig) % gsz); u.pn = (wgid % nig) / gsz; return true;
.LBB0_1536:
	s_or_b64 exec, exec, s[4:5]
	s_mov_b64 s[4:5], s[46:47]
	s_mov_b64 s[6:7], s[46:47]
	s_mov_b64 s[0:1], s[46:47]
	s_mov_b64 s[8:9], s[46:47]
	s_mov_b64 s[10:11], s[46:47]
	s_mov_b64 s[12:13], s[46:47]
	s_mov_b64 s[14:15], s[46:47]
	s_mov_b32 s2, -1
	s_waitcnt lgkmcnt(0)
	s_barrier
	s_cselect_b32 s98, 1, 0
	s_cmp_ge_u32 s82, 0x100
	s_cbranch_scc0 .Lprio_skip_19
	s_setprio 1
.Lprio_skip_19:
	s_cmp_lg_u32 s98, 0
	s_and_b64 vcc, exec, s[62:63]
	v_mbcnt_lo_u32_b32 v0, s2, 0
	v_mbcnt_hi_u32_b32 v0, s2, v0
	s_nop 0
	v_or_b32_e32 v8, s84, v0
	s_nop 0
	v_readfirstlane_b32 s24, v8
	s_cbranch_vccnz .LBB0_1538
	s_lshr_b32 s2, s87, 29
	s_add_i32 s2, s86, s2
	s_ashr_i32 s3, s2, 3
	s_and_b32 s2, s2, -8
	s_sub_i32 s2, s86, s2
	s_cmp_lt_i32 s2, 0
	s_movk_i32 s16, 0x161
	s_cselect_b32 s16, s16, 0x160
	s_mul_i32 s2, s16, s2
	s_add_i32 s2, s2, s3
	s_mul_hi_i32 s3, s2, 0x2e8ba2e9
	s_lshr_b32 s16, s3, 31
	s_ashr_i32 s3, s3, 5
	s_add_i32 s3, s3, s16
	s_lshl_b32 s16, s3, 3
	s_mulk_i32 s3, 0xb0
	s_sub_i32 s2, s2, s3
	s_sext_i32_i16 s3, s2
	s_bfe_u32 s3, s3, 0x3001c
	s_add_i32 s3, s2, s3
	s_sext_i32_i16 s17, s3
	s_and_b32 s3, s3, 0xfff8
	s_sub_i32 s2, s2, s3
	s_sext_i32_i16 s2, s2
	s_add_i32 s38, s16, s2
	s_ashr_i32 s40, s17, 3

; #define PG8_STAGE(bufoff, gbase, voff) do { _Pragma("unroll") for (int _i = 0; _i < 2; ++_i) \
;         __builtin_amdgcn_global_load_lds((const unsigned*)((const char*)(gbase) + (voff)[_i]), (PG8_LAS unsigned*)(lds + (bufoff) + ldsw + _i * 8192), 16, 0, 0); } while (0)
; #define PG8_LDA(dst, b, h) do { _Pragma("unroll") for (int m = 0; m < 4; ++m) _Pragma("unroll") for (int k = 0; k < 2; ++k) dst[m][k] = *(const PG8_LAS bf16x8*)(lds + PG8_SA(b, h) + aoff + m * 2048 + k * 1024); } while (0)
; #define PG8_WAIT_V(n) asm volatile("s_waitcnt vmcnt(" #n ")" ::: "memory")
; #define PG8_WAIT_L(n) asm volatile("s_waitcnt lgkmcnt(" #n ")" ::: "memory")
; #define PG8_BAR __builtin_amdgcn_s_barrier()
; template <class Epi, class Sched, bool ALIGN_EPI = false, bool SP2 = false>
; __device__ __forceinline__ void gemm_phase(PG8_LAS unsigned char* lds, const Gemm g, const Sched& S, const Epi& E, const int tid_arg) {
;     ...
;         for (int t = 0; t < nt; t += 2) {
;             const bool last = (t == nt - 2);
;             const char* a1 = cA + (size_t)(t + 1) * kstep;
;             const char* a2 = last ? nA : cA + (size_t)(t + 2) * kstep; const char* b2 = last ? nB : cB + (size_t)(t + 2) * kstep;
;             const char* a3 = a2 + kstep; const char* b3 = b2 + kstep;
;             if (last && has_next) S.a_ready(nxt);
;             if constexpr (SP2) {
;             PG8_LDB(B0, 0, 0); PG8_LDB(B1, 0, 1); PG8_SCHED; PG8_LDA(At, 0, 0); PG8_STAGE(PG8_SA(1, 1), a1 + hstep, voffA);
;             PG8_WAIT_V(8); PG8_WAIT_L(0); PG8_BAR; PG8_MMA(0, 0, At, B0); PG8_MMA(0, 1, At, B1); PG8_BAR; PG8_SCHED;
;             PG8_LDA(At, 0, 1); PG8_STAGE(PG8_SB(0, 0), b2, voffB); PG8_STAGE(PG8_SB(0, 1), b2 + hstep, voffB); PG8_STAGE(PG8_SA(0, 0), a2, voffA);
;             PG8_WAIT_V(8); PG8_WAIT_L(0); PG8_BAR; PG8_MMA(1, 0, At, B0); PG8_MMA(1, 1, At, B1); PG8_BAR; PG8_SCHED;
;             PG8_LDB(B0, 1, 0); PG8_LDB(B1, 1, 1); PG8_SCHED; PG8_LDA(At, 1, 0); PG8_STAGE(PG8_SA(0, 1), a2 + hstep, voffA);
;             PG8_WAIT_V(8); PG8_WAIT_L(0); PG8_BAR; PG8_MMA(0, 0, At, B0); PG8_MMA(0, 1, At, B1); PG8_BAR; PG8_SCHED;
;             PG8_LDA(At, 1, 1); PG8_STAGE(PG8_SB(1, 0), b3, voffB); PG8_STAGE(PG8_SB(1, 1), b3 + hstep, voffB); PG8_STAGE(PG8_SA(1, 0), a3, voffA);
;             PG8_WAIT_V(8); PG8_WAIT_L(0); PG8_BAR; PG8_MMA(1, 0, At, B0); PG8_MMA(1, 1, At, B1); PG8_BAR; PG8_SCHED;
.LBB0_1547:
	ds_read_b128 v[72:75], v207
	ds_read_b128 v[100:103], v208
	ds_read_b128 v[136:139], v209
	ds_read_b128 v[140:143], v210
	ds_read_b128 v[144:147], v211
	ds_read_b128 v[148:151], v212
	ds_read_b128 v[152:155], v213
	ds_read_b128 v[156:159], v214
	s_add_u32 s6, s4, 0x100
	s_addc_u32 s7, s5, 0
	s_cmp_eq_u32 s78, 12
	s_cselect_b32 s11, s13, s7
	s_cselect_b32 s10, s31, s6
	s_cselect_b32 s1, s29, s75
	s_cselect_b32 s0, s42, s43
	s_mov_b32 m0, s71
	v_lshl_add_u64 v[184:185], s[4:5], 0, v[196:197]
	ds_read_b128 v[160:163], v206
	ds_read_b128 v[164:167], v206 offset:1024
	ds_read_b128 v[168:171], v206 offset:2048
	ds_read_b128 v[172:175], v206 offset:3072
	ds_read_b128 v[176:179], v206 offset:4096
	ds_read_b128 v[180:183], v206 offset:5120
	ds_read_b128 v[226:229], v206 offset:6144
	ds_read_b128 v[230:233], v206 offset:7168
	global_load_lds_dwordx4 v[184:185], off
	v_lshl_add_u64 v[184:185], s[4:5], 0, v[194:195]
	s_mov_b32 m0, s72
	s_nop 0
	global_load_lds_dwordx4 v[184:185], off
	s_waitcnt vmcnt(8)
	s_waitcnt lgkmcnt(0)
	s_barrier
	v_mfma_f32_16x16x32_bf16 v[132:135], v[72:75], v[160:163], v[132:135]
	v_mfma_f32_16x16x32_bf16 v[60:63], v[136:139], v[160:163], v[60:63]
	v_mfma_f32_16x16x32_bf16 v[124:127], v[72:75], v[168:171], v[124:127]
	v_mfma_f32_16x16x32_bf16 v[52:55], v[136:139], v[168:171], v[52:55]
	v_mfma_f32_16x16x32_bf16 v[116:119], v[72:75], v[176:179], v[116:119]
	v_mfma_f32_16x16x32_bf16 v[44:47], v[136:139], v[176:179], v[44:47]
	v_mfma_f32_16x16x32_bf16 v[108:111], v[72:75], v[226:229], v[108:111]
	v_mfma_f32_16x16x32_bf16 v[36:39], v[136:139], v[226:229], v[36:39]
	v_mfma_f32_16x16x32_bf16 v[132:135], v[100:103], v[164:167], v[132:135]
	v_mfma_f32_16x16x32_bf16 v[60:63], v[140:143], v[164:167], v[60:63]
	v_mfma_f32_16x16x32_bf16 v[124:127], v[100:103], v[172:175], v[124:127]
	v_mfma_f32_16x16x32_bf16 v[52:55], v[140:143], v[172:175], v[52:55]
	v_mfma_f32_16x16x32_bf16 v[116:119], v[100:103], v[180:183], v[116:119]
	v_mfma_f32_16x16x32_bf16 v[44:47], v[140:143], v[180:183], v[44:47]
	v_mfma_f32_16x16x32_bf16 v[108:111], v[100:103], v[230:233], v[108:111]
	v_mfma_f32_16x16x32_bf16 v[36:39], v[140:143], v[230:233], v[36:39]
	v_mfma_f32_16x16x32_bf16 v[128:131], v[144:147], v[160:163], v[128:131]
	v_mfma_f32_16x16x32_bf16 v[56:59], v[152:155], v[160:163], v[56:59]
	v_mfma_f32_16x16x32_bf16 v[120:123], v[144:147], v[168:171], v[120:123]
	v_mfma_f32_16x16x32_bf16 v[48:51], v[152:155], v[168:171], v[48:51]
	v_mfma_f32_16x16x32_bf16 v[112:115], v[144:147], v[176:179], v[112:115]
	v_mfma_f32_16x16x32_bf16 v[40:43], v[152:155], v[176:179], v[40:43]
	v_mfma_f32_16x16x32_bf16 v[104:107], v[144:147], v[226:229], v[104:107]
	v_mfma_f32_16x16x32_bf16 v[32:35], v[152:155], v[226:229], v[32:35]
	v_mfma_f32_16x16x32_bf16 v[128:131], v[148:151], v[164:167], v[128:131]
	v_mfma_f32_16x16x32_bf16 v[56:59], v[156:159], v[164:167], v[56:59]
	v_mfma_f32_16x16x32_bf16 v[120:123], v[148:151], v[172:175], v[120:123]
	v_mfma_f32_16x16x32_bf16 v[48:51], v[156:159], v[172:175], v[48:51]
	v_mfma_f32_16x16x32_bf16 v[112:115], v[148:151], v[180:183], v[112:115]
	v_mfma_f32_16x16x32_bf16 v[40:43], v[156:159], v[180:183], v[40:43]
	v_mfma_f32_16x16x32_bf16 v[104:107], v[148:151], v[230:233], v[104:107]
	v_mfma_f32_16x16x32_bf16 v[32:35], v[156:159], v[230:233], v[32:35]
	s_barrier
	s_mov_b32 m0, s39
	v_lshl_add_u64 v[184:185], s[0:1], 0, v[188:189]
	s_add_u32 s4, s0, 0x40000
	ds_read_b128 v[160:163], v206 offset:16384
	ds_read_b128 v[164:167], v206 offset:17408
	ds_read_b128 v[168:171], v206 offset:18432
	ds_read_b128 v[172:175], v206 offset:19456
	ds_read_b128 v[176:179], v206 offset:20480
	ds_read_b128 v[180:183], v206 offset:21504
	ds_read_b128 v[226:229], v206 offset:22528
	ds_read_b128 v[230:233], v206 offset:23552
	global_load_lds_dwordx4 v[184:185], off
	v_lshl_add_u64 v[202:203], s[0:1], 0, v[192:193]
	s_mov_b32 m0, s41
	s_addc_u32 s5, s1, 0
	global_load_lds_dwordx4 v[202:203], off
	v_lshl_add_u64 v[234:235], s[4:5], 0, v[188:189]
	s_mov_b32 m0, s47
	v_lshl_add_u64 v[236:237], s[10:11], 0, v[190:191]
	global_load_lds_dwordx4 v[234:235], off
	v_lshl_add_u64 v[234:235], s[4:5], 0, v[192:193]
	s_mov_b32 m0, s48
	s_nop 0
	global_load_lds_dwordx4 v[234:235], off
	v_lshl_add_u64 v[234:235], s[10:11], 0, v[186:187]
	s_mov_b32 m0, s46
	s_nop 0
	global_load_lds_dwordx4 v[234:235], off
	s_mov_b32 m0, s49
	s_nop 0
	global_load_lds_dwordx4 v[236:237], off
	s_waitcnt vmcnt(8)
	s_waitcnt lgkmcnt(0)
	s_barrier
	v_mfma_f32_16x16x32_bf16 v[96:99], v[72:75], v[160:163], v[96:99]
	v_mfma_f32_16x16x32_bf16 v[28:31], v[136:139], v[160:163], v[28:31]
	v_mfma_f32_16x16x32_bf16 v[88:91], v[72:75], v[168:171], v[88:91]
	v_mfma_f32_16x16x32_bf16 v[20:23], v[136:139], v[168:171], v[20:23]
	v_mfma_f32_16x16x32_bf16 v[80:83], v[72:75], v[176:179], v[80:83]
	v_mfma_f32_16x16x32_bf16 v[12:15], v[136:139], v[176:179], v[12:15]
	v_mfma_f32_16x16x32_bf16 v[68:71], v[72:75], v[226:229], v[68:71]
	v_mfma_f32_16x16x32_bf16 v[4:7], v[136:139], v[226:229], v[4:7]
	v_mfma_f32_16x16x32_bf16 v[96:99], v[100:103], v[164:167], v[96:99]
	v_mfma_f32_16x16x32_bf16 v[28:31], v[140:143], v[164:167], v[28:31]
	v_mfma_f32_16x16x32_bf16 v[88:91], v[100:103], v[172:175], v[88:91]
	v_mfma_f32_16x16x32_bf16 v[20:23], v[140:143], v[172:175], v[20:23]
	v_mfma_f32_16x16x32_bf16 v[80:83], v[100:103], v[180:183], v[80:83]
	v_mfma_f32_16x16x32_bf16 v[12:15], v[140:143], v[180:183], v[12:15]
	v_mfma_f32_16x16x32_bf16 v[68:71], v[100:103], v[230:233], v[68:71]
	v_mfma_f32_16x16x32_bf16 v[4:7], v[140:143], v[230:233], v[4:7]
	v_mfma_f32_16x16x32_bf16 v[24:27], v[152:155], v[160:163], v[24:27]
	v_mfma_f32_16x16x32_bf16 v[84:87], v[144:147], v[168:171], v[84:87]
	v_mfma_f32_16x16x32_bf16 v[16:19], v[152:155], v[168:171], v[16:19]
	v_mfma_f32_16x16x32_bf16 v[76:79], v[144:147], v[176:179], v[76:79]
	v_mfma_f32_16x16x32_bf16 v[8:11], v[152:155], v[176:179], v[8:11]
	v_mfma_f32_16x16x32_bf16 v[64:67], v[144:147], v[226:229], v[64:67]
	v_mfma_f32_16x16x32_bf16 v[0:3], v[152:155], v[226:229], v[0:3]
	v_mfma_f32_16x16x32_bf16 v[72:75], v[144:147], v[160:163], v[92:95]
	v_mfma_f32_16x16x32_bf16 v[24:27], v[156:159], v[164:167], v[24:27]
	v_mfma_f32_16x16x32_bf16 v[84:87], v[148:151], v[172:175], v[84:87]
	v_mfma_f32_16x16x32_bf16 v[16:19], v[156:159], v[172:175], v[16:19]
	v_mfma_f32_16x16x32_bf16 v[76:79], v[148:151], v[180:183], v[76:79]
	v_mfma_f32_16x16x32_bf16 v[8:11], v[156:159], v[180:183], v[8:11]
	v_mfma_f32_16x16x32_bf16 v[64:67], v[148:151], v[230:233], v[64:67]
	v_mfma_f32_16x16x32_bf16 v[0:3], v[156:159], v[230:233], v[0:3]
	v_mfma_f32_16x16x32_bf16 v[72:75], v[148:151], v[164:167], v[72:75]
	s_barrier
; #define PG8_STAGE(bufoff, gbase, voff) do { _Pragma("unroll") for (int _i = 0; _i < 2; ++_i) \
;         __builtin_amdgcn_global_load_lds((const unsigned*)((const char*)(gbase) + (voff)[_i]), (PG8_LAS unsigned*)(lds + (bufoff) + ldsw + _i * 8192), 16, 0, 0); } while (0)
; #define PG8_LDA(dst, b, h) do { _Pragma("unroll") for (int m = 0; m < 4; ++m) _Pragma("unroll") for (int k = 0; k < 2; ++k) dst[m][k] = *(const PG8_LAS bf16x8*)(lds + PG8_SA(b, h) + aoff + m * 2048 + k * 1024); } while (0)
; #define PG8_WAIT_V(n) asm volatile("s_waitcnt vmcnt(" #n ")" ::: "memory")
; #define PG8_WAIT_L(n) asm volatile("s_waitcnt lgkmcnt(" #n ")" ::: "memory")
; #define PG8_BAR __builtin_amdgcn_s_barrier()
; template <class Epi, class Sched, bool ALIGN_EPI = false, bool SP2 = false>
; __device__ __forceinline__ void gemm_phase(PG8_LAS unsigned char* lds, const Gemm g, const Sched& S, const Epi& E, const int tid_arg) {
;     ...
;         for (int t = 0; t < nt; t += 2) {
;             const bool last = (t == nt - 2);
;             const char* a1 = cA + (size_t)(t + 1) * kstep;
;             const char* a2 = last ? nA : cA + (size_t)(t + 2) * kstep; const char* b2 = last ? nB : cB + (size_t)(t + 2) * kstep;
;             const char* a3 = a2 + kstep; const char* b3 = b2 + kstep;
;             if (last && has_next) S.a_ready(nxt);
;             if constexpr (SP2) {
;             PG8_LDB(B0, 0, 0); PG8_LDB(B1, 0, 1); PG8_SCHED; PG8_LDA(At, 0, 0); PG8_STAGE(PG8_SA(1, 1), a1 + hstep, voffA);
;             PG8_WAIT_V(8); PG8_WAIT_L(0); PG8_BAR; PG8_MMA(0, 0, At, B0); PG8_MMA(0, 1, At, B1); PG8_BAR; PG8_SCHED;
;             PG8_LDA(At, 0, 1); PG8_STAGE(PG8_SB(0, 0), b2, voffB); PG8_STAGE(PG8_SB(0, 1), b2 + hstep, voffB); PG8_STAGE(PG8_SA(0, 0), a2, voffA);
;             PG8_WAIT_V(8); PG8_WAIT_L(0); PG8_BAR; PG8_MMA(1, 0, At, B0); PG8_MMA(1, 1, At, B1); PG8_BAR; PG8_SCHED;
;             PG8_LDB(B0, 1, 0); PG8_LDB(B1, 1, 1); PG8_SCHED; PG8_LDA(At, 1, 0); PG8_STAGE(PG8_SA(0, 1), a2 + hstep, voffA);
;             PG8_WAIT_V(8); PG8_WAIT_L(0); PG8_BAR; PG8_MMA(0, 0, At, B0); PG8_MMA(0, 1, At, B1); PG8_BAR; PG8_SCHED;
;             PG8_LDA(At, 1, 1); PG8_STAGE(PG8_SB(1, 0), b3, voffB); PG8_STAGE(PG8_SB(1, 1), b3 + hstep, voffB); PG8_STAGE(PG8_SA(1, 0), a3, voffA);
;             PG8_WAIT_V(8); PG8_WAIT_L(0); PG8_BAR; PG8_MMA(1, 0, At, B0); PG8_MMA(1, 1, At, B1); PG8_BAR; PG8_SCHED;
	ds_read_b128 v[92:95], v215
	ds_read_b128 v[100:103], v216
	ds_read_b128 v[136:139], v217
	ds_read_b128 v[140:143], v218
	ds_read_b128 v[144:147], v219
	ds_read_b128 v[148:151], v220
	ds_read_b128 v[152:155], v221
	ds_read_b128 v[156:159], v222
	s_add_u32 s4, s10, 0x40000
	s_addc_u32 s5, s11, 0
	s_mov_b32 m0, s50
	v_lshl_add_u64 v[238:239], s[4:5], 0, v[186:187]
	ds_read_b128 v[160:163], v206 offset:32768
	ds_read_b128 v[164:167], v206 offset:33792
	ds_read_b128 v[168:171], v206 offset:34816
	ds_read_b128 v[172:175], v206 offset:35840
	ds_read_b128 v[176:179], v206 offset:36864
	ds_read_b128 v[180:183], v206 offset:37888
	ds_read_b128 v[226:229], v206 offset:38912
	ds_read_b128 v[230:233], v206 offset:39936
	global_load_lds_dwordx4 v[238:239], off
	v_lshl_add_u64 v[238:239], s[4:5], 0, v[190:191]
	s_mov_b32 m0, s51
	s_nop 0
	global_load_lds_dwordx4 v[238:239], off
	s_waitcnt vmcnt(8)
	s_waitcnt lgkmcnt(0)
	s_barrier
	v_mfma_f32_16x16x32_bf16 v[132:135], v[92:95], v[160:163], v[132:135]
	v_mfma_f32_16x16x32_bf16 v[60:63], v[136:139], v[160:163], v[60:63]
	v_mfma_f32_16x16x32_bf16 v[124:127], v[92:95], v[168:171], v[124:127]
	v_mfma_f32_16x16x32_bf16 v[52:55], v[136:139], v[168:171], v[52:55]
	v_mfma_f32_16x16x32_bf16 v[116:119], v[92:95], v[176:179], v[116:119]
	v_mfma_f32_16x16x32_bf16 v[44:47], v[136:139], v[176:179], v[44:47]
	v_mfma_f32_16x16x32_bf16 v[108:111], v[92:95], v[226:229], v[108:111]
	v_mfma_f32_16x16x32_bf16 v[36:39], v[136:139], v[226:229], v[36:39]
	v_mfma_f32_16x16x32_bf16 v[132:135], v[100:103], v[164:167], v[132:135]
	v_mfma_f32_16x16x32_bf16 v[60:63], v[140:143], v[164:167], v[60:63]
	v_mfma_f32_16x16x32_bf16 v[124:127], v[100:103], v[172:175], v[124:127]
	v_mfma_f32_16x16x32_bf16 v[52:55], v[140:143], v[172:175], v[52:55]
	v_mfma_f32_16x16x32_bf16 v[116:119], v[100:103], v[180:183], v[116:119]
	v_mfma_f32_16x16x32_bf16 v[44:47], v[140:143], v[180:183], v[44:47]
	v_mfma_f32_16x16x32_bf16 v[108:111], v[100:103], v[230:233], v[108:111]
	v_mfma_f32_16x16x32_bf16 v[36:39], v[140:143], v[230:233], v[36:39]
	v_mfma_f32_16x16x32_bf16 v[128:131], v[144:147], v[160:163], v[128:131]
	v_mfma_f32_16x16x32_bf16 v[56:59], v[152:155], v[160:163], v[56:59]
	v_mfma_f32_16x16x32_bf16 v[120:123], v[144:147], v[168:171], v[120:123]
	v_mfma_f32_16x16x32_bf16 v[48:51], v[152:155], v[168:171], v[48:51]
	v_mfma_f32_16x16x32_bf16 v[112:115], v[144:147], v[176:179], v[112:115]
	v_mfma_f32_16x16x32_bf16 v[40:43], v[152:155], v[176:179], v[40:43]
	v_mfma_f32_16x16x32_bf16 v[104:107], v[144:147], v[226:229], v[104:107]
	v_mfma_f32_16x16x32_bf16 v[32:35], v[152:155], v[226:229], v[32:35]
	v_mfma_f32_16x16x32_bf16 v[128:131], v[148:151], v[164:167], v[128:131]
	v_mfma_f32_16x16x32_bf16 v[56:59], v[156:159], v[164:167], v[56:59]
	v_mfma_f32_16x16x32_bf16 v[120:123], v[148:151], v[172:175], v[120:123]
	v_mfma_f32_16x16x32_bf16 v[48:51], v[156:159], v[172:175], v[48:51]
	v_mfma_f32_16x16x32_bf16 v[112:115], v[148:151], v[180:183], v[112:115]
	v_mfma_f32_16x16x32_bf16 v[40:43], v[156:159], v[180:183], v[40:43]
	v_mfma_f32_16x16x32_bf16 v[104:107], v[148:151], v[230:233], v[104:107]
	v_mfma_f32_16x16x32_bf16 v[32:35], v[156:159], v[230:233], v[32:35]
	s_barrier
	s_mov_b32 m0, s60
	v_lshl_add_u64 v[184:185], v[184:185], 0, s[20:21]
	s_add_u32 s0, s0, 0x40080
	ds_read_b128 v[160:163], v206 offset:49152
	ds_read_b128 v[164:167], v206 offset:50176
	ds_read_b128 v[168:171], v206 offset:51200
	ds_read_b128 v[172:175], v206 offset:52224
	ds_read_b128 v[176:179], v206 offset:53248
	ds_read_b128 v[180:183], v206 offset:54272
	ds_read_b128 v[226:229], v206 offset:55296
	ds_read_b128 v[230:233], v206 offset:56320
	global_load_lds_dwordx4 v[184:185], off
	v_lshl_add_u64 v[184:185], v[202:203], 0, s[20:21]
	s_mov_b32 m0, s61
	s_addc_u32 s1, s1, 0
	global_load_lds_dwordx4 v[184:185], off
	v_lshl_add_u64 v[184:185], s[0:1], 0, v[188:189]
	s_mov_b32 m0, s64
	s_nop 0
	global_load_lds_dwordx4 v[184:185], off
	v_lshl_add_u64 v[184:185], s[0:1], 0, v[192:193]
	s_mov_b32 m0, s65
	s_nop 0
	global_load_lds_dwordx4 v[184:185], off
	v_lshl_add_u64 v[184:185], v[234:235], 0, s[20:21]
	s_mov_b32 m0, s62
	s_nop 0
	global_load_lds_dwordx4 v[184:185], off
	v_lshl_add_u64 v[184:185], v[236:237], 0, s[20:21]
	s_mov_b32 m0, s63
	s_nop 0
	global_load_lds_dwordx4 v[184:185], off
	s_waitcnt vmcnt(8)
	s_waitcnt lgkmcnt(0)
	s_barrier
	v_mfma_f32_16x16x32_bf16 v[96:99], v[92:95], v[160:163], v[96:99]
	v_mfma_f32_16x16x32_bf16 v[28:31], v[136:139], v[160:163], v[28:31]
	v_mfma_f32_16x16x32_bf16 v[88:91], v[92:95], v[168:171], v[88:91]
	v_mfma_f32_16x16x32_bf16 v[20:23], v[136:139], v[168:171], v[20:23]
	v_mfma_f32_16x16x32_bf16 v[80:83], v[92:95], v[176:179], v[80:83]
	v_mfma_f32_16x16x32_bf16 v[12:15], v[136:139], v[176:179], v[12:15]
	v_mfma_f32_16x16x32_bf16 v[68:71], v[92:95], v[226:229], v[68:71]
	v_mfma_f32_16x16x32_bf16 v[4:7], v[136:139], v[226:229], v[4:7]
	v_mfma_f32_16x16x32_bf16 v[96:99], v[100:103], v[164:167], v[96:99]
	v_mfma_f32_16x16x32_bf16 v[28:31], v[140:143], v[164:167], v[28:31]
	v_mfma_f32_16x16x32_bf16 v[88:91], v[100:103], v[172:175], v[88:91]
	v_mfma_f32_16x16x32_bf16 v[20:23], v[140:143], v[172:175], v[20:23]
	v_mfma_f32_16x16x32_bf16 v[80:83], v[100:103], v[180:183], v[80:83]
	v_mfma_f32_16x16x32_bf16 v[12:15], v[140:143], v[180:183], v[12:15]
	v_mfma_f32_16x16x32_bf16 v[68:71], v[100:103], v[230:233], v[68:71]
	v_mfma_f32_16x16x32_bf16 v[4:7], v[140:143], v[230:233], v[4:7]
	v_mfma_f32_16x16x32_bf16 v[72:75], v[144:147], v[160:163], v[72:75]
	v_mfma_f32_16x16x32_bf16 v[92:95], v[148:151], v[164:167], v[72:75]
	v_mfma_f32_16x16x32_bf16 v[72:75], v[144:147], v[168:171], v[84:87]
	v_mfma_f32_16x16x32_bf16 v[24:27], v[152:155], v[160:163], v[24:27]
	v_mfma_f32_16x16x32_bf16 v[84:87], v[148:151], v[172:175], v[72:75]
	v_mfma_f32_16x16x32_bf16 v[16:19], v[152:155], v[168:171], v[16:19]
	v_mfma_f32_16x16x32_bf16 v[72:75], v[144:147], v[176:179], v[76:79]
	v_mfma_f32_16x16x32_bf16 v[8:11], v[152:155], v[176:179], v[8:11]
	v_mfma_f32_16x16x32_bf16 v[64:67], v[144:147], v[226:229], v[64:67]
	v_mfma_f32_16x16x32_bf16 v[0:3], v[152:155], v[226:229], v[0:3]
	v_mfma_f32_16x16x32_bf16 v[24:27], v[156:159], v[164:167], v[24:27]
	v_mfma_f32_16x16x32_bf16 v[16:19], v[156:159], v[172:175], v[16:19]
	v_mfma_f32_16x16x32_bf16 v[76:79], v[148:151], v[180:183], v[72:75]
	v_mfma_f32_16x16x32_bf16 v[8:11], v[156:159], v[180:183], v[8:11]
	v_mfma_f32_16x16x32_bf16 v[64:67], v[148:151], v[230:233], v[64:67]
	v_mfma_f32_16x16x32_bf16 v[0:3], v[156:159], v[230:233], v[0:3]
	s_barrier
	s_add_i32 s78, s78, 2
	s_add_u32 s43, s43, 0x100
	s_addc_u32 s75, s75, 0
	s_cmp_gt_u32 s78, 13
	s_mov_b64 s[4:5], s[6:7]
	s_cbranch_scc0 .LBB0_1547
	s_and_b64 vcc, exec, s[22:23]
	s_cbranch_vccz .LBB0_1550
	s_barrier

; #define PG8_WAIT_V(n) asm volatile("s_waitcnt vmcnt(" #n ")" ::: "memory")
; #define PG8_BAR __builtin_amdgcn_s_barrier()
; __device__ __forceinline__ void xcd_barrier(const XcdBarrier& b, const bool xb_is_leader) {
;     asm volatile("s_waitcnt vmcnt(0)" ::: "memory");
;     __syncthreads();
;     if (xb_is_leader) {
;         unsigned* bar = b.bar;
;         __builtin_amdgcn_s_waitcnt(0);
;         unsigned nloc = b.st[0], nx = b.st[1];
;         if (nloc == 0u) { xcd_barrier_complete(bar, b.x, nloc, nx); b.st[0] = nloc; b.st[1] = nx; }
; template <class Epi, class Sched, bool ALIGN_EPI = false, bool SP2 = false>
; __device__ __forceinline__ void gemm_phase(PG8_LAS unsigned char* lds, const Gemm g, const Sched& S, const Epi& E, const int tid_arg) {
;     ...
;     PG8_WAIT_V(0);
;     if constexpr (!ALIGN_EPI) { if (wr == 0) PG8_BAR; }
;     PG8_BAR;
.LBB0_1593:
	s_mov_b32 s0, -1
	s_nop 0
	v_mbcnt_lo_u32_b32 v0, s0, 0
	v_mbcnt_hi_u32_b32 v0, s0, v0
	s_setprio 0
	s_waitcnt vmcnt(0)
	s_waitcnt vmcnt(0) lgkmcnt(0)
	v_or_b32_e32 v0, s84, v0
	v_cmp_eq_u32_e32 vcc, 0, v0
	s_barrier
	s_and_saveexec_b64 s[4:5], vcc
	s_cbranch_execz .LBB0_1645
	v_mov_b32_e32 v0, 0x22000
	s_waitcnt vmcnt(0) expcnt(0) lgkmcnt(0)
	ds_read_b32 v2, v0
	v_mov_b32_e32 v0, 0x22004
	ds_read_b32 v0, v0
	s_waitcnt lgkmcnt(1)
	v_cmp_ne_u32_e32 vcc, 0, v2
	s_cbranch_vccnz .LBB0_1609
	v_readlane_b32 s0, v251, 0
	v_readlane_b32 s1, v251, 1
	v_readlane_b32 s2, v251, 2
	s_mul_i32 s2, s1, s2
	s_mul_i32 s2, s2, s0
	s_add_u32 s0, s76, 0x1000
	s_addc_u32 s1, s77, 0
	s_add_u32 s6, s76, 0x1100
	s_addc_u32 s7, s77, 0
	s_add_u32 s8, s76, 0x1200
	s_addc_u32 s9, s77, 0
	s_add_u32 s10, s76, 0x1300
	s_addc_u32 s11, s77, 0
	s_mov_b32 s3, 1
	v_mov_b32_e32 v16, 0
	s_branch .LBB0_1597

; #define AIN(i) (kargs()->in[i])
; #define AWS (kargs()->ws)
; #define K_TID ((wave_s << 6) | lane_fresh())
; __device__ __forceinline__ void fix_rows(bf16_t* A, const float* edge, const float* cw, const float* cb, int pm, int tid) {
;     const bool hasprev = (pm & 15) != 0;
; #pragma unroll
;     for (int it_ = 0; it_ < 6; ++it_) {
;         const int ch = tid + 512 * it_; if (ch >= DFF) break;
;         const int pn = ch >> 7, ci = ch & 127;
;         const float* E = edge + (size_t)(pm * 22 + pn) * 1024;
;         const float* P = hasprev ? edge + (size_t)((pm - 1) * 22 + pn) * 1024 : E;
;         float c0[2], c1[2];
; #pragma unroll
;         for (int gv = 0; gv < 2; ++gv) {
;             const int col = gv * 128 + ci, cc = gv * DFF + ch;
;             const float u0 = E[col], u1 = E[256 + col], p254 = hasprev ? P[512 + col] : 0.f, p255 = hasprev ? P[768 + col] : 0.f;
;             const float w0 = cw[cc], w1 = cw[UPN + cc], w2 = cw[2 * UPN + cc], bb = cb[cc];
; __global__ void __launch_bounds__(512, 2) fwd_megakernel(Args a) {
;     ...
;             pg8::Gemm g{P_Zb, (const bf16_t*)(AWS + WS_WDN + l * SZ_WDN), T, DM, DFF}; pg8::StaticOrder S; S.init(T, DM, G, bx);
;             pg8::Unit u;
;             int tid_l = K_TID; asm volatile("" : "+v"(tid_l));
;             for (int i = 0; S.next(i, u); ++i) fix_rows(P_Zb, P_EDGE, AIN(12) + (size_t)l * 3 * UPN, AIN(13) + l * UPN, u.pm, tid_l);
.Lprio_skip_20:
	s_cmp_lg_u32 s98, 0
	s_load_dwordx2 s[4:5], s[0:1], 0x98
	s_mov_b64 s[0:1], s[46:47]
	s_load_dwordx2 s[22:23], s[0:1], 0x98
	s_mov_b32 s0, -1
	v_mov_b32_e32 v1, 0
	v_mbcnt_lo_u32_b32 v0, s0, 0
	v_mbcnt_hi_u32_b32 v0, s0, v0
	s_movk_i32 s0, 0xb00
	v_or_b32_e32 v8, s84, v0
	v_mov_b64_e32 v[4:5], 0x1ff
	v_cmp_gt_i32_e64 s[6:7], s0, v8
	v_add_u32_e32 v2, 0x200, v8
	s_movk_i32 s0, 0x900
	v_cmp_gt_i32_e64 s[8:9], s0, v8
	v_ashrrev_i32_e32 v23, 7, v2
	v_add_u32_e32 v2, 0x400, v8
	s_movk_i32 s0, 0x700
	v_cmp_gt_i32_e64 s[10:11], s0, v8
	v_ashrrev_i32_e32 v24, 7, v2
	v_add_u32_e32 v2, 0x600, v8
	s_movk_i32 s0, 0x500
	v_cmp_gt_i32_e64 s[12:13], s0, v8
	v_ashrrev_i32_e32 v25, 7, v2
	v_add_u32_e32 v2, 0x800, v8
	s_movk_i32 s0, 0x300
	v_and_b32_e32 v0, 0x7f, v8
	v_ashrrev_i32_e32 v9, 31, v8
	v_cmp_gt_i32_e64 s[14:15], s0, v8
	v_ashrrev_i32_e32 v26, 7, v2
	v_add_u32_e32 v2, 0xa00, v8
	s_movk_i32 s0, 0x100
	v_ashrrev_i32_e32 v22, 7, v8
	v_cmp_gt_i32_e64 s[16:17], s0, v8
	v_ashrrev_i32_e32 v27, 7, v2
	v_mov_b64_e32 v[2:3], 0x200
	v_lshlrev_b64 v[6:7], 2, v[8:9]
	s_mov_b64 s[24:25], 0x10800
	s_mov_b32 s2, 0x10000
	s_mov_b64 s[26:27], 0x5800
	s_movk_i32 s3, 0x2000
	s_mov_b32 s33, 0x8000
	s_mov_b32 s40, 0xd000
	v_lshlrev_b64 v[8:9], 1, v[8:9]
	v_lshlrev_b32_e32 v0, 2, v0
	s_mov_b64 s[28:29], s[86:87]
	s_branch .LBB0_1649

; #define PG8_STAGE(bufoff, gbase, voff) do { _Pragma("unroll") for (int _i = 0; _i < 2; ++_i) \
;         __builtin_amdgcn_global_load_lds((const unsigned*)((const char*)(gbase) + (voff)[_i]), (PG8_LAS unsigned*)(lds + (bufoff) + ldsw + _i * 8192), 16, 0, 0); } while (0)
; #define PG8_LDA(dst, b, h) do { _Pragma("unroll") for (int m = 0; m < 4; ++m) _Pragma("unroll") for (int k = 0; k < 2; ++k) dst[m][k] = *(const PG8_LAS bf16x8*)(lds + PG8_SA(b, h) + aoff + m * 2048 + k * 1024); } while (0)
; #define PG8_WAIT_V(n) asm volatile("s_waitcnt vmcnt(" #n ")" ::: "memory")
; #define PG8_WAIT_L(n) asm volatile("s_waitcnt lgkmcnt(" #n ")" ::: "memory")
; #define PG8_BAR __builtin_amdgcn_s_barrier()
; template <class Epi, class Sched, bool ALIGN_EPI = false, bool SP2 = false>
; __device__ __forceinline__ void gemm_phase(PG8_LAS unsigned char* lds, const Gemm g, const Sched& S, const Epi& E, const int tid_arg) {
;     ...
;         for (int t = 0; t < nt; t += 2) {
;             const bool last = (t == nt - 2);
;             const char* a1 = cA + (size_t)(t + 1) * kstep;
;             const char* a2 = last ? nA : cA + (size_t)(t + 2) * kstep; const char* b2 = last ? nB : cB + (size_t)(t + 2) * kstep;
;             const char* a3 = a2 + kstep; const char* b3 = b2 + kstep;
;             if (last && has_next) S.a_ready(nxt);
;             if constexpr (SP2) {
;             PG8_LDB(B0, 0, 0); PG8_LDB(B1, 0, 1); PG8_SCHED; PG8_LDA(At, 0, 0); PG8_STAGE(PG8_SA(1, 1), a1 + hstep, voffA);
;             PG8_WAIT_V(8); PG8_WAIT_L(0); PG8_BAR; PG8_MMA(0, 0, At, B0); PG8_MMA(0, 1, At, B1); PG8_BAR; PG8_SCHED;
;             PG8_LDA(At, 0, 1); PG8_STAGE(PG8_SB(0, 0), b2, voffB); PG8_STAGE(PG8_SB(0, 1), b2 + hstep, voffB); PG8_STAGE(PG8_SA(0, 0), a2, voffA);
;             PG8_WAIT_V(8); PG8_WAIT_L(0); PG8_BAR; PG8_MMA(1, 0, At, B0); PG8_MMA(1, 1, At, B1); PG8_BAR; PG8_SCHED;
;             PG8_LDB(B0, 1, 0); PG8_LDB(B1, 1, 1); PG8_SCHED; PG8_LDA(At, 1, 0); PG8_STAGE(PG8_SA(0, 1), a2 + hstep, voffA);
;             PG8_WAIT_V(8); PG8_WAIT_L(0); PG8_BAR; PG8_MMA(0, 0, At, B0); PG8_MMA(0, 1, At, B1); PG8_BAR; PG8_SCHED;
;             PG8_LDA(At, 1, 1); PG8_STAGE(PG8_SB(1, 0), b3, voffB); PG8_STAGE(PG8_SB(1, 1), b3 + hstep, voffB); PG8_STAGE(PG8_SA(1, 0), a3, voffA);
;             PG8_WAIT_V(8); PG8_WAIT_L(0); PG8_BAR; PG8_MMA(1, 0, At, B0); PG8_MMA(1, 1, At, B1); PG8_BAR; PG8_SCHED;
.LBB0_1733:
	ds_read_b128 v[144:147], v151
	ds_read_b128 v[168:171], v152
	ds_read_b128 v[172:175], v153
	ds_read_b128 v[176:179], v154
	ds_read_b128 v[180:183], v155
	ds_read_b128 v[184:187], v156
	ds_read_b128 v[188:191], v157
	ds_read_b128 v[192:195], v158
	s_add_u32 s22, s4, 0x100
	s_addc_u32 s23, s5, 0
	s_cmp_eq_u32 s57, 40
	s_cselect_b32 s25, s9, s23
	s_cselect_b32 s24, s8, s22
	s_cselect_b32 s1, s21, s56
	s_cselect_b32 s0, s20, s55
	s_mov_b32 m0, s48
	v_lshl_add_u64 v[228:229], s[4:5], 0, v[138:139]
	ds_read_b128 v[196:199], v150
	ds_read_b128 v[200:203], v150 offset:1024
	ds_read_b128 v[204:207], v150 offset:2048
	ds_read_b128 v[208:211], v150 offset:3072
	ds_read_b128 v[212:215], v150 offset:4096
	ds_read_b128 v[216:219], v150 offset:5120
	ds_read_b128 v[220:223], v150 offset:6144
	ds_read_b128 v[224:227], v150 offset:7168
	global_load_lds_dwordx4 v[228:229], off
	v_lshl_add_u64 v[228:229], s[4:5], 0, v[136:137]
	s_mov_b32 m0, s49
	s_nop 0
	global_load_lds_dwordx4 v[228:229], off
	s_waitcnt vmcnt(8)
	s_waitcnt lgkmcnt(0)
	s_barrier
	v_mfma_f32_16x16x32_bf16 v[124:127], v[144:147], v[196:199], v[124:127]
	v_mfma_f32_16x16x32_bf16 v[120:123], v[172:175], v[196:199], v[120:123]
	v_mfma_f32_16x16x32_bf16 v[108:111], v[144:147], v[204:207], v[108:111]
	v_mfma_f32_16x16x32_bf16 v[104:107], v[172:175], v[204:207], v[104:107]
	v_mfma_f32_16x16x32_bf16 v[92:95], v[144:147], v[212:215], v[92:95]
	v_mfma_f32_16x16x32_bf16 v[88:91], v[172:175], v[212:215], v[88:91]
	v_mfma_f32_16x16x32_bf16 v[76:79], v[144:147], v[220:223], v[76:79]
	v_mfma_f32_16x16x32_bf16 v[72:75], v[172:175], v[220:223], v[72:75]
	v_mfma_f32_16x16x32_bf16 v[124:127], v[168:171], v[200:203], v[124:127]
	v_mfma_f32_16x16x32_bf16 v[120:123], v[176:179], v[200:203], v[120:123]
	v_mfma_f32_16x16x32_bf16 v[108:111], v[168:171], v[208:211], v[108:111]
	v_mfma_f32_16x16x32_bf16 v[104:107], v[176:179], v[208:211], v[104:107]
	v_mfma_f32_16x16x32_bf16 v[92:95], v[168:171], v[216:219], v[92:95]
	v_mfma_f32_16x16x32_bf16 v[88:91], v[176:179], v[216:219], v[88:91]
	v_mfma_f32_16x16x32_bf16 v[76:79], v[168:171], v[224:227], v[76:79]
	v_mfma_f32_16x16x32_bf16 v[72:75], v[176:179], v[224:227], v[72:75]
	v_mfma_f32_16x16x32_bf16 v[116:119], v[180:183], v[196:199], v[116:119]
	v_mfma_f32_16x16x32_bf16 v[112:115], v[188:191], v[196:199], v[112:115]
	v_mfma_f32_16x16x32_bf16 v[100:103], v[180:183], v[204:207], v[100:103]
	v_mfma_f32_16x16x32_bf16 v[96:99], v[188:191], v[204:207], v[96:99]
	v_mfma_f32_16x16x32_bf16 v[84:87], v[180:183], v[212:215], v[84:87]
	v_mfma_f32_16x16x32_bf16 v[80:83], v[188:191], v[212:215], v[80:83]
	v_mfma_f32_16x16x32_bf16 v[68:71], v[180:183], v[220:223], v[68:71]
	v_mfma_f32_16x16x32_bf16 v[64:67], v[188:191], v[220:223], v[64:67]
	v_mfma_f32_16x16x32_bf16 v[116:119], v[184:187], v[200:203], v[116:119]
	v_mfma_f32_16x16x32_bf16 v[112:115], v[192:195], v[200:203], v[112:115]
	v_mfma_f32_16x16x32_bf16 v[100:103], v[184:187], v[208:211], v[100:103]
	v_mfma_f32_16x16x32_bf16 v[96:99], v[192:195], v[208:211], v[96:99]
	v_mfma_f32_16x16x32_bf16 v[84:87], v[184:187], v[216:219], v[84:87]
	v_mfma_f32_16x16x32_bf16 v[80:83], v[192:195], v[216:219], v[80:83]
	v_mfma_f32_16x16x32_bf16 v[68:71], v[184:187], v[224:227], v[68:71]
	v_mfma_f32_16x16x32_bf16 v[64:67], v[192:195], v[224:227], v[64:67]
	s_barrier
	s_mov_b32 m0, s29
	v_lshl_add_u64 v[228:229], s[0:1], 0, v[130:131]
	s_add_u32 s4, s0, 0xb0000
	ds_read_b128 v[196:199], v150 offset:16384
	ds_read_b128 v[200:203], v150 offset:17408
	ds_read_b128 v[204:207], v150 offset:18432
	ds_read_b128 v[208:211], v150 offset:19456
	ds_read_b128 v[212:215], v150 offset:20480
	ds_read_b128 v[216:219], v150 offset:21504
	ds_read_b128 v[220:223], v150 offset:22528
	ds_read_b128 v[224:227], v150 offset:23552
	global_load_lds_dwordx4 v[228:229], off
	v_lshl_add_u64 v[230:231], s[0:1], 0, v[134:135]
	s_mov_b32 m0, s30
	s_addc_u32 s5, s1, 0
	global_load_lds_dwordx4 v[230:231], off
	v_lshl_add_u64 v[232:233], s[4:5], 0, v[130:131]
	s_mov_b32 m0, s31
	v_lshl_add_u64 v[234:235], s[24:25], 0, v[132:133]
	global_load_lds_dwordx4 v[232:233], off
	v_lshl_add_u64 v[232:233], s[4:5], 0, v[134:135]
	s_mov_b32 m0, s33
	s_nop 0
	global_load_lds_dwordx4 v[232:233], off
	v_lshl_add_u64 v[232:233], s[24:25], 0, v[128:129]
	s_mov_b32 m0, s28
	s_nop 0
	global_load_lds_dwordx4 v[232:233], off
	s_mov_b32 m0, s34
	s_nop 0
	global_load_lds_dwordx4 v[234:235], off
	s_waitcnt vmcnt(8)
	s_waitcnt lgkmcnt(0)
	s_barrier
	v_mfma_f32_16x16x32_bf16 v[60:63], v[144:147], v[196:199], v[60:63]
	v_mfma_f32_16x16x32_bf16 v[56:59], v[172:175], v[196:199], v[56:59]
	v_mfma_f32_16x16x32_bf16 v[44:47], v[144:147], v[204:207], v[44:47]
	v_mfma_f32_16x16x32_bf16 v[40:43], v[172:175], v[204:207], v[40:43]
	v_mfma_f32_16x16x32_bf16 v[28:31], v[144:147], v[212:215], v[28:31]
	v_mfma_f32_16x16x32_bf16 v[24:27], v[172:175], v[212:215], v[24:27]
	v_mfma_f32_16x16x32_bf16 v[12:15], v[144:147], v[220:223], v[12:15]
	v_mfma_f32_16x16x32_bf16 v[8:11], v[172:175], v[220:223], v[8:11]
	v_mfma_f32_16x16x32_bf16 v[60:63], v[168:171], v[200:203], v[60:63]
	v_mfma_f32_16x16x32_bf16 v[56:59], v[176:179], v[200:203], v[56:59]
	v_mfma_f32_16x16x32_bf16 v[44:47], v[168:171], v[208:211], v[44:47]
	v_mfma_f32_16x16x32_bf16 v[40:43], v[176:179], v[208:211], v[40:43]
	v_mfma_f32_16x16x32_bf16 v[28:31], v[168:171], v[216:219], v[28:31]
	v_mfma_f32_16x16x32_bf16 v[24:27], v[176:179], v[216:219], v[24:27]
	v_mfma_f32_16x16x32_bf16 v[12:15], v[168:171], v[224:227], v[12:15]
	v_mfma_f32_16x16x32_bf16 v[8:11], v[176:179], v[224:227], v[8:11]
	v_mfma_f32_16x16x32_bf16 v[52:55], v[180:183], v[196:199], v[52:55]
	v_mfma_f32_16x16x32_bf16 v[48:51], v[188:191], v[196:199], v[48:51]
	v_mfma_f32_16x16x32_bf16 v[36:39], v[180:183], v[204:207], v[36:39]
	v_mfma_f32_16x16x32_bf16 v[32:35], v[188:191], v[204:207], v[32:35]
	v_mfma_f32_16x16x32_bf16 v[20:23], v[180:183], v[212:215], v[20:23]
	v_mfma_f32_16x16x32_bf16 v[16:19], v[188:191], v[212:215], v[16:19]
	v_mfma_f32_16x16x32_bf16 v[4:7], v[180:183], v[220:223], v[4:7]
	v_mfma_f32_16x16x32_bf16 v[0:3], v[188:191], v[220:223], v[0:3]
	v_mfma_f32_16x16x32_bf16 v[52:55], v[184:187], v[200:203], v[52:55]
	v_mfma_f32_16x16x32_bf16 v[48:51], v[192:195], v[200:203], v[48:51]
	v_mfma_f32_16x16x32_bf16 v[36:39], v[184:187], v[208:211], v[36:39]
	v_mfma_f32_16x16x32_bf16 v[32:35], v[192:195], v[208:211], v[32:35]
	v_mfma_f32_16x16x32_bf16 v[20:23], v[184:187], v[216:219], v[20:23]
	v_mfma_f32_16x16x32_bf16 v[16:19], v[192:195], v[216:219], v[16:19]
	v_mfma_f32_16x16x32_bf16 v[4:7], v[184:187], v[224:227], v[4:7]
	v_mfma_f32_16x16x32_bf16 v[0:3], v[192:195], v[224:227], v[0:3]
	s_barrier
; #define PG8_STAGE(bufoff, gbase, voff) do { _Pragma("unroll") for (int _i = 0; _i < 2; ++_i) \
;         __builtin_amdgcn_global_load_lds((const unsigned*)((const char*)(gbase) + (voff)[_i]), (PG8_LAS unsigned*)(lds + (bufoff) + ldsw + _i * 8192), 16, 0, 0); } while (0)
; #define PG8_LDA(dst, b, h) do { _Pragma("unroll") for (int m = 0; m < 4; ++m) _Pragma("unroll") for (int k = 0; k < 2; ++k) dst[m][k] = *(const PG8_LAS bf16x8*)(lds + PG8_SA(b, h) + aoff + m * 2048 + k * 1024); } while (0)
; #define PG8_WAIT_V(n) asm volatile("s_waitcnt vmcnt(" #n ")" ::: "memory")
; #define PG8_WAIT_L(n) asm volatile("s_waitcnt lgkmcnt(" #n ")" ::: "memory")
; #define PG8_BAR __builtin_amdgcn_s_barrier()
; template <class Epi, class Sched, bool ALIGN_EPI = false, bool SP2 = false>
; __device__ __forceinline__ void gemm_phase(PG8_LAS unsigned char* lds, const Gemm g, const Sched& S, const Epi& E, const int tid_arg) {
;     ...
;         for (int t = 0; t < nt; t += 2) {
;             const bool last = (t == nt - 2);
;             const char* a1 = cA + (size_t)(t + 1) * kstep;
;             const char* a2 = last ? nA : cA + (size_t)(t + 2) * kstep; const char* b2 = last ? nB : cB + (size_t)(t + 2) * kstep;
;             const char* a3 = a2 + kstep; const char* b3 = b2 + kstep;
;             if (last && has_next) S.a_ready(nxt);
;             if constexpr (SP2) {
;             PG8_LDB(B0, 0, 0); PG8_LDB(B1, 0, 1); PG8_SCHED; PG8_LDA(At, 0, 0); PG8_STAGE(PG8_SA(1, 1), a1 + hstep, voffA);
;             PG8_WAIT_V(8); PG8_WAIT_L(0); PG8_BAR; PG8_MMA(0, 0, At, B0); PG8_MMA(0, 1, At, B1); PG8_BAR; PG8_SCHED;
;             PG8_LDA(At, 0, 1); PG8_STAGE(PG8_SB(0, 0), b2, voffB); PG8_STAGE(PG8_SB(0, 1), b2 + hstep, voffB); PG8_STAGE(PG8_SA(0, 0), a2, voffA);
;             PG8_WAIT_V(8); PG8_WAIT_L(0); PG8_BAR; PG8_MMA(1, 0, At, B0); PG8_MMA(1, 1, At, B1); PG8_BAR; PG8_SCHED;
;             PG8_LDB(B0, 1, 0); PG8_LDB(B1, 1, 1); PG8_SCHED; PG8_LDA(At, 1, 0); PG8_STAGE(PG8_SA(0, 1), a2 + hstep, voffA);
;             PG8_WAIT_V(8); PG8_WAIT_L(0); PG8_BAR; PG8_MMA(0, 0, At, B0); PG8_MMA(0, 1, At, B1); PG8_BAR; PG8_SCHED;
;             PG8_LDA(At, 1, 1); PG8_STAGE(PG8_SB(1, 0), b3, voffB); PG8_STAGE(PG8_SB(1, 1), b3 + hstep, voffB); PG8_STAGE(PG8_SA(1, 0), a3, voffA);
;             PG8_WAIT_V(8); PG8_WAIT_L(0); PG8_BAR; PG8_MMA(1, 0, At, B0); PG8_MMA(1, 1, At, B1); PG8_BAR; PG8_SCHED;
	ds_read_b128 v[144:147], v159
	ds_read_b128 v[168:171], v160
	ds_read_b128 v[172:175], v161
	ds_read_b128 v[176:179], v162
	ds_read_b128 v[180:183], v163
	ds_read_b128 v[184:187], v164
	ds_read_b128 v[188:191], v165
	ds_read_b128 v[192:195], v166
	s_add_u32 s4, s24, 0xb0000
	s_addc_u32 s5, s25, 0
	s_mov_b32 m0, s35
	v_lshl_add_u64 v[236:237], s[4:5], 0, v[128:129]
	ds_read_b128 v[196:199], v150 offset:32768
	ds_read_b128 v[200:203], v150 offset:33792
	ds_read_b128 v[204:207], v150 offset:34816
	ds_read_b128 v[208:211], v150 offset:35840
	ds_read_b128 v[212:215], v150 offset:36864
	ds_read_b128 v[216:219], v150 offset:37888
	ds_read_b128 v[220:223], v150 offset:38912
	ds_read_b128 v[224:227], v150 offset:39936
	global_load_lds_dwordx4 v[236:237], off
	v_lshl_add_u64 v[236:237], s[4:5], 0, v[132:133]
	s_mov_b32 m0, s36
	s_nop 0
	global_load_lds_dwordx4 v[236:237], off
	s_waitcnt vmcnt(8)
	s_waitcnt lgkmcnt(0)
	s_barrier
	v_mfma_f32_16x16x32_bf16 v[124:127], v[144:147], v[196:199], v[124:127]
	v_mfma_f32_16x16x32_bf16 v[120:123], v[172:175], v[196:199], v[120:123]
	v_mfma_f32_16x16x32_bf16 v[108:111], v[144:147], v[204:207], v[108:111]
	v_mfma_f32_16x16x32_bf16 v[104:107], v[172:175], v[204:207], v[104:107]
	v_mfma_f32_16x16x32_bf16 v[92:95], v[144:147], v[212:215], v[92:95]
	v_mfma_f32_16x16x32_bf16 v[88:91], v[172:175], v[212:215], v[88:91]
	v_mfma_f32_16x16x32_bf16 v[76:79], v[144:147], v[220:223], v[76:79]
	v_mfma_f32_16x16x32_bf16 v[72:75], v[172:175], v[220:223], v[72:75]
	v_mfma_f32_16x16x32_bf16 v[124:127], v[168:171], v[200:203], v[124:127]
	v_mfma_f32_16x16x32_bf16 v[120:123], v[176:179], v[200:203], v[120:123]
	v_mfma_f32_16x16x32_bf16 v[108:111], v[168:171], v[208:211], v[108:111]
	v_mfma_f32_16x16x32_bf16 v[104:107], v[176:179], v[208:211], v[104:107]
	v_mfma_f32_16x16x32_bf16 v[92:95], v[168:171], v[216:219], v[92:95]
	v_mfma_f32_16x16x32_bf16 v[88:91], v[176:179], v[216:219], v[88:91]
	v_mfma_f32_16x16x32_bf16 v[76:79], v[168:171], v[224:227], v[76:79]
	v_mfma_f32_16x16x32_bf16 v[72:75], v[176:179], v[224:227], v[72:75]
	v_mfma_f32_16x16x32_bf16 v[116:119], v[180:183], v[196:199], v[116:119]
	v_mfma_f32_16x16x32_bf16 v[112:115], v[188:191], v[196:199], v[112:115]
	v_mfma_f32_16x16x32_bf16 v[100:103], v[180:183], v[204:207], v[100:103]
	v_mfma_f32_16x16x32_bf16 v[96:99], v[188:191], v[204:207], v[96:99]
	v_mfma_f32_16x16x32_bf16 v[84:87], v[180:183], v[212:215], v[84:87]
	v_mfma_f32_16x16x32_bf16 v[80:83], v[188:191], v[212:215], v[80:83]
	v_mfma_f32_16x16x32_bf16 v[68:71], v[180:183], v[220:223], v[68:71]
	v_mfma_f32_16x16x32_bf16 v[64:67], v[188:191], v[220:223], v[64:67]
	v_mfma_f32_16x16x32_bf16 v[116:119], v[184:187], v[200:203], v[116:119]
	v_mfma_f32_16x16x32_bf16 v[112:115], v[192:195], v[200:203], v[112:115]
	v_mfma_f32_16x16x32_bf16 v[100:103], v[184:187], v[208:211], v[100:103]
	v_mfma_f32_16x16x32_bf16 v[96:99], v[192:195], v[208:211], v[96:99]
	v_mfma_f32_16x16x32_bf16 v[84:87], v[184:187], v[216:219], v[84:87]
	v_mfma_f32_16x16x32_bf16 v[80:83], v[192:195], v[216:219], v[80:83]
	v_mfma_f32_16x16x32_bf16 v[68:71], v[184:187], v[224:227], v[68:71]
	v_mfma_f32_16x16x32_bf16 v[64:67], v[192:195], v[224:227], v[64:67]
	s_barrier
	s_mov_b32 m0, s40
	v_lshl_add_u64 v[228:229], v[228:229], 0, s[16:17]
	s_add_u32 s0, s0, 0xb0080
	ds_read_b128 v[196:199], v150 offset:49152
	ds_read_b128 v[200:203], v150 offset:50176
	ds_read_b128 v[204:207], v150 offset:51200
	ds_read_b128 v[208:211], v150 offset:52224
	ds_read_b128 v[212:215], v150 offset:53248
	ds_read_b128 v[216:219], v150 offset:54272
	ds_read_b128 v[220:223], v150 offset:55296
	ds_read_b128 v[224:227], v150 offset:56320
	global_load_lds_dwordx4 v[228:229], off
	v_lshl_add_u64 v[228:229], v[230:231], 0, s[16:17]
	s_mov_b32 m0, s41
	s_addc_u32 s1, s1, 0
	global_load_lds_dwordx4 v[228:229], off
	v_lshl_add_u64 v[228:229], s[0:1], 0, v[130:131]
	s_mov_b32 m0, s44
	s_nop 0
	global_load_lds_dwordx4 v[228:229], off
	v_lshl_add_u64 v[228:229], s[0:1], 0, v[134:135]
	s_mov_b32 m0, s45
	s_nop 0
	global_load_lds_dwordx4 v[228:229], off
	v_lshl_add_u64 v[228:229], v[232:233], 0, s[16:17]
	s_mov_b32 m0, s42
	s_nop 0
	global_load_lds_dwordx4 v[228:229], off
	v_lshl_add_u64 v[228:229], v[234:235], 0, s[16:17]
	s_mov_b32 m0, s43
	s_nop 0
	global_load_lds_dwordx4 v[228:229], off
	s_waitcnt vmcnt(8)
	s_waitcnt lgkmcnt(0)
	s_barrier
	v_mfma_f32_16x16x32_bf16 v[60:63], v[144:147], v[196:199], v[60:63]
	v_mfma_f32_16x16x32_bf16 v[56:59], v[172:175], v[196:199], v[56:59]
	v_mfma_f32_16x16x32_bf16 v[44:47], v[144:147], v[204:207], v[44:47]
	v_mfma_f32_16x16x32_bf16 v[40:43], v[172:175], v[204:207], v[40:43]
	v_mfma_f32_16x16x32_bf16 v[28:31], v[144:147], v[212:215], v[28:31]
	v_mfma_f32_16x16x32_bf16 v[24:27], v[172:175], v[212:215], v[24:27]
	v_mfma_f32_16x16x32_bf16 v[12:15], v[144:147], v[220:223], v[12:15]
	v_mfma_f32_16x16x32_bf16 v[8:11], v[172:175], v[220:223], v[8:11]
	v_mfma_f32_16x16x32_bf16 v[60:63], v[168:171], v[200:203], v[60:63]
	v_mfma_f32_16x16x32_bf16 v[56:59], v[176:179], v[200:203], v[56:59]
	v_mfma_f32_16x16x32_bf16 v[44:47], v[168:171], v[208:211], v[44:47]
	v_mfma_f32_16x16x32_bf16 v[40:43], v[176:179], v[208:211], v[40:43]
	v_mfma_f32_16x16x32_bf16 v[28:31], v[168:171], v[216:219], v[28:31]
	v_mfma_f32_16x16x32_bf16 v[24:27], v[176:179], v[216:219], v[24:27]
	v_mfma_f32_16x16x32_bf16 v[12:15], v[168:171], v[224:227], v[12:15]
	v_mfma_f32_16x16x32_bf16 v[8:11], v[176:179], v[224:227], v[8:11]
	v_mfma_f32_16x16x32_bf16 v[52:55], v[180:183], v[196:199], v[52:55]
	v_mfma_f32_16x16x32_bf16 v[48:51], v[188:191], v[196:199], v[48:51]
	v_mfma_f32_16x16x32_bf16 v[36:39], v[180:183], v[204:207], v[36:39]
	v_mfma_f32_16x16x32_bf16 v[32:35], v[188:191], v[204:207], v[32:35]
	v_mfma_f32_16x16x32_bf16 v[20:23], v[180:183], v[212:215], v[20:23]
	v_mfma_f32_16x16x32_bf16 v[16:19], v[188:191], v[212:215], v[16:19]
	v_mfma_f32_16x16x32_bf16 v[4:7], v[180:183], v[220:223], v[4:7]
	v_mfma_f32_16x16x32_bf16 v[0:3], v[188:191], v[220:223], v[0:3]
	v_mfma_f32_16x16x32_bf16 v[52:55], v[184:187], v[200:203], v[52:55]
	v_mfma_f32_16x16x32_bf16 v[48:51], v[192:195], v[200:203], v[48:51]
	v_mfma_f32_16x16x32_bf16 v[36:39], v[184:187], v[208:211], v[36:39]
	v_mfma_f32_16x16x32_bf16 v[32:35], v[192:195], v[208:211], v[32:35]
	v_mfma_f32_16x16x32_bf16 v[20:23], v[184:187], v[216:219], v[20:23]
	v_mfma_f32_16x16x32_bf16 v[16:19], v[192:195], v[216:219], v[16:19]
	v_mfma_f32_16x16x32_bf16 v[4:7], v[184:187], v[224:227], v[4:7]
	v_mfma_f32_16x16x32_bf16 v[0:3], v[192:195], v[224:227], v[0:3]
	s_barrier
	s_add_i32 s57, s57, 2
	s_add_u32 s55, s55, 0x100
	s_addc_u32 s56, s56, 0
	s_cmp_gt_u32 s57, 41
	s_mov_b64 s[4:5], s[22:23]
	s_cbranch_scc0 .LBB0_1733
	s_and_b64 vcc, exec, s[18:19]
	s_cbranch_vccz .LBB0_1736
	s_barrier

; #define PG8_WAIT_V(n) asm volatile("s_waitcnt vmcnt(" #n ")" ::: "memory")
; #define PG8_BAR __builtin_amdgcn_s_barrier()
; __device__ __forceinline__ void xcd_barrier(const XcdBarrier& b, const bool xb_is_leader) {
;     asm volatile("s_waitcnt vmcnt(0)" ::: "memory");
;     __syncthreads();
;     if (xb_is_leader) {
;         unsigned* bar = b.bar;
;         __builtin_amdgcn_s_waitcnt(0);
;         unsigned nloc = b.st[0], nx = b.st[1];
;         if (nloc == 0u) { xcd_barrier_complete(bar, b.x, nloc, nx); b.st[0] = nloc; b.st[1] = nx; }
; template <class Epi, class Sched, bool ALIGN_EPI = false, bool SP2 = false>
; __device__ __forceinline__ void gemm_phase(PG8_LAS unsigned char* lds, const Gemm g, const Sched& S, const Epi& E, const int tid_arg) {
;     ...
;     PG8_WAIT_V(0);
;     if constexpr (!ALIGN_EPI) { if (wr == 0) PG8_BAR; }
;     PG8_BAR;
.LBB0_1758:
	s_mov_b32 s0, -1
	s_nop 0
	v_mbcnt_lo_u32_b32 v0, s0, 0
	v_mbcnt_hi_u32_b32 v0, s0, v0
	s_setprio 0
	s_waitcnt vmcnt(0)
	s_waitcnt lgkmcnt(0)
	v_or_b32_e32 v0, s84, v0
	v_cmp_eq_u32_e32 vcc, 0, v0
	s_barrier
	s_and_saveexec_b64 s[4:5], vcc
	s_cbranch_execz .LBB0_1810
	v_mov_b32_e32 v0, 0x22000
	s_waitcnt vmcnt(0) expcnt(0) lgkmcnt(0)
	ds_read_b32 v2, v0
	v_mov_b32_e32 v0, 0x22004
	ds_read_b32 v0, v0
	s_waitcnt lgkmcnt(1)
	v_cmp_ne_u32_e32 vcc, 0, v2
	s_cbranch_vccnz .LBB0_1774
	v_readlane_b32 s0, v251, 0
	v_readlane_b32 s1, v251, 1
	v_readlane_b32 s2, v251, 2
	s_mul_i32 s2, s1, s2
	s_mul_i32 s2, s2, s0
	s_add_u32 s0, s76, 0x1000
	s_addc_u32 s1, s77, 0
	s_add_u32 s6, s76, 0x1100
	s_addc_u32 s7, s77, 0
	s_add_u32 s8, s76, 0x1200
	s_addc_u32 s9, s77, 0
	s_add_u32 s10, s76, 0x1300
	s_addc_u32 s11, s77, 0
	s_mov_b32 s3, 1
	v_mov_b32_e32 v16, 0
	s_branch .LBB0_1762

; #define AWS (kargs()->ws)
; #define K_TID ((wave_s << 6) | lane_fresh())
;     __host__ __device__ bool next(int i, Unit& u) const {
;         const long L = (long)i * G + c; if (L >= nwg) return false;
;         int wgid = (int)L; { const int q = nwg / NXCD, r = nwg % NXCD, xcd = wgid % NXCD, off = wgid / NXCD; wgid = (xcd < r ? xcd * (q + 1) : r * (q + 1) + (xcd - r) * q) + off; }
;         const int nig = WGM * nN, gid = wgid / nig, fm = gid * WGM, gsz = (nM - fm) < WGM ? (nM - fm) : WGM;
;         u.pm = fm + ((wgid % nig) % gsz); u.pn = (wgid % nig) / gsz; return true;
; __global__ void __launch_bounds__(512, 2) fwd_megakernel(Args a) {
;     ...
;         {
;             bf16_t* SG = P_Zb;
;             pg8::StaticOrder S; S.init(T, DM, G, bx);
;             { pg8::Gemm g{P_HB, (const bf16_t*)(AWS + WS_WGT + l * SZ_WGT), T, DM, DM}; pg8::EpiSig E{SG, P_RSQ + (size_t)(2 * l + 1) * T};
;               pg8::gemm_phase<pg8::EpiSig, pg8::StaticOrder, true, true>(lds, g, S, E, K_TID);
.Lprio_skip_21:
	s_cmp_lg_u32 s98, 0
	s_load_dwordx2 s[0:1], s[0:1], 0x98
	s_mov_b64 s[10:11], s[46:47]
	s_mov_b64 s[12:13], s[46:47]
	s_mov_b32 s3, -1
	s_waitcnt lgkmcnt(0)
	s_add_u32 s8, s0, 0x9804000
	s_addc_u32 s9, s1, 0
	s_mov_b64 s[0:1], s[46:47]
	s_mov_b32 s2, -1
	v_mbcnt_lo_u32_b32 v0, s3, 0
	v_mbcnt_hi_u32_b32 v0, s3, v0
	s_and_b64 vcc, exec, s[88:89]
	v_or_b32_e32 v8, s84, v0
	s_nop 0
	v_readfirstlane_b32 s18, v8
	s_cbranch_vccnz .LBB0_1834
	s_load_dwordx2 s[6:7], s[10:11], 0x98
	s_load_dwordx2 s[4:5], s[12:13], 0x98
	s_lshr_b32 s3, s87, 29
	s_add_i32 s3, s86, s3
	s_and_b32 s10, s3, -8
	s_sub_i32 s13, s86, s10
	s_cmp_gt_i32 s13, -1
	s_cbranch_scc0 .LBB0_1813
	s_lshl_b32 s12, s13, 6
	s_load_dwordx2 s[0:1], s[0:1], 0x98
	s_cbranch_execz .LBB0_1814
	s_branch .LBB0_1815

; #define PG8_STAGE(bufoff, gbase, voff) do { _Pragma("unroll") for (int _i = 0; _i < 2; ++_i) \
;         __builtin_amdgcn_global_load_lds((const unsigned*)((const char*)(gbase) + (voff)[_i]), (PG8_LAS unsigned*)(lds + (bufoff) + ldsw + _i * 8192), 16, 0, 0); } while (0)
; #define PG8_LDA(dst, b, h) do { _Pragma("unroll") for (int m = 0; m < 4; ++m) _Pragma("unroll") for (int k = 0; k < 2; ++k) dst[m][k] = *(const PG8_LAS bf16x8*)(lds + PG8_SA(b, h) + aoff + m * 2048 + k * 1024); } while (0)
; #define PG8_WAIT_V(n) asm volatile("s_waitcnt vmcnt(" #n ")" ::: "memory")
; #define PG8_WAIT_L(n) asm volatile("s_waitcnt lgkmcnt(" #n ")" ::: "memory")
; #define PG8_BAR __builtin_amdgcn_s_barrier()
; template <class Epi, class Sched, bool ALIGN_EPI = false, bool SP2 = false>
; __device__ __forceinline__ void gemm_phase(PG8_LAS unsigned char* lds, const Gemm g, const Sched& S, const Epi& E, const int tid_arg) {
;     ...
;         for (int t = 0; t < nt; t += 2) {
;             const bool last = (t == nt - 2);
;             const char* a1 = cA + (size_t)(t + 1) * kstep;
;             const char* a2 = last ? nA : cA + (size_t)(t + 2) * kstep; const char* b2 = last ? nB : cB + (size_t)(t + 2) * kstep;
;             const char* a3 = a2 + kstep; const char* b3 = b2 + kstep;
;             if (last && has_next) S.a_ready(nxt);
;             if constexpr (SP2) {
;             PG8_LDB(B0, 0, 0); PG8_LDB(B1, 0, 1); PG8_SCHED; PG8_LDA(At, 0, 0); PG8_STAGE(PG8_SA(1, 1), a1 + hstep, voffA);
;             PG8_WAIT_V(8); PG8_WAIT_L(0); PG8_BAR; PG8_MMA(0, 0, At, B0); PG8_MMA(0, 1, At, B1); PG8_BAR; PG8_SCHED;
;             PG8_LDA(At, 0, 1); PG8_STAGE(PG8_SB(0, 0), b2, voffB); PG8_STAGE(PG8_SB(0, 1), b2 + hstep, voffB); PG8_STAGE(PG8_SA(0, 0), a2, voffA);
;             PG8_WAIT_V(8); PG8_WAIT_L(0); PG8_BAR; PG8_MMA(1, 0, At, B0); PG8_MMA(1, 1, At, B1); PG8_BAR; PG8_SCHED;
;             PG8_LDB(B0, 1, 0); PG8_LDB(B1, 1, 1); PG8_SCHED; PG8_LDA(At, 1, 0); PG8_STAGE(PG8_SA(0, 1), a2 + hstep, voffA);
;             PG8_WAIT_V(8); PG8_WAIT_L(0); PG8_BAR; PG8_MMA(0, 0, At, B0); PG8_MMA(0, 1, At, B1); PG8_BAR; PG8_SCHED;
;             PG8_LDA(At, 1, 1); PG8_STAGE(PG8_SB(1, 0), b3, voffB); PG8_STAGE(PG8_SB(1, 1), b3 + hstep, voffB); PG8_STAGE(PG8_SA(1, 0), a3, voffA);
;             PG8_WAIT_V(8); PG8_WAIT_L(0); PG8_BAR; PG8_MMA(1, 0, At, B0); PG8_MMA(1, 1, At, B1); PG8_BAR; PG8_SCHED;
.LBB0_1827:
	ds_read_b128 v[170:173], v151
	ds_read_b128 v[174:177], v153
	ds_read_b128 v[178:181], v155
	ds_read_b128 v[182:185], v156
	ds_read_b128 v[186:189], v157
	ds_read_b128 v[190:193], v158
	ds_read_b128 v[194:197], v159
	ds_read_b128 v[198:201], v160
	s_add_u32 s0, s44, 0xfffc0080
	s_addc_u32 s1, s45, -1
	s_cmp_eq_u32 s81, 12
	s_cselect_b32 s47, s39, s1
	s_cselect_b32 s46, s75, s0
	s_cselect_b32 s1, s37, s80
	s_cselect_b32 s0, s78, s79
	s_mov_b32 m0, s67
	v_lshl_add_u64 v[234:235], s[44:45], 0, v[138:139]
	ds_read_b128 v[202:205], v149
	ds_read_b128 v[206:209], v149 offset:1024
	ds_read_b128 v[210:213], v149 offset:2048
	ds_read_b128 v[214:217], v149 offset:3072
	ds_read_b128 v[218:221], v149 offset:4096
	ds_read_b128 v[222:225], v149 offset:5120
	ds_read_b128 v[226:229], v149 offset:6144
	ds_read_b128 v[230:233], v149 offset:7168
	global_load_lds_dwordx4 v[234:235], off
	v_lshl_add_u64 v[234:235], s[44:45], 0, v[136:137]
	s_mov_b32 m0, s68
	s_nop 0
	global_load_lds_dwordx4 v[234:235], off
	s_waitcnt vmcnt(8)
	s_waitcnt lgkmcnt(0)
	s_barrier
	v_mfma_f32_16x16x32_bf16 v[124:127], v[170:173], v[202:205], v[124:127]
	v_mfma_f32_16x16x32_bf16 v[120:123], v[178:181], v[202:205], v[120:123]
	v_mfma_f32_16x16x32_bf16 v[108:111], v[170:173], v[210:213], v[108:111]
	v_mfma_f32_16x16x32_bf16 v[104:107], v[178:181], v[210:213], v[104:107]
	v_mfma_f32_16x16x32_bf16 v[92:95], v[170:173], v[218:221], v[92:95]
	v_mfma_f32_16x16x32_bf16 v[88:91], v[178:181], v[218:221], v[88:91]
	v_mfma_f32_16x16x32_bf16 v[76:79], v[170:173], v[226:229], v[76:79]
	v_mfma_f32_16x16x32_bf16 v[72:75], v[178:181], v[226:229], v[72:75]
	v_mfma_f32_16x16x32_bf16 v[124:127], v[174:177], v[206:209], v[124:127]
	v_mfma_f32_16x16x32_bf16 v[120:123], v[182:185], v[206:209], v[120:123]
	v_mfma_f32_16x16x32_bf16 v[108:111], v[174:177], v[214:217], v[108:111]
	v_mfma_f32_16x16x32_bf16 v[104:107], v[182:185], v[214:217], v[104:107]
	v_mfma_f32_16x16x32_bf16 v[92:95], v[174:177], v[222:225], v[92:95]
	v_mfma_f32_16x16x32_bf16 v[88:91], v[182:185], v[222:225], v[88:91]
	v_mfma_f32_16x16x32_bf16 v[76:79], v[174:177], v[230:233], v[76:79]
	v_mfma_f32_16x16x32_bf16 v[72:75], v[182:185], v[230:233], v[72:75]
	v_mfma_f32_16x16x32_bf16 v[116:119], v[186:189], v[202:205], v[116:119]
	v_mfma_f32_16x16x32_bf16 v[112:115], v[194:197], v[202:205], v[112:115]
	v_mfma_f32_16x16x32_bf16 v[100:103], v[186:189], v[210:213], v[100:103]
	v_mfma_f32_16x16x32_bf16 v[96:99], v[194:197], v[210:213], v[96:99]
	v_mfma_f32_16x16x32_bf16 v[84:87], v[186:189], v[218:221], v[84:87]
	v_mfma_f32_16x16x32_bf16 v[80:83], v[194:197], v[218:221], v[80:83]
	v_mfma_f32_16x16x32_bf16 v[68:71], v[186:189], v[226:229], v[68:71]
	v_mfma_f32_16x16x32_bf16 v[64:67], v[194:197], v[226:229], v[64:67]
	v_mfma_f32_16x16x32_bf16 v[116:119], v[190:193], v[206:209], v[116:119]
	v_mfma_f32_16x16x32_bf16 v[112:115], v[198:201], v[206:209], v[112:115]
	v_mfma_f32_16x16x32_bf16 v[100:103], v[190:193], v[214:217], v[100:103]
	v_mfma_f32_16x16x32_bf16 v[96:99], v[198:201], v[214:217], v[96:99]
	v_mfma_f32_16x16x32_bf16 v[84:87], v[190:193], v[222:225], v[84:87]
	v_mfma_f32_16x16x32_bf16 v[80:83], v[198:201], v[222:225], v[80:83]
	v_mfma_f32_16x16x32_bf16 v[68:71], v[190:193], v[230:233], v[68:71]
	v_mfma_f32_16x16x32_bf16 v[64:67], v[198:201], v[230:233], v[64:67]
	s_barrier
	s_mov_b32 m0, s5
	v_lshl_add_u64 v[234:235], s[0:1], 0, v[130:131]
	s_add_u32 s82, s0, 0x40000
	ds_read_b128 v[202:205], v149 offset:16384
	ds_read_b128 v[206:209], v149 offset:17408
	ds_read_b128 v[210:213], v149 offset:18432
	ds_read_b128 v[214:217], v149 offset:19456
	ds_read_b128 v[218:221], v149 offset:20480
	ds_read_b128 v[222:225], v149 offset:21504
	ds_read_b128 v[226:229], v149 offset:22528
	ds_read_b128 v[230:233], v149 offset:23552
	global_load_lds_dwordx4 v[234:235], off
	v_lshl_add_u64 v[236:237], s[0:1], 0, v[134:135]
	s_mov_b32 m0, s51
	s_addc_u32 s83, s1, 0
	global_load_lds_dwordx4 v[236:237], off
	v_lshl_add_u64 v[238:239], s[82:83], 0, v[130:131]
	s_mov_b32 m0, s52
	v_lshl_add_u64 v[240:241], s[46:47], 0, v[132:133]
	global_load_lds_dwordx4 v[238:239], off
	v_lshl_add_u64 v[238:239], s[82:83], 0, v[134:135]
	s_mov_b32 m0, s53
	s_nop 0
	global_load_lds_dwordx4 v[238:239], off
	v_lshl_add_u64 v[238:239], s[46:47], 0, v[128:129]
	s_mov_b32 m0, s50
	s_nop 0
	global_load_lds_dwordx4 v[238:239], off
	s_mov_b32 m0, s54
	s_nop 0
	global_load_lds_dwordx4 v[240:241], off
	s_waitcnt vmcnt(8)
	s_waitcnt lgkmcnt(0)
	s_barrier
	v_mfma_f32_16x16x32_bf16 v[60:63], v[170:173], v[202:205], v[60:63]
	v_mfma_f32_16x16x32_bf16 v[56:59], v[178:181], v[202:205], v[56:59]
	v_mfma_f32_16x16x32_bf16 v[44:47], v[170:173], v[210:213], v[44:47]
	v_mfma_f32_16x16x32_bf16 v[40:43], v[178:181], v[210:213], v[40:43]
	v_mfma_f32_16x16x32_bf16 v[28:31], v[170:173], v[218:221], v[28:31]
	v_mfma_f32_16x16x32_bf16 v[24:27], v[178:181], v[218:221], v[24:27]
	v_mfma_f32_16x16x32_bf16 v[12:15], v[170:173], v[226:229], v[12:15]
	v_mfma_f32_16x16x32_bf16 v[8:11], v[178:181], v[226:229], v[8:11]
	v_mfma_f32_16x16x32_bf16 v[60:63], v[174:177], v[206:209], v[60:63]
	v_mfma_f32_16x16x32_bf16 v[56:59], v[182:185], v[206:209], v[56:59]
	v_mfma_f32_16x16x32_bf16 v[44:47], v[174:177], v[214:217], v[44:47]
	v_mfma_f32_16x16x32_bf16 v[40:43], v[182:185], v[214:217], v[40:43]
	v_mfma_f32_16x16x32_bf16 v[28:31], v[174:177], v[222:225], v[28:31]
	v_mfma_f32_16x16x32_bf16 v[24:27], v[182:185], v[222:225], v[24:27]
	v_mfma_f32_16x16x32_bf16 v[12:15], v[174:177], v[230:233], v[12:15]
	v_mfma_f32_16x16x32_bf16 v[8:11], v[182:185], v[230:233], v[8:11]
	v_mfma_f32_16x16x32_bf16 v[52:55], v[186:189], v[202:205], v[52:55]
	v_mfma_f32_16x16x32_bf16 v[48:51], v[194:197], v[202:205], v[48:51]
	v_mfma_f32_16x16x32_bf16 v[36:39], v[186:189], v[210:213], v[36:39]
	v_mfma_f32_16x16x32_bf16 v[32:35], v[194:197], v[210:213], v[32:35]
	v_mfma_f32_16x16x32_bf16 v[20:23], v[186:189], v[218:221], v[20:23]
	v_mfma_f32_16x16x32_bf16 v[16:19], v[194:197], v[218:221], v[16:19]
	v_mfma_f32_16x16x32_bf16 v[4:7], v[186:189], v[226:229], v[4:7]
	v_mfma_f32_16x16x32_bf16 v[0:3], v[194:197], v[226:229], v[0:3]
	v_mfma_f32_16x16x32_bf16 v[52:55], v[190:193], v[206:209], v[52:55]
	v_mfma_f32_16x16x32_bf16 v[48:51], v[198:201], v[206:209], v[48:51]
	v_mfma_f32_16x16x32_bf16 v[36:39], v[190:193], v[214:217], v[36:39]
	v_mfma_f32_16x16x32_bf16 v[32:35], v[198:201], v[214:217], v[32:35]
	v_mfma_f32_16x16x32_bf16 v[20:23], v[190:193], v[222:225], v[20:23]
	v_mfma_f32_16x16x32_bf16 v[16:19], v[198:201], v[222:225], v[16:19]
	v_mfma_f32_16x16x32_bf16 v[4:7], v[190:193], v[230:233], v[4:7]
	v_mfma_f32_16x16x32_bf16 v[0:3], v[198:201], v[230:233], v[0:3]
	s_barrier
; #define PG8_STAGE(bufoff, gbase, voff) do { _Pragma("unroll") for (int _i = 0; _i < 2; ++_i) \
;         __builtin_amdgcn_global_load_lds((const unsigned*)((const char*)(gbase) + (voff)[_i]), (PG8_LAS unsigned*)(lds + (bufoff) + ldsw + _i * 8192), 16, 0, 0); } while (0)
; #define PG8_LDA(dst, b, h) do { _Pragma("unroll") for (int m = 0; m < 4; ++m) _Pragma("unroll") for (int k = 0; k < 2; ++k) dst[m][k] = *(const PG8_LAS bf16x8*)(lds + PG8_SA(b, h) + aoff + m * 2048 + k * 1024); } while (0)
; #define PG8_WAIT_V(n) asm volatile("s_waitcnt vmcnt(" #n ")" ::: "memory")
; #define PG8_WAIT_L(n) asm volatile("s_waitcnt lgkmcnt(" #n ")" ::: "memory")
; #define PG8_BAR __builtin_amdgcn_s_barrier()
; template <class Epi, class Sched, bool ALIGN_EPI = false, bool SP2 = false>
; __device__ __forceinline__ void gemm_phase(PG8_LAS unsigned char* lds, const Gemm g, const Sched& S, const Epi& E, const int tid_arg) {
;     ...
;         for (int t = 0; t < nt; t += 2) {
;             const bool last = (t == nt - 2);
;             const char* a1 = cA + (size_t)(t + 1) * kstep;
;             const char* a2 = last ? nA : cA + (size_t)(t + 2) * kstep; const char* b2 = last ? nB : cB + (size_t)(t + 2) * kstep;
;             const char* a3 = a2 + kstep; const char* b3 = b2 + kstep;
;             if (last && has_next) S.a_ready(nxt);
;             if constexpr (SP2) {
;             PG8_LDB(B0, 0, 0); PG8_LDB(B1, 0, 1); PG8_SCHED; PG8_LDA(At, 0, 0); PG8_STAGE(PG8_SA(1, 1), a1 + hstep, voffA);
;             PG8_WAIT_V(8); PG8_WAIT_L(0); PG8_BAR; PG8_MMA(0, 0, At, B0); PG8_MMA(0, 1, At, B1); PG8_BAR; PG8_SCHED;
;             PG8_LDA(At, 0, 1); PG8_STAGE(PG8_SB(0, 0), b2, voffB); PG8_STAGE(PG8_SB(0, 1), b2 + hstep, voffB); PG8_STAGE(PG8_SA(0, 0), a2, voffA);
;             PG8_WAIT_V(8); PG8_WAIT_L(0); PG8_BAR; PG8_MMA(1, 0, At, B0); PG8_MMA(1, 1, At, B1); PG8_BAR; PG8_SCHED;
;             PG8_LDB(B0, 1, 0); PG8_LDB(B1, 1, 1); PG8_SCHED; PG8_LDA(At, 1, 0); PG8_STAGE(PG8_SA(0, 1), a2 + hstep, voffA);
;             PG8_WAIT_V(8); PG8_WAIT_L(0); PG8_BAR; PG8_MMA(0, 0, At, B0); PG8_MMA(0, 1, At, B1); PG8_BAR; PG8_SCHED;
;             PG8_LDA(At, 1, 1); PG8_STAGE(PG8_SB(1, 0), b3, voffB); PG8_STAGE(PG8_SB(1, 1), b3 + hstep, voffB); PG8_STAGE(PG8_SA(1, 0), a3, voffA);
;             PG8_WAIT_V(8); PG8_WAIT_L(0); PG8_BAR; PG8_MMA(1, 0, At, B0); PG8_MMA(1, 1, At, B1); PG8_BAR; PG8_SCHED;
	ds_read_b128 v[170:173], v161
	ds_read_b128 v[174:177], v162
	ds_read_b128 v[178:181], v163
	ds_read_b128 v[182:185], v164
	ds_read_b128 v[186:189], v165
	ds_read_b128 v[190:193], v166
	ds_read_b128 v[194:197], v167
	ds_read_b128 v[198:201], v168
	s_add_u32 s46, s46, 0x40000
	s_addc_u32 s47, s47, 0
	s_mov_b32 m0, s55
	v_lshl_add_u64 v[242:243], s[46:47], 0, v[128:129]
	ds_read_b128 v[202:205], v149 offset:32768
	ds_read_b128 v[206:209], v149 offset:33792
	ds_read_b128 v[210:213], v149 offset:34816
	ds_read_b128 v[214:217], v149 offset:35840
	ds_read_b128 v[218:221], v149 offset:36864
	ds_read_b128 v[222:225], v149 offset:37888
	ds_read_b128 v[226:229], v149 offset:38912
	ds_read_b128 v[230:233], v149 offset:39936
	global_load_lds_dwordx4 v[242:243], off
	v_lshl_add_u64 v[242:243], s[46:47], 0, v[132:133]
	s_mov_b32 m0, s56
	s_nop 0
	global_load_lds_dwordx4 v[242:243], off
	s_waitcnt vmcnt(8)
	s_waitcnt lgkmcnt(0)
	s_barrier
	v_mfma_f32_16x16x32_bf16 v[124:127], v[170:173], v[202:205], v[124:127]
	v_mfma_f32_16x16x32_bf16 v[120:123], v[178:181], v[202:205], v[120:123]
	v_mfma_f32_16x16x32_bf16 v[108:111], v[170:173], v[210:213], v[108:111]
	v_mfma_f32_16x16x32_bf16 v[104:107], v[178:181], v[210:213], v[104:107]
	v_mfma_f32_16x16x32_bf16 v[92:95], v[170:173], v[218:221], v[92:95]
	v_mfma_f32_16x16x32_bf16 v[88:91], v[178:181], v[218:221], v[88:91]
	v_mfma_f32_16x16x32_bf16 v[76:79], v[170:173], v[226:229], v[76:79]
	v_mfma_f32_16x16x32_bf16 v[72:75], v[178:181], v[226:229], v[72:75]
	v_mfma_f32_16x16x32_bf16 v[124:127], v[174:177], v[206:209], v[124:127]
	v_mfma_f32_16x16x32_bf16 v[120:123], v[182:185], v[206:209], v[120:123]
	v_mfma_f32_16x16x32_bf16 v[108:111], v[174:177], v[214:217], v[108:111]
	v_mfma_f32_16x16x32_bf16 v[104:107], v[182:185], v[214:217], v[104:107]
	v_mfma_f32_16x16x32_bf16 v[92:95], v[174:177], v[222:225], v[92:95]
	v_mfma_f32_16x16x32_bf16 v[88:91], v[182:185], v[222:225], v[88:91]
	v_mfma_f32_16x16x32_bf16 v[76:79], v[174:177], v[230:233], v[76:79]
	v_mfma_f32_16x16x32_bf16 v[72:75], v[182:185], v[230:233], v[72:75]
	v_mfma_f32_16x16x32_bf16 v[116:119], v[186:189], v[202:205], v[116:119]
	v_mfma_f32_16x16x32_bf16 v[112:115], v[194:197], v[202:205], v[112:115]
	v_mfma_f32_16x16x32_bf16 v[100:103], v[186:189], v[210:213], v[100:103]
	v_mfma_f32_16x16x32_bf16 v[96:99], v[194:197], v[210:213], v[96:99]
	v_mfma_f32_16x16x32_bf16 v[84:87], v[186:189], v[218:221], v[84:87]
	v_mfma_f32_16x16x32_bf16 v[80:83], v[194:197], v[218:221], v[80:83]
	v_mfma_f32_16x16x32_bf16 v[68:71], v[186:189], v[226:229], v[68:71]
	v_mfma_f32_16x16x32_bf16 v[64:67], v[194:197], v[226:229], v[64:67]
	v_mfma_f32_16x16x32_bf16 v[116:119], v[190:193], v[206:209], v[116:119]
	v_mfma_f32_16x16x32_bf16 v[112:115], v[198:201], v[206:209], v[112:115]
	v_mfma_f32_16x16x32_bf16 v[100:103], v[190:193], v[214:217], v[100:103]
	v_mfma_f32_16x16x32_bf16 v[96:99], v[198:201], v[214:217], v[96:99]
	v_mfma_f32_16x16x32_bf16 v[84:87], v[190:193], v[222:225], v[84:87]
	v_mfma_f32_16x16x32_bf16 v[80:83], v[198:201], v[222:225], v[80:83]
	v_mfma_f32_16x16x32_bf16 v[68:71], v[190:193], v[230:233], v[68:71]
	v_mfma_f32_16x16x32_bf16 v[64:67], v[198:201], v[230:233], v[64:67]
	s_barrier
	s_mov_b32 m0, s59
	v_lshl_add_u64 v[234:235], v[234:235], 0, s[16:17]
	s_add_u32 s0, s0, 0x40080
	ds_read_b128 v[202:205], v149 offset:49152
	ds_read_b128 v[206:209], v149 offset:50176
	ds_read_b128 v[210:213], v149 offset:51200
	ds_read_b128 v[214:217], v149 offset:52224
	ds_read_b128 v[218:221], v149 offset:53248
	ds_read_b128 v[222:225], v149 offset:54272
	ds_read_b128 v[226:229], v149 offset:55296
	ds_read_b128 v[230:233], v149 offset:56320
	global_load_lds_dwordx4 v[234:235], off
	v_lshl_add_u64 v[234:235], v[236:237], 0, s[16:17]
	s_mov_b32 m0, s60
	s_addc_u32 s1, s1, 0
	global_load_lds_dwordx4 v[234:235], off
	v_lshl_add_u64 v[234:235], s[0:1], 0, v[130:131]
	s_mov_b32 m0, s63
	s_nop 0
	global_load_lds_dwordx4 v[234:235], off
	v_lshl_add_u64 v[234:235], s[0:1], 0, v[134:135]
	s_mov_b32 m0, s64
	s_nop 0
	global_load_lds_dwordx4 v[234:235], off
	v_lshl_add_u64 v[234:235], v[238:239], 0, s[16:17]
	s_mov_b32 m0, s61
	s_nop 0
	global_load_lds_dwordx4 v[234:235], off
	v_lshl_add_u64 v[234:235], v[240:241], 0, s[16:17]
	s_mov_b32 m0, s62
	s_nop 0
	global_load_lds_dwordx4 v[234:235], off
	s_waitcnt vmcnt(8)
	s_waitcnt lgkmcnt(0)
	s_barrier
	v_mfma_f32_16x16x32_bf16 v[60:63], v[170:173], v[202:205], v[60:63]
	v_mfma_f32_16x16x32_bf16 v[56:59], v[178:181], v[202:205], v[56:59]
	v_mfma_f32_16x16x32_bf16 v[44:47], v[170:173], v[210:213], v[44:47]
	v_mfma_f32_16x16x32_bf16 v[40:43], v[178:181], v[210:213], v[40:43]
	v_mfma_f32_16x16x32_bf16 v[28:31], v[170:173], v[218:221], v[28:31]
	v_mfma_f32_16x16x32_bf16 v[24:27], v[178:181], v[218:221], v[24:27]
	v_mfma_f32_16x16x32_bf16 v[12:15], v[170:173], v[226:229], v[12:15]
	v_mfma_f32_16x16x32_bf16 v[8:11], v[178:181], v[226:229], v[8:11]
	v_mfma_f32_16x16x32_bf16 v[60:63], v[174:177], v[206:209], v[60:63]
	v_mfma_f32_16x16x32_bf16 v[56:59], v[182:185], v[206:209], v[56:59]
	v_mfma_f32_16x16x32_bf16 v[44:47], v[174:177], v[214:217], v[44:47]
	v_mfma_f32_16x16x32_bf16 v[40:43], v[182:185], v[214:217], v[40:43]
	v_mfma_f32_16x16x32_bf16 v[28:31], v[174:177], v[222:225], v[28:31]
	v_mfma_f32_16x16x32_bf16 v[24:27], v[182:185], v[222:225], v[24:27]
	v_mfma_f32_16x16x32_bf16 v[12:15], v[174:177], v[230:233], v[12:15]
	v_mfma_f32_16x16x32_bf16 v[8:11], v[182:185], v[230:233], v[8:11]
	v_mfma_f32_16x16x32_bf16 v[52:55], v[186:189], v[202:205], v[52:55]
	v_mfma_f32_16x16x32_bf16 v[48:51], v[194:197], v[202:205], v[48:51]
	v_mfma_f32_16x16x32_bf16 v[36:39], v[186:189], v[210:213], v[36:39]
	v_mfma_f32_16x16x32_bf16 v[32:35], v[194:197], v[210:213], v[32:35]
	v_mfma_f32_16x16x32_bf16 v[20:23], v[186:189], v[218:221], v[20:23]
	v_mfma_f32_16x16x32_bf16 v[16:19], v[194:197], v[218:221], v[16:19]
	v_mfma_f32_16x16x32_bf16 v[4:7], v[186:189], v[226:229], v[4:7]
	v_mfma_f32_16x16x32_bf16 v[0:3], v[194:197], v[226:229], v[0:3]
	v_mfma_f32_16x16x32_bf16 v[52:55], v[190:193], v[206:209], v[52:55]
	v_mfma_f32_16x16x32_bf16 v[48:51], v[198:201], v[206:209], v[48:51]
	v_mfma_f32_16x16x32_bf16 v[36:39], v[190:193], v[214:217], v[36:39]
	v_mfma_f32_16x16x32_bf16 v[32:35], v[198:201], v[214:217], v[32:35]
	v_mfma_f32_16x16x32_bf16 v[20:23], v[190:193], v[222:225], v[20:23]
	v_mfma_f32_16x16x32_bf16 v[16:19], v[198:201], v[222:225], v[16:19]
	v_mfma_f32_16x16x32_bf16 v[4:7], v[190:193], v[230:233], v[4:7]
	v_mfma_f32_16x16x32_bf16 v[0:3], v[198:201], v[230:233], v[0:3]
	s_barrier
	s_add_i32 s81, s81, 2
	s_add_u32 s79, s79, 0x100
	s_addc_u32 s80, s80, 0
	s_add_u32 s44, s44, 0x100
	s_addc_u32 s45, s45, 0
	s_cmp_gt_u32 s81, 13
	s_cbranch_scc0 .LBB0_1827
	s_and_b64 vcc, exec, s[18:19]
	s_cbranch_vccz .LBB0_1830
	s_barrier

; #define PG8_WAIT_V(n) asm volatile("s_waitcnt vmcnt(" #n ")" ::: "memory")
; #define PG8_BAR __builtin_amdgcn_s_barrier()
; __device__ __forceinline__ void xcd_barrier(const XcdBarrier& b, const bool xb_is_leader) {
;     asm volatile("s_waitcnt vmcnt(0)" ::: "memory");
;     __syncthreads();
;     if (xb_is_leader) {
;         unsigned* bar = b.bar;
;         __builtin_amdgcn_s_waitcnt(0);
;         unsigned nloc = b.st[0], nx = b.st[1];
;         if (nloc == 0u) { xcd_barrier_complete(bar, b.x, nloc, nx); b.st[0] = nloc; b.st[1] = nx; }
; template <class Epi, class Sched, bool ALIGN_EPI = false, bool SP2 = false>
; __device__ __forceinline__ void gemm_phase(PG8_LAS unsigned char* lds, const Gemm g, const Sched& S, const Epi& E, const int tid_arg) {
;     ...
;     PG8_WAIT_V(0);
;     if constexpr (!ALIGN_EPI) { if (wr == 0) PG8_BAR; }
;     PG8_BAR;
.LBB0_1834:
	s_nop 0
	v_mbcnt_lo_u32_b32 v0, s2, 0
	v_mbcnt_hi_u32_b32 v0, s2, v0
	s_setprio 0
	s_waitcnt vmcnt(0)
	s_nop 0
	v_or_b32_e32 v0, s84, v0
	v_cmp_eq_u32_e32 vcc, 0, v0
	s_mov_b64 vcc, 0
	s_barrier
	s_and_saveexec_b64 s[4:5], vcc
	s_cbranch_execz .LBB0_1886
	v_mov_b32_e32 v0, 0x22000
	s_waitcnt vmcnt(0) expcnt(0) lgkmcnt(0)
	ds_read_b32 v2, v0
	v_mov_b32_e32 v0, 0x22004
	ds_read_b32 v0, v0
	s_waitcnt lgkmcnt(1)
	v_cmp_ne_u32_e32 vcc, 0, v2
	s_cbranch_vccnz .LBB0_1850
	v_readlane_b32 s0, v251, 0
	v_readlane_b32 s1, v251, 1
	v_readlane_b32 s2, v251, 2
	s_mul_i32 s2, s1, s2
	s_mul_i32 s2, s2, s0
	s_add_u32 s0, s76, 0x1000
	s_addc_u32 s1, s77, 0
	s_add_u32 s6, s76, 0x1100
	s_addc_u32 s7, s77, 0
	s_add_u32 s10, s76, 0x1200
	s_addc_u32 s11, s77, 0
	s_add_u32 s12, s76, 0x1300
	s_addc_u32 s13, s77, 0
	s_mov_b32 s3, 1
	v_mov_b32_e32 v16, 0
	s_branch .LBB0_1838

; #define AOUT (kargs()->out)
; #define AWS (kargs()->ws)
; #define K_TID ((wave_s << 6) | lane_fresh())
; __device__ __forceinline__ void xcd_barrier(const XcdBarrier& b, const bool xb_is_leader) {
;     ...
;     }
;     __syncthreads();
; }
; __global__ void __launch_bounds__(512, 2) fwd_megakernel(Args a) {
;     ...
;             { int kple = PLED; asm volatile("" : "+s"(kple));
;               pg8::Gemm g{P_PB + (size_t)l * T * PLED, (const bf16_t*)(AWS + WS_WPJ + l * SZ_WPJ), T, DM, kple}; pg8::EpiMulAdd E{SG, P_HB, (l == 1) ? AOUT : (float*)nullptr};
;               pg8::gemm_phase<pg8::EpiMulAdd, pg8::StaticOrder, true, true>(lds, g, S, E, K_TID); }
.LBB0_1886:
	s_or_b64 exec, exec, s[4:5]
	s_movk_i32 s4, 0x100
	s_mov_b64 s[0:1], s[46:47]
	s_waitcnt lgkmcnt(0)
	s_barrier
	s_cselect_b32 s98, 1, 0
	s_cmp_ge_u32 s82, 0x100
	s_cbranch_scc0 .Lprio_skip_22
	s_setprio 1
.Lprio_skip_22:
	s_cmp_lg_u32 s98, 0
	s_mov_b64 s[2:3], s[46:47]
	s_load_dwordx2 s[0:1], s[0:1], 0x98
	s_load_dwordx2 s[12:13], s[2:3], 0x98
	s_mov_b64 s[2:3], s[46:47]
	s_load_dwordx2 s[6:7], s[2:3], 0x98
	s_load_dwordx2 s[10:11], s[46:47], 0x90
	s_mov_b32 s2, -1
	s_nop 0
	v_mbcnt_lo_u32_b32 v0, s2, 0
	v_mbcnt_hi_u32_b32 v0, s2, v0
	v_readlane_b32 s2, v251, 33
	v_readlane_b32 s3, v251, 34
	v_or_b32_e32 v12, s84, v0
	s_and_b64 vcc, exec, s[2:3]
	v_readfirstlane_b32 s23, v12
	s_cbranch_vccnz .LBB0_1889
	s_and_b64 vcc, exec, s[88:89]
	s_cbranch_vccz .LBB0_1894

; #define PG8_STAGE(bufoff, gbase, voff) do { _Pragma("unroll") for (int _i = 0; _i < 2; ++_i) \
;         __builtin_amdgcn_global_load_lds((const unsigned*)((const char*)(gbase) + (voff)[_i]), (PG8_LAS unsigned*)(lds + (bufoff) + ldsw + _i * 8192), 16, 0, 0); } while (0)
; #define PG8_LDA(dst, b, h) do { _Pragma("unroll") for (int m = 0; m < 4; ++m) _Pragma("unroll") for (int k = 0; k < 2; ++k) dst[m][k] = *(const PG8_LAS bf16x8*)(lds + PG8_SA(b, h) + aoff + m * 2048 + k * 1024); } while (0)
; #define PG8_WAIT_V(n) asm volatile("s_waitcnt vmcnt(" #n ")" ::: "memory")
; #define PG8_WAIT_L(n) asm volatile("s_waitcnt lgkmcnt(" #n ")" ::: "memory")
; #define PG8_BAR __builtin_amdgcn_s_barrier()
; template <class Epi, class Sched, bool ALIGN_EPI = false, bool SP2 = false>
; __device__ __forceinline__ void gemm_phase(PG8_LAS unsigned char* lds, const Gemm g, const Sched& S, const Epi& E, const int tid_arg) {
;     ...
;         for (int t = 0; t < nt; t += 2) {
;             const bool last = (t == nt - 2);
;             const char* a1 = cA + (size_t)(t + 1) * kstep;
;             const char* a2 = last ? nA : cA + (size_t)(t + 2) * kstep; const char* b2 = last ? nB : cB + (size_t)(t + 2) * kstep;
;             const char* a3 = a2 + kstep; const char* b3 = b2 + kstep;
;             if (last && has_next) S.a_ready(nxt);
;             if constexpr (SP2) {
;             PG8_LDB(B0, 0, 0); PG8_LDB(B1, 0, 1); PG8_SCHED; PG8_LDA(At, 0, 0); PG8_STAGE(PG8_SA(1, 1), a1 + hstep, voffA);
;             PG8_WAIT_V(8); PG8_WAIT_L(0); PG8_BAR; PG8_MMA(0, 0, At, B0); PG8_MMA(0, 1, At, B1); PG8_BAR; PG8_SCHED;
;             PG8_LDA(At, 0, 1); PG8_STAGE(PG8_SB(0, 0), b2, voffB); PG8_STAGE(PG8_SB(0, 1), b2 + hstep, voffB); PG8_STAGE(PG8_SA(0, 0), a2, voffA);
;             PG8_WAIT_V(8); PG8_WAIT_L(0); PG8_BAR; PG8_MMA(1, 0, At, B0); PG8_MMA(1, 1, At, B1); PG8_BAR; PG8_SCHED;
;             PG8_LDB(B0, 1, 0); PG8_LDB(B1, 1, 1); PG8_SCHED; PG8_LDA(At, 1, 0); PG8_STAGE(PG8_SA(0, 1), a2 + hstep, voffA);
;             PG8_WAIT_V(8); PG8_WAIT_L(0); PG8_BAR; PG8_MMA(0, 0, At, B0); PG8_MMA(0, 1, At, B1); PG8_BAR; PG8_SCHED;
;             PG8_LDA(At, 1, 1); PG8_STAGE(PG8_SB(1, 0), b3, voffB); PG8_STAGE(PG8_SB(1, 1), b3 + hstep, voffB); PG8_STAGE(PG8_SA(1, 0), a3, voffA);
;             PG8_WAIT_V(8); PG8_WAIT_L(0); PG8_BAR; PG8_MMA(1, 0, At, B0); PG8_MMA(1, 1, At, B1); PG8_BAR; PG8_SCHED;
.LBB0_1911:
	ds_read_b128 v[144:147], v157
	ds_read_b128 v[148:151], v158
	ds_read_b128 v[174:177], v159
	ds_read_b128 v[178:181], v160
	ds_read_b128 v[182:185], v161
	ds_read_b128 v[186:189], v162
	ds_read_b128 v[190:193], v163
	ds_read_b128 v[194:197], v164
	s_add_i32 s36, s34, 2
	s_add_u32 s37, s6, 0x80
	s_addc_u32 s35, s7, 0
	s_cmp_eq_u32 s57, s34
	s_cselect_b32 s34, s28, s37
	s_cselect_b32 s35, s29, s35
	s_cselect_b32 s67, s31, s64
	s_cselect_b32 s66, s30, s63
	s_mov_b32 m0, s58
	v_lshl_add_u64 v[152:153], s[6:7], 0, v[138:139]
	ds_read_b128 v[198:201], v156
	ds_read_b128 v[202:205], v156 offset:1024
	ds_read_b128 v[206:209], v156 offset:2048
	ds_read_b128 v[210:213], v156 offset:3072
	ds_read_b128 v[214:217], v156 offset:4096
	ds_read_b128 v[218:221], v156 offset:5120
	ds_read_b128 v[222:225], v156 offset:6144
	ds_read_b128 v[226:229], v156 offset:7168
	global_load_lds_dwordx4 v[152:153], off
	v_lshl_add_u64 v[152:153], s[6:7], 0, v[136:137]
	s_mov_b32 m0, s59
	s_nop 0
	global_load_lds_dwordx4 v[152:153], off
	s_waitcnt vmcnt(8)
	s_waitcnt lgkmcnt(0)
	s_barrier
	v_mfma_f32_16x16x32_bf16 v[124:127], v[144:147], v[198:201], v[124:127]
	v_mfma_f32_16x16x32_bf16 v[120:123], v[174:177], v[198:201], v[120:123]
	v_mfma_f32_16x16x32_bf16 v[108:111], v[144:147], v[206:209], v[108:111]
	v_mfma_f32_16x16x32_bf16 v[104:107], v[174:177], v[206:209], v[104:107]
	v_mfma_f32_16x16x32_bf16 v[92:95], v[144:147], v[214:217], v[92:95]
	v_mfma_f32_16x16x32_bf16 v[88:91], v[174:177], v[214:217], v[88:91]
	v_mfma_f32_16x16x32_bf16 v[76:79], v[144:147], v[222:225], v[76:79]
	v_mfma_f32_16x16x32_bf16 v[72:75], v[174:177], v[222:225], v[72:75]
	v_mfma_f32_16x16x32_bf16 v[124:127], v[148:151], v[202:205], v[124:127]
	v_mfma_f32_16x16x32_bf16 v[120:123], v[178:181], v[202:205], v[120:123]
	v_mfma_f32_16x16x32_bf16 v[108:111], v[148:151], v[210:213], v[108:111]
	v_mfma_f32_16x16x32_bf16 v[104:107], v[178:181], v[210:213], v[104:107]
	v_mfma_f32_16x16x32_bf16 v[92:95], v[148:151], v[218:221], v[92:95]
	v_mfma_f32_16x16x32_bf16 v[88:91], v[178:181], v[218:221], v[88:91]
	v_mfma_f32_16x16x32_bf16 v[76:79], v[148:151], v[226:229], v[76:79]
	v_mfma_f32_16x16x32_bf16 v[72:75], v[178:181], v[226:229], v[72:75]
	v_mfma_f32_16x16x32_bf16 v[116:119], v[182:185], v[198:201], v[116:119]
	v_mfma_f32_16x16x32_bf16 v[112:115], v[190:193], v[198:201], v[112:115]
	v_mfma_f32_16x16x32_bf16 v[100:103], v[182:185], v[206:209], v[100:103]
	v_mfma_f32_16x16x32_bf16 v[96:99], v[190:193], v[206:209], v[96:99]
	v_mfma_f32_16x16x32_bf16 v[84:87], v[182:185], v[214:217], v[84:87]
	v_mfma_f32_16x16x32_bf16 v[80:83], v[190:193], v[214:217], v[80:83]
	v_mfma_f32_16x16x32_bf16 v[68:71], v[182:185], v[222:225], v[68:71]
	v_mfma_f32_16x16x32_bf16 v[64:67], v[190:193], v[222:225], v[64:67]
	v_mfma_f32_16x16x32_bf16 v[116:119], v[186:189], v[202:205], v[116:119]
	v_mfma_f32_16x16x32_bf16 v[112:115], v[194:197], v[202:205], v[112:115]
	v_mfma_f32_16x16x32_bf16 v[100:103], v[186:189], v[210:213], v[100:103]
	v_mfma_f32_16x16x32_bf16 v[96:99], v[194:197], v[210:213], v[96:99]
	v_mfma_f32_16x16x32_bf16 v[84:87], v[186:189], v[218:221], v[84:87]
	v_mfma_f32_16x16x32_bf16 v[80:83], v[194:197], v[218:221], v[80:83]
	v_mfma_f32_16x16x32_bf16 v[68:71], v[186:189], v[226:229], v[68:71]
	v_mfma_f32_16x16x32_bf16 v[64:67], v[194:197], v[226:229], v[64:67]
	s_barrier
	s_mov_b32 m0, s42
	v_lshl_add_u64 v[152:153], s[66:67], 0, v[130:131]
	v_lshl_add_u64 v[230:231], s[66:67], 0, v[134:135]
	s_add_u32 s66, s66, s12
	ds_read_b128 v[198:201], v156 offset:16384
	ds_read_b128 v[202:205], v156 offset:17408
	ds_read_b128 v[206:209], v156 offset:18432
	ds_read_b128 v[210:213], v156 offset:19456
	ds_read_b128 v[214:217], v156 offset:20480
	ds_read_b128 v[218:221], v156 offset:21504
	ds_read_b128 v[222:225], v156 offset:22528
	ds_read_b128 v[226:229], v156 offset:23552
	global_load_lds_dwordx4 v[152:153], off
	s_mov_b32 m0, s43
	s_addc_u32 s67, s67, s13
	global_load_lds_dwordx4 v[230:231], off
	v_lshl_add_u64 v[232:233], s[66:67], 0, v[130:131]
	s_mov_b32 m0, s44
	v_lshl_add_u64 v[234:235], s[66:67], 0, v[134:135]
	global_load_lds_dwordx4 v[232:233], off
	s_mov_b32 m0, s45
	v_lshl_add_u64 v[236:237], s[34:35], 0, v[128:129]
	global_load_lds_dwordx4 v[234:235], off
	s_mov_b32 m0, s41
	v_lshl_add_u64 v[238:239], s[34:35], 0, v[132:133]
	global_load_lds_dwordx4 v[236:237], off
	s_mov_b32 m0, s46
	s_nop 0
	global_load_lds_dwordx4 v[238:239], off
	s_waitcnt vmcnt(8)
	s_waitcnt lgkmcnt(0)
	s_barrier
	v_mfma_f32_16x16x32_bf16 v[60:63], v[144:147], v[198:201], v[60:63]
	v_mfma_f32_16x16x32_bf16 v[56:59], v[174:177], v[198:201], v[56:59]
	v_mfma_f32_16x16x32_bf16 v[44:47], v[144:147], v[206:209], v[44:47]
	v_mfma_f32_16x16x32_bf16 v[40:43], v[174:177], v[206:209], v[40:43]
	v_mfma_f32_16x16x32_bf16 v[28:31], v[144:147], v[214:217], v[28:31]
	v_mfma_f32_16x16x32_bf16 v[24:27], v[174:177], v[214:217], v[24:27]
	v_mfma_f32_16x16x32_bf16 v[12:15], v[144:147], v[222:225], v[12:15]
	v_mfma_f32_16x16x32_bf16 v[8:11], v[174:177], v[222:225], v[8:11]
	v_mfma_f32_16x16x32_bf16 v[60:63], v[148:151], v[202:205], v[60:63]
	v_mfma_f32_16x16x32_bf16 v[56:59], v[178:181], v[202:205], v[56:59]
	v_mfma_f32_16x16x32_bf16 v[44:47], v[148:151], v[210:213], v[44:47]
	v_mfma_f32_16x16x32_bf16 v[40:43], v[178:181], v[210:213], v[40:43]
	v_mfma_f32_16x16x32_bf16 v[28:31], v[148:151], v[218:221], v[28:31]
	v_mfma_f32_16x16x32_bf16 v[24:27], v[178:181], v[218:221], v[24:27]
	v_mfma_f32_16x16x32_bf16 v[12:15], v[148:151], v[226:229], v[12:15]
	v_mfma_f32_16x16x32_bf16 v[8:11], v[178:181], v[226:229], v[8:11]
	v_mfma_f32_16x16x32_bf16 v[52:55], v[182:185], v[198:201], v[52:55]
	v_mfma_f32_16x16x32_bf16 v[48:51], v[190:193], v[198:201], v[48:51]
	v_mfma_f32_16x16x32_bf16 v[36:39], v[182:185], v[206:209], v[36:39]
	v_mfma_f32_16x16x32_bf16 v[32:35], v[190:193], v[206:209], v[32:35]
	v_mfma_f32_16x16x32_bf16 v[20:23], v[182:185], v[214:217], v[20:23]
	v_mfma_f32_16x16x32_bf16 v[16:19], v[190:193], v[214:217], v[16:19]
	v_mfma_f32_16x16x32_bf16 v[4:7], v[182:185], v[222:225], v[4:7]
	v_mfma_f32_16x16x32_bf16 v[0:3], v[190:193], v[222:225], v[0:3]
	v_mfma_f32_16x16x32_bf16 v[52:55], v[186:189], v[202:205], v[52:55]
	v_mfma_f32_16x16x32_bf16 v[48:51], v[194:197], v[202:205], v[48:51]
	v_mfma_f32_16x16x32_bf16 v[36:39], v[186:189], v[210:213], v[36:39]
	v_mfma_f32_16x16x32_bf16 v[32:35], v[194:197], v[210:213], v[32:35]
	v_mfma_f32_16x16x32_bf16 v[20:23], v[186:189], v[218:221], v[20:23]
	v_mfma_f32_16x16x32_bf16 v[16:19], v[194:197], v[218:221], v[16:19]
	v_mfma_f32_16x16x32_bf16 v[4:7], v[186:189], v[226:229], v[4:7]
	v_mfma_f32_16x16x32_bf16 v[0:3], v[194:197], v[226:229], v[0:3]
	s_barrier
; #define PG8_STAGE(bufoff, gbase, voff) do { _Pragma("unroll") for (int _i = 0; _i < 2; ++_i) \
;         __builtin_amdgcn_global_load_lds((const unsigned*)((const char*)(gbase) + (voff)[_i]), (PG8_LAS unsigned*)(lds + (bufoff) + ldsw + _i * 8192), 16, 0, 0); } while (0)
; #define PG8_LDA(dst, b, h) do { _Pragma("unroll") for (int m = 0; m < 4; ++m) _Pragma("unroll") for (int k = 0; k < 2; ++k) dst[m][k] = *(const PG8_LAS bf16x8*)(lds + PG8_SA(b, h) + aoff + m * 2048 + k * 1024); } while (0)
; #define PG8_WAIT_V(n) asm volatile("s_waitcnt vmcnt(" #n ")" ::: "memory")
; #define PG8_WAIT_L(n) asm volatile("s_waitcnt lgkmcnt(" #n ")" ::: "memory")
; #define PG8_BAR __builtin_amdgcn_s_barrier()
; template <class Epi, class Sched, bool ALIGN_EPI = false, bool SP2 = false>
; __device__ __forceinline__ void gemm_phase(PG8_LAS unsigned char* lds, const Gemm g, const Sched& S, const Epi& E, const int tid_arg) {
;     ...
;         for (int t = 0; t < nt; t += 2) {
;             const bool last = (t == nt - 2);
;             const char* a1 = cA + (size_t)(t + 1) * kstep;
;             const char* a2 = last ? nA : cA + (size_t)(t + 2) * kstep; const char* b2 = last ? nB : cB + (size_t)(t + 2) * kstep;
;             const char* a3 = a2 + kstep; const char* b3 = b2 + kstep;
;             if (last && has_next) S.a_ready(nxt);
;             if constexpr (SP2) {
;             PG8_LDB(B0, 0, 0); PG8_LDB(B1, 0, 1); PG8_SCHED; PG8_LDA(At, 0, 0); PG8_STAGE(PG8_SA(1, 1), a1 + hstep, voffA);
;             PG8_WAIT_V(8); PG8_WAIT_L(0); PG8_BAR; PG8_MMA(0, 0, At, B0); PG8_MMA(0, 1, At, B1); PG8_BAR; PG8_SCHED;
;             PG8_LDA(At, 0, 1); PG8_STAGE(PG8_SB(0, 0), b2, voffB); PG8_STAGE(PG8_SB(0, 1), b2 + hstep, voffB); PG8_STAGE(PG8_SA(0, 0), a2, voffA);
;             PG8_WAIT_V(8); PG8_WAIT_L(0); PG8_BAR; PG8_MMA(1, 0, At, B0); PG8_MMA(1, 1, At, B1); PG8_BAR; PG8_SCHED;
;             PG8_LDB(B0, 1, 0); PG8_LDB(B1, 1, 1); PG8_SCHED; PG8_LDA(At, 1, 0); PG8_STAGE(PG8_SA(0, 1), a2 + hstep, voffA);
;             PG8_WAIT_V(8); PG8_WAIT_L(0); PG8_BAR; PG8_MMA(0, 0, At, B0); PG8_MMA(0, 1, At, B1); PG8_BAR; PG8_SCHED;
;             PG8_LDA(At, 1, 1); PG8_STAGE(PG8_SB(1, 0), b3, voffB); PG8_STAGE(PG8_SB(1, 1), b3 + hstep, voffB); PG8_STAGE(PG8_SA(1, 0), a3, voffA);
;             PG8_WAIT_V(8); PG8_WAIT_L(0); PG8_BAR; PG8_MMA(1, 0, At, B0); PG8_MMA(1, 1, At, B1); PG8_BAR; PG8_SCHED;
	ds_read_b128 v[144:147], v165
	ds_read_b128 v[148:151], v166
	ds_read_b128 v[174:177], v167
	ds_read_b128 v[178:181], v168
	ds_read_b128 v[182:185], v169
	ds_read_b128 v[186:189], v170
	ds_read_b128 v[190:193], v171
	ds_read_b128 v[194:197], v172
	s_add_u32 s34, s34, s12
	s_addc_u32 s35, s35, s13
	s_mov_b32 m0, s47
	v_lshl_add_u64 v[240:241], s[34:35], 0, v[128:129]
	ds_read_b128 v[198:201], v156 offset:32768
	ds_read_b128 v[202:205], v156 offset:33792
	ds_read_b128 v[206:209], v156 offset:34816
	ds_read_b128 v[210:213], v156 offset:35840
	ds_read_b128 v[214:217], v156 offset:36864
	ds_read_b128 v[218:221], v156 offset:37888
	ds_read_b128 v[222:225], v156 offset:38912
	ds_read_b128 v[226:229], v156 offset:39936
	global_load_lds_dwordx4 v[240:241], off
	v_lshl_add_u64 v[240:241], s[34:35], 0, v[132:133]
	s_mov_b32 m0, s48
	s_nop 0
	global_load_lds_dwordx4 v[240:241], off
	s_waitcnt vmcnt(8)
	s_waitcnt lgkmcnt(0)
	s_barrier
	v_mfma_f32_16x16x32_bf16 v[124:127], v[144:147], v[198:201], v[124:127]
	v_mfma_f32_16x16x32_bf16 v[120:123], v[174:177], v[198:201], v[120:123]
	v_mfma_f32_16x16x32_bf16 v[108:111], v[144:147], v[206:209], v[108:111]
	v_mfma_f32_16x16x32_bf16 v[104:107], v[174:177], v[206:209], v[104:107]
	v_mfma_f32_16x16x32_bf16 v[92:95], v[144:147], v[214:217], v[92:95]
	v_mfma_f32_16x16x32_bf16 v[88:91], v[174:177], v[214:217], v[88:91]
	v_mfma_f32_16x16x32_bf16 v[76:79], v[144:147], v[222:225], v[76:79]
	v_mfma_f32_16x16x32_bf16 v[72:75], v[174:177], v[222:225], v[72:75]
	v_mfma_f32_16x16x32_bf16 v[124:127], v[148:151], v[202:205], v[124:127]
	v_mfma_f32_16x16x32_bf16 v[120:123], v[178:181], v[202:205], v[120:123]
	v_mfma_f32_16x16x32_bf16 v[108:111], v[148:151], v[210:213], v[108:111]
	v_mfma_f32_16x16x32_bf16 v[104:107], v[178:181], v[210:213], v[104:107]
	v_mfma_f32_16x16x32_bf16 v[92:95], v[148:151], v[218:221], v[92:95]
	v_mfma_f32_16x16x32_bf16 v[88:91], v[178:181], v[218:221], v[88:91]
	v_mfma_f32_16x16x32_bf16 v[76:79], v[148:151], v[226:229], v[76:79]
	v_mfma_f32_16x16x32_bf16 v[72:75], v[178:181], v[226:229], v[72:75]
	v_mfma_f32_16x16x32_bf16 v[116:119], v[182:185], v[198:201], v[116:119]
	v_mfma_f32_16x16x32_bf16 v[112:115], v[190:193], v[198:201], v[112:115]
	v_mfma_f32_16x16x32_bf16 v[100:103], v[182:185], v[206:209], v[100:103]
	v_mfma_f32_16x16x32_bf16 v[96:99], v[190:193], v[206:209], v[96:99]
	v_mfma_f32_16x16x32_bf16 v[84:87], v[182:185], v[214:217], v[84:87]
	v_mfma_f32_16x16x32_bf16 v[80:83], v[190:193], v[214:217], v[80:83]
	v_mfma_f32_16x16x32_bf16 v[68:71], v[182:185], v[222:225], v[68:71]
	v_mfma_f32_16x16x32_bf16 v[64:67], v[190:193], v[222:225], v[64:67]
	v_mfma_f32_16x16x32_bf16 v[116:119], v[186:189], v[202:205], v[116:119]
	v_mfma_f32_16x16x32_bf16 v[112:115], v[194:197], v[202:205], v[112:115]
	v_mfma_f32_16x16x32_bf16 v[100:103], v[186:189], v[210:213], v[100:103]
	v_mfma_f32_16x16x32_bf16 v[96:99], v[194:197], v[210:213], v[96:99]
	v_mfma_f32_16x16x32_bf16 v[84:87], v[186:189], v[218:221], v[84:87]
	v_mfma_f32_16x16x32_bf16 v[80:83], v[194:197], v[218:221], v[80:83]
	v_mfma_f32_16x16x32_bf16 v[68:71], v[186:189], v[226:229], v[68:71]
	v_mfma_f32_16x16x32_bf16 v[64:67], v[194:197], v[226:229], v[64:67]
	s_barrier
	s_mov_b32 m0, s49
	v_lshl_add_u64 v[152:153], v[152:153], 0, s[20:21]
	ds_read_b128 v[198:201], v156 offset:49152
	ds_read_b128 v[202:205], v156 offset:50176
	ds_read_b128 v[206:209], v156 offset:51200
	ds_read_b128 v[210:213], v156 offset:52224
	ds_read_b128 v[214:217], v156 offset:53248
	ds_read_b128 v[218:221], v156 offset:54272
	ds_read_b128 v[222:225], v156 offset:55296
	ds_read_b128 v[226:229], v156 offset:56320
	global_load_lds_dwordx4 v[152:153], off
	v_lshl_add_u64 v[152:153], v[230:231], 0, s[20:21]
	s_mov_b32 m0, s50
	s_nop 0
	global_load_lds_dwordx4 v[152:153], off
	v_lshl_add_u64 v[152:153], v[232:233], 0, s[20:21]
	s_mov_b32 m0, s53
	s_nop 0
	global_load_lds_dwordx4 v[152:153], off
	v_lshl_add_u64 v[152:153], v[234:235], 0, s[20:21]
	s_mov_b32 m0, s54
	s_nop 0
	global_load_lds_dwordx4 v[152:153], off
	v_lshl_add_u64 v[152:153], v[236:237], 0, s[20:21]
	s_mov_b32 m0, s51
	s_nop 0
	global_load_lds_dwordx4 v[152:153], off
	v_lshl_add_u64 v[152:153], v[238:239], 0, s[20:21]
	s_mov_b32 m0, s52
	s_nop 0
	global_load_lds_dwordx4 v[152:153], off
	s_waitcnt vmcnt(8)
	s_waitcnt lgkmcnt(0)
	s_barrier
	v_mfma_f32_16x16x32_bf16 v[60:63], v[144:147], v[198:201], v[60:63]
	v_mfma_f32_16x16x32_bf16 v[56:59], v[174:177], v[198:201], v[56:59]
	v_mfma_f32_16x16x32_bf16 v[44:47], v[144:147], v[206:209], v[44:47]
	v_mfma_f32_16x16x32_bf16 v[40:43], v[174:177], v[206:209], v[40:43]
	v_mfma_f32_16x16x32_bf16 v[28:31], v[144:147], v[214:217], v[28:31]
	v_mfma_f32_16x16x32_bf16 v[24:27], v[174:177], v[214:217], v[24:27]
	v_mfma_f32_16x16x32_bf16 v[12:15], v[144:147], v[222:225], v[12:15]
	v_mfma_f32_16x16x32_bf16 v[8:11], v[174:177], v[222:225], v[8:11]
	v_mfma_f32_16x16x32_bf16 v[60:63], v[148:151], v[202:205], v[60:63]
	v_mfma_f32_16x16x32_bf16 v[56:59], v[178:181], v[202:205], v[56:59]
	v_mfma_f32_16x16x32_bf16 v[44:47], v[148:151], v[210:213], v[44:47]
	v_mfma_f32_16x16x32_bf16 v[40:43], v[178:181], v[210:213], v[40:43]
	v_mfma_f32_16x16x32_bf16 v[28:31], v[148:151], v[218:221], v[28:31]
	v_mfma_f32_16x16x32_bf16 v[24:27], v[178:181], v[218:221], v[24:27]
	v_mfma_f32_16x16x32_bf16 v[12:15], v[148:151], v[226:229], v[12:15]
	v_mfma_f32_16x16x32_bf16 v[8:11], v[178:181], v[226:229], v[8:11]
	v_mfma_f32_16x16x32_bf16 v[52:55], v[182:185], v[198:201], v[52:55]
	v_mfma_f32_16x16x32_bf16 v[48:51], v[190:193], v[198:201], v[48:51]
	v_mfma_f32_16x16x32_bf16 v[36:39], v[182:185], v[206:209], v[36:39]
	v_mfma_f32_16x16x32_bf16 v[32:35], v[190:193], v[206:209], v[32:35]
	v_mfma_f32_16x16x32_bf16 v[20:23], v[182:185], v[214:217], v[20:23]
	v_mfma_f32_16x16x32_bf16 v[16:19], v[190:193], v[214:217], v[16:19]
	v_mfma_f32_16x16x32_bf16 v[4:7], v[182:185], v[222:225], v[4:7]
	v_mfma_f32_16x16x32_bf16 v[0:3], v[190:193], v[222:225], v[0:3]
	v_mfma_f32_16x16x32_bf16 v[52:55], v[186:189], v[202:205], v[52:55]
	v_mfma_f32_16x16x32_bf16 v[48:51], v[194:197], v[202:205], v[48:51]
	v_mfma_f32_16x16x32_bf16 v[36:39], v[186:189], v[210:213], v[36:39]
	v_mfma_f32_16x16x32_bf16 v[32:35], v[194:197], v[210:213], v[32:35]
	v_mfma_f32_16x16x32_bf16 v[20:23], v[186:189], v[218:221], v[20:23]
	v_mfma_f32_16x16x32_bf16 v[16:19], v[194:197], v[218:221], v[16:19]
	v_mfma_f32_16x16x32_bf16 v[4:7], v[186:189], v[226:229], v[4:7]
	v_mfma_f32_16x16x32_bf16 v[0:3], v[194:197], v[226:229], v[0:3]
	s_barrier
	s_add_u32 s63, s63, 0x100
	s_addc_u32 s64, s64, 0
	s_add_u32 s6, s6, 0x100
	s_addc_u32 s7, s7, 0
	s_cmp_ge_i32 s36, s55
	s_mov_b32 s34, s36
	s_cbranch_scc0 .LBB0_1911
